# PEER stage A/B rewritten by hand: lane = (token, head), scores transposed through LDS, Batcher sort16 (63 comparators) + half-cleaner merges with no cross-lane traffic, same keys / candidate set / gat
# speedup vs baseline: 1.0158x; 1.0146x over previous
; #define LAS __attribute__((address_space(3)))
; __device__ __forceinline__ unsigned f2key(float f) { const unsigned u = __float_as_uint(f); return (u & 0x80000000u) ? ~u : (u | 0x80000000u); }
; __device__ __forceinline__ void peer_tile(const Args& A, LAS unsigned char* lds, int tile) {
;     int tid_o = threadIdx.x; asm volatile("" : "+v"(tid_o)); const int tid = tid_o, lane = tid & 63, w = tid >> 6, g = lane >> 4, l15 = lane & 15;
;     const bf16_t* QRY = (const bf16_t*)(A.ws + WS_QRY);
;     const bf16_t* KEYS = (const bf16_t*)(A.ws + WS_KEYS);
;     const bf16_t* ACT = (const bf16_t*)(A.ws + WS_ACT);
;     const float* MOD = (const float*)(A.ws + WS_MOD);
;     LAS unsigned* idx = (LAS unsigned*)(lds + PE_IDX) + (w * 64 + lane) * 33;
;     LAS u32x2* SEL = (LAS u32x2*)(lds + PE_SEL);
;     {
;         const int tg = w & 3, hg = w >> 2, tl = 16 * tg + l15;
;         const size_t m = (size_t)tile * 64 + tl;
;         unsigned LA[4][2][16];
; #pragma unroll
;         for (int hh = 0; hh < 4; ++hh) {
;             const int h = 4 * hg + hh;
; #pragma unroll
;             for (int p = 0; p < 2; ++p) {
;                 const int hp = 2 * h + p;
;                 unsigned k0[16], k1[16];
;                 { const bf16_t* sp = QRY + m * 2048 + hp * 128 + 32 * g;
;                   const u32x4 s0 = *(const u32x4*)sp, s1 = *(const u32x4*)(sp + 8), s2 = *(const u32x4*)(sp + 16), s3 = *(const u32x4*)(sp + 24);
;                   const unsigned sw[16] = {s0.x, s0.y, s0.z, s0.w, s1.x, s1.y, s1.z, s1.w, s2.x, s2.y, s2.z, s2.w, s3.x, s3.y, s3.z, s3.w};
; #pragma unroll
;                   for (int i = 0; i < 16; ++i) {
;                       const float lo = (float)__builtin_bit_cast(_Float16, (unsigned short)(sw[i] & 0xffffu)), hi = (float)__builtin_bit_cast(_Float16, (unsigned short)(sw[i] >> 16));
;                       const unsigned klo = (f2key(lo) & ~127u) | (unsigned)(127 - (32 * g + 2 * i)), khi = (f2key(hi) & ~127u) | (unsigned)(127 - (32 * g + 2 * i + 1));
;                       if (i < 8) { k0[2 * i] = klo; k0[2 * i + 1] = khi; } else { k1[2 * (i - 8)] = klo; k1[2 * (i - 8) + 1] = khi; } } }
.LBB0_699:
	s_mov_b64 exec, -1
	s_mov_b32 s33, 0x80000000
	v_and_b32_e32 v68, 63, v214
	v_lshrrev_b32_e32 v66, 6, v214
	s_nop 0
	v_readfirstlane_b32 s36, v66
	s_lshl_b32 s0, s2, 18
	s_lshl_b32 s1, s36, 9
	s_add_u32 s34, s54, s0
	s_addc_u32 s35, s55, 0
	s_add_u32 s34, s34, s1
	s_addc_u32 s35, s35, 0
	v_lshrrev_b32_e32 v66, 3, v68
	v_and_b32_e32 v64, 7, v68
	v_lshlrev_b32_e32 v64, 4, v64
	v_mul_u32_u24_e32 v65, 0x90, v66
	v_lshl_add_u32 v66, v66, 12, v64
	s_mul_i32 s0, s36, 0x2400
	s_cmp_eq_u32 s36, 7
	s_cselect_b32 s0, 0x21000, s0
	v_add3_u32 v64, v64, v65, s0
	v_mul_u32_u24_e32 v65, 0x90, v68
	v_add_u32_e32 v65, s0, v65
	v_mul_u32_u24_e32 v67, 0x84, v68
	v_lshlrev_b32_e32 v68, 10, v68
	s_lshl_b32 s1, s36, 7
	s_add_i32 s1, s1, 0x11000
	v_add_u32_e32 v67, s0, v67
	v_add_u32_e32 v68, s1, v68
	s_mov_b64 s[38:39], s[34:35]
	global_load_dwordx4 v[0:3], v66, s[38:39] offset:0
	s_add_u32 s38, s38, 0x8000
	s_addc_u32 s39, s39, 0
	global_load_dwordx4 v[4:7], v66, s[38:39] offset:0
	s_add_u32 s38, s38, 0x8000
	s_addc_u32 s39, s39, 0
	global_load_dwordx4 v[8:11], v66, s[38:39] offset:0
	s_add_u32 s38, s38, 0x8000
	s_addc_u32 s39, s39, 0
	global_load_dwordx4 v[12:15], v66, s[38:39] offset:0
	s_add_u32 s38, s38, 0x8000
	s_addc_u32 s39, s39, 0
	global_load_dwordx4 v[16:19], v66, s[38:39] offset:0
	s_add_u32 s38, s38, 0x8000
	s_addc_u32 s39, s39, 0
	global_load_dwordx4 v[20:23], v66, s[38:39] offset:0
	s_add_u32 s38, s38, 0x8000
	s_addc_u32 s39, s39, 0
	global_load_dwordx4 v[24:27], v66, s[38:39] offset:0
	s_add_u32 s38, s38, 0x8000
	s_addc_u32 s39, s39, 0
	global_load_dwordx4 v[28:31], v66, s[38:39] offset:0
	s_mov_b64 s[38:39], s[34:35]
	global_load_dwordx4 v[32:35], v66, s[38:39] offset:128
	s_add_u32 s38, s38, 0x8000
	s_addc_u32 s39, s39, 0
	global_load_dwordx4 v[36:39], v66, s[38:39] offset:128
	s_add_u32 s38, s38, 0x8000
	s_addc_u32 s39, s39, 0
	global_load_dwordx4 v[40:43], v66, s[38:39] offset:128
	s_add_u32 s38, s38, 0x8000
	s_addc_u32 s39, s39, 0
	global_load_dwordx4 v[44:47], v66, s[38:39] offset:128
	s_add_u32 s38, s38, 0x8000
	s_addc_u32 s39, s39, 0
	global_load_dwordx4 v[48:51], v66, s[38:39] offset:128
	s_add_u32 s38, s38, 0x8000
	s_addc_u32 s39, s39, 0
	global_load_dwordx4 v[52:55], v66, s[38:39] offset:128
	s_add_u32 s38, s38, 0x8000
	s_addc_u32 s39, s39, 0
	global_load_dwordx4 v[56:59], v66, s[38:39] offset:128
	s_add_u32 s38, s38, 0x8000
	s_addc_u32 s39, s39, 0
	global_load_dwordx4 v[60:63], v66, s[38:39] offset:128
	s_waitcnt vmcnt(8)
	ds_write_b128 v64, v[0:3] offset:0
	ds_write_b128 v64, v[4:7] offset:1152
	ds_write_b128 v64, v[8:11] offset:2304
	ds_write_b128 v64, v[12:15] offset:3456
	ds_write_b128 v64, v[16:19] offset:4608
	ds_write_b128 v64, v[20:23] offset:5760
	ds_write_b128 v64, v[24:27] offset:6912
	ds_write_b128 v64, v[28:31] offset:8064
	s_waitcnt lgkmcnt(0)
	ds_read_b128 v[0:3], v65 offset:0
	ds_read_b128 v[4:7], v65 offset:16
	ds_read_b128 v[8:11], v65 offset:32
	ds_read_b128 v[12:15], v65 offset:48
	ds_read_b128 v[16:19], v65 offset:64
	ds_read_b128 v[20:23], v65 offset:80
	ds_read_b128 v[24:27], v65 offset:96
	ds_read_b128 v[28:31], v65 offset:112
	s_waitcnt lgkmcnt(0)
	v_cvt_f32_f16_e32 v70, v0
	v_cvt_f32_f16_sdwa v71, v0 dst_sel:DWORD dst_unused:UNUSED_PAD src0_sel:WORD_1
	v_ashrrev_i32_e32 v72, 31, v70
	v_lshl_or_b32 v72, v72, 7, s33
	v_xor_b32_e32 v70, v70, v72
	v_xor_b32_e32 v70, 0x7f, v70
	v_ashrrev_i32_e32 v72, 31, v71
	v_lshl_or_b32 v72, v72, 7, s33
	v_xor_b32_e32 v71, v71, v72
	v_xor_b32_e32 v71, 0x7e, v71
	v_cvt_f32_f16_e32 v72, v1
	v_cvt_f32_f16_sdwa v73, v1 dst_sel:DWORD dst_unused:UNUSED_PAD src0_sel:WORD_1
	v_ashrrev_i32_e32 v74, 31, v72
	v_lshl_or_b32 v74, v74, 7, s33
	v_xor_b32_e32 v72, v72, v74
	v_xor_b32_e32 v72, 0x7d, v72
	v_ashrrev_i32_e32 v74, 31, v73
	v_lshl_or_b32 v74, v74, 7, s33
	v_xor_b32_e32 v73, v73, v74
	v_xor_b32_e32 v73, 0x7c, v73
	v_cvt_f32_f16_e32 v74, v2
	v_cvt_f32_f16_sdwa v75, v2 dst_sel:DWORD dst_unused:UNUSED_PAD src0_sel:WORD_1
	v_ashrrev_i32_e32 v76, 31, v74
	v_lshl_or_b32 v76, v76, 7, s33
	v_xor_b32_e32 v74, v74, v76
	v_xor_b32_e32 v74, 0x7b, v74
	v_ashrrev_i32_e32 v76, 31, v75
	v_lshl_or_b32 v76, v76, 7, s33
	v_xor_b32_e32 v75, v75, v76
	v_xor_b32_e32 v75, 0x7a, v75
	v_cvt_f32_f16_e32 v76, v3
	v_cvt_f32_f16_sdwa v77, v3 dst_sel:DWORD dst_unused:UNUSED_PAD src0_sel:WORD_1
	v_ashrrev_i32_e32 v78, 31, v76
	v_lshl_or_b32 v78, v78, 7, s33
	v_xor_b32_e32 v76, v76, v78
	v_xor_b32_e32 v76, 0x79, v76
	v_ashrrev_i32_e32 v78, 31, v77
	v_lshl_or_b32 v78, v78, 7, s33
	v_xor_b32_e32 v77, v77, v78
	v_xor_b32_e32 v77, 0x78, v77
	v_cvt_f32_f16_e32 v78, v4
	v_cvt_f32_f16_sdwa v79, v4 dst_sel:DWORD dst_unused:UNUSED_PAD src0_sel:WORD_1
	v_ashrrev_i32_e32 v80, 31, v78
	v_lshl_or_b32 v80, v80, 7, s33
	v_xor_b32_e32 v78, v78, v80
	v_xor_b32_e32 v78, 0x77, v78
	v_ashrrev_i32_e32 v80, 31, v79
	v_lshl_or_b32 v80, v80, 7, s33
	v_xor_b32_e32 v79, v79, v80
	v_xor_b32_e32 v79, 0x76, v79
	v_cvt_f32_f16_e32 v80, v5
	v_cvt_f32_f16_sdwa v81, v5 dst_sel:DWORD dst_unused:UNUSED_PAD src0_sel:WORD_1
	v_ashrrev_i32_e32 v82, 31, v80
	v_lshl_or_b32 v82, v82, 7, s33
	v_xor_b32_e32 v80, v80, v82
	v_xor_b32_e32 v80, 0x75, v80
	v_ashrrev_i32_e32 v82, 31, v81
	v_lshl_or_b32 v82, v82, 7, s33
	v_xor_b32_e32 v81, v81, v82
	v_xor_b32_e32 v81, 0x74, v81
	v_cvt_f32_f16_e32 v82, v6
	v_cvt_f32_f16_sdwa v83, v6 dst_sel:DWORD dst_unused:UNUSED_PAD src0_sel:WORD_1
	v_ashrrev_i32_e32 v84, 31, v82
	v_lshl_or_b32 v84, v84, 7, s33
	v_xor_b32_e32 v82, v82, v84
	v_xor_b32_e32 v82, 0x73, v82
	v_ashrrev_i32_e32 v84, 31, v83
	v_lshl_or_b32 v84, v84, 7, s33
	v_xor_b32_e32 v83, v83, v84
	v_xor_b32_e32 v83, 0x72, v83
	v_cvt_f32_f16_e32 v84, v7
; __device__ __forceinline__ unsigned f2key(float f) { const unsigned u = __float_as_uint(f); return (u & 0x80000000u) ? ~u : (u | 0x80000000u); }
; #define CE_DESC(a, b) do { const unsigned _mx = (a) > (b) ? (a) : (b), _mn = (a) > (b) ? (b) : (a); (a) = _mx; (b) = _mn; } while (0)
; __device__ __forceinline__ void sort16_desc(unsigned (&k)[16]) {
; #pragma unroll
;     for (int size = 2; size <= 16; size <<= 1)
; #pragma unroll
;         for (int stride = size >> 1; stride > 0; stride >>= 1)
; #pragma unroll
;             for (int i = 0; i < 16; ++i) { const int j = i ^ stride;
;                 if (j > i) { if ((i & size) == 0) CE_DESC(k[i], k[j]); else CE_DESC(k[j], k[i]); } }
; }
; __device__ __forceinline__ void peer_tile(const Args& A, LAS unsigned char* lds, int tile) {
;     ...
;                   for (int i = 0; i < 16; ++i) {
;                       const float lo = (float)__builtin_bit_cast(_Float16, (unsigned short)(sw[i] & 0xffffu)), hi = (float)__builtin_bit_cast(_Float16, (unsigned short)(sw[i] >> 16));
;                       const unsigned klo = (f2key(lo) & ~127u) | (unsigned)(127 - (32 * g + 2 * i)), khi = (f2key(hi) & ~127u) | (unsigned)(127 - (32 * g + 2 * i + 1));
;                       if (i < 8) { k0[2 * i] = klo; k0[2 * i + 1] = khi; } else { k1[2 * (i - 8)] = klo; k1[2 * (i - 8) + 1] = khi; } } }
;                 sort16_desc(k0); sort16_desc(k1); merge16(k0, k1);
	v_cvt_f32_f16_sdwa v85, v7 dst_sel:DWORD dst_unused:UNUSED_PAD src0_sel:WORD_1
	v_ashrrev_i32_e32 v86, 31, v84
	v_lshl_or_b32 v86, v86, 7, s33
	v_xor_b32_e32 v84, v84, v86
	v_xor_b32_e32 v84, 0x71, v84
	v_ashrrev_i32_e32 v86, 31, v85
	v_lshl_or_b32 v86, v86, 7, s33
	v_xor_b32_e32 v85, v85, v86
	v_xor_b32_e32 v85, 0x70, v85
	v_max_u32_e32 v86, v70, v71
	v_min_u32_e32 v71, v70, v71
	v_max_u32_e32 v70, v72, v73
	v_min_u32_e32 v73, v72, v73
	v_max_u32_e32 v72, v86, v70
	v_min_u32_e32 v70, v86, v70
	v_max_u32_e32 v86, v71, v73
	v_min_u32_e32 v73, v71, v73
	v_max_u32_e32 v71, v86, v70
	v_min_u32_e32 v70, v86, v70
	v_max_u32_e32 v86, v74, v75
	v_min_u32_e32 v75, v74, v75
	v_max_u32_e32 v74, v76, v77
	v_min_u32_e32 v77, v76, v77
	v_max_u32_e32 v76, v86, v74
	v_min_u32_e32 v74, v86, v74
	v_max_u32_e32 v86, v75, v77
	v_min_u32_e32 v77, v75, v77
	v_max_u32_e32 v75, v86, v74
	v_min_u32_e32 v74, v86, v74
	v_max_u32_e32 v86, v72, v76
	v_min_u32_e32 v76, v72, v76
	v_max_u32_e32 v72, v70, v74
	v_min_u32_e32 v74, v70, v74
	v_max_u32_e32 v70, v72, v76
	v_min_u32_e32 v76, v72, v76
	v_max_u32_e32 v72, v71, v75
	v_min_u32_e32 v75, v71, v75
	v_max_u32_e32 v71, v73, v77
	v_min_u32_e32 v77, v73, v77
	v_max_u32_e32 v73, v71, v75
	v_min_u32_e32 v75, v71, v75
	v_max_u32_e32 v71, v72, v70
	v_min_u32_e32 v70, v72, v70
	v_max_u32_e32 v72, v73, v76
	v_min_u32_e32 v76, v73, v76
	v_max_u32_e32 v73, v75, v74
	v_min_u32_e32 v74, v75, v74
	v_max_u32_e32 v75, v78, v79
	v_min_u32_e32 v79, v78, v79
	v_max_u32_e32 v78, v80, v81
	v_min_u32_e32 v81, v80, v81
	v_max_u32_e32 v80, v75, v78
	v_min_u32_e32 v78, v75, v78
	v_max_u32_e32 v75, v79, v81
	v_min_u32_e32 v81, v79, v81
	v_max_u32_e32 v79, v75, v78
	v_min_u32_e32 v78, v75, v78
	v_max_u32_e32 v75, v82, v83
	v_min_u32_e32 v83, v82, v83
	v_max_u32_e32 v82, v84, v85
	v_min_u32_e32 v85, v84, v85
	v_max_u32_e32 v84, v75, v82
	v_min_u32_e32 v82, v75, v82
	v_max_u32_e32 v75, v83, v85
	v_min_u32_e32 v85, v83, v85
	v_max_u32_e32 v83, v75, v82
	v_min_u32_e32 v82, v75, v82
	v_max_u32_e32 v75, v80, v84
	v_min_u32_e32 v84, v80, v84
	v_max_u32_e32 v80, v78, v82
	v_min_u32_e32 v82, v78, v82
	v_max_u32_e32 v78, v80, v84
	v_min_u32_e32 v84, v80, v84
	v_max_u32_e32 v80, v79, v83
	v_min_u32_e32 v83, v79, v83
	v_max_u32_e32 v79, v81, v85
	v_min_u32_e32 v85, v81, v85
	v_max_u32_e32 v81, v79, v83
	v_min_u32_e32 v83, v79, v83
	v_max_u32_e32 v79, v80, v78
	v_min_u32_e32 v78, v80, v78
	v_max_u32_e32 v80, v81, v84
	v_min_u32_e32 v84, v81, v84
	v_max_u32_e32 v81, v83, v82
	v_min_u32_e32 v82, v83, v82
	v_max_u32_e32 v83, v86, v75
	v_min_u32_e32 v75, v86, v75
	v_max_u32_e32 v86, v76, v84
	v_min_u32_e32 v84, v76, v84
	v_max_u32_e32 v76, v86, v75
	v_min_u32_e32 v75, v86, v75
	v_max_u32_e32 v86, v70, v78
	v_min_u32_e32 v78, v70, v78
	v_max_u32_e32 v70, v74, v82
	v_min_u32_e32 v82, v74, v82
	v_max_u32_e32 v74, v70, v78
	v_min_u32_e32 v78, v70, v78
	v_max_u32_e32 v70, v86, v76
	v_min_u32_e32 v76, v86, v76
	v_max_u32_e32 v86, v74, v75
	v_min_u32_e32 v75, v74, v75
	v_max_u32_e32 v74, v78, v84
	v_min_u32_e32 v84, v78, v84
	v_max_u32_e32 v78, v71, v79
	v_min_u32_e32 v79, v71, v79
	v_max_u32_e32 v71, v73, v81
	v_min_u32_e32 v81, v73, v81
	v_max_u32_e32 v73, v71, v79
	v_min_u32_e32 v79, v71, v79
	v_max_u32_e32 v71, v72, v80
	v_min_u32_e32 v80, v72, v80
	v_max_u32_e32 v72, v77, v85
	v_min_u32_e32 v85, v77, v85
	v_max_u32_e32 v77, v72, v80
	v_min_u32_e32 v80, v72, v80
	v_max_u32_e32 v72, v71, v73
	v_min_u32_e32 v73, v71, v73
	v_max_u32_e32 v71, v77, v79
	v_min_u32_e32 v79, v77, v79
	v_max_u32_e32 v77, v80, v81
	v_min_u32_e32 v81, v80, v81
	v_max_u32_e32 v80, v78, v70
	v_min_u32_e32 v70, v78, v70
	v_max_u32_e32 v78, v72, v76
	v_min_u32_e32 v76, v72, v76
	v_max_u32_e32 v72, v73, v86
	v_min_u32_e32 v86, v73, v86
	v_max_u32_e32 v73, v71, v75
	v_min_u32_e32 v75, v71, v75
	v_max_u32_e32 v71, v79, v74
	v_min_u32_e32 v74, v79, v74
	v_max_u32_e32 v79, v77, v84
	v_min_u32_e32 v84, v77, v84
	v_max_u32_e32 v77, v81, v82
	v_min_u32_e32 v82, v81, v82
	v_cvt_f32_f16_e32 v81, v8
	v_cvt_f32_f16_sdwa v87, v8 dst_sel:DWORD dst_unused:UNUSED_PAD src0_sel:WORD_1
	v_ashrrev_i32_e32 v88, 31, v81
	v_lshl_or_b32 v88, v88, 7, s33
	v_xor_b32_e32 v81, v81, v88
	v_xor_b32_e32 v81, 0x6f, v81
	v_ashrrev_i32_e32 v88, 31, v87
	v_lshl_or_b32 v88, v88, 7, s33
	v_xor_b32_e32 v87, v87, v88
	v_xor_b32_e32 v87, 0x6e, v87
	v_cvt_f32_f16_e32 v88, v9
	v_cvt_f32_f16_sdwa v89, v9 dst_sel:DWORD dst_unused:UNUSED_PAD src0_sel:WORD_1
	v_ashrrev_i32_e32 v90, 31, v88
	v_lshl_or_b32 v90, v90, 7, s33
	v_xor_b32_e32 v88, v88, v90
	v_xor_b32_e32 v88, 0x6d, v88
	v_ashrrev_i32_e32 v90, 31, v89
	v_lshl_or_b32 v90, v90, 7, s33
	v_xor_b32_e32 v89, v89, v90
	v_xor_b32_e32 v89, 0x6c, v89
	v_cvt_f32_f16_e32 v90, v10
	v_cvt_f32_f16_sdwa v91, v10 dst_sel:DWORD dst_unused:UNUSED_PAD src0_sel:WORD_1
	v_ashrrev_i32_e32 v92, 31, v90
	v_lshl_or_b32 v92, v92, 7, s33
	v_xor_b32_e32 v90, v90, v92
	v_xor_b32_e32 v90, 0x6b, v90
	v_ashrrev_i32_e32 v92, 31, v91
	v_lshl_or_b32 v92, v92, 7, s33
	v_xor_b32_e32 v91, v91, v92
	v_xor_b32_e32 v91, 0x6a, v91
	v_cvt_f32_f16_e32 v92, v11
	v_cvt_f32_f16_sdwa v93, v11 dst_sel:DWORD dst_unused:UNUSED_PAD src0_sel:WORD_1
	v_ashrrev_i32_e32 v94, 31, v92
	v_lshl_or_b32 v94, v94, 7, s33
	v_xor_b32_e32 v92, v92, v94
	v_xor_b32_e32 v92, 0x69, v92
	v_ashrrev_i32_e32 v94, 31, v93
	v_lshl_or_b32 v94, v94, 7, s33
	v_xor_b32_e32 v93, v93, v94
	v_xor_b32_e32 v93, 0x68, v93
	v_cvt_f32_f16_e32 v94, v12
	v_cvt_f32_f16_sdwa v95, v12 dst_sel:DWORD dst_unused:UNUSED_PAD src0_sel:WORD_1
	v_ashrrev_i32_e32 v96, 31, v94
	v_lshl_or_b32 v96, v96, 7, s33
	v_xor_b32_e32 v94, v94, v96
	v_xor_b32_e32 v94, 0x67, v94
; __device__ __forceinline__ unsigned f2key(float f) { const unsigned u = __float_as_uint(f); return (u & 0x80000000u) ? ~u : (u | 0x80000000u); }
; #define CE_DESC(a, b) do { const unsigned _mx = (a) > (b) ? (a) : (b), _mn = (a) > (b) ? (b) : (a); (a) = _mx; (b) = _mn; } while (0)
; __device__ __forceinline__ void sort16_desc(unsigned (&k)[16]) {
; #pragma unroll
;     for (int size = 2; size <= 16; size <<= 1)
; #pragma unroll
;         for (int stride = size >> 1; stride > 0; stride >>= 1)
; #pragma unroll
;             for (int i = 0; i < 16; ++i) { const int j = i ^ stride;
;                 if (j > i) { if ((i & size) == 0) CE_DESC(k[i], k[j]); else CE_DESC(k[j], k[i]); } }
; }
; __device__ __forceinline__ void merge16(unsigned (&a)[16], const unsigned (&b)[16]) {
; #pragma unroll
;     for (int i = 0; i < 16; ++i) a[i] = a[i] > b[15 - i] ? a[i] : b[15 - i];
; #pragma unroll
;     for (int stride = 8; stride > 0; stride >>= 1)
; #pragma unroll
;         for (int i = 0; i < 16; ++i) { const int j = i ^ stride; if (j > i) CE_DESC(a[i], a[j]); }
; }
; __device__ __forceinline__ void peer_tile(const Args& A, LAS unsigned char* lds, int tile) {
;     ...
;                   for (int i = 0; i < 16; ++i) {
;                       const float lo = (float)__builtin_bit_cast(_Float16, (unsigned short)(sw[i] & 0xffffu)), hi = (float)__builtin_bit_cast(_Float16, (unsigned short)(sw[i] >> 16));
;                       const unsigned klo = (f2key(lo) & ~127u) | (unsigned)(127 - (32 * g + 2 * i)), khi = (f2key(hi) & ~127u) | (unsigned)(127 - (32 * g + 2 * i + 1));
;                       if (i < 8) { k0[2 * i] = klo; k0[2 * i + 1] = khi; } else { k1[2 * (i - 8)] = klo; k1[2 * (i - 8) + 1] = khi; } } }
;                 sort16_desc(k0); sort16_desc(k1); merge16(k0, k1);
	v_ashrrev_i32_e32 v96, 31, v95
	v_lshl_or_b32 v96, v96, 7, s33
	v_xor_b32_e32 v95, v95, v96
	v_xor_b32_e32 v95, 0x66, v95
	v_cvt_f32_f16_e32 v96, v13
	v_cvt_f32_f16_sdwa v97, v13 dst_sel:DWORD dst_unused:UNUSED_PAD src0_sel:WORD_1
	v_ashrrev_i32_e32 v98, 31, v96
	v_lshl_or_b32 v98, v98, 7, s33
	v_xor_b32_e32 v96, v96, v98
	v_xor_b32_e32 v96, 0x65, v96
	v_ashrrev_i32_e32 v98, 31, v97
	v_lshl_or_b32 v98, v98, 7, s33
	v_xor_b32_e32 v97, v97, v98
	v_xor_b32_e32 v97, 0x64, v97
	v_cvt_f32_f16_e32 v98, v14
	v_cvt_f32_f16_sdwa v99, v14 dst_sel:DWORD dst_unused:UNUSED_PAD src0_sel:WORD_1
	v_ashrrev_i32_e32 v100, 31, v98
	v_lshl_or_b32 v100, v100, 7, s33
	v_xor_b32_e32 v98, v98, v100
	v_xor_b32_e32 v98, 0x63, v98
	v_ashrrev_i32_e32 v100, 31, v99
	v_lshl_or_b32 v100, v100, 7, s33
	v_xor_b32_e32 v99, v99, v100
	v_xor_b32_e32 v99, 0x62, v99
	v_cvt_f32_f16_e32 v100, v15
	v_cvt_f32_f16_sdwa v101, v15 dst_sel:DWORD dst_unused:UNUSED_PAD src0_sel:WORD_1
	v_ashrrev_i32_e32 v102, 31, v100
	v_lshl_or_b32 v102, v102, 7, s33
	v_xor_b32_e32 v100, v100, v102
	v_xor_b32_e32 v100, 0x61, v100
	v_ashrrev_i32_e32 v102, 31, v101
	v_lshl_or_b32 v102, v102, 7, s33
	v_xor_b32_e32 v101, v101, v102
	v_xor_b32_e32 v101, 0x60, v101
	v_max_u32_e32 v102, v81, v87
	v_min_u32_e32 v87, v81, v87
	v_max_u32_e32 v81, v88, v89
	v_min_u32_e32 v89, v88, v89
	v_max_u32_e32 v88, v102, v81
	v_min_u32_e32 v81, v102, v81
	v_max_u32_e32 v102, v87, v89
	v_min_u32_e32 v89, v87, v89
	v_max_u32_e32 v87, v102, v81
	v_min_u32_e32 v81, v102, v81
	v_max_u32_e32 v102, v90, v91
	v_min_u32_e32 v91, v90, v91
	v_max_u32_e32 v90, v92, v93
	v_min_u32_e32 v93, v92, v93
	v_max_u32_e32 v92, v102, v90
	v_min_u32_e32 v90, v102, v90
	v_max_u32_e32 v102, v91, v93
	v_min_u32_e32 v93, v91, v93
	v_max_u32_e32 v91, v102, v90
	v_min_u32_e32 v90, v102, v90
	v_max_u32_e32 v102, v88, v92
	v_min_u32_e32 v92, v88, v92
	v_max_u32_e32 v88, v81, v90
	v_min_u32_e32 v90, v81, v90
	v_max_u32_e32 v81, v88, v92
	v_min_u32_e32 v92, v88, v92
	v_max_u32_e32 v88, v87, v91
	v_min_u32_e32 v91, v87, v91
	v_max_u32_e32 v87, v89, v93
	v_min_u32_e32 v93, v89, v93
	v_max_u32_e32 v89, v87, v91
	v_min_u32_e32 v91, v87, v91
	v_max_u32_e32 v87, v88, v81
	v_min_u32_e32 v81, v88, v81
	v_max_u32_e32 v88, v89, v92
	v_min_u32_e32 v92, v89, v92
	v_max_u32_e32 v89, v91, v90
	v_min_u32_e32 v90, v91, v90
	v_max_u32_e32 v91, v94, v95
	v_min_u32_e32 v95, v94, v95
	v_max_u32_e32 v94, v96, v97
	v_min_u32_e32 v97, v96, v97
	v_max_u32_e32 v96, v91, v94
	v_min_u32_e32 v94, v91, v94
	v_max_u32_e32 v91, v95, v97
	v_min_u32_e32 v97, v95, v97
	v_max_u32_e32 v95, v91, v94
	v_min_u32_e32 v94, v91, v94
	v_max_u32_e32 v91, v98, v99
	v_min_u32_e32 v99, v98, v99
	v_max_u32_e32 v98, v100, v101
	v_min_u32_e32 v101, v100, v101
	v_max_u32_e32 v100, v91, v98
	v_min_u32_e32 v98, v91, v98
	v_max_u32_e32 v91, v99, v101
	v_min_u32_e32 v101, v99, v101
	v_max_u32_e32 v99, v91, v98
	v_min_u32_e32 v98, v91, v98
	v_max_u32_e32 v91, v96, v100
	v_min_u32_e32 v100, v96, v100
	v_max_u32_e32 v96, v94, v98
	v_min_u32_e32 v98, v94, v98
	v_max_u32_e32 v94, v96, v100
	v_min_u32_e32 v100, v96, v100
	v_max_u32_e32 v96, v95, v99
	v_min_u32_e32 v99, v95, v99
	v_max_u32_e32 v95, v97, v101
	v_min_u32_e32 v101, v97, v101
	v_max_u32_e32 v97, v95, v99
	v_min_u32_e32 v99, v95, v99
	v_max_u32_e32 v95, v96, v94
	v_min_u32_e32 v94, v96, v94
	v_max_u32_e32 v96, v97, v100
	v_min_u32_e32 v100, v97, v100
	v_max_u32_e32 v97, v99, v98
	v_min_u32_e32 v98, v99, v98
	v_max_u32_e32 v99, v102, v91
	v_min_u32_e32 v91, v102, v91
	v_max_u32_e32 v102, v92, v100
	v_min_u32_e32 v100, v92, v100
	v_max_u32_e32 v92, v102, v91
	v_min_u32_e32 v91, v102, v91
	v_max_u32_e32 v102, v81, v94
	v_min_u32_e32 v94, v81, v94
	v_max_u32_e32 v81, v90, v98
	v_min_u32_e32 v98, v90, v98
	v_max_u32_e32 v90, v81, v94
	v_min_u32_e32 v94, v81, v94
	v_max_u32_e32 v81, v102, v92
	v_min_u32_e32 v92, v102, v92
	v_max_u32_e32 v102, v90, v91
	v_min_u32_e32 v91, v90, v91
	v_max_u32_e32 v90, v94, v100
	v_min_u32_e32 v100, v94, v100
	v_max_u32_e32 v94, v87, v95
	v_min_u32_e32 v95, v87, v95
	v_max_u32_e32 v87, v89, v97
	v_min_u32_e32 v97, v89, v97
	v_max_u32_e32 v89, v87, v95
	v_min_u32_e32 v95, v87, v95
	v_max_u32_e32 v87, v88, v96
	v_min_u32_e32 v96, v88, v96
	v_max_u32_e32 v88, v93, v101
	v_min_u32_e32 v101, v93, v101
	v_max_u32_e32 v93, v88, v96
	v_min_u32_e32 v96, v88, v96
	v_max_u32_e32 v88, v87, v89
	v_min_u32_e32 v89, v87, v89
	v_max_u32_e32 v87, v93, v95
	v_min_u32_e32 v95, v93, v95
	v_max_u32_e32 v93, v96, v97
	v_min_u32_e32 v97, v96, v97
	v_max_u32_e32 v96, v94, v81
	v_min_u32_e32 v81, v94, v81
	v_max_u32_e32 v94, v88, v92
	v_min_u32_e32 v92, v88, v92
	v_max_u32_e32 v88, v89, v102
	v_min_u32_e32 v102, v89, v102
	v_max_u32_e32 v89, v87, v91
	v_min_u32_e32 v91, v87, v91
	v_max_u32_e32 v87, v95, v90
	v_min_u32_e32 v90, v95, v90
	v_max_u32_e32 v95, v93, v100
	v_min_u32_e32 v100, v93, v100
	v_max_u32_e32 v93, v97, v98
	v_min_u32_e32 v98, v97, v98
	v_max_u32_e32 v83, v83, v101
	v_max_u32_e32 v80, v80, v98
	v_max_u32_e32 v70, v70, v93
	v_max_u32_e32 v78, v78, v100
	v_max_u32_e32 v76, v76, v95
	v_max_u32_e32 v72, v72, v90
	v_max_u32_e32 v86, v86, v87
	v_max_u32_e32 v73, v73, v91
	v_max_u32_e32 v75, v75, v89
	v_max_u32_e32 v71, v71, v102
	v_max_u32_e32 v74, v74, v88
	v_max_u32_e32 v79, v79, v92
	v_max_u32_e32 v84, v84, v94
	v_max_u32_e32 v77, v77, v81
	v_max_u32_e32 v82, v82, v96
	v_max_u32_e32 v85, v85, v99
	v_max_u32_e32 v101, v83, v75
	v_min_u32_e32 v75, v83, v75
	v_max_u32_e32 v83, v80, v71
	v_min_u32_e32 v71, v80, v71
	v_max_u32_e32 v80, v70, v74
	v_min_u32_e32 v74, v70, v74
	v_max_u32_e32 v70, v78, v79
	v_min_u32_e32 v79, v78, v79
; __device__ __forceinline__ unsigned f2key(float f) { const unsigned u = __float_as_uint(f); return (u & 0x80000000u) ? ~u : (u | 0x80000000u); }
; #define CE_DESC(a, b) do { const unsigned _mx = (a) > (b) ? (a) : (b), _mn = (a) > (b) ? (b) : (a); (a) = _mx; (b) = _mn; } while (0)
; __device__ __forceinline__ void merge16(unsigned (&a)[16], const unsigned (&b)[16]) {
; #pragma unroll
;     for (int i = 0; i < 16; ++i) a[i] = a[i] > b[15 - i] ? a[i] : b[15 - i];
; #pragma unroll
;     for (int stride = 8; stride > 0; stride >>= 1)
; #pragma unroll
;         for (int i = 0; i < 16; ++i) { const int j = i ^ stride; if (j > i) CE_DESC(a[i], a[j]); }
; }
; __device__ __forceinline__ void peer_tile(const Args& A, LAS unsigned char* lds, int tile) {
;     ...
;                 { const bf16_t* sp = QRY + m * 2048 + hp * 128 + 32 * g;
;                   const u32x4 s0 = *(const u32x4*)sp, s1 = *(const u32x4*)(sp + 8), s2 = *(const u32x4*)(sp + 16), s3 = *(const u32x4*)(sp + 24);
;                   const unsigned sw[16] = {s0.x, s0.y, s0.z, s0.w, s1.x, s1.y, s1.z, s1.w, s2.x, s2.y, s2.z, s2.w, s3.x, s3.y, s3.z, s3.w};
; #pragma unroll
;                   for (int i = 0; i < 16; ++i) {
;                       const float lo = (float)__builtin_bit_cast(_Float16, (unsigned short)(sw[i] & 0xffffu)), hi = (float)__builtin_bit_cast(_Float16, (unsigned short)(sw[i] >> 16));
;                       const unsigned klo = (f2key(lo) & ~127u) | (unsigned)(127 - (32 * g + 2 * i)), khi = (f2key(hi) & ~127u) | (unsigned)(127 - (32 * g + 2 * i + 1));
;                       if (i < 8) { k0[2 * i] = klo; k0[2 * i + 1] = khi; } else { k1[2 * (i - 8)] = klo; k1[2 * (i - 8) + 1] = khi; } } }
	v_max_u32_e32 v78, v76, v84
	v_min_u32_e32 v84, v76, v84
	v_max_u32_e32 v76, v72, v77
	v_min_u32_e32 v77, v72, v77
	v_max_u32_e32 v72, v86, v82
	v_min_u32_e32 v82, v86, v82
	v_max_u32_e32 v86, v73, v85
	v_min_u32_e32 v85, v73, v85
	v_max_u32_e32 v73, v101, v78
	v_min_u32_e32 v78, v101, v78
	v_max_u32_e32 v101, v83, v76
	v_min_u32_e32 v76, v83, v76
	v_max_u32_e32 v83, v80, v72
	v_min_u32_e32 v72, v80, v72
	v_max_u32_e32 v80, v70, v86
	v_min_u32_e32 v86, v70, v86
	v_max_u32_e32 v70, v75, v84
	v_min_u32_e32 v84, v75, v84
	v_max_u32_e32 v75, v71, v77
	v_min_u32_e32 v77, v71, v77
	v_max_u32_e32 v71, v74, v82
	v_min_u32_e32 v82, v74, v82
	v_max_u32_e32 v74, v79, v85
	v_min_u32_e32 v85, v79, v85
	v_max_u32_e32 v79, v73, v83
	v_min_u32_e32 v83, v73, v83
	v_max_u32_e32 v73, v101, v80
	v_min_u32_e32 v80, v101, v80
	v_max_u32_e32 v101, v78, v72
	v_min_u32_e32 v72, v78, v72
	v_max_u32_e32 v78, v76, v86
	v_min_u32_e32 v86, v76, v86
	v_max_u32_e32 v76, v70, v71
	v_min_u32_e32 v71, v70, v71
	v_max_u32_e32 v70, v75, v74
	v_min_u32_e32 v74, v75, v74
	v_max_u32_e32 v75, v84, v82
	v_min_u32_e32 v82, v84, v82
	v_max_u32_e32 v84, v77, v85
	v_min_u32_e32 v85, v77, v85
	v_max_u32_e32 v77, v79, v73
	v_min_u32_e32 v73, v79, v73
	v_max_u32_e32 v79, v83, v80
	v_min_u32_e32 v80, v83, v80
	v_max_u32_e32 v83, v101, v78
	v_min_u32_e32 v78, v101, v78
	v_max_u32_e32 v101, v72, v86
	v_min_u32_e32 v86, v72, v86
	v_max_u32_e32 v72, v76, v70
	v_min_u32_e32 v70, v76, v70
	v_max_u32_e32 v76, v71, v74
	v_min_u32_e32 v74, v71, v74
	v_max_u32_e32 v71, v75, v84
	v_min_u32_e32 v84, v75, v84
	v_max_u32_e32 v75, v82, v85
	v_min_u32_e32 v85, v82, v85
	v_cvt_f32_f16_e32 v82, v16
	v_cvt_f32_f16_sdwa v98, v16 dst_sel:DWORD dst_unused:UNUSED_PAD src0_sel:WORD_1
	v_ashrrev_i32_e32 v93, 31, v82
	v_lshl_or_b32 v93, v93, 7, s33
	v_xor_b32_e32 v82, v82, v93
	v_xor_b32_e32 v82, 0x5f, v82
	v_ashrrev_i32_e32 v93, 31, v98
	v_lshl_or_b32 v93, v93, 7, s33
	v_xor_b32_e32 v98, v98, v93
	v_xor_b32_e32 v98, 0x5e, v98
	v_cvt_f32_f16_e32 v93, v17
	v_cvt_f32_f16_sdwa v100, v17 dst_sel:DWORD dst_unused:UNUSED_PAD src0_sel:WORD_1
	v_ashrrev_i32_e32 v95, 31, v93
	v_lshl_or_b32 v95, v95, 7, s33
	v_xor_b32_e32 v93, v93, v95
	v_xor_b32_e32 v93, 0x5d, v93
	v_ashrrev_i32_e32 v95, 31, v100
	v_lshl_or_b32 v95, v95, 7, s33
	v_xor_b32_e32 v100, v100, v95
	v_xor_b32_e32 v100, 0x5c, v100
	v_cvt_f32_f16_e32 v95, v18
	v_cvt_f32_f16_sdwa v90, v18 dst_sel:DWORD dst_unused:UNUSED_PAD src0_sel:WORD_1
	v_ashrrev_i32_e32 v87, 31, v95
	v_lshl_or_b32 v87, v87, 7, s33
	v_xor_b32_e32 v95, v95, v87
	v_xor_b32_e32 v95, 0x5b, v95
	v_ashrrev_i32_e32 v87, 31, v90
	v_lshl_or_b32 v87, v87, 7, s33
	v_xor_b32_e32 v90, v90, v87
	v_xor_b32_e32 v90, 0x5a, v90
	v_cvt_f32_f16_e32 v87, v19
	v_cvt_f32_f16_sdwa v91, v19 dst_sel:DWORD dst_unused:UNUSED_PAD src0_sel:WORD_1
	v_ashrrev_i32_e32 v89, 31, v87
	v_lshl_or_b32 v89, v89, 7, s33
	v_xor_b32_e32 v87, v87, v89
	v_xor_b32_e32 v87, 0x59, v87
	v_ashrrev_i32_e32 v89, 31, v91
	v_lshl_or_b32 v89, v89, 7, s33
	v_xor_b32_e32 v91, v91, v89
	v_xor_b32_e32 v91, 0x58, v91
	v_cvt_f32_f16_e32 v89, v20
	v_cvt_f32_f16_sdwa v102, v20 dst_sel:DWORD dst_unused:UNUSED_PAD src0_sel:WORD_1
	v_ashrrev_i32_e32 v88, 31, v89
	v_lshl_or_b32 v88, v88, 7, s33
	v_xor_b32_e32 v89, v89, v88
	v_xor_b32_e32 v89, 0x57, v89
	v_ashrrev_i32_e32 v88, 31, v102
	v_lshl_or_b32 v88, v88, 7, s33
	v_xor_b32_e32 v102, v102, v88
	v_xor_b32_e32 v102, 0x56, v102
	v_cvt_f32_f16_e32 v88, v21
	v_cvt_f32_f16_sdwa v92, v21 dst_sel:DWORD dst_unused:UNUSED_PAD src0_sel:WORD_1
	v_ashrrev_i32_e32 v94, 31, v88
	v_lshl_or_b32 v94, v94, 7, s33
	v_xor_b32_e32 v88, v88, v94
	v_xor_b32_e32 v88, 0x55, v88
	v_ashrrev_i32_e32 v94, 31, v92
	v_lshl_or_b32 v94, v94, 7, s33
	v_xor_b32_e32 v92, v92, v94
	v_xor_b32_e32 v92, 0x54, v92
	v_cvt_f32_f16_e32 v94, v22
	v_cvt_f32_f16_sdwa v81, v22 dst_sel:DWORD dst_unused:UNUSED_PAD src0_sel:WORD_1
	v_ashrrev_i32_e32 v96, 31, v94
	v_lshl_or_b32 v96, v96, 7, s33
	v_xor_b32_e32 v94, v94, v96
	v_xor_b32_e32 v94, 0x53, v94
	v_ashrrev_i32_e32 v96, 31, v81
	v_lshl_or_b32 v96, v96, 7, s33
	v_xor_b32_e32 v81, v81, v96
	v_xor_b32_e32 v81, 0x52, v81
	v_cvt_f32_f16_e32 v96, v23
	v_cvt_f32_f16_sdwa v99, v23 dst_sel:DWORD dst_unused:UNUSED_PAD src0_sel:WORD_1
	v_ashrrev_i32_e32 v97, 31, v96
	v_lshl_or_b32 v97, v97, 7, s33
	v_xor_b32_e32 v96, v96, v97
	v_xor_b32_e32 v96, 0x51, v96
	v_ashrrev_i32_e32 v97, 31, v99
	v_lshl_or_b32 v97, v97, 7, s33
	v_xor_b32_e32 v99, v99, v97
	v_xor_b32_e32 v99, 0x50, v99
	v_max_u32_e32 v97, v82, v98
	v_min_u32_e32 v98, v82, v98
	v_max_u32_e32 v82, v93, v100
	v_min_u32_e32 v100, v93, v100
	v_max_u32_e32 v93, v97, v82
	v_min_u32_e32 v82, v97, v82
	v_max_u32_e32 v97, v98, v100
	v_min_u32_e32 v100, v98, v100
	v_max_u32_e32 v98, v97, v82
	v_min_u32_e32 v82, v97, v82
	v_max_u32_e32 v97, v95, v90
	v_min_u32_e32 v90, v95, v90
	v_max_u32_e32 v95, v87, v91
	v_min_u32_e32 v91, v87, v91
	v_max_u32_e32 v87, v97, v95
	v_min_u32_e32 v95, v97, v95
	v_max_u32_e32 v97, v90, v91
	v_min_u32_e32 v91, v90, v91
	v_max_u32_e32 v90, v97, v95
	v_min_u32_e32 v95, v97, v95
	v_max_u32_e32 v97, v93, v87
	v_min_u32_e32 v87, v93, v87
	v_max_u32_e32 v93, v82, v95
	v_min_u32_e32 v95, v82, v95
	v_max_u32_e32 v82, v93, v87
	v_min_u32_e32 v87, v93, v87
	v_max_u32_e32 v93, v98, v90
	v_min_u32_e32 v90, v98, v90
	v_max_u32_e32 v98, v100, v91
	v_min_u32_e32 v91, v100, v91
	v_max_u32_e32 v100, v98, v90
	v_min_u32_e32 v90, v98, v90
	v_max_u32_e32 v98, v93, v82
	v_min_u32_e32 v82, v93, v82
	v_max_u32_e32 v93, v100, v87
	v_min_u32_e32 v87, v100, v87
	v_max_u32_e32 v100, v90, v95
	v_min_u32_e32 v95, v90, v95
	v_max_u32_e32 v90, v89, v102
; #define CE_DESC(a, b) do { const unsigned _mx = (a) > (b) ? (a) : (b), _mn = (a) > (b) ? (b) : (a); (a) = _mx; (b) = _mn; } while (0)
; __device__ __forceinline__ void sort16_desc(unsigned (&k)[16]) {
; #pragma unroll
;     for (int size = 2; size <= 16; size <<= 1)
; #pragma unroll
;         for (int stride = size >> 1; stride > 0; stride >>= 1)
; #pragma unroll
;             for (int i = 0; i < 16; ++i) { const int j = i ^ stride;
;                 if (j > i) { if ((i & size) == 0) CE_DESC(k[i], k[j]); else CE_DESC(k[j], k[i]); } }
; }
; __device__ __forceinline__ void merge16(unsigned (&a)[16], const unsigned (&b)[16]) {
; #pragma unroll
;     for (int i = 0; i < 16; ++i) a[i] = a[i] > b[15 - i] ? a[i] : b[15 - i];
; #pragma unroll
;     for (int stride = 8; stride > 0; stride >>= 1)
; #pragma unroll
;         for (int i = 0; i < 16; ++i) { const int j = i ^ stride; if (j > i) CE_DESC(a[i], a[j]); }
; }
	v_min_u32_e32 v102, v89, v102
	v_max_u32_e32 v89, v88, v92
	v_min_u32_e32 v92, v88, v92
	v_max_u32_e32 v88, v90, v89
	v_min_u32_e32 v89, v90, v89
	v_max_u32_e32 v90, v102, v92
	v_min_u32_e32 v92, v102, v92
	v_max_u32_e32 v102, v90, v89
	v_min_u32_e32 v89, v90, v89
	v_max_u32_e32 v90, v94, v81
	v_min_u32_e32 v81, v94, v81
	v_max_u32_e32 v94, v96, v99
	v_min_u32_e32 v99, v96, v99
	v_max_u32_e32 v96, v90, v94
	v_min_u32_e32 v94, v90, v94
	v_max_u32_e32 v90, v81, v99
	v_min_u32_e32 v99, v81, v99
	v_max_u32_e32 v81, v90, v94
	v_min_u32_e32 v94, v90, v94
	v_max_u32_e32 v90, v88, v96
	v_min_u32_e32 v96, v88, v96
	v_max_u32_e32 v88, v89, v94
	v_min_u32_e32 v94, v89, v94
	v_max_u32_e32 v89, v88, v96
	v_min_u32_e32 v96, v88, v96
	v_max_u32_e32 v88, v102, v81
	v_min_u32_e32 v81, v102, v81
	v_max_u32_e32 v102, v92, v99
	v_min_u32_e32 v99, v92, v99
	v_max_u32_e32 v92, v102, v81
	v_min_u32_e32 v81, v102, v81
	v_max_u32_e32 v102, v88, v89
	v_min_u32_e32 v89, v88, v89
	v_max_u32_e32 v88, v92, v96
	v_min_u32_e32 v96, v92, v96
	v_max_u32_e32 v92, v81, v94
	v_min_u32_e32 v94, v81, v94
	v_max_u32_e32 v81, v97, v90
	v_min_u32_e32 v90, v97, v90
	v_max_u32_e32 v97, v87, v96
	v_min_u32_e32 v96, v87, v96
	v_max_u32_e32 v87, v97, v90
	v_min_u32_e32 v90, v97, v90
	v_max_u32_e32 v97, v82, v89
	v_min_u32_e32 v89, v82, v89
	v_max_u32_e32 v82, v95, v94
	v_min_u32_e32 v94, v95, v94
	v_max_u32_e32 v95, v82, v89
	v_min_u32_e32 v89, v82, v89
	v_max_u32_e32 v82, v97, v87
	v_min_u32_e32 v87, v97, v87
	v_max_u32_e32 v97, v95, v90
	v_min_u32_e32 v90, v95, v90
	v_max_u32_e32 v95, v89, v96
	v_min_u32_e32 v96, v89, v96
	v_max_u32_e32 v89, v98, v102
	v_min_u32_e32 v102, v98, v102
	v_max_u32_e32 v98, v100, v92
	v_min_u32_e32 v92, v100, v92
	v_max_u32_e32 v100, v98, v102
	v_min_u32_e32 v102, v98, v102
	v_max_u32_e32 v98, v93, v88
	v_min_u32_e32 v88, v93, v88
	v_max_u32_e32 v93, v91, v99
	v_min_u32_e32 v99, v91, v99
	v_max_u32_e32 v91, v93, v88
	v_min_u32_e32 v88, v93, v88
	v_max_u32_e32 v93, v98, v100
	v_min_u32_e32 v100, v98, v100
	v_max_u32_e32 v98, v91, v102
	v_min_u32_e32 v102, v91, v102
	v_max_u32_e32 v91, v88, v92
	v_min_u32_e32 v92, v88, v92
	v_max_u32_e32 v88, v89, v82
	v_min_u32_e32 v82, v89, v82
	v_max_u32_e32 v89, v93, v87
	v_min_u32_e32 v87, v93, v87
	v_max_u32_e32 v93, v100, v97
	v_min_u32_e32 v97, v100, v97
	v_max_u32_e32 v100, v98, v90
	v_min_u32_e32 v90, v98, v90
	v_max_u32_e32 v98, v102, v95
	v_min_u32_e32 v95, v102, v95
	v_max_u32_e32 v102, v91, v96
	v_min_u32_e32 v96, v91, v96
	v_max_u32_e32 v91, v92, v94
	v_min_u32_e32 v94, v92, v94
	v_max_u32_e32 v77, v77, v99
	v_max_u32_e32 v73, v73, v94
	v_max_u32_e32 v79, v79, v91
	v_max_u32_e32 v80, v80, v96
	v_max_u32_e32 v83, v83, v102
	v_max_u32_e32 v78, v78, v95
	v_max_u32_e32 v101, v101, v98
	v_max_u32_e32 v86, v86, v90
	v_max_u32_e32 v72, v72, v100
	v_max_u32_e32 v70, v70, v97
	v_max_u32_e32 v76, v76, v93
	v_max_u32_e32 v74, v74, v87
	v_max_u32_e32 v71, v71, v89
	v_max_u32_e32 v84, v84, v82
	v_max_u32_e32 v75, v75, v88
	v_max_u32_e32 v85, v85, v81
	v_max_u32_e32 v99, v77, v72
	v_min_u32_e32 v72, v77, v72
	v_max_u32_e32 v77, v73, v70
	v_min_u32_e32 v70, v73, v70
	v_max_u32_e32 v73, v79, v76
	v_min_u32_e32 v76, v79, v76
	v_max_u32_e32 v79, v80, v74
	v_min_u32_e32 v74, v80, v74
	v_max_u32_e32 v80, v83, v71
	v_min_u32_e32 v71, v83, v71
	v_max_u32_e32 v83, v78, v84
	v_min_u32_e32 v84, v78, v84
	v_max_u32_e32 v78, v101, v75
	v_min_u32_e32 v75, v101, v75
	v_max_u32_e32 v101, v86, v85
	v_min_u32_e32 v85, v86, v85
	v_max_u32_e32 v86, v99, v80
	v_min_u32_e32 v80, v99, v80
	v_max_u32_e32 v99, v77, v83
	v_min_u32_e32 v83, v77, v83
	v_max_u32_e32 v77, v73, v78
	v_min_u32_e32 v78, v73, v78
	v_max_u32_e32 v73, v79, v101
	v_min_u32_e32 v101, v79, v101
	v_max_u32_e32 v79, v72, v71
	v_min_u32_e32 v71, v72, v71
	v_max_u32_e32 v72, v70, v84
	v_min_u32_e32 v84, v70, v84
	v_max_u32_e32 v70, v76, v75
	v_min_u32_e32 v75, v76, v75
	v_max_u32_e32 v76, v74, v85
	v_min_u32_e32 v85, v74, v85
	v_max_u32_e32 v74, v86, v77
	v_min_u32_e32 v77, v86, v77
	v_max_u32_e32 v86, v99, v73
	v_min_u32_e32 v73, v99, v73
	v_max_u32_e32 v99, v80, v78
	v_min_u32_e32 v78, v80, v78
	v_max_u32_e32 v80, v83, v101
	v_min_u32_e32 v101, v83, v101
	v_max_u32_e32 v83, v79, v70
	v_min_u32_e32 v70, v79, v70
	v_max_u32_e32 v79, v72, v76
	v_min_u32_e32 v76, v72, v76
	v_max_u32_e32 v72, v71, v75
	v_min_u32_e32 v75, v71, v75
	v_max_u32_e32 v71, v84, v85
	v_min_u32_e32 v85, v84, v85
	v_max_u32_e32 v84, v74, v86
	v_min_u32_e32 v86, v74, v86
	v_max_u32_e32 v74, v77, v73
	v_min_u32_e32 v73, v77, v73
	v_max_u32_e32 v77, v99, v80
	v_min_u32_e32 v80, v99, v80
	v_max_u32_e32 v99, v78, v101
	v_min_u32_e32 v101, v78, v101
	v_max_u32_e32 v78, v83, v79
	v_min_u32_e32 v79, v83, v79
	v_max_u32_e32 v83, v70, v76
	v_min_u32_e32 v76, v70, v76
	v_max_u32_e32 v70, v72, v71
	v_min_u32_e32 v71, v72, v71
	v_max_u32_e32 v72, v75, v85
	v_min_u32_e32 v85, v75, v85
	v_cvt_f32_f16_e32 v75, v24
	v_cvt_f32_f16_sdwa v94, v24 dst_sel:DWORD dst_unused:UNUSED_PAD src0_sel:WORD_1
	v_ashrrev_i32_e32 v91, 31, v75
	v_lshl_or_b32 v91, v91, 7, s33
	v_xor_b32_e32 v75, v75, v91
	v_xor_b32_e32 v75, 0x4f, v75
	v_ashrrev_i32_e32 v91, 31, v94
	v_lshl_or_b32 v91, v91, 7, s33
	v_xor_b32_e32 v94, v94, v91
	v_xor_b32_e32 v94, 0x4e, v94
	v_cvt_f32_f16_e32 v91, v25
	v_cvt_f32_f16_sdwa v96, v25 dst_sel:DWORD dst_unused:UNUSED_PAD src0_sel:WORD_1
	v_ashrrev_i32_e32 v102, 31, v91
	v_lshl_or_b32 v102, v102, 7, s33
	v_xor_b32_e32 v91, v91, v102
	v_xor_b32_e32 v91, 0x4d, v91
	v_ashrrev_i32_e32 v102, 31, v96
	v_lshl_or_b32 v102, v102, 7, s33
	v_xor_b32_e32 v96, v96, v102
	v_xor_b32_e32 v96, 0x4c, v96
	v_cvt_f32_f16_e32 v102, v26
; __device__ __forceinline__ unsigned f2key(float f) { const unsigned u = __float_as_uint(f); return (u & 0x80000000u) ? ~u : (u | 0x80000000u); }
; #define CE_DESC(a, b) do { const unsigned _mx = (a) > (b) ? (a) : (b), _mn = (a) > (b) ? (b) : (a); (a) = _mx; (b) = _mn; } while (0)
; __device__ __forceinline__ void sort16_desc(unsigned (&k)[16]) {
; #pragma unroll
;     for (int size = 2; size <= 16; size <<= 1)
; #pragma unroll
;         for (int stride = size >> 1; stride > 0; stride >>= 1)
; #pragma unroll
;             for (int i = 0; i < 16; ++i) { const int j = i ^ stride;
;                 if (j > i) { if ((i & size) == 0) CE_DESC(k[i], k[j]); else CE_DESC(k[j], k[i]); } }
; }
; __device__ __forceinline__ void peer_tile(const Args& A, LAS unsigned char* lds, int tile) {
;     ...
;                   for (int i = 0; i < 16; ++i) {
;                       const float lo = (float)__builtin_bit_cast(_Float16, (unsigned short)(sw[i] & 0xffffu)), hi = (float)__builtin_bit_cast(_Float16, (unsigned short)(sw[i] >> 16));
;                       const unsigned klo = (f2key(lo) & ~127u) | (unsigned)(127 - (32 * g + 2 * i)), khi = (f2key(hi) & ~127u) | (unsigned)(127 - (32 * g + 2 * i + 1));
;                       if (i < 8) { k0[2 * i] = klo; k0[2 * i + 1] = khi; } else { k1[2 * (i - 8)] = klo; k1[2 * (i - 8) + 1] = khi; } } }
	v_cvt_f32_f16_sdwa v95, v26 dst_sel:DWORD dst_unused:UNUSED_PAD src0_sel:WORD_1
	v_ashrrev_i32_e32 v98, 31, v102
	v_lshl_or_b32 v98, v98, 7, s33
	v_xor_b32_e32 v102, v102, v98
	v_xor_b32_e32 v102, 0x4b, v102
	v_ashrrev_i32_e32 v98, 31, v95
	v_lshl_or_b32 v98, v98, 7, s33
	v_xor_b32_e32 v95, v95, v98
	v_xor_b32_e32 v95, 0x4a, v95
	v_cvt_f32_f16_e32 v98, v27
	v_cvt_f32_f16_sdwa v90, v27 dst_sel:DWORD dst_unused:UNUSED_PAD src0_sel:WORD_1
	v_ashrrev_i32_e32 v100, 31, v98
	v_lshl_or_b32 v100, v100, 7, s33
	v_xor_b32_e32 v98, v98, v100
	v_xor_b32_e32 v98, 0x49, v98
	v_ashrrev_i32_e32 v100, 31, v90
	v_lshl_or_b32 v100, v100, 7, s33
	v_xor_b32_e32 v90, v90, v100
	v_xor_b32_e32 v90, 0x48, v90
	v_cvt_f32_f16_e32 v100, v28
	v_cvt_f32_f16_sdwa v97, v28 dst_sel:DWORD dst_unused:UNUSED_PAD src0_sel:WORD_1
	v_ashrrev_i32_e32 v93, 31, v100
	v_lshl_or_b32 v93, v93, 7, s33
	v_xor_b32_e32 v100, v100, v93
	v_xor_b32_e32 v100, 0x47, v100
	v_ashrrev_i32_e32 v93, 31, v97
	v_lshl_or_b32 v93, v93, 7, s33
	v_xor_b32_e32 v97, v97, v93
	v_xor_b32_e32 v97, 0x46, v97
	v_cvt_f32_f16_e32 v93, v29
	v_cvt_f32_f16_sdwa v87, v29 dst_sel:DWORD dst_unused:UNUSED_PAD src0_sel:WORD_1
	v_ashrrev_i32_e32 v89, 31, v93
	v_lshl_or_b32 v89, v89, 7, s33
	v_xor_b32_e32 v93, v93, v89
	v_xor_b32_e32 v93, 0x45, v93
	v_ashrrev_i32_e32 v89, 31, v87
	v_lshl_or_b32 v89, v89, 7, s33
	v_xor_b32_e32 v87, v87, v89
	v_xor_b32_e32 v87, 0x44, v87
	v_cvt_f32_f16_e32 v89, v30
	v_cvt_f32_f16_sdwa v82, v30 dst_sel:DWORD dst_unused:UNUSED_PAD src0_sel:WORD_1
	v_ashrrev_i32_e32 v88, 31, v89
	v_lshl_or_b32 v88, v88, 7, s33
	v_xor_b32_e32 v89, v89, v88
	v_xor_b32_e32 v89, 0x43, v89
	v_ashrrev_i32_e32 v88, 31, v82
	v_lshl_or_b32 v88, v88, 7, s33
	v_xor_b32_e32 v82, v82, v88
	v_xor_b32_e32 v82, 0x42, v82
	v_cvt_f32_f16_e32 v88, v31
	v_cvt_f32_f16_sdwa v81, v31 dst_sel:DWORD dst_unused:UNUSED_PAD src0_sel:WORD_1
	v_ashrrev_i32_e32 v92, 31, v88
	v_lshl_or_b32 v92, v92, 7, s33
	v_xor_b32_e32 v88, v88, v92
	v_xor_b32_e32 v88, 0x41, v88
	v_ashrrev_i32_e32 v92, 31, v81
	v_lshl_or_b32 v92, v92, 7, s33
	v_xor_b32_e32 v81, v81, v92
	v_xor_b32_e32 v81, 64, v81
	v_max_u32_e32 v92, v75, v94
	v_min_u32_e32 v94, v75, v94
	v_max_u32_e32 v75, v91, v96
	v_min_u32_e32 v96, v91, v96
	v_max_u32_e32 v91, v92, v75
	v_min_u32_e32 v75, v92, v75
	v_max_u32_e32 v92, v94, v96
	v_min_u32_e32 v96, v94, v96
	v_max_u32_e32 v94, v92, v75
	v_min_u32_e32 v75, v92, v75
	v_max_u32_e32 v92, v102, v95
	v_min_u32_e32 v95, v102, v95
	v_max_u32_e32 v102, v98, v90
	v_min_u32_e32 v90, v98, v90
	v_max_u32_e32 v98, v92, v102
	v_min_u32_e32 v102, v92, v102
	v_max_u32_e32 v92, v95, v90
	v_min_u32_e32 v90, v95, v90
	v_max_u32_e32 v95, v92, v102
	v_min_u32_e32 v102, v92, v102
	v_max_u32_e32 v92, v91, v98
	v_min_u32_e32 v98, v91, v98
	v_max_u32_e32 v91, v75, v102
	v_min_u32_e32 v102, v75, v102
	v_max_u32_e32 v75, v91, v98
	v_min_u32_e32 v98, v91, v98
	v_max_u32_e32 v91, v94, v95
	v_min_u32_e32 v95, v94, v95
	v_max_u32_e32 v94, v96, v90
	v_min_u32_e32 v90, v96, v90
	v_max_u32_e32 v96, v94, v95
	v_min_u32_e32 v95, v94, v95
	v_max_u32_e32 v94, v91, v75
	v_min_u32_e32 v75, v91, v75
	v_max_u32_e32 v91, v96, v98
	v_min_u32_e32 v98, v96, v98
	v_max_u32_e32 v96, v95, v102
	v_min_u32_e32 v102, v95, v102
	v_max_u32_e32 v95, v100, v97
	v_min_u32_e32 v97, v100, v97
	v_max_u32_e32 v100, v93, v87
	v_min_u32_e32 v87, v93, v87
	v_max_u32_e32 v93, v95, v100
	v_min_u32_e32 v100, v95, v100
	v_max_u32_e32 v95, v97, v87
	v_min_u32_e32 v87, v97, v87
	v_max_u32_e32 v97, v95, v100
	v_min_u32_e32 v100, v95, v100
	v_max_u32_e32 v95, v89, v82
	v_min_u32_e32 v82, v89, v82
	v_max_u32_e32 v89, v88, v81
	v_min_u32_e32 v81, v88, v81
	v_max_u32_e32 v88, v95, v89
	v_min_u32_e32 v89, v95, v89
	v_max_u32_e32 v95, v82, v81
	v_min_u32_e32 v81, v82, v81
	v_max_u32_e32 v82, v95, v89
	v_min_u32_e32 v89, v95, v89
	v_max_u32_e32 v95, v93, v88
	v_min_u32_e32 v88, v93, v88
	v_max_u32_e32 v93, v100, v89
	v_min_u32_e32 v89, v100, v89
	v_max_u32_e32 v100, v93, v88
	v_min_u32_e32 v88, v93, v88
	v_max_u32_e32 v93, v97, v82
	v_min_u32_e32 v82, v97, v82
	v_max_u32_e32 v97, v87, v81
	v_min_u32_e32 v81, v87, v81
	v_max_u32_e32 v87, v97, v82
	v_min_u32_e32 v82, v97, v82
	v_max_u32_e32 v97, v93, v100
	v_min_u32_e32 v100, v93, v100
	v_max_u32_e32 v93, v87, v88
	v_min_u32_e32 v88, v87, v88
	v_max_u32_e32 v87, v82, v89
	v_min_u32_e32 v89, v82, v89
	v_max_u32_e32 v82, v92, v95
	v_min_u32_e32 v95, v92, v95
	v_max_u32_e32 v92, v98, v88
	v_min_u32_e32 v88, v98, v88
	v_max_u32_e32 v98, v92, v95
	v_min_u32_e32 v95, v92, v95
	v_max_u32_e32 v92, v75, v100
	v_min_u32_e32 v100, v75, v100
	v_max_u32_e32 v75, v102, v89
	v_min_u32_e32 v89, v102, v89
	v_max_u32_e32 v102, v75, v100
	v_min_u32_e32 v100, v75, v100
	v_max_u32_e32 v75, v92, v98
	v_min_u32_e32 v98, v92, v98
	v_max_u32_e32 v92, v102, v95
	v_min_u32_e32 v95, v102, v95
	v_max_u32_e32 v102, v100, v88
	v_min_u32_e32 v88, v100, v88
	v_max_u32_e32 v100, v94, v97
	v_min_u32_e32 v97, v94, v97
	v_max_u32_e32 v94, v96, v87
	v_min_u32_e32 v87, v96, v87
	v_max_u32_e32 v96, v94, v97
	v_min_u32_e32 v97, v94, v97
	v_max_u32_e32 v94, v91, v93
	v_min_u32_e32 v93, v91, v93
	v_max_u32_e32 v91, v90, v81
	v_min_u32_e32 v81, v90, v81
	v_max_u32_e32 v90, v91, v93
	v_min_u32_e32 v93, v91, v93
	v_max_u32_e32 v91, v94, v96
	v_min_u32_e32 v96, v94, v96
	v_max_u32_e32 v94, v90, v97
	v_min_u32_e32 v97, v90, v97
	v_max_u32_e32 v90, v93, v87
	v_min_u32_e32 v87, v93, v87
	v_max_u32_e32 v93, v100, v75
	v_min_u32_e32 v75, v100, v75
	v_max_u32_e32 v100, v91, v98
	v_min_u32_e32 v98, v91, v98
	v_max_u32_e32 v91, v96, v92
	v_min_u32_e32 v92, v96, v92
	v_max_u32_e32 v96, v94, v95
	v_min_u32_e32 v95, v94, v95
; __device__ __forceinline__ unsigned f2key(float f) { const unsigned u = __float_as_uint(f); return (u & 0x80000000u) ? ~u : (u | 0x80000000u); }
; #define CE_DESC(a, b) do { const unsigned _mx = (a) > (b) ? (a) : (b), _mn = (a) > (b) ? (b) : (a); (a) = _mx; (b) = _mn; } while (0)
; __device__ __forceinline__ void sort16_desc(unsigned (&k)[16]) {
; #pragma unroll
;     for (int size = 2; size <= 16; size <<= 1)
; #pragma unroll
;         for (int stride = size >> 1; stride > 0; stride >>= 1)
; #pragma unroll
;             for (int i = 0; i < 16; ++i) { const int j = i ^ stride;
;                 if (j > i) { if ((i & size) == 0) CE_DESC(k[i], k[j]); else CE_DESC(k[j], k[i]); } }
; }
; __device__ __forceinline__ void merge16(unsigned (&a)[16], const unsigned (&b)[16]) {
; #pragma unroll
;     for (int i = 0; i < 16; ++i) a[i] = a[i] > b[15 - i] ? a[i] : b[15 - i];
; #pragma unroll
;     for (int stride = 8; stride > 0; stride >>= 1)
; #pragma unroll
;         for (int i = 0; i < 16; ++i) { const int j = i ^ stride; if (j > i) CE_DESC(a[i], a[j]); }
; }
; __device__ __forceinline__ void peer_tile(const Args& A, LAS unsigned char* lds, int tile) {
;     ...
;                 { const bf16_t* sp = QRY + m * 2048 + hp * 128 + 32 * g;
;                   const u32x4 s0 = *(const u32x4*)sp, s1 = *(const u32x4*)(sp + 8), s2 = *(const u32x4*)(sp + 16), s3 = *(const u32x4*)(sp + 24);
;                   const unsigned sw[16] = {s0.x, s0.y, s0.z, s0.w, s1.x, s1.y, s1.z, s1.w, s2.x, s2.y, s2.z, s2.w, s3.x, s3.y, s3.z, s3.w};
; #pragma unroll
;                   for (int i = 0; i < 16; ++i) {
;                       const float lo = (float)__builtin_bit_cast(_Float16, (unsigned short)(sw[i] & 0xffffu)), hi = (float)__builtin_bit_cast(_Float16, (unsigned short)(sw[i] >> 16));
;                       const unsigned klo = (f2key(lo) & ~127u) | (unsigned)(127 - (32 * g + 2 * i)), khi = (f2key(hi) & ~127u) | (unsigned)(127 - (32 * g + 2 * i + 1));
;                       if (i < 8) { k0[2 * i] = klo; k0[2 * i + 1] = khi; } else { k1[2 * (i - 8)] = klo; k1[2 * (i - 8) + 1] = khi; } } }
	v_max_u32_e32 v94, v97, v102
	v_min_u32_e32 v102, v97, v102
	v_max_u32_e32 v97, v90, v88
	v_min_u32_e32 v88, v90, v88
	v_max_u32_e32 v90, v87, v89
	v_min_u32_e32 v89, v87, v89
	v_max_u32_e32 v84, v84, v81
	v_max_u32_e32 v86, v86, v89
	v_max_u32_e32 v74, v74, v90
	v_max_u32_e32 v73, v73, v88
	v_max_u32_e32 v77, v77, v97
	v_max_u32_e32 v80, v80, v102
	v_max_u32_e32 v99, v99, v94
	v_max_u32_e32 v101, v101, v95
	v_max_u32_e32 v78, v78, v96
	v_max_u32_e32 v79, v79, v92
	v_max_u32_e32 v83, v83, v91
	v_max_u32_e32 v76, v76, v98
	v_max_u32_e32 v70, v70, v100
	v_max_u32_e32 v71, v71, v75
	v_max_u32_e32 v72, v72, v93
	v_max_u32_e32 v85, v85, v82
	v_max_u32_e32 v81, v84, v78
	v_min_u32_e32 v78, v84, v78
	v_max_u32_e32 v84, v86, v79
	v_min_u32_e32 v79, v86, v79
	v_max_u32_e32 v86, v74, v83
	v_min_u32_e32 v83, v74, v83
	v_max_u32_e32 v74, v73, v76
	v_min_u32_e32 v76, v73, v76
	v_max_u32_e32 v73, v77, v70
	v_min_u32_e32 v70, v77, v70
	v_max_u32_e32 v77, v80, v71
	v_min_u32_e32 v71, v80, v71
	v_max_u32_e32 v80, v99, v72
	v_min_u32_e32 v72, v99, v72
	v_max_u32_e32 v99, v101, v85
	v_min_u32_e32 v85, v101, v85
	v_max_u32_e32 v101, v81, v73
	v_min_u32_e32 v73, v81, v73
	v_max_u32_e32 v81, v84, v77
	v_min_u32_e32 v77, v84, v77
	v_max_u32_e32 v84, v86, v80
	v_min_u32_e32 v80, v86, v80
	v_max_u32_e32 v86, v74, v99
	v_min_u32_e32 v99, v74, v99
	v_max_u32_e32 v74, v78, v70
	v_min_u32_e32 v70, v78, v70
	v_max_u32_e32 v78, v79, v71
	v_min_u32_e32 v71, v79, v71
	v_max_u32_e32 v79, v83, v72
	v_min_u32_e32 v72, v83, v72
	v_max_u32_e32 v83, v76, v85
	v_min_u32_e32 v85, v76, v85
	v_max_u32_e32 v76, v101, v84
	v_min_u32_e32 v84, v101, v84
	v_max_u32_e32 v101, v81, v86
	v_min_u32_e32 v86, v81, v86
	v_max_u32_e32 v81, v73, v80
	v_min_u32_e32 v80, v73, v80
	v_max_u32_e32 v73, v77, v99
	v_min_u32_e32 v99, v77, v99
	v_max_u32_e32 v77, v74, v79
	v_min_u32_e32 v79, v74, v79
	v_max_u32_e32 v74, v78, v83
	v_min_u32_e32 v83, v78, v83
	v_max_u32_e32 v78, v70, v72
	v_min_u32_e32 v72, v70, v72
	v_max_u32_e32 v70, v71, v85
	v_min_u32_e32 v85, v71, v85
	v_max_u32_e32 v71, v76, v101
	v_min_u32_e32 v101, v76, v101
	v_max_u32_e32 v76, v84, v86
	v_min_u32_e32 v86, v84, v86
	v_max_u32_e32 v84, v81, v73
	v_min_u32_e32 v73, v81, v73
	v_max_u32_e32 v81, v80, v99
	v_min_u32_e32 v99, v80, v99
	v_max_u32_e32 v80, v77, v74
	v_min_u32_e32 v74, v77, v74
	v_max_u32_e32 v77, v79, v83
	v_min_u32_e32 v83, v79, v83
	v_max_u32_e32 v79, v78, v70
	v_min_u32_e32 v70, v78, v70
	v_max_u32_e32 v78, v72, v85
	v_min_u32_e32 v85, v72, v85
	s_mov_b64 s[38:39], s[34:35]
	global_load_dwordx4 v[0:3], v66, s[38:39] offset:256
	s_add_u32 s38, s38, 0x8000
	s_addc_u32 s39, s39, 0
	global_load_dwordx4 v[4:7], v66, s[38:39] offset:256
	s_add_u32 s38, s38, 0x8000
	s_addc_u32 s39, s39, 0
	global_load_dwordx4 v[8:11], v66, s[38:39] offset:256
	s_add_u32 s38, s38, 0x8000
	s_addc_u32 s39, s39, 0
	global_load_dwordx4 v[12:15], v66, s[38:39] offset:256
	s_add_u32 s38, s38, 0x8000
	s_addc_u32 s39, s39, 0
	global_load_dwordx4 v[16:19], v66, s[38:39] offset:256
	s_add_u32 s38, s38, 0x8000
	s_addc_u32 s39, s39, 0
	global_load_dwordx4 v[20:23], v66, s[38:39] offset:256
	s_add_u32 s38, s38, 0x8000
	s_addc_u32 s39, s39, 0
	global_load_dwordx4 v[24:27], v66, s[38:39] offset:256
	s_add_u32 s38, s38, 0x8000
	s_addc_u32 s39, s39, 0
	global_load_dwordx4 v[28:31], v66, s[38:39] offset:256
	s_waitcnt vmcnt(8)
	ds_write_b128 v64, v[32:35] offset:0
	ds_write_b128 v64, v[36:39] offset:1152
	ds_write_b128 v64, v[40:43] offset:2304
	ds_write_b128 v64, v[44:47] offset:3456
	ds_write_b128 v64, v[48:51] offset:4608
	ds_write_b128 v64, v[52:55] offset:5760
	ds_write_b128 v64, v[56:59] offset:6912
	ds_write_b128 v64, v[60:63] offset:8064
	s_waitcnt lgkmcnt(0)
	ds_read_b128 v[32:35], v65 offset:0
	ds_read_b128 v[36:39], v65 offset:16
	ds_read_b128 v[40:43], v65 offset:32
	ds_read_b128 v[44:47], v65 offset:48
	ds_read_b128 v[48:51], v65 offset:64
	ds_read_b128 v[52:55], v65 offset:80
	ds_read_b128 v[56:59], v65 offset:96
	ds_read_b128 v[60:63], v65 offset:112
	s_waitcnt lgkmcnt(0)
	v_cvt_f32_f16_e32 v72, v32
	v_cvt_f32_f16_sdwa v89, v32 dst_sel:DWORD dst_unused:UNUSED_PAD src0_sel:WORD_1
	v_ashrrev_i32_e32 v90, 31, v72
	v_lshl_or_b32 v90, v90, 7, s33
	v_xor_b32_e32 v72, v72, v90
	v_xor_b32_e32 v72, 63, v72
	v_ashrrev_i32_e32 v90, 31, v89
	v_lshl_or_b32 v90, v90, 7, s33
	v_xor_b32_e32 v89, v89, v90
	v_xor_b32_e32 v89, 62, v89
	v_cvt_f32_f16_e32 v90, v33
	v_cvt_f32_f16_sdwa v88, v33 dst_sel:DWORD dst_unused:UNUSED_PAD src0_sel:WORD_1
	v_ashrrev_i32_e32 v97, 31, v90
	v_lshl_or_b32 v97, v97, 7, s33
	v_xor_b32_e32 v90, v90, v97
	v_xor_b32_e32 v90, 61, v90
	v_ashrrev_i32_e32 v97, 31, v88
	v_lshl_or_b32 v97, v97, 7, s33
	v_xor_b32_e32 v88, v88, v97
	v_xor_b32_e32 v88, 60, v88
	v_cvt_f32_f16_e32 v97, v34
	v_cvt_f32_f16_sdwa v102, v34 dst_sel:DWORD dst_unused:UNUSED_PAD src0_sel:WORD_1
	v_ashrrev_i32_e32 v94, 31, v97
	v_lshl_or_b32 v94, v94, 7, s33
	v_xor_b32_e32 v97, v97, v94
	v_xor_b32_e32 v97, 59, v97
	v_ashrrev_i32_e32 v94, 31, v102
	v_lshl_or_b32 v94, v94, 7, s33
	v_xor_b32_e32 v102, v102, v94
	v_xor_b32_e32 v102, 58, v102
	v_cvt_f32_f16_e32 v94, v35
	v_cvt_f32_f16_sdwa v95, v35 dst_sel:DWORD dst_unused:UNUSED_PAD src0_sel:WORD_1
	v_ashrrev_i32_e32 v96, 31, v94
	v_lshl_or_b32 v96, v96, 7, s33
	v_xor_b32_e32 v94, v94, v96
	v_xor_b32_e32 v94, 57, v94
	v_ashrrev_i32_e32 v96, 31, v95
	v_lshl_or_b32 v96, v96, 7, s33
	v_xor_b32_e32 v95, v95, v96
	v_xor_b32_e32 v95, 56, v95
	v_cvt_f32_f16_e32 v96, v36
	v_cvt_f32_f16_sdwa v92, v36 dst_sel:DWORD dst_unused:UNUSED_PAD src0_sel:WORD_1
	v_ashrrev_i32_e32 v91, 31, v96
	v_lshl_or_b32 v91, v91, 7, s33
	v_xor_b32_e32 v96, v96, v91
; __device__ __forceinline__ unsigned f2key(float f) { const unsigned u = __float_as_uint(f); return (u & 0x80000000u) ? ~u : (u | 0x80000000u); }
; #define CE_DESC(a, b) do { const unsigned _mx = (a) > (b) ? (a) : (b), _mn = (a) > (b) ? (b) : (a); (a) = _mx; (b) = _mn; } while (0)
; __device__ __forceinline__ void sort16_desc(unsigned (&k)[16]) {
; #pragma unroll
;     for (int size = 2; size <= 16; size <<= 1)
; #pragma unroll
;         for (int stride = size >> 1; stride > 0; stride >>= 1)
; #pragma unroll
;             for (int i = 0; i < 16; ++i) { const int j = i ^ stride;
;                 if (j > i) { if ((i & size) == 0) CE_DESC(k[i], k[j]); else CE_DESC(k[j], k[i]); } }
; }
; __device__ __forceinline__ void merge16(unsigned (&a)[16], const unsigned (&b)[16]) {
; #pragma unroll
;     for (int i = 0; i < 16; ++i) a[i] = a[i] > b[15 - i] ? a[i] : b[15 - i];
; #pragma unroll
;     for (int stride = 8; stride > 0; stride >>= 1)
; #pragma unroll
;         for (int i = 0; i < 16; ++i) { const int j = i ^ stride; if (j > i) CE_DESC(a[i], a[j]); }
; }
; __device__ __forceinline__ void peer_tile(const Args& A, LAS unsigned char* lds, int tile) {
;     ...
;                   for (int i = 0; i < 16; ++i) {
;                       const float lo = (float)__builtin_bit_cast(_Float16, (unsigned short)(sw[i] & 0xffffu)), hi = (float)__builtin_bit_cast(_Float16, (unsigned short)(sw[i] >> 16));
;                       const unsigned klo = (f2key(lo) & ~127u) | (unsigned)(127 - (32 * g + 2 * i)), khi = (f2key(hi) & ~127u) | (unsigned)(127 - (32 * g + 2 * i + 1));
;                       if (i < 8) { k0[2 * i] = klo; k0[2 * i + 1] = khi; } else { k1[2 * (i - 8)] = klo; k1[2 * (i - 8) + 1] = khi; } } }
	v_xor_b32_e32 v96, 55, v96
	v_ashrrev_i32_e32 v91, 31, v92
	v_lshl_or_b32 v91, v91, 7, s33
	v_xor_b32_e32 v92, v92, v91
	v_xor_b32_e32 v92, 54, v92
	v_cvt_f32_f16_e32 v91, v37
	v_cvt_f32_f16_sdwa v98, v37 dst_sel:DWORD dst_unused:UNUSED_PAD src0_sel:WORD_1
	v_ashrrev_i32_e32 v100, 31, v91
	v_lshl_or_b32 v100, v100, 7, s33
	v_xor_b32_e32 v91, v91, v100
	v_xor_b32_e32 v91, 53, v91
	v_ashrrev_i32_e32 v100, 31, v98
	v_lshl_or_b32 v100, v100, 7, s33
	v_xor_b32_e32 v98, v98, v100
	v_xor_b32_e32 v98, 52, v98
	v_cvt_f32_f16_e32 v100, v38
	v_cvt_f32_f16_sdwa v75, v38 dst_sel:DWORD dst_unused:UNUSED_PAD src0_sel:WORD_1
	v_ashrrev_i32_e32 v93, 31, v100
	v_lshl_or_b32 v93, v93, 7, s33
	v_xor_b32_e32 v100, v100, v93
	v_xor_b32_e32 v100, 51, v100
	v_ashrrev_i32_e32 v93, 31, v75
	v_lshl_or_b32 v93, v93, 7, s33
	v_xor_b32_e32 v75, v75, v93
	v_xor_b32_e32 v75, 50, v75
	v_cvt_f32_f16_e32 v93, v39
	v_cvt_f32_f16_sdwa v82, v39 dst_sel:DWORD dst_unused:UNUSED_PAD src0_sel:WORD_1
	v_ashrrev_i32_e32 v87, 31, v93
	v_lshl_or_b32 v87, v87, 7, s33
	v_xor_b32_e32 v93, v93, v87
	v_xor_b32_e32 v93, 49, v93
	v_ashrrev_i32_e32 v87, 31, v82
	v_lshl_or_b32 v87, v87, 7, s33
	v_xor_b32_e32 v82, v82, v87
	v_xor_b32_e32 v82, 48, v82
	v_max_u32_e32 v87, v72, v89
	v_min_u32_e32 v89, v72, v89
	v_max_u32_e32 v72, v90, v88
	v_min_u32_e32 v88, v90, v88
	v_max_u32_e32 v90, v87, v72
	v_min_u32_e32 v72, v87, v72
	v_max_u32_e32 v87, v89, v88
	v_min_u32_e32 v88, v89, v88
	v_max_u32_e32 v89, v87, v72
	v_min_u32_e32 v72, v87, v72
	v_max_u32_e32 v87, v97, v102
	v_min_u32_e32 v102, v97, v102
	v_max_u32_e32 v97, v94, v95
	v_min_u32_e32 v95, v94, v95
	v_max_u32_e32 v94, v87, v97
	v_min_u32_e32 v97, v87, v97
	v_max_u32_e32 v87, v102, v95
	v_min_u32_e32 v95, v102, v95
	v_max_u32_e32 v102, v87, v97
	v_min_u32_e32 v97, v87, v97
	v_max_u32_e32 v87, v90, v94
	v_min_u32_e32 v94, v90, v94
	v_max_u32_e32 v90, v72, v97
	v_min_u32_e32 v97, v72, v97
	v_max_u32_e32 v72, v90, v94
	v_min_u32_e32 v94, v90, v94
	v_max_u32_e32 v90, v89, v102
	v_min_u32_e32 v102, v89, v102
	v_max_u32_e32 v89, v88, v95
	v_min_u32_e32 v95, v88, v95
	v_max_u32_e32 v88, v89, v102
	v_min_u32_e32 v102, v89, v102
	v_max_u32_e32 v89, v90, v72
	v_min_u32_e32 v72, v90, v72
	v_max_u32_e32 v90, v88, v94
	v_min_u32_e32 v94, v88, v94
	v_max_u32_e32 v88, v102, v97
	v_min_u32_e32 v97, v102, v97
	v_max_u32_e32 v102, v96, v92
	v_min_u32_e32 v92, v96, v92
	v_max_u32_e32 v96, v91, v98
	v_min_u32_e32 v98, v91, v98
	v_max_u32_e32 v91, v102, v96
	v_min_u32_e32 v96, v102, v96
	v_max_u32_e32 v102, v92, v98
	v_min_u32_e32 v98, v92, v98
	v_max_u32_e32 v92, v102, v96
	v_min_u32_e32 v96, v102, v96
	v_max_u32_e32 v102, v100, v75
	v_min_u32_e32 v75, v100, v75
	v_max_u32_e32 v100, v93, v82
	v_min_u32_e32 v82, v93, v82
	v_max_u32_e32 v93, v102, v100
	v_min_u32_e32 v100, v102, v100
	v_max_u32_e32 v102, v75, v82
	v_min_u32_e32 v82, v75, v82
	v_max_u32_e32 v75, v102, v100
	v_min_u32_e32 v100, v102, v100
	v_max_u32_e32 v102, v91, v93
	v_min_u32_e32 v93, v91, v93
	v_max_u32_e32 v91, v96, v100
	v_min_u32_e32 v100, v96, v100
	v_max_u32_e32 v96, v91, v93
	v_min_u32_e32 v93, v91, v93
	v_max_u32_e32 v91, v92, v75
	v_min_u32_e32 v75, v92, v75
	v_max_u32_e32 v92, v98, v82
	v_min_u32_e32 v82, v98, v82
	v_max_u32_e32 v98, v92, v75
	v_min_u32_e32 v75, v92, v75
	v_max_u32_e32 v92, v91, v96
	v_min_u32_e32 v96, v91, v96
	v_max_u32_e32 v91, v98, v93
	v_min_u32_e32 v93, v98, v93
	v_max_u32_e32 v98, v75, v100
	v_min_u32_e32 v100, v75, v100
	v_max_u32_e32 v75, v87, v102
	v_min_u32_e32 v102, v87, v102
	v_max_u32_e32 v87, v94, v93
	v_min_u32_e32 v93, v94, v93
	v_max_u32_e32 v94, v87, v102
	v_min_u32_e32 v102, v87, v102
	v_max_u32_e32 v87, v72, v96
	v_min_u32_e32 v96, v72, v96
	v_max_u32_e32 v72, v97, v100
	v_min_u32_e32 v100, v97, v100
	v_max_u32_e32 v97, v72, v96
	v_min_u32_e32 v96, v72, v96
	v_max_u32_e32 v72, v87, v94
	v_min_u32_e32 v94, v87, v94
	v_max_u32_e32 v87, v97, v102
	v_min_u32_e32 v102, v97, v102
	v_max_u32_e32 v97, v96, v93
	v_min_u32_e32 v93, v96, v93
	v_max_u32_e32 v96, v89, v92
	v_min_u32_e32 v92, v89, v92
	v_max_u32_e32 v89, v88, v98
	v_min_u32_e32 v98, v88, v98
	v_max_u32_e32 v88, v89, v92
	v_min_u32_e32 v92, v89, v92
	v_max_u32_e32 v89, v90, v91
	v_min_u32_e32 v91, v90, v91
	v_max_u32_e32 v90, v95, v82
	v_min_u32_e32 v82, v95, v82
	v_max_u32_e32 v95, v90, v91
	v_min_u32_e32 v91, v90, v91
	v_max_u32_e32 v90, v89, v88
	v_min_u32_e32 v88, v89, v88
	v_max_u32_e32 v89, v95, v92
	v_min_u32_e32 v92, v95, v92
	v_max_u32_e32 v95, v91, v98
	v_min_u32_e32 v98, v91, v98
	v_max_u32_e32 v91, v96, v72
	v_min_u32_e32 v72, v96, v72
	v_max_u32_e32 v96, v90, v94
	v_min_u32_e32 v94, v90, v94
	v_max_u32_e32 v90, v88, v87
	v_min_u32_e32 v87, v88, v87
	v_max_u32_e32 v88, v89, v102
	v_min_u32_e32 v102, v89, v102
	v_max_u32_e32 v89, v92, v97
	v_min_u32_e32 v97, v92, v97
	v_max_u32_e32 v92, v95, v93
	v_min_u32_e32 v93, v95, v93
	v_max_u32_e32 v95, v98, v100
	v_min_u32_e32 v100, v98, v100
	v_max_u32_e32 v71, v71, v82
	v_max_u32_e32 v101, v101, v100
	v_max_u32_e32 v76, v76, v95
	v_max_u32_e32 v86, v86, v93
	v_max_u32_e32 v84, v84, v92
	v_max_u32_e32 v73, v73, v97
	v_max_u32_e32 v81, v81, v89
	v_max_u32_e32 v99, v99, v102
	v_max_u32_e32 v80, v80, v88
	v_max_u32_e32 v74, v74, v87
	v_max_u32_e32 v77, v77, v90
	v_max_u32_e32 v83, v83, v94
	v_max_u32_e32 v79, v79, v96
	v_max_u32_e32 v70, v70, v72
	v_max_u32_e32 v78, v78, v91
	v_max_u32_e32 v85, v85, v75
	v_max_u32_e32 v82, v71, v80
	v_min_u32_e32 v80, v71, v80
	v_max_u32_e32 v71, v101, v74
	v_min_u32_e32 v74, v101, v74
	v_max_u32_e32 v101, v76, v77
	v_min_u32_e32 v77, v76, v77
	v_max_u32_e32 v76, v86, v83
	v_min_u32_e32 v83, v86, v83
; __device__ __forceinline__ unsigned f2key(float f) { const unsigned u = __float_as_uint(f); return (u & 0x80000000u) ? ~u : (u | 0x80000000u); }
; #define CE_DESC(a, b) do { const unsigned _mx = (a) > (b) ? (a) : (b), _mn = (a) > (b) ? (b) : (a); (a) = _mx; (b) = _mn; } while (0)
; __device__ __forceinline__ void merge16(unsigned (&a)[16], const unsigned (&b)[16]) {
; #pragma unroll
;     for (int i = 0; i < 16; ++i) a[i] = a[i] > b[15 - i] ? a[i] : b[15 - i];
; #pragma unroll
;     for (int stride = 8; stride > 0; stride >>= 1)
; #pragma unroll
;         for (int i = 0; i < 16; ++i) { const int j = i ^ stride; if (j > i) CE_DESC(a[i], a[j]); }
; }
; __device__ __forceinline__ void peer_tile(const Args& A, LAS unsigned char* lds, int tile) {
;     ...
;                 { const bf16_t* sp = QRY + m * 2048 + hp * 128 + 32 * g;
;                   const u32x4 s0 = *(const u32x4*)sp, s1 = *(const u32x4*)(sp + 8), s2 = *(const u32x4*)(sp + 16), s3 = *(const u32x4*)(sp + 24);
;                   const unsigned sw[16] = {s0.x, s0.y, s0.z, s0.w, s1.x, s1.y, s1.z, s1.w, s2.x, s2.y, s2.z, s2.w, s3.x, s3.y, s3.z, s3.w};
; #pragma unroll
;                   for (int i = 0; i < 16; ++i) {
;                       const float lo = (float)__builtin_bit_cast(_Float16, (unsigned short)(sw[i] & 0xffffu)), hi = (float)__builtin_bit_cast(_Float16, (unsigned short)(sw[i] >> 16));
;                       const unsigned klo = (f2key(lo) & ~127u) | (unsigned)(127 - (32 * g + 2 * i)), khi = (f2key(hi) & ~127u) | (unsigned)(127 - (32 * g + 2 * i + 1));
;                       if (i < 8) { k0[2 * i] = klo; k0[2 * i + 1] = khi; } else { k1[2 * (i - 8)] = klo; k1[2 * (i - 8) + 1] = khi; } } }
	v_max_u32_e32 v86, v84, v79
	v_min_u32_e32 v79, v84, v79
	v_max_u32_e32 v84, v73, v70
	v_min_u32_e32 v70, v73, v70
	v_max_u32_e32 v73, v81, v78
	v_min_u32_e32 v78, v81, v78
	v_max_u32_e32 v81, v99, v85
	v_min_u32_e32 v85, v99, v85
	v_max_u32_e32 v99, v82, v86
	v_min_u32_e32 v86, v82, v86
	v_max_u32_e32 v82, v71, v84
	v_min_u32_e32 v84, v71, v84
	v_max_u32_e32 v71, v101, v73
	v_min_u32_e32 v73, v101, v73
	v_max_u32_e32 v101, v76, v81
	v_min_u32_e32 v81, v76, v81
	v_max_u32_e32 v76, v80, v79
	v_min_u32_e32 v79, v80, v79
	v_max_u32_e32 v80, v74, v70
	v_min_u32_e32 v70, v74, v70
	v_max_u32_e32 v74, v77, v78
	v_min_u32_e32 v78, v77, v78
	v_max_u32_e32 v77, v83, v85
	v_min_u32_e32 v85, v83, v85
	v_max_u32_e32 v83, v99, v71
	v_min_u32_e32 v71, v99, v71
	v_max_u32_e32 v99, v82, v101
	v_min_u32_e32 v101, v82, v101
	v_max_u32_e32 v82, v86, v73
	v_min_u32_e32 v73, v86, v73
	v_max_u32_e32 v86, v84, v81
	v_min_u32_e32 v81, v84, v81
	v_max_u32_e32 v84, v76, v74
	v_min_u32_e32 v74, v76, v74
	v_max_u32_e32 v76, v80, v77
	v_min_u32_e32 v77, v80, v77
	v_max_u32_e32 v80, v79, v78
	v_min_u32_e32 v78, v79, v78
	v_max_u32_e32 v79, v70, v85
	v_min_u32_e32 v85, v70, v85
	v_max_u32_e32 v70, v83, v99
	v_min_u32_e32 v99, v83, v99
	v_max_u32_e32 v83, v71, v101
	v_min_u32_e32 v101, v71, v101
	v_max_u32_e32 v71, v82, v86
	v_min_u32_e32 v86, v82, v86
	v_max_u32_e32 v82, v73, v81
	v_min_u32_e32 v81, v73, v81
	v_max_u32_e32 v73, v84, v76
	v_min_u32_e32 v76, v84, v76
	v_max_u32_e32 v84, v74, v77
	v_min_u32_e32 v77, v74, v77
	v_max_u32_e32 v74, v80, v79
	v_min_u32_e32 v79, v80, v79
	v_max_u32_e32 v80, v78, v85
	v_min_u32_e32 v85, v78, v85
	v_cvt_f32_f16_e32 v78, v40
	v_cvt_f32_f16_sdwa v100, v40 dst_sel:DWORD dst_unused:UNUSED_PAD src0_sel:WORD_1
	v_ashrrev_i32_e32 v95, 31, v78
	v_lshl_or_b32 v95, v95, 7, s33
	v_xor_b32_e32 v78, v78, v95
	v_xor_b32_e32 v78, 47, v78
	v_ashrrev_i32_e32 v95, 31, v100
	v_lshl_or_b32 v95, v95, 7, s33
	v_xor_b32_e32 v100, v100, v95
	v_xor_b32_e32 v100, 46, v100
	v_cvt_f32_f16_e32 v95, v41
	v_cvt_f32_f16_sdwa v93, v41 dst_sel:DWORD dst_unused:UNUSED_PAD src0_sel:WORD_1
	v_ashrrev_i32_e32 v92, 31, v95
	v_lshl_or_b32 v92, v92, 7, s33
	v_xor_b32_e32 v95, v95, v92
	v_xor_b32_e32 v95, 45, v95
	v_ashrrev_i32_e32 v92, 31, v93
	v_lshl_or_b32 v92, v92, 7, s33
	v_xor_b32_e32 v93, v93, v92
	v_xor_b32_e32 v93, 44, v93
	v_cvt_f32_f16_e32 v92, v42
	v_cvt_f32_f16_sdwa v97, v42 dst_sel:DWORD dst_unused:UNUSED_PAD src0_sel:WORD_1
	v_ashrrev_i32_e32 v89, 31, v92
	v_lshl_or_b32 v89, v89, 7, s33
	v_xor_b32_e32 v92, v92, v89
	v_xor_b32_e32 v92, 43, v92
	v_ashrrev_i32_e32 v89, 31, v97
	v_lshl_or_b32 v89, v89, 7, s33
	v_xor_b32_e32 v97, v97, v89
	v_xor_b32_e32 v97, 42, v97
	v_cvt_f32_f16_e32 v89, v43
	v_cvt_f32_f16_sdwa v102, v43 dst_sel:DWORD dst_unused:UNUSED_PAD src0_sel:WORD_1
	v_ashrrev_i32_e32 v88, 31, v89
	v_lshl_or_b32 v88, v88, 7, s33
	v_xor_b32_e32 v89, v89, v88
	v_xor_b32_e32 v89, 41, v89
	v_ashrrev_i32_e32 v88, 31, v102
	v_lshl_or_b32 v88, v88, 7, s33
	v_xor_b32_e32 v102, v102, v88
	v_xor_b32_e32 v102, 40, v102
	v_cvt_f32_f16_e32 v88, v44
	v_cvt_f32_f16_sdwa v87, v44 dst_sel:DWORD dst_unused:UNUSED_PAD src0_sel:WORD_1
	v_ashrrev_i32_e32 v90, 31, v88
	v_lshl_or_b32 v90, v90, 7, s33
	v_xor_b32_e32 v88, v88, v90
	v_xor_b32_e32 v88, 39, v88
	v_ashrrev_i32_e32 v90, 31, v87
	v_lshl_or_b32 v90, v90, 7, s33
	v_xor_b32_e32 v87, v87, v90
	v_xor_b32_e32 v87, 38, v87
	v_cvt_f32_f16_e32 v90, v45
	v_cvt_f32_f16_sdwa v94, v45 dst_sel:DWORD dst_unused:UNUSED_PAD src0_sel:WORD_1
	v_ashrrev_i32_e32 v96, 31, v90
	v_lshl_or_b32 v96, v96, 7, s33
	v_xor_b32_e32 v90, v90, v96
	v_xor_b32_e32 v90, 37, v90
	v_ashrrev_i32_e32 v96, 31, v94
	v_lshl_or_b32 v96, v96, 7, s33
	v_xor_b32_e32 v94, v94, v96
	v_xor_b32_e32 v94, 36, v94
	v_cvt_f32_f16_e32 v96, v46
	v_cvt_f32_f16_sdwa v72, v46 dst_sel:DWORD dst_unused:UNUSED_PAD src0_sel:WORD_1
	v_ashrrev_i32_e32 v91, 31, v96
	v_lshl_or_b32 v91, v91, 7, s33
	v_xor_b32_e32 v96, v96, v91
	v_xor_b32_e32 v96, 35, v96
	v_ashrrev_i32_e32 v91, 31, v72
	v_lshl_or_b32 v91, v91, 7, s33
	v_xor_b32_e32 v72, v72, v91
	v_xor_b32_e32 v72, 34, v72
	v_cvt_f32_f16_e32 v91, v47
	v_cvt_f32_f16_sdwa v75, v47 dst_sel:DWORD dst_unused:UNUSED_PAD src0_sel:WORD_1
	v_ashrrev_i32_e32 v98, 31, v91
	v_lshl_or_b32 v98, v98, 7, s33
	v_xor_b32_e32 v91, v91, v98
	v_xor_b32_e32 v91, 33, v91
	v_ashrrev_i32_e32 v98, 31, v75
	v_lshl_or_b32 v98, v98, 7, s33
	v_xor_b32_e32 v75, v75, v98
	v_xor_b32_e32 v75, 32, v75
	v_max_u32_e32 v98, v78, v100
	v_min_u32_e32 v100, v78, v100
	v_max_u32_e32 v78, v95, v93
	v_min_u32_e32 v93, v95, v93
	v_max_u32_e32 v95, v98, v78
	v_min_u32_e32 v78, v98, v78
	v_max_u32_e32 v98, v100, v93
	v_min_u32_e32 v93, v100, v93
	v_max_u32_e32 v100, v98, v78
	v_min_u32_e32 v78, v98, v78
	v_max_u32_e32 v98, v92, v97
	v_min_u32_e32 v97, v92, v97
	v_max_u32_e32 v92, v89, v102
	v_min_u32_e32 v102, v89, v102
	v_max_u32_e32 v89, v98, v92
	v_min_u32_e32 v92, v98, v92
	v_max_u32_e32 v98, v97, v102
	v_min_u32_e32 v102, v97, v102
	v_max_u32_e32 v97, v98, v92
	v_min_u32_e32 v92, v98, v92
	v_max_u32_e32 v98, v95, v89
	v_min_u32_e32 v89, v95, v89
	v_max_u32_e32 v95, v78, v92
	v_min_u32_e32 v92, v78, v92
	v_max_u32_e32 v78, v95, v89
	v_min_u32_e32 v89, v95, v89
	v_max_u32_e32 v95, v100, v97
	v_min_u32_e32 v97, v100, v97
	v_max_u32_e32 v100, v93, v102
	v_min_u32_e32 v102, v93, v102
	v_max_u32_e32 v93, v100, v97
	v_min_u32_e32 v97, v100, v97
	v_max_u32_e32 v100, v95, v78
	v_min_u32_e32 v78, v95, v78
	v_max_u32_e32 v95, v93, v89
	v_min_u32_e32 v89, v93, v89
	v_max_u32_e32 v93, v97, v92
	v_min_u32_e32 v92, v97, v92
	v_max_u32_e32 v97, v88, v87
	v_min_u32_e32 v87, v88, v87
; __device__ __forceinline__ unsigned f2key(float f) { const unsigned u = __float_as_uint(f); return (u & 0x80000000u) ? ~u : (u | 0x80000000u); }
; #define CE_DESC(a, b) do { const unsigned _mx = (a) > (b) ? (a) : (b), _mn = (a) > (b) ? (b) : (a); (a) = _mx; (b) = _mn; } while (0)
; __device__ __forceinline__ void sort16_desc(unsigned (&k)[16]) {
; #pragma unroll
;     for (int size = 2; size <= 16; size <<= 1)
; #pragma unroll
;         for (int stride = size >> 1; stride > 0; stride >>= 1)
; #pragma unroll
;             for (int i = 0; i < 16; ++i) { const int j = i ^ stride;
;                 if (j > i) { if ((i & size) == 0) CE_DESC(k[i], k[j]); else CE_DESC(k[j], k[i]); } }
; }
; __device__ __forceinline__ void merge16(unsigned (&a)[16], const unsigned (&b)[16]) {
; #pragma unroll
;     for (int i = 0; i < 16; ++i) a[i] = a[i] > b[15 - i] ? a[i] : b[15 - i];
; #pragma unroll
;     for (int stride = 8; stride > 0; stride >>= 1)
; #pragma unroll
;         for (int i = 0; i < 16; ++i) { const int j = i ^ stride; if (j > i) CE_DESC(a[i], a[j]); }
; }
; __device__ __forceinline__ void peer_tile(const Args& A, LAS unsigned char* lds, int tile) {
;     ...
;                 { const bf16_t* sp = QRY + m * 2048 + hp * 128 + 32 * g;
;                   const u32x4 s0 = *(const u32x4*)sp, s1 = *(const u32x4*)(sp + 8), s2 = *(const u32x4*)(sp + 16), s3 = *(const u32x4*)(sp + 24);
;                   const unsigned sw[16] = {s0.x, s0.y, s0.z, s0.w, s1.x, s1.y, s1.z, s1.w, s2.x, s2.y, s2.z, s2.w, s3.x, s3.y, s3.z, s3.w};
; #pragma unroll
;                   for (int i = 0; i < 16; ++i) {
;                       const float lo = (float)__builtin_bit_cast(_Float16, (unsigned short)(sw[i] & 0xffffu)), hi = (float)__builtin_bit_cast(_Float16, (unsigned short)(sw[i] >> 16));
;                       const unsigned klo = (f2key(lo) & ~127u) | (unsigned)(127 - (32 * g + 2 * i)), khi = (f2key(hi) & ~127u) | (unsigned)(127 - (32 * g + 2 * i + 1));
;                       if (i < 8) { k0[2 * i] = klo; k0[2 * i + 1] = khi; } else { k1[2 * (i - 8)] = klo; k1[2 * (i - 8) + 1] = khi; } } }
	v_max_u32_e32 v88, v90, v94
	v_min_u32_e32 v94, v90, v94
	v_max_u32_e32 v90, v97, v88
	v_min_u32_e32 v88, v97, v88
	v_max_u32_e32 v97, v87, v94
	v_min_u32_e32 v94, v87, v94
	v_max_u32_e32 v87, v97, v88
	v_min_u32_e32 v88, v97, v88
	v_max_u32_e32 v97, v96, v72
	v_min_u32_e32 v72, v96, v72
	v_max_u32_e32 v96, v91, v75
	v_min_u32_e32 v75, v91, v75
	v_max_u32_e32 v91, v97, v96
	v_min_u32_e32 v96, v97, v96
	v_max_u32_e32 v97, v72, v75
	v_min_u32_e32 v75, v72, v75
	v_max_u32_e32 v72, v97, v96
	v_min_u32_e32 v96, v97, v96
	v_max_u32_e32 v97, v90, v91
	v_min_u32_e32 v91, v90, v91
	v_max_u32_e32 v90, v88, v96
	v_min_u32_e32 v96, v88, v96
	v_max_u32_e32 v88, v90, v91
	v_min_u32_e32 v91, v90, v91
	v_max_u32_e32 v90, v87, v72
	v_min_u32_e32 v72, v87, v72
	v_max_u32_e32 v87, v94, v75
	v_min_u32_e32 v75, v94, v75
	v_max_u32_e32 v94, v87, v72
	v_min_u32_e32 v72, v87, v72
	v_max_u32_e32 v87, v90, v88
	v_min_u32_e32 v88, v90, v88
	v_max_u32_e32 v90, v94, v91
	v_min_u32_e32 v91, v94, v91
	v_max_u32_e32 v94, v72, v96
	v_min_u32_e32 v96, v72, v96
	v_max_u32_e32 v72, v98, v97
	v_min_u32_e32 v97, v98, v97
	v_max_u32_e32 v98, v89, v91
	v_min_u32_e32 v91, v89, v91
	v_max_u32_e32 v89, v98, v97
	v_min_u32_e32 v97, v98, v97
	v_max_u32_e32 v98, v78, v88
	v_min_u32_e32 v88, v78, v88
	v_max_u32_e32 v78, v92, v96
	v_min_u32_e32 v96, v92, v96
	v_max_u32_e32 v92, v78, v88
	v_min_u32_e32 v88, v78, v88
	v_max_u32_e32 v78, v98, v89
	v_min_u32_e32 v89, v98, v89
	v_max_u32_e32 v98, v92, v97
	v_min_u32_e32 v97, v92, v97
	v_max_u32_e32 v92, v88, v91
	v_min_u32_e32 v91, v88, v91
	v_max_u32_e32 v88, v100, v87
	v_min_u32_e32 v87, v100, v87
	v_max_u32_e32 v100, v93, v94
	v_min_u32_e32 v94, v93, v94
	v_max_u32_e32 v93, v100, v87
	v_min_u32_e32 v87, v100, v87
	v_max_u32_e32 v100, v95, v90
	v_min_u32_e32 v90, v95, v90
	v_max_u32_e32 v95, v102, v75
	v_min_u32_e32 v75, v102, v75
	v_max_u32_e32 v102, v95, v90
	v_min_u32_e32 v90, v95, v90
	v_max_u32_e32 v95, v100, v93
	v_min_u32_e32 v93, v100, v93
	v_max_u32_e32 v100, v102, v87
	v_min_u32_e32 v87, v102, v87
	v_max_u32_e32 v102, v90, v94
	v_min_u32_e32 v94, v90, v94
	v_max_u32_e32 v90, v88, v78
	v_min_u32_e32 v78, v88, v78
	v_max_u32_e32 v88, v95, v89
	v_min_u32_e32 v89, v95, v89
	v_max_u32_e32 v95, v93, v98
	v_min_u32_e32 v98, v93, v98
	v_max_u32_e32 v93, v100, v97
	v_min_u32_e32 v97, v100, v97
	v_max_u32_e32 v100, v87, v92
	v_min_u32_e32 v92, v87, v92
	v_max_u32_e32 v87, v102, v91
	v_min_u32_e32 v91, v102, v91
	v_max_u32_e32 v102, v94, v96
	v_min_u32_e32 v96, v94, v96
	v_max_u32_e32 v70, v70, v75
	v_max_u32_e32 v99, v99, v96
	v_max_u32_e32 v83, v83, v102
	v_max_u32_e32 v101, v101, v91
	v_max_u32_e32 v71, v71, v87
	v_max_u32_e32 v86, v86, v92
	v_max_u32_e32 v82, v82, v100
	v_max_u32_e32 v81, v81, v97
	v_max_u32_e32 v73, v73, v93
	v_max_u32_e32 v76, v76, v98
	v_max_u32_e32 v84, v84, v95
	v_max_u32_e32 v77, v77, v89
	v_max_u32_e32 v74, v74, v88
	v_max_u32_e32 v79, v79, v78
	v_max_u32_e32 v80, v80, v90
	v_max_u32_e32 v85, v85, v72
	v_max_u32_e32 v75, v70, v73
	v_min_u32_e32 v73, v70, v73
	v_max_u32_e32 v70, v99, v76
	v_min_u32_e32 v76, v99, v76
	v_max_u32_e32 v99, v83, v84
	v_min_u32_e32 v84, v83, v84
	v_max_u32_e32 v83, v101, v77
	v_min_u32_e32 v77, v101, v77
	v_max_u32_e32 v101, v71, v74
	v_min_u32_e32 v74, v71, v74
	v_max_u32_e32 v71, v86, v79
	v_min_u32_e32 v79, v86, v79
	v_max_u32_e32 v86, v82, v80
	v_min_u32_e32 v80, v82, v80
	v_max_u32_e32 v82, v81, v85
	v_min_u32_e32 v85, v81, v85
	v_max_u32_e32 v81, v75, v101
	v_min_u32_e32 v101, v75, v101
	v_max_u32_e32 v75, v70, v71
	v_min_u32_e32 v71, v70, v71
	v_max_u32_e32 v70, v99, v86
	v_min_u32_e32 v86, v99, v86
	v_max_u32_e32 v99, v83, v82
	v_min_u32_e32 v82, v83, v82
	v_max_u32_e32 v83, v73, v74
	v_min_u32_e32 v74, v73, v74
	v_max_u32_e32 v73, v76, v79
	v_min_u32_e32 v79, v76, v79
	v_max_u32_e32 v76, v84, v80
	v_min_u32_e32 v80, v84, v80
	v_max_u32_e32 v84, v77, v85
	v_min_u32_e32 v85, v77, v85
	v_max_u32_e32 v77, v81, v70
	v_min_u32_e32 v70, v81, v70
	v_max_u32_e32 v81, v75, v99
	v_min_u32_e32 v99, v75, v99
	v_max_u32_e32 v75, v101, v86
	v_min_u32_e32 v86, v101, v86
	v_max_u32_e32 v101, v71, v82
	v_min_u32_e32 v82, v71, v82
	v_max_u32_e32 v71, v83, v76
	v_min_u32_e32 v76, v83, v76
	v_max_u32_e32 v83, v73, v84
	v_min_u32_e32 v84, v73, v84
	v_max_u32_e32 v73, v74, v80
	v_min_u32_e32 v80, v74, v80
	v_max_u32_e32 v74, v79, v85
	v_min_u32_e32 v85, v79, v85
	v_max_u32_e32 v79, v77, v81
	v_min_u32_e32 v81, v77, v81
	v_max_u32_e32 v77, v70, v99
	v_min_u32_e32 v99, v70, v99
	v_max_u32_e32 v70, v75, v101
	v_min_u32_e32 v101, v75, v101
	v_max_u32_e32 v75, v86, v82
	v_min_u32_e32 v82, v86, v82
	v_max_u32_e32 v86, v71, v83
	v_min_u32_e32 v83, v71, v83
	v_max_u32_e32 v71, v76, v84
	v_min_u32_e32 v84, v76, v84
	v_max_u32_e32 v76, v73, v74
	v_min_u32_e32 v74, v73, v74
	v_max_u32_e32 v73, v80, v85
	v_min_u32_e32 v85, v80, v85
	v_cvt_f32_f16_e32 v80, v48
	v_cvt_f32_f16_sdwa v96, v48 dst_sel:DWORD dst_unused:UNUSED_PAD src0_sel:WORD_1
	v_ashrrev_i32_e32 v102, 31, v80
	v_lshl_or_b32 v102, v102, 7, s33
	v_xor_b32_e32 v80, v80, v102
	v_xor_b32_e32 v80, 31, v80
	v_ashrrev_i32_e32 v102, 31, v96
	v_lshl_or_b32 v102, v102, 7, s33
	v_xor_b32_e32 v96, v96, v102
	v_xor_b32_e32 v96, 30, v96
	v_cvt_f32_f16_e32 v102, v49
	v_cvt_f32_f16_sdwa v91, v49 dst_sel:DWORD dst_unused:UNUSED_PAD src0_sel:WORD_1
	v_ashrrev_i32_e32 v87, 31, v102
	v_lshl_or_b32 v87, v87, 7, s33
	v_xor_b32_e32 v102, v102, v87
	v_xor_b32_e32 v102, 29, v102
	v_ashrrev_i32_e32 v87, 31, v91
	v_lshl_or_b32 v87, v87, 7, s33
	v_xor_b32_e32 v91, v91, v87
	v_xor_b32_e32 v91, 28, v91
	v_cvt_f32_f16_e32 v87, v50
	v_cvt_f32_f16_sdwa v92, v50 dst_sel:DWORD dst_unused:UNUSED_PAD src0_sel:WORD_1
; __device__ __forceinline__ unsigned f2key(float f) { const unsigned u = __float_as_uint(f); return (u & 0x80000000u) ? ~u : (u | 0x80000000u); }
; #define CE_DESC(a, b) do { const unsigned _mx = (a) > (b) ? (a) : (b), _mn = (a) > (b) ? (b) : (a); (a) = _mx; (b) = _mn; } while (0)
; __device__ __forceinline__ void sort16_desc(unsigned (&k)[16]) {
; #pragma unroll
;     for (int size = 2; size <= 16; size <<= 1)
; #pragma unroll
;         for (int stride = size >> 1; stride > 0; stride >>= 1)
; #pragma unroll
;             for (int i = 0; i < 16; ++i) { const int j = i ^ stride;
;                 if (j > i) { if ((i & size) == 0) CE_DESC(k[i], k[j]); else CE_DESC(k[j], k[i]); } }
; }
; __device__ __forceinline__ void peer_tile(const Args& A, LAS unsigned char* lds, int tile) {
;     ...
;                   for (int i = 0; i < 16; ++i) {
;                       const float lo = (float)__builtin_bit_cast(_Float16, (unsigned short)(sw[i] & 0xffffu)), hi = (float)__builtin_bit_cast(_Float16, (unsigned short)(sw[i] >> 16));
;                       const unsigned klo = (f2key(lo) & ~127u) | (unsigned)(127 - (32 * g + 2 * i)), khi = (f2key(hi) & ~127u) | (unsigned)(127 - (32 * g + 2 * i + 1));
;                       if (i < 8) { k0[2 * i] = klo; k0[2 * i + 1] = khi; } else { k1[2 * (i - 8)] = klo; k1[2 * (i - 8) + 1] = khi; } } }
	v_ashrrev_i32_e32 v100, 31, v87
	v_lshl_or_b32 v100, v100, 7, s33
	v_xor_b32_e32 v87, v87, v100
	v_xor_b32_e32 v87, 27, v87
	v_ashrrev_i32_e32 v100, 31, v92
	v_lshl_or_b32 v100, v100, 7, s33
	v_xor_b32_e32 v92, v92, v100
	v_xor_b32_e32 v92, 26, v92
	v_cvt_f32_f16_e32 v100, v51
	v_cvt_f32_f16_sdwa v97, v51 dst_sel:DWORD dst_unused:UNUSED_PAD src0_sel:WORD_1
	v_ashrrev_i32_e32 v93, 31, v100
	v_lshl_or_b32 v93, v93, 7, s33
	v_xor_b32_e32 v100, v100, v93
	v_xor_b32_e32 v100, 25, v100
	v_ashrrev_i32_e32 v93, 31, v97
	v_lshl_or_b32 v93, v93, 7, s33
	v_xor_b32_e32 v97, v97, v93
	v_xor_b32_e32 v97, 24, v97
	v_cvt_f32_f16_e32 v93, v52
	v_cvt_f32_f16_sdwa v98, v52 dst_sel:DWORD dst_unused:UNUSED_PAD src0_sel:WORD_1
	v_ashrrev_i32_e32 v95, 31, v93
	v_lshl_or_b32 v95, v95, 7, s33
	v_xor_b32_e32 v93, v93, v95
	v_xor_b32_e32 v93, 23, v93
	v_ashrrev_i32_e32 v95, 31, v98
	v_lshl_or_b32 v95, v95, 7, s33
	v_xor_b32_e32 v98, v98, v95
	v_xor_b32_e32 v98, 22, v98
	v_cvt_f32_f16_e32 v95, v53
	v_cvt_f32_f16_sdwa v89, v53 dst_sel:DWORD dst_unused:UNUSED_PAD src0_sel:WORD_1
	v_ashrrev_i32_e32 v88, 31, v95
	v_lshl_or_b32 v88, v88, 7, s33
	v_xor_b32_e32 v95, v95, v88
	v_xor_b32_e32 v95, 21, v95
	v_ashrrev_i32_e32 v88, 31, v89
	v_lshl_or_b32 v88, v88, 7, s33
	v_xor_b32_e32 v89, v89, v88
	v_xor_b32_e32 v89, 20, v89
	v_cvt_f32_f16_e32 v88, v54
	v_cvt_f32_f16_sdwa v78, v54 dst_sel:DWORD dst_unused:UNUSED_PAD src0_sel:WORD_1
	v_ashrrev_i32_e32 v90, 31, v88
	v_lshl_or_b32 v90, v90, 7, s33
	v_xor_b32_e32 v88, v88, v90
	v_xor_b32_e32 v88, 19, v88
	v_ashrrev_i32_e32 v90, 31, v78
	v_lshl_or_b32 v90, v90, 7, s33
	v_xor_b32_e32 v78, v78, v90
	v_xor_b32_e32 v78, 18, v78
	v_cvt_f32_f16_e32 v90, v55
	v_cvt_f32_f16_sdwa v72, v55 dst_sel:DWORD dst_unused:UNUSED_PAD src0_sel:WORD_1
	v_ashrrev_i32_e32 v94, 31, v90
	v_lshl_or_b32 v94, v94, 7, s33
	v_xor_b32_e32 v90, v90, v94
	v_xor_b32_e32 v90, 17, v90
	v_ashrrev_i32_e32 v94, 31, v72
	v_lshl_or_b32 v94, v94, 7, s33
	v_xor_b32_e32 v72, v72, v94
	v_xor_b32_e32 v72, 16, v72
	v_max_u32_e32 v94, v80, v96
	v_min_u32_e32 v96, v80, v96
	v_max_u32_e32 v80, v102, v91
	v_min_u32_e32 v91, v102, v91
	v_max_u32_e32 v102, v94, v80
	v_min_u32_e32 v80, v94, v80
	v_max_u32_e32 v94, v96, v91
	v_min_u32_e32 v91, v96, v91
	v_max_u32_e32 v96, v94, v80
	v_min_u32_e32 v80, v94, v80
	v_max_u32_e32 v94, v87, v92
	v_min_u32_e32 v92, v87, v92
	v_max_u32_e32 v87, v100, v97
	v_min_u32_e32 v97, v100, v97
	v_max_u32_e32 v100, v94, v87
	v_min_u32_e32 v87, v94, v87
	v_max_u32_e32 v94, v92, v97
	v_min_u32_e32 v97, v92, v97
	v_max_u32_e32 v92, v94, v87
	v_min_u32_e32 v87, v94, v87
	v_max_u32_e32 v94, v102, v100
	v_min_u32_e32 v100, v102, v100
	v_max_u32_e32 v102, v80, v87
	v_min_u32_e32 v87, v80, v87
	v_max_u32_e32 v80, v102, v100
	v_min_u32_e32 v100, v102, v100
	v_max_u32_e32 v102, v96, v92
	v_min_u32_e32 v92, v96, v92
	v_max_u32_e32 v96, v91, v97
	v_min_u32_e32 v97, v91, v97
	v_max_u32_e32 v91, v96, v92
	v_min_u32_e32 v92, v96, v92
	v_max_u32_e32 v96, v102, v80
	v_min_u32_e32 v80, v102, v80
	v_max_u32_e32 v102, v91, v100
	v_min_u32_e32 v100, v91, v100
	v_max_u32_e32 v91, v92, v87
	v_min_u32_e32 v87, v92, v87
	v_max_u32_e32 v92, v93, v98
	v_min_u32_e32 v98, v93, v98
	v_max_u32_e32 v93, v95, v89
	v_min_u32_e32 v89, v95, v89
	v_max_u32_e32 v95, v92, v93
	v_min_u32_e32 v93, v92, v93
	v_max_u32_e32 v92, v98, v89
	v_min_u32_e32 v89, v98, v89
	v_max_u32_e32 v98, v92, v93
	v_min_u32_e32 v93, v92, v93
	v_max_u32_e32 v92, v88, v78
	v_min_u32_e32 v78, v88, v78
	v_max_u32_e32 v88, v90, v72
	v_min_u32_e32 v72, v90, v72
	v_max_u32_e32 v90, v92, v88
	v_min_u32_e32 v88, v92, v88
	v_max_u32_e32 v92, v78, v72
	v_min_u32_e32 v72, v78, v72
	v_max_u32_e32 v78, v92, v88
	v_min_u32_e32 v88, v92, v88
	v_max_u32_e32 v92, v95, v90
	v_min_u32_e32 v90, v95, v90
	v_max_u32_e32 v95, v93, v88
	v_min_u32_e32 v88, v93, v88
	v_max_u32_e32 v93, v95, v90
	v_min_u32_e32 v90, v95, v90
	v_max_u32_e32 v95, v98, v78
	v_min_u32_e32 v78, v98, v78
	v_max_u32_e32 v98, v89, v72
	v_min_u32_e32 v72, v89, v72
	v_max_u32_e32 v89, v98, v78
	v_min_u32_e32 v78, v98, v78
	v_max_u32_e32 v98, v95, v93
	v_min_u32_e32 v93, v95, v93
	v_max_u32_e32 v95, v89, v90
	v_min_u32_e32 v90, v89, v90
	v_max_u32_e32 v89, v78, v88
	v_min_u32_e32 v88, v78, v88
	v_max_u32_e32 v78, v94, v92
	v_min_u32_e32 v92, v94, v92
	v_max_u32_e32 v94, v100, v90
	v_min_u32_e32 v90, v100, v90
	v_max_u32_e32 v100, v94, v92
	v_min_u32_e32 v92, v94, v92
	v_max_u32_e32 v94, v80, v93
	v_min_u32_e32 v93, v80, v93
	v_max_u32_e32 v80, v87, v88
	v_min_u32_e32 v88, v87, v88
	v_max_u32_e32 v87, v80, v93
	v_min_u32_e32 v93, v80, v93
	v_max_u32_e32 v80, v94, v100
	v_min_u32_e32 v100, v94, v100
	v_max_u32_e32 v94, v87, v92
	v_min_u32_e32 v92, v87, v92
	v_max_u32_e32 v87, v93, v90
	v_min_u32_e32 v90, v93, v90
	v_max_u32_e32 v93, v96, v98
	v_min_u32_e32 v98, v96, v98
	v_max_u32_e32 v96, v91, v89
	v_min_u32_e32 v89, v91, v89
	v_max_u32_e32 v91, v96, v98
	v_min_u32_e32 v98, v96, v98
	v_max_u32_e32 v96, v102, v95
	v_min_u32_e32 v95, v102, v95
	v_max_u32_e32 v102, v97, v72
	v_min_u32_e32 v72, v97, v72
	v_max_u32_e32 v97, v102, v95
	v_min_u32_e32 v95, v102, v95
	v_max_u32_e32 v102, v96, v91
	v_min_u32_e32 v91, v96, v91
	v_max_u32_e32 v96, v97, v98
	v_min_u32_e32 v98, v97, v98
	v_max_u32_e32 v97, v95, v89
	v_min_u32_e32 v89, v95, v89
	v_max_u32_e32 v95, v93, v80
	v_min_u32_e32 v80, v93, v80
	v_max_u32_e32 v93, v102, v100
	v_min_u32_e32 v100, v102, v100
	v_max_u32_e32 v102, v91, v94
	v_min_u32_e32 v94, v91, v94
	v_max_u32_e32 v91, v96, v92
	v_min_u32_e32 v92, v96, v92
	v_max_u32_e32 v96, v98, v87
	v_min_u32_e32 v87, v98, v87
	v_max_u32_e32 v98, v97, v90
	v_min_u32_e32 v90, v97, v90
; __device__ __forceinline__ unsigned f2key(float f) { const unsigned u = __float_as_uint(f); return (u & 0x80000000u) ? ~u : (u | 0x80000000u); }
; #define CE_DESC(a, b) do { const unsigned _mx = (a) > (b) ? (a) : (b), _mn = (a) > (b) ? (b) : (a); (a) = _mx; (b) = _mn; } while (0)
; __device__ __forceinline__ void sort16_desc(unsigned (&k)[16]) {
; #pragma unroll
;     for (int size = 2; size <= 16; size <<= 1)
; #pragma unroll
;         for (int stride = size >> 1; stride > 0; stride >>= 1)
; #pragma unroll
;             for (int i = 0; i < 16; ++i) { const int j = i ^ stride;
;                 if (j > i) { if ((i & size) == 0) CE_DESC(k[i], k[j]); else CE_DESC(k[j], k[i]); } }
; }
; __device__ __forceinline__ void merge16(unsigned (&a)[16], const unsigned (&b)[16]) {
; #pragma unroll
;     for (int i = 0; i < 16; ++i) a[i] = a[i] > b[15 - i] ? a[i] : b[15 - i];
; #pragma unroll
;     for (int stride = 8; stride > 0; stride >>= 1)
; #pragma unroll
;         for (int i = 0; i < 16; ++i) { const int j = i ^ stride; if (j > i) CE_DESC(a[i], a[j]); }
; }
; __device__ __forceinline__ void peer_tile(const Args& A, LAS unsigned char* lds, int tile) {
;     ...
;                 { const bf16_t* sp = QRY + m * 2048 + hp * 128 + 32 * g;
;                   const u32x4 s0 = *(const u32x4*)sp, s1 = *(const u32x4*)(sp + 8), s2 = *(const u32x4*)(sp + 16), s3 = *(const u32x4*)(sp + 24);
;                   const unsigned sw[16] = {s0.x, s0.y, s0.z, s0.w, s1.x, s1.y, s1.z, s1.w, s2.x, s2.y, s2.z, s2.w, s3.x, s3.y, s3.z, s3.w};
; #pragma unroll
;                   for (int i = 0; i < 16; ++i) {
;                       const float lo = (float)__builtin_bit_cast(_Float16, (unsigned short)(sw[i] & 0xffffu)), hi = (float)__builtin_bit_cast(_Float16, (unsigned short)(sw[i] >> 16));
;                       const unsigned klo = (f2key(lo) & ~127u) | (unsigned)(127 - (32 * g + 2 * i)), khi = (f2key(hi) & ~127u) | (unsigned)(127 - (32 * g + 2 * i + 1));
;                       if (i < 8) { k0[2 * i] = klo; k0[2 * i + 1] = khi; } else { k1[2 * (i - 8)] = klo; k1[2 * (i - 8) + 1] = khi; } } }
	v_max_u32_e32 v97, v89, v88
	v_min_u32_e32 v88, v89, v88
	v_max_u32_e32 v79, v79, v72
	v_max_u32_e32 v81, v81, v88
	v_max_u32_e32 v77, v77, v97
	v_max_u32_e32 v99, v99, v90
	v_max_u32_e32 v70, v70, v98
	v_max_u32_e32 v101, v101, v87
	v_max_u32_e32 v75, v75, v96
	v_max_u32_e32 v82, v82, v92
	v_max_u32_e32 v86, v86, v91
	v_max_u32_e32 v83, v83, v94
	v_max_u32_e32 v71, v71, v102
	v_max_u32_e32 v84, v84, v100
	v_max_u32_e32 v76, v76, v93
	v_max_u32_e32 v74, v74, v80
	v_max_u32_e32 v73, v73, v95
	v_max_u32_e32 v85, v85, v78
	v_max_u32_e32 v72, v79, v86
	v_min_u32_e32 v86, v79, v86
	v_max_u32_e32 v79, v81, v83
	v_min_u32_e32 v83, v81, v83
	v_max_u32_e32 v81, v77, v71
	v_min_u32_e32 v71, v77, v71
	v_max_u32_e32 v77, v99, v84
	v_min_u32_e32 v84, v99, v84
	v_max_u32_e32 v99, v70, v76
	v_min_u32_e32 v76, v70, v76
	v_max_u32_e32 v70, v101, v74
	v_min_u32_e32 v74, v101, v74
	v_max_u32_e32 v101, v75, v73
	v_min_u32_e32 v73, v75, v73
	v_max_u32_e32 v75, v82, v85
	v_min_u32_e32 v85, v82, v85
	v_max_u32_e32 v82, v72, v99
	v_min_u32_e32 v99, v72, v99
	v_max_u32_e32 v72, v79, v70
	v_min_u32_e32 v70, v79, v70
	v_max_u32_e32 v79, v81, v101
	v_min_u32_e32 v101, v81, v101
	v_max_u32_e32 v81, v77, v75
	v_min_u32_e32 v75, v77, v75
	v_max_u32_e32 v77, v86, v76
	v_min_u32_e32 v76, v86, v76
	v_max_u32_e32 v86, v83, v74
	v_min_u32_e32 v74, v83, v74
	v_max_u32_e32 v83, v71, v73
	v_min_u32_e32 v73, v71, v73
	v_max_u32_e32 v71, v84, v85
	v_min_u32_e32 v85, v84, v85
	v_max_u32_e32 v84, v82, v79
	v_min_u32_e32 v79, v82, v79
	v_max_u32_e32 v82, v72, v81
	v_min_u32_e32 v81, v72, v81
	v_max_u32_e32 v72, v99, v101
	v_min_u32_e32 v101, v99, v101
	v_max_u32_e32 v99, v70, v75
	v_min_u32_e32 v75, v70, v75
	v_max_u32_e32 v70, v77, v83
	v_min_u32_e32 v83, v77, v83
	v_max_u32_e32 v77, v86, v71
	v_min_u32_e32 v71, v86, v71
	v_max_u32_e32 v86, v76, v73
	v_min_u32_e32 v73, v76, v73
	v_max_u32_e32 v76, v74, v85
	v_min_u32_e32 v85, v74, v85
	v_max_u32_e32 v74, v84, v82
	v_min_u32_e32 v82, v84, v82
	v_max_u32_e32 v84, v79, v81
	v_min_u32_e32 v81, v79, v81
	v_max_u32_e32 v79, v72, v99
	v_min_u32_e32 v99, v72, v99
	v_max_u32_e32 v72, v101, v75
	v_min_u32_e32 v75, v101, v75
	v_max_u32_e32 v101, v70, v77
	v_min_u32_e32 v77, v70, v77
	v_max_u32_e32 v70, v83, v71
	v_min_u32_e32 v71, v83, v71
	v_max_u32_e32 v83, v86, v76
	v_min_u32_e32 v76, v86, v76
	v_max_u32_e32 v86, v73, v85
	v_min_u32_e32 v85, v73, v85
	v_cvt_f32_f16_e32 v73, v56
	v_cvt_f32_f16_sdwa v88, v56 dst_sel:DWORD dst_unused:UNUSED_PAD src0_sel:WORD_1
	v_ashrrev_i32_e32 v97, 31, v73
	v_lshl_or_b32 v97, v97, 7, s33
	v_xor_b32_e32 v73, v73, v97
	v_xor_b32_e32 v73, 15, v73
	v_ashrrev_i32_e32 v97, 31, v88
	v_lshl_or_b32 v97, v97, 7, s33
	v_xor_b32_e32 v88, v88, v97
	v_xor_b32_e32 v88, 14, v88
	v_cvt_f32_f16_e32 v97, v57
	v_cvt_f32_f16_sdwa v90, v57 dst_sel:DWORD dst_unused:UNUSED_PAD src0_sel:WORD_1
	v_ashrrev_i32_e32 v98, 31, v97
	v_lshl_or_b32 v98, v98, 7, s33
	v_xor_b32_e32 v97, v97, v98
	v_xor_b32_e32 v97, 13, v97
	v_ashrrev_i32_e32 v98, 31, v90
	v_lshl_or_b32 v98, v98, 7, s33
	v_xor_b32_e32 v90, v90, v98
	v_xor_b32_e32 v90, 12, v90
	v_cvt_f32_f16_e32 v98, v58
	v_cvt_f32_f16_sdwa v87, v58 dst_sel:DWORD dst_unused:UNUSED_PAD src0_sel:WORD_1
	v_ashrrev_i32_e32 v96, 31, v98
	v_lshl_or_b32 v96, v96, 7, s33
	v_xor_b32_e32 v98, v98, v96
	v_xor_b32_e32 v98, 11, v98
	v_ashrrev_i32_e32 v96, 31, v87
	v_lshl_or_b32 v96, v96, 7, s33
	v_xor_b32_e32 v87, v87, v96
	v_xor_b32_e32 v87, 10, v87
	v_cvt_f32_f16_e32 v96, v59
	v_cvt_f32_f16_sdwa v92, v59 dst_sel:DWORD dst_unused:UNUSED_PAD src0_sel:WORD_1
	v_ashrrev_i32_e32 v91, 31, v96
	v_lshl_or_b32 v91, v91, 7, s33
	v_xor_b32_e32 v96, v96, v91
	v_xor_b32_e32 v96, 9, v96
	v_ashrrev_i32_e32 v91, 31, v92
	v_lshl_or_b32 v91, v91, 7, s33
	v_xor_b32_e32 v92, v92, v91
	v_xor_b32_e32 v92, 8, v92
	v_cvt_f32_f16_e32 v91, v60
	v_cvt_f32_f16_sdwa v94, v60 dst_sel:DWORD dst_unused:UNUSED_PAD src0_sel:WORD_1
	v_ashrrev_i32_e32 v102, 31, v91
	v_lshl_or_b32 v102, v102, 7, s33
	v_xor_b32_e32 v91, v91, v102
	v_xor_b32_e32 v91, 7, v91
	v_ashrrev_i32_e32 v102, 31, v94
	v_lshl_or_b32 v102, v102, 7, s33
	v_xor_b32_e32 v94, v94, v102
	v_xor_b32_e32 v94, 6, v94
	v_cvt_f32_f16_e32 v102, v61
	v_cvt_f32_f16_sdwa v100, v61 dst_sel:DWORD dst_unused:UNUSED_PAD src0_sel:WORD_1
	v_ashrrev_i32_e32 v93, 31, v102
	v_lshl_or_b32 v93, v93, 7, s33
	v_xor_b32_e32 v102, v102, v93
	v_xor_b32_e32 v102, 5, v102
	v_ashrrev_i32_e32 v93, 31, v100
	v_lshl_or_b32 v93, v93, 7, s33
	v_xor_b32_e32 v100, v100, v93
	v_xor_b32_e32 v100, 4, v100
	v_cvt_f32_f16_e32 v93, v62
	v_cvt_f32_f16_sdwa v80, v62 dst_sel:DWORD dst_unused:UNUSED_PAD src0_sel:WORD_1
	v_ashrrev_i32_e32 v95, 31, v93
	v_lshl_or_b32 v95, v95, 7, s33
	v_xor_b32_e32 v93, v93, v95
	v_xor_b32_e32 v93, 3, v93
	v_ashrrev_i32_e32 v95, 31, v80
	v_lshl_or_b32 v95, v95, 7, s33
	v_xor_b32_e32 v80, v80, v95
	v_xor_b32_e32 v80, 2, v80
	v_cvt_f32_f16_e32 v95, v63
	v_cvt_f32_f16_sdwa v78, v63 dst_sel:DWORD dst_unused:UNUSED_PAD src0_sel:WORD_1
	v_ashrrev_i32_e32 v89, 31, v95
	v_lshl_or_b32 v89, v89, 7, s33
	v_xor_b32_e32 v95, v95, v89
	v_xor_b32_e32 v95, 1, v95
	v_ashrrev_i32_e32 v89, 31, v78
	v_lshl_or_b32 v89, v89, 7, s33
	v_xor_b32_e32 v78, v78, v89
	v_xor_b32_e32 v78, 0, v78
	v_max_u32_e32 v89, v73, v88
	v_min_u32_e32 v88, v73, v88
	v_max_u32_e32 v73, v97, v90
	v_min_u32_e32 v90, v97, v90
	v_max_u32_e32 v97, v89, v73
	v_min_u32_e32 v73, v89, v73
	v_max_u32_e32 v89, v88, v90
	v_min_u32_e32 v90, v88, v90
	v_max_u32_e32 v88, v89, v73
	v_min_u32_e32 v73, v89, v73
	v_max_u32_e32 v89, v98, v87
	v_min_u32_e32 v87, v98, v87
	v_max_u32_e32 v98, v96, v92
	v_min_u32_e32 v92, v96, v92
	v_max_u32_e32 v96, v89, v98
; #define CE_DESC(a, b) do { const unsigned _mx = (a) > (b) ? (a) : (b), _mn = (a) > (b) ? (b) : (a); (a) = _mx; (b) = _mn; } while (0)
; __device__ __forceinline__ void sort16_desc(unsigned (&k)[16]) {
; #pragma unroll
;     for (int size = 2; size <= 16; size <<= 1)
; #pragma unroll
;         for (int stride = size >> 1; stride > 0; stride >>= 1)
; #pragma unroll
;             for (int i = 0; i < 16; ++i) { const int j = i ^ stride;
;                 if (j > i) { if ((i & size) == 0) CE_DESC(k[i], k[j]); else CE_DESC(k[j], k[i]); } }
; }
; __device__ __forceinline__ void merge16(unsigned (&a)[16], const unsigned (&b)[16]) {
; #pragma unroll
;     for (int i = 0; i < 16; ++i) a[i] = a[i] > b[15 - i] ? a[i] : b[15 - i];
; #pragma unroll
;     for (int stride = 8; stride > 0; stride >>= 1)
; #pragma unroll
;         for (int i = 0; i < 16; ++i) { const int j = i ^ stride; if (j > i) CE_DESC(a[i], a[j]); }
; }
; __device__ __forceinline__ void peer_tile(const Args& A, LAS unsigned char* lds, int tile) {
;     ...
;                 { const bf16_t* sp = QRY + m * 2048 + hp * 128 + 32 * g;
;                   const u32x4 s0 = *(const u32x4*)sp, s1 = *(const u32x4*)(sp + 8), s2 = *(const u32x4*)(sp + 16), s3 = *(const u32x4*)(sp + 24);
;                   const unsigned sw[16] = {s0.x, s0.y, s0.z, s0.w, s1.x, s1.y, s1.z, s1.w, s2.x, s2.y, s2.z, s2.w, s3.x, s3.y, s3.z, s3.w};
	v_min_u32_e32 v98, v89, v98
	v_max_u32_e32 v89, v87, v92
	v_min_u32_e32 v92, v87, v92
	v_max_u32_e32 v87, v89, v98
	v_min_u32_e32 v98, v89, v98
	v_max_u32_e32 v89, v97, v96
	v_min_u32_e32 v96, v97, v96
	v_max_u32_e32 v97, v73, v98
	v_min_u32_e32 v98, v73, v98
	v_max_u32_e32 v73, v97, v96
	v_min_u32_e32 v96, v97, v96
	v_max_u32_e32 v97, v88, v87
	v_min_u32_e32 v87, v88, v87
	v_max_u32_e32 v88, v90, v92
	v_min_u32_e32 v92, v90, v92
	v_max_u32_e32 v90, v88, v87
	v_min_u32_e32 v87, v88, v87
	v_max_u32_e32 v88, v97, v73
	v_min_u32_e32 v73, v97, v73
	v_max_u32_e32 v97, v90, v96
	v_min_u32_e32 v96, v90, v96
	v_max_u32_e32 v90, v87, v98
	v_min_u32_e32 v98, v87, v98
	v_max_u32_e32 v87, v91, v94
	v_min_u32_e32 v94, v91, v94
	v_max_u32_e32 v91, v102, v100
	v_min_u32_e32 v100, v102, v100
	v_max_u32_e32 v102, v87, v91
	v_min_u32_e32 v91, v87, v91
	v_max_u32_e32 v87, v94, v100
	v_min_u32_e32 v100, v94, v100
	v_max_u32_e32 v94, v87, v91
	v_min_u32_e32 v91, v87, v91
	v_max_u32_e32 v87, v93, v80
	v_min_u32_e32 v80, v93, v80
	v_max_u32_e32 v93, v95, v78
	v_min_u32_e32 v78, v95, v78
	v_max_u32_e32 v95, v87, v93
	v_min_u32_e32 v93, v87, v93
	v_max_u32_e32 v87, v80, v78
	v_min_u32_e32 v78, v80, v78
	v_max_u32_e32 v80, v87, v93
	v_min_u32_e32 v93, v87, v93
	v_max_u32_e32 v87, v102, v95
	v_min_u32_e32 v95, v102, v95
	v_max_u32_e32 v102, v91, v93
	v_min_u32_e32 v93, v91, v93
	v_max_u32_e32 v91, v102, v95
	v_min_u32_e32 v95, v102, v95
	v_max_u32_e32 v102, v94, v80
	v_min_u32_e32 v80, v94, v80
	v_max_u32_e32 v94, v100, v78
	v_min_u32_e32 v78, v100, v78
	v_max_u32_e32 v100, v94, v80
	v_min_u32_e32 v80, v94, v80
	v_max_u32_e32 v94, v102, v91
	v_min_u32_e32 v91, v102, v91
	v_max_u32_e32 v102, v100, v95
	v_min_u32_e32 v95, v100, v95
	v_max_u32_e32 v100, v80, v93
	v_min_u32_e32 v93, v80, v93
	v_max_u32_e32 v80, v89, v87
	v_min_u32_e32 v87, v89, v87
	v_max_u32_e32 v89, v96, v95
	v_min_u32_e32 v95, v96, v95
	v_max_u32_e32 v96, v89, v87
	v_min_u32_e32 v87, v89, v87
	v_max_u32_e32 v89, v73, v91
	v_min_u32_e32 v91, v73, v91
	v_max_u32_e32 v73, v98, v93
	v_min_u32_e32 v93, v98, v93
	v_max_u32_e32 v98, v73, v91
	v_min_u32_e32 v91, v73, v91
	v_max_u32_e32 v73, v89, v96
	v_min_u32_e32 v96, v89, v96
	v_max_u32_e32 v89, v98, v87
	v_min_u32_e32 v87, v98, v87
	v_max_u32_e32 v98, v91, v95
	v_min_u32_e32 v95, v91, v95
	v_max_u32_e32 v91, v88, v94
	v_min_u32_e32 v94, v88, v94
	v_max_u32_e32 v88, v90, v100
	v_min_u32_e32 v100, v90, v100
	v_max_u32_e32 v90, v88, v94
	v_min_u32_e32 v94, v88, v94
	v_max_u32_e32 v88, v97, v102
	v_min_u32_e32 v102, v97, v102
	v_max_u32_e32 v97, v92, v78
	v_min_u32_e32 v78, v92, v78
	v_max_u32_e32 v92, v97, v102
	v_min_u32_e32 v102, v97, v102
	v_max_u32_e32 v97, v88, v90
	v_min_u32_e32 v90, v88, v90
	v_max_u32_e32 v88, v92, v94
	v_min_u32_e32 v94, v92, v94
	v_max_u32_e32 v92, v102, v100
	v_min_u32_e32 v100, v102, v100
	v_max_u32_e32 v102, v91, v73
	v_min_u32_e32 v73, v91, v73
	v_max_u32_e32 v91, v97, v96
	v_min_u32_e32 v96, v97, v96
	v_max_u32_e32 v97, v90, v89
	v_min_u32_e32 v89, v90, v89
	v_max_u32_e32 v90, v88, v87
	v_min_u32_e32 v87, v88, v87
	v_max_u32_e32 v88, v94, v98
	v_min_u32_e32 v98, v94, v98
	v_max_u32_e32 v94, v92, v95
	v_min_u32_e32 v95, v92, v95
	v_max_u32_e32 v92, v100, v93
	v_min_u32_e32 v93, v100, v93
	v_max_u32_e32 v74, v74, v78
	v_max_u32_e32 v82, v82, v93
	v_max_u32_e32 v84, v84, v92
	v_max_u32_e32 v81, v81, v95
	v_max_u32_e32 v79, v79, v94
	v_max_u32_e32 v99, v99, v98
	v_max_u32_e32 v72, v72, v88
	v_max_u32_e32 v75, v75, v87
	v_max_u32_e32 v101, v101, v90
	v_max_u32_e32 v77, v77, v89
	v_max_u32_e32 v70, v70, v97
	v_max_u32_e32 v71, v71, v96
	v_max_u32_e32 v83, v83, v91
	v_max_u32_e32 v76, v76, v73
	v_max_u32_e32 v86, v86, v102
	v_max_u32_e32 v85, v85, v80
	v_max_u32_e32 v78, v74, v101
	v_min_u32_e32 v101, v74, v101
	v_max_u32_e32 v74, v82, v77
	v_min_u32_e32 v77, v82, v77
	v_max_u32_e32 v82, v84, v70
	v_min_u32_e32 v70, v84, v70
	v_max_u32_e32 v84, v81, v71
	v_min_u32_e32 v71, v81, v71
	v_max_u32_e32 v81, v79, v83
	v_min_u32_e32 v83, v79, v83
	v_max_u32_e32 v79, v99, v76
	v_min_u32_e32 v76, v99, v76
	v_max_u32_e32 v99, v72, v86
	v_min_u32_e32 v86, v72, v86
	v_max_u32_e32 v72, v75, v85
	v_min_u32_e32 v85, v75, v85
	v_max_u32_e32 v75, v78, v81
	v_min_u32_e32 v81, v78, v81
	v_max_u32_e32 v78, v74, v79
	v_min_u32_e32 v79, v74, v79
	v_max_u32_e32 v74, v82, v99
	v_min_u32_e32 v99, v82, v99
	v_max_u32_e32 v82, v84, v72
	v_min_u32_e32 v72, v84, v72
	v_max_u32_e32 v84, v101, v83
	v_min_u32_e32 v83, v101, v83
	v_max_u32_e32 v101, v77, v76
	v_min_u32_e32 v76, v77, v76
	v_max_u32_e32 v77, v70, v86
	v_min_u32_e32 v86, v70, v86
	v_max_u32_e32 v70, v71, v85
	v_min_u32_e32 v85, v71, v85
	v_max_u32_e32 v71, v75, v74
	v_min_u32_e32 v74, v75, v74
	v_max_u32_e32 v75, v78, v82
	v_min_u32_e32 v82, v78, v82
	v_max_u32_e32 v78, v81, v99
	v_min_u32_e32 v99, v81, v99
	v_max_u32_e32 v81, v79, v72
	v_min_u32_e32 v72, v79, v72
	v_max_u32_e32 v79, v84, v77
	v_min_u32_e32 v77, v84, v77
	v_max_u32_e32 v84, v101, v70
	v_min_u32_e32 v70, v101, v70
	v_max_u32_e32 v101, v83, v86
	v_min_u32_e32 v86, v83, v86
	v_max_u32_e32 v83, v76, v85
	v_min_u32_e32 v85, v76, v85
	v_max_u32_e32 v76, v71, v75
	v_min_u32_e32 v75, v71, v75
	v_max_u32_e32 v71, v74, v82
	v_min_u32_e32 v82, v74, v82
	v_max_u32_e32 v74, v78, v81
	v_min_u32_e32 v81, v78, v81
	v_max_u32_e32 v78, v99, v72
	v_min_u32_e32 v72, v99, v72
	v_max_u32_e32 v99, v79, v84
	v_min_u32_e32 v84, v79, v84
	v_max_u32_e32 v79, v77, v70
	v_min_u32_e32 v70, v77, v70
	v_max_u32_e32 v77, v101, v83
	v_min_u32_e32 v83, v101, v83
	v_max_u32_e32 v101, v86, v85
	v_min_u32_e32 v85, v86, v85
	s_mov_b64 s[38:39], s[34:35]
	global_load_dwordx4 v[32:35], v66, s[38:39] offset:384
	s_add_u32 s38, s38, 0x8000
	s_addc_u32 s39, s39, 0
	global_load_dwordx4 v[36:39], v66, s[38:39] offset:384
	s_add_u32 s38, s38, 0x8000
	s_addc_u32 s39, s39, 0
	global_load_dwordx4 v[40:43], v66, s[38:39] offset:384
	s_add_u32 s38, s38, 0x8000
	s_addc_u32 s39, s39, 0
	global_load_dwordx4 v[44:47], v66, s[38:39] offset:384
	s_add_u32 s38, s38, 0x8000
	s_addc_u32 s39, s39, 0
	global_load_dwordx4 v[48:51], v66, s[38:39] offset:384
	s_add_u32 s38, s38, 0x8000
	s_addc_u32 s39, s39, 0
	global_load_dwordx4 v[52:55], v66, s[38:39] offset:384
	s_add_u32 s38, s38, 0x8000
	s_addc_u32 s39, s39, 0
	global_load_dwordx4 v[56:59], v66, s[38:39] offset:384
	s_add_u32 s38, s38, 0x8000
	s_addc_u32 s39, s39, 0
	global_load_dwordx4 v[60:63], v66, s[38:39] offset:384
	s_waitcnt vmcnt(8)
; __device__ __forceinline__ unsigned f2key(float f) { const unsigned u = __float_as_uint(f); return (u & 0x80000000u) ? ~u : (u | 0x80000000u); }
; #define CE_DESC(a, b) do { const unsigned _mx = (a) > (b) ? (a) : (b), _mn = (a) > (b) ? (b) : (a); (a) = _mx; (b) = _mn; } while (0)
; __device__ __forceinline__ void sort16_desc(unsigned (&k)[16]) {
; #pragma unroll
;     for (int size = 2; size <= 16; size <<= 1)
; #pragma unroll
;         for (int stride = size >> 1; stride > 0; stride >>= 1)
; #pragma unroll
;             for (int i = 0; i < 16; ++i) { const int j = i ^ stride;
;                 if (j > i) { if ((i & size) == 0) CE_DESC(k[i], k[j]); else CE_DESC(k[j], k[i]); } }
; }
; __device__ __forceinline__ void peer_tile(const Args& A, LAS unsigned char* lds, int tile) {
;     ...
;                 { const bf16_t* sp = QRY + m * 2048 + hp * 128 + 32 * g;
;                   const u32x4 s0 = *(const u32x4*)sp, s1 = *(const u32x4*)(sp + 8), s2 = *(const u32x4*)(sp + 16), s3 = *(const u32x4*)(sp + 24);
;                   const unsigned sw[16] = {s0.x, s0.y, s0.z, s0.w, s1.x, s1.y, s1.z, s1.w, s2.x, s2.y, s2.z, s2.w, s3.x, s3.y, s3.z, s3.w};
; #pragma unroll
;                   for (int i = 0; i < 16; ++i) {
;                       const float lo = (float)__builtin_bit_cast(_Float16, (unsigned short)(sw[i] & 0xffffu)), hi = (float)__builtin_bit_cast(_Float16, (unsigned short)(sw[i] >> 16));
;                       const unsigned klo = (f2key(lo) & ~127u) | (unsigned)(127 - (32 * g + 2 * i)), khi = (f2key(hi) & ~127u) | (unsigned)(127 - (32 * g + 2 * i + 1));
;                       if (i < 8) { k0[2 * i] = klo; k0[2 * i + 1] = khi; } else { k1[2 * (i - 8)] = klo; k1[2 * (i - 8) + 1] = khi; } } }
;                 sort16_desc(k0); sort16_desc(k1); merge16(k0, k1);
	ds_write_b128 v64, v[0:3] offset:0
	ds_write_b128 v64, v[4:7] offset:1152
	ds_write_b128 v64, v[8:11] offset:2304
	ds_write_b128 v64, v[12:15] offset:3456
	ds_write_b128 v64, v[16:19] offset:4608
	ds_write_b128 v64, v[20:23] offset:5760
	ds_write_b128 v64, v[24:27] offset:6912
	ds_write_b128 v64, v[28:31] offset:8064
	s_waitcnt lgkmcnt(0)
	ds_read_b128 v[0:3], v65 offset:0
	ds_read_b128 v[4:7], v65 offset:16
	ds_read_b128 v[8:11], v65 offset:32
	ds_read_b128 v[12:15], v65 offset:48
	ds_read_b128 v[16:19], v65 offset:64
	ds_read_b128 v[20:23], v65 offset:80
	ds_read_b128 v[24:27], v65 offset:96
	ds_read_b128 v[28:31], v65 offset:112
	s_waitcnt lgkmcnt(0)
	v_cvt_f32_f16_e32 v86, v0
	v_cvt_f32_f16_sdwa v93, v0 dst_sel:DWORD dst_unused:UNUSED_PAD src0_sel:WORD_1
	v_ashrrev_i32_e32 v92, 31, v86
	v_lshl_or_b32 v92, v92, 7, s33
	v_xor_b32_e32 v86, v86, v92
	v_xor_b32_e32 v86, 0x7f, v86
	v_ashrrev_i32_e32 v92, 31, v93
	v_lshl_or_b32 v92, v92, 7, s33
	v_xor_b32_e32 v93, v93, v92
	v_xor_b32_e32 v93, 0x7e, v93
	v_cvt_f32_f16_e32 v92, v1
	v_cvt_f32_f16_sdwa v95, v1 dst_sel:DWORD dst_unused:UNUSED_PAD src0_sel:WORD_1
	v_ashrrev_i32_e32 v94, 31, v92
	v_lshl_or_b32 v94, v94, 7, s33
	v_xor_b32_e32 v92, v92, v94
	v_xor_b32_e32 v92, 0x7d, v92
	v_ashrrev_i32_e32 v94, 31, v95
	v_lshl_or_b32 v94, v94, 7, s33
	v_xor_b32_e32 v95, v95, v94
	v_xor_b32_e32 v95, 0x7c, v95
	v_cvt_f32_f16_e32 v94, v2
	v_cvt_f32_f16_sdwa v98, v2 dst_sel:DWORD dst_unused:UNUSED_PAD src0_sel:WORD_1
	v_ashrrev_i32_e32 v88, 31, v94
	v_lshl_or_b32 v88, v88, 7, s33
	v_xor_b32_e32 v94, v94, v88
	v_xor_b32_e32 v94, 0x7b, v94
	v_ashrrev_i32_e32 v88, 31, v98
	v_lshl_or_b32 v88, v88, 7, s33
	v_xor_b32_e32 v98, v98, v88
	v_xor_b32_e32 v98, 0x7a, v98
	v_cvt_f32_f16_e32 v88, v3
	v_cvt_f32_f16_sdwa v87, v3 dst_sel:DWORD dst_unused:UNUSED_PAD src0_sel:WORD_1
	v_ashrrev_i32_e32 v90, 31, v88
	v_lshl_or_b32 v90, v90, 7, s33
	v_xor_b32_e32 v88, v88, v90
	v_xor_b32_e32 v88, 0x79, v88
	v_ashrrev_i32_e32 v90, 31, v87
	v_lshl_or_b32 v90, v90, 7, s33
	v_xor_b32_e32 v87, v87, v90
	v_xor_b32_e32 v87, 0x78, v87
	v_cvt_f32_f16_e32 v90, v4
	v_cvt_f32_f16_sdwa v89, v4 dst_sel:DWORD dst_unused:UNUSED_PAD src0_sel:WORD_1
	v_ashrrev_i32_e32 v97, 31, v90
	v_lshl_or_b32 v97, v97, 7, s33
	v_xor_b32_e32 v90, v90, v97
	v_xor_b32_e32 v90, 0x77, v90
	v_ashrrev_i32_e32 v97, 31, v89
	v_lshl_or_b32 v97, v97, 7, s33
	v_xor_b32_e32 v89, v89, v97
	v_xor_b32_e32 v89, 0x76, v89
	v_cvt_f32_f16_e32 v97, v5
	v_cvt_f32_f16_sdwa v96, v5 dst_sel:DWORD dst_unused:UNUSED_PAD src0_sel:WORD_1
	v_ashrrev_i32_e32 v91, 31, v97
	v_lshl_or_b32 v91, v91, 7, s33
	v_xor_b32_e32 v97, v97, v91
	v_xor_b32_e32 v97, 0x75, v97
	v_ashrrev_i32_e32 v91, 31, v96
	v_lshl_or_b32 v91, v91, 7, s33
	v_xor_b32_e32 v96, v96, v91
	v_xor_b32_e32 v96, 0x74, v96
	v_cvt_f32_f16_e32 v91, v6
	v_cvt_f32_f16_sdwa v73, v6 dst_sel:DWORD dst_unused:UNUSED_PAD src0_sel:WORD_1
	v_ashrrev_i32_e32 v102, 31, v91
	v_lshl_or_b32 v102, v102, 7, s33
	v_xor_b32_e32 v91, v91, v102
	v_xor_b32_e32 v91, 0x73, v91
	v_ashrrev_i32_e32 v102, 31, v73
	v_lshl_or_b32 v102, v102, 7, s33
	v_xor_b32_e32 v73, v73, v102
	v_xor_b32_e32 v73, 0x72, v73
	v_cvt_f32_f16_e32 v102, v7
	v_cvt_f32_f16_sdwa v80, v7 dst_sel:DWORD dst_unused:UNUSED_PAD src0_sel:WORD_1
	v_ashrrev_i32_e32 v100, 31, v102
	v_lshl_or_b32 v100, v100, 7, s33
	v_xor_b32_e32 v102, v102, v100
	v_xor_b32_e32 v102, 0x71, v102
	v_ashrrev_i32_e32 v100, 31, v80
	v_lshl_or_b32 v100, v100, 7, s33
	v_xor_b32_e32 v80, v80, v100
	v_xor_b32_e32 v80, 0x70, v80
	v_max_u32_e32 v100, v86, v93
	v_min_u32_e32 v93, v86, v93
	v_max_u32_e32 v86, v92, v95
	v_min_u32_e32 v95, v92, v95
	v_max_u32_e32 v92, v100, v86
	v_min_u32_e32 v86, v100, v86
	v_max_u32_e32 v100, v93, v95
	v_min_u32_e32 v95, v93, v95
	v_max_u32_e32 v93, v100, v86
	v_min_u32_e32 v86, v100, v86
	v_max_u32_e32 v100, v94, v98
	v_min_u32_e32 v98, v94, v98
	v_max_u32_e32 v94, v88, v87
	v_min_u32_e32 v87, v88, v87
	v_max_u32_e32 v88, v100, v94
	v_min_u32_e32 v94, v100, v94
	v_max_u32_e32 v100, v98, v87
	v_min_u32_e32 v87, v98, v87
	v_max_u32_e32 v98, v100, v94
	v_min_u32_e32 v94, v100, v94
	v_max_u32_e32 v100, v92, v88
	v_min_u32_e32 v88, v92, v88
	v_max_u32_e32 v92, v86, v94
	v_min_u32_e32 v94, v86, v94
	v_max_u32_e32 v86, v92, v88
	v_min_u32_e32 v88, v92, v88
	v_max_u32_e32 v92, v93, v98
	v_min_u32_e32 v98, v93, v98
	v_max_u32_e32 v93, v95, v87
	v_min_u32_e32 v87, v95, v87
	v_max_u32_e32 v95, v93, v98
	v_min_u32_e32 v98, v93, v98
	v_max_u32_e32 v93, v92, v86
	v_min_u32_e32 v86, v92, v86
	v_max_u32_e32 v92, v95, v88
	v_min_u32_e32 v88, v95, v88
	v_max_u32_e32 v95, v98, v94
	v_min_u32_e32 v94, v98, v94
	v_max_u32_e32 v98, v90, v89
	v_min_u32_e32 v89, v90, v89
	v_max_u32_e32 v90, v97, v96
	v_min_u32_e32 v96, v97, v96
	v_max_u32_e32 v97, v98, v90
	v_min_u32_e32 v90, v98, v90
	v_max_u32_e32 v98, v89, v96
	v_min_u32_e32 v96, v89, v96
	v_max_u32_e32 v89, v98, v90
	v_min_u32_e32 v90, v98, v90
	v_max_u32_e32 v98, v91, v73
	v_min_u32_e32 v73, v91, v73
	v_max_u32_e32 v91, v102, v80
	v_min_u32_e32 v80, v102, v80
	v_max_u32_e32 v102, v98, v91
	v_min_u32_e32 v91, v98, v91
	v_max_u32_e32 v98, v73, v80
	v_min_u32_e32 v80, v73, v80
	v_max_u32_e32 v73, v98, v91
	v_min_u32_e32 v91, v98, v91
	v_max_u32_e32 v98, v97, v102
	v_min_u32_e32 v102, v97, v102
	v_max_u32_e32 v97, v90, v91
	v_min_u32_e32 v91, v90, v91
	v_max_u32_e32 v90, v97, v102
	v_min_u32_e32 v102, v97, v102
	v_max_u32_e32 v97, v89, v73
	v_min_u32_e32 v73, v89, v73
	v_max_u32_e32 v89, v96, v80
	v_min_u32_e32 v80, v96, v80
	v_max_u32_e32 v96, v89, v73
	v_min_u32_e32 v73, v89, v73
	v_max_u32_e32 v89, v97, v90
	v_min_u32_e32 v90, v97, v90
	v_max_u32_e32 v97, v96, v102
; __device__ __forceinline__ unsigned f2key(float f) { const unsigned u = __float_as_uint(f); return (u & 0x80000000u) ? ~u : (u | 0x80000000u); }
; #define CE_DESC(a, b) do { const unsigned _mx = (a) > (b) ? (a) : (b), _mn = (a) > (b) ? (b) : (a); (a) = _mx; (b) = _mn; } while (0)
; __device__ __forceinline__ void sort16_desc(unsigned (&k)[16]) {
; #pragma unroll
;     for (int size = 2; size <= 16; size <<= 1)
; #pragma unroll
;         for (int stride = size >> 1; stride > 0; stride >>= 1)
; #pragma unroll
;             for (int i = 0; i < 16; ++i) { const int j = i ^ stride;
;                 if (j > i) { if ((i & size) == 0) CE_DESC(k[i], k[j]); else CE_DESC(k[j], k[i]); } }
; }
; __device__ __forceinline__ void peer_tile(const Args& A, LAS unsigned char* lds, int tile) {
;     ...
;                   for (int i = 0; i < 16; ++i) {
;                       const float lo = (float)__builtin_bit_cast(_Float16, (unsigned short)(sw[i] & 0xffffu)), hi = (float)__builtin_bit_cast(_Float16, (unsigned short)(sw[i] >> 16));
;                       const unsigned klo = (f2key(lo) & ~127u) | (unsigned)(127 - (32 * g + 2 * i)), khi = (f2key(hi) & ~127u) | (unsigned)(127 - (32 * g + 2 * i + 1));
;                       if (i < 8) { k0[2 * i] = klo; k0[2 * i + 1] = khi; } else { k1[2 * (i - 8)] = klo; k1[2 * (i - 8) + 1] = khi; } } }
	v_min_u32_e32 v102, v96, v102
	v_max_u32_e32 v96, v73, v91
	v_min_u32_e32 v91, v73, v91
	v_max_u32_e32 v73, v100, v98
	v_min_u32_e32 v98, v100, v98
	v_max_u32_e32 v100, v88, v102
	v_min_u32_e32 v102, v88, v102
	v_max_u32_e32 v88, v100, v98
	v_min_u32_e32 v98, v100, v98
	v_max_u32_e32 v100, v86, v90
	v_min_u32_e32 v90, v86, v90
	v_max_u32_e32 v86, v94, v91
	v_min_u32_e32 v91, v94, v91
	v_max_u32_e32 v94, v86, v90
	v_min_u32_e32 v90, v86, v90
	v_max_u32_e32 v86, v100, v88
	v_min_u32_e32 v88, v100, v88
	v_max_u32_e32 v100, v94, v98
	v_min_u32_e32 v98, v94, v98
	v_max_u32_e32 v94, v90, v102
	v_min_u32_e32 v102, v90, v102
	v_max_u32_e32 v90, v93, v89
	v_min_u32_e32 v89, v93, v89
	v_max_u32_e32 v93, v95, v96
	v_min_u32_e32 v96, v95, v96
	v_max_u32_e32 v95, v93, v89
	v_min_u32_e32 v89, v93, v89
	v_max_u32_e32 v93, v92, v97
	v_min_u32_e32 v97, v92, v97
	v_max_u32_e32 v92, v87, v80
	v_min_u32_e32 v80, v87, v80
	v_max_u32_e32 v87, v92, v97
	v_min_u32_e32 v97, v92, v97
	v_max_u32_e32 v92, v93, v95
	v_min_u32_e32 v95, v93, v95
	v_max_u32_e32 v93, v87, v89
	v_min_u32_e32 v89, v87, v89
	v_max_u32_e32 v87, v97, v96
	v_min_u32_e32 v96, v97, v96
	v_max_u32_e32 v97, v90, v86
	v_min_u32_e32 v86, v90, v86
	v_max_u32_e32 v90, v92, v88
	v_min_u32_e32 v88, v92, v88
	v_max_u32_e32 v92, v95, v100
	v_min_u32_e32 v100, v95, v100
	v_max_u32_e32 v95, v93, v98
	v_min_u32_e32 v98, v93, v98
	v_max_u32_e32 v93, v89, v94
	v_min_u32_e32 v94, v89, v94
	v_max_u32_e32 v89, v87, v102
	v_min_u32_e32 v102, v87, v102
	v_max_u32_e32 v87, v96, v91
	v_min_u32_e32 v91, v96, v91
	v_cvt_f32_f16_e32 v96, v8
	v_cvt_f32_f16_sdwa v103, v8 dst_sel:DWORD dst_unused:UNUSED_PAD src0_sel:WORD_1
	v_ashrrev_i32_e32 v104, 31, v96
	v_lshl_or_b32 v104, v104, 7, s33
	v_xor_b32_e32 v96, v96, v104
	v_xor_b32_e32 v96, 0x6f, v96
	v_ashrrev_i32_e32 v104, 31, v103
	v_lshl_or_b32 v104, v104, 7, s33
	v_xor_b32_e32 v103, v103, v104
	v_xor_b32_e32 v103, 0x6e, v103
	v_cvt_f32_f16_e32 v104, v9
	v_cvt_f32_f16_sdwa v105, v9 dst_sel:DWORD dst_unused:UNUSED_PAD src0_sel:WORD_1
	v_ashrrev_i32_e32 v106, 31, v104
	v_lshl_or_b32 v106, v106, 7, s33
	v_xor_b32_e32 v104, v104, v106
	v_xor_b32_e32 v104, 0x6d, v104
	v_ashrrev_i32_e32 v106, 31, v105
	v_lshl_or_b32 v106, v106, 7, s33
	v_xor_b32_e32 v105, v105, v106
	v_xor_b32_e32 v105, 0x6c, v105
	v_cvt_f32_f16_e32 v106, v10
	v_cvt_f32_f16_sdwa v107, v10 dst_sel:DWORD dst_unused:UNUSED_PAD src0_sel:WORD_1
	v_ashrrev_i32_e32 v108, 31, v106
	v_lshl_or_b32 v108, v108, 7, s33
	v_xor_b32_e32 v106, v106, v108
	v_xor_b32_e32 v106, 0x6b, v106
	v_ashrrev_i32_e32 v108, 31, v107
	v_lshl_or_b32 v108, v108, 7, s33
	v_xor_b32_e32 v107, v107, v108
	v_xor_b32_e32 v107, 0x6a, v107
	v_cvt_f32_f16_e32 v108, v11
	v_cvt_f32_f16_sdwa v109, v11 dst_sel:DWORD dst_unused:UNUSED_PAD src0_sel:WORD_1
	v_ashrrev_i32_e32 v110, 31, v108
	v_lshl_or_b32 v110, v110, 7, s33
	v_xor_b32_e32 v108, v108, v110
	v_xor_b32_e32 v108, 0x69, v108
	v_ashrrev_i32_e32 v110, 31, v109
	v_lshl_or_b32 v110, v110, 7, s33
	v_xor_b32_e32 v109, v109, v110
	v_xor_b32_e32 v109, 0x68, v109
	v_cvt_f32_f16_e32 v110, v12
	v_cvt_f32_f16_sdwa v111, v12 dst_sel:DWORD dst_unused:UNUSED_PAD src0_sel:WORD_1
	v_ashrrev_i32_e32 v112, 31, v110
	v_lshl_or_b32 v112, v112, 7, s33
	v_xor_b32_e32 v110, v110, v112
	v_xor_b32_e32 v110, 0x67, v110
	v_ashrrev_i32_e32 v112, 31, v111
	v_lshl_or_b32 v112, v112, 7, s33
	v_xor_b32_e32 v111, v111, v112
	v_xor_b32_e32 v111, 0x66, v111
	v_cvt_f32_f16_e32 v112, v13
	v_cvt_f32_f16_sdwa v114, v13 dst_sel:DWORD dst_unused:UNUSED_PAD src0_sel:WORD_1
	v_ashrrev_i32_e32 v115, 31, v112
	v_lshl_or_b32 v115, v115, 7, s33
	v_xor_b32_e32 v112, v112, v115
	v_xor_b32_e32 v112, 0x65, v112
	v_ashrrev_i32_e32 v115, 31, v114
	v_lshl_or_b32 v115, v115, 7, s33
	v_xor_b32_e32 v114, v114, v115
	v_xor_b32_e32 v114, 0x64, v114
	v_cvt_f32_f16_e32 v115, v14
	v_cvt_f32_f16_sdwa v116, v14 dst_sel:DWORD dst_unused:UNUSED_PAD src0_sel:WORD_1
	v_ashrrev_i32_e32 v117, 31, v115
	v_lshl_or_b32 v117, v117, 7, s33
	v_xor_b32_e32 v115, v115, v117
	v_xor_b32_e32 v115, 0x63, v115
	v_ashrrev_i32_e32 v117, 31, v116
	v_lshl_or_b32 v117, v117, 7, s33
	v_xor_b32_e32 v116, v116, v117
	v_xor_b32_e32 v116, 0x62, v116
	v_cvt_f32_f16_e32 v117, v15
	v_cvt_f32_f16_sdwa v118, v15 dst_sel:DWORD dst_unused:UNUSED_PAD src0_sel:WORD_1
	v_ashrrev_i32_e32 v119, 31, v117
	v_lshl_or_b32 v119, v119, 7, s33
	v_xor_b32_e32 v117, v117, v119
	v_xor_b32_e32 v117, 0x61, v117
	v_ashrrev_i32_e32 v119, 31, v118
	v_lshl_or_b32 v119, v119, 7, s33
	v_xor_b32_e32 v118, v118, v119
	v_xor_b32_e32 v118, 0x60, v118
	v_max_u32_e32 v119, v96, v103
	v_min_u32_e32 v103, v96, v103
	v_max_u32_e32 v96, v104, v105
	v_min_u32_e32 v105, v104, v105
	v_max_u32_e32 v104, v119, v96
	v_min_u32_e32 v96, v119, v96
	v_max_u32_e32 v119, v103, v105
	v_min_u32_e32 v105, v103, v105
	v_max_u32_e32 v103, v119, v96
	v_min_u32_e32 v96, v119, v96
	v_max_u32_e32 v119, v106, v107
	v_min_u32_e32 v107, v106, v107
	v_max_u32_e32 v106, v108, v109
	v_min_u32_e32 v109, v108, v109
	v_max_u32_e32 v108, v119, v106
	v_min_u32_e32 v106, v119, v106
	v_max_u32_e32 v119, v107, v109
	v_min_u32_e32 v109, v107, v109
	v_max_u32_e32 v107, v119, v106
	v_min_u32_e32 v106, v119, v106
	v_max_u32_e32 v119, v104, v108
	v_min_u32_e32 v108, v104, v108
	v_max_u32_e32 v104, v96, v106
	v_min_u32_e32 v106, v96, v106
	v_max_u32_e32 v96, v104, v108
	v_min_u32_e32 v108, v104, v108
	v_max_u32_e32 v104, v103, v107
	v_min_u32_e32 v107, v103, v107
	v_max_u32_e32 v103, v105, v109
	v_min_u32_e32 v109, v105, v109
	v_max_u32_e32 v105, v103, v107
	v_min_u32_e32 v107, v103, v107
	v_max_u32_e32 v103, v104, v96
	v_min_u32_e32 v96, v104, v96
	v_max_u32_e32 v104, v105, v108
; __device__ __forceinline__ unsigned f2key(float f) { const unsigned u = __float_as_uint(f); return (u & 0x80000000u) ? ~u : (u | 0x80000000u); }
; #define CE_DESC(a, b) do { const unsigned _mx = (a) > (b) ? (a) : (b), _mn = (a) > (b) ? (b) : (a); (a) = _mx; (b) = _mn; } while (0)
; __device__ __forceinline__ void sort16_desc(unsigned (&k)[16]) {
; #pragma unroll
;     for (int size = 2; size <= 16; size <<= 1)
; #pragma unroll
;         for (int stride = size >> 1; stride > 0; stride >>= 1)
; #pragma unroll
;             for (int i = 0; i < 16; ++i) { const int j = i ^ stride;
;                 if (j > i) { if ((i & size) == 0) CE_DESC(k[i], k[j]); else CE_DESC(k[j], k[i]); } }
; }
; __device__ __forceinline__ void merge16(unsigned (&a)[16], const unsigned (&b)[16]) {
; #pragma unroll
;     for (int i = 0; i < 16; ++i) a[i] = a[i] > b[15 - i] ? a[i] : b[15 - i];
; #pragma unroll
;     for (int stride = 8; stride > 0; stride >>= 1)
; #pragma unroll
;         for (int i = 0; i < 16; ++i) { const int j = i ^ stride; if (j > i) CE_DESC(a[i], a[j]); }
; }
; __device__ __forceinline__ void peer_tile(const Args& A, LAS unsigned char* lds, int tile) {
;     ...
;                   for (int i = 0; i < 16; ++i) {
;                       const float lo = (float)__builtin_bit_cast(_Float16, (unsigned short)(sw[i] & 0xffffu)), hi = (float)__builtin_bit_cast(_Float16, (unsigned short)(sw[i] >> 16));
;                       const unsigned klo = (f2key(lo) & ~127u) | (unsigned)(127 - (32 * g + 2 * i)), khi = (f2key(hi) & ~127u) | (unsigned)(127 - (32 * g + 2 * i + 1));
;                       if (i < 8) { k0[2 * i] = klo; k0[2 * i + 1] = khi; } else { k1[2 * (i - 8)] = klo; k1[2 * (i - 8) + 1] = khi; } } }
	v_min_u32_e32 v108, v105, v108
	v_max_u32_e32 v105, v107, v106
	v_min_u32_e32 v106, v107, v106
	v_max_u32_e32 v107, v110, v111
	v_min_u32_e32 v111, v110, v111
	v_max_u32_e32 v110, v112, v114
	v_min_u32_e32 v114, v112, v114
	v_max_u32_e32 v112, v107, v110
	v_min_u32_e32 v110, v107, v110
	v_max_u32_e32 v107, v111, v114
	v_min_u32_e32 v114, v111, v114
	v_max_u32_e32 v111, v107, v110
	v_min_u32_e32 v110, v107, v110
	v_max_u32_e32 v107, v115, v116
	v_min_u32_e32 v116, v115, v116
	v_max_u32_e32 v115, v117, v118
	v_min_u32_e32 v118, v117, v118
	v_max_u32_e32 v117, v107, v115
	v_min_u32_e32 v115, v107, v115
	v_max_u32_e32 v107, v116, v118
	v_min_u32_e32 v118, v116, v118
	v_max_u32_e32 v116, v107, v115
	v_min_u32_e32 v115, v107, v115
	v_max_u32_e32 v107, v112, v117
	v_min_u32_e32 v117, v112, v117
	v_max_u32_e32 v112, v110, v115
	v_min_u32_e32 v115, v110, v115
	v_max_u32_e32 v110, v112, v117
	v_min_u32_e32 v117, v112, v117
	v_max_u32_e32 v112, v111, v116
	v_min_u32_e32 v116, v111, v116
	v_max_u32_e32 v111, v114, v118
	v_min_u32_e32 v118, v114, v118
	v_max_u32_e32 v114, v111, v116
	v_min_u32_e32 v116, v111, v116
	v_max_u32_e32 v111, v112, v110
	v_min_u32_e32 v110, v112, v110
	v_max_u32_e32 v112, v114, v117
	v_min_u32_e32 v117, v114, v117
	v_max_u32_e32 v114, v116, v115
	v_min_u32_e32 v115, v116, v115
	v_max_u32_e32 v116, v119, v107
	v_min_u32_e32 v107, v119, v107
	v_max_u32_e32 v119, v108, v117
	v_min_u32_e32 v117, v108, v117
	v_max_u32_e32 v108, v119, v107
	v_min_u32_e32 v107, v119, v107
	v_max_u32_e32 v119, v96, v110
	v_min_u32_e32 v110, v96, v110
	v_max_u32_e32 v96, v106, v115
	v_min_u32_e32 v115, v106, v115
	v_max_u32_e32 v106, v96, v110
	v_min_u32_e32 v110, v96, v110
	v_max_u32_e32 v96, v119, v108
	v_min_u32_e32 v108, v119, v108
	v_max_u32_e32 v119, v106, v107
	v_min_u32_e32 v107, v106, v107
	v_max_u32_e32 v106, v110, v117
	v_min_u32_e32 v117, v110, v117
	v_max_u32_e32 v110, v103, v111
	v_min_u32_e32 v111, v103, v111
	v_max_u32_e32 v103, v105, v114
	v_min_u32_e32 v114, v105, v114
	v_max_u32_e32 v105, v103, v111
	v_min_u32_e32 v111, v103, v111
	v_max_u32_e32 v103, v104, v112
	v_min_u32_e32 v112, v104, v112
	v_max_u32_e32 v104, v109, v118
	v_min_u32_e32 v118, v109, v118
	v_max_u32_e32 v109, v104, v112
	v_min_u32_e32 v112, v104, v112
	v_max_u32_e32 v104, v103, v105
	v_min_u32_e32 v105, v103, v105
	v_max_u32_e32 v103, v109, v111
	v_min_u32_e32 v111, v109, v111
	v_max_u32_e32 v109, v112, v114
	v_min_u32_e32 v114, v112, v114
	v_max_u32_e32 v112, v110, v96
	v_min_u32_e32 v96, v110, v96
	v_max_u32_e32 v110, v104, v108
	v_min_u32_e32 v108, v104, v108
	v_max_u32_e32 v104, v105, v119
	v_min_u32_e32 v119, v105, v119
	v_max_u32_e32 v105, v103, v107
	v_min_u32_e32 v107, v103, v107
	v_max_u32_e32 v103, v111, v106
	v_min_u32_e32 v106, v111, v106
	v_max_u32_e32 v111, v109, v117
	v_min_u32_e32 v117, v109, v117
	v_max_u32_e32 v109, v114, v115
	v_min_u32_e32 v115, v114, v115
	v_max_u32_e32 v73, v73, v118
	v_max_u32_e32 v97, v97, v115
	v_max_u32_e32 v86, v86, v109
	v_max_u32_e32 v90, v90, v117
	v_max_u32_e32 v88, v88, v111
	v_max_u32_e32 v92, v92, v106
	v_max_u32_e32 v100, v100, v103
	v_max_u32_e32 v95, v95, v107
	v_max_u32_e32 v98, v98, v105
	v_max_u32_e32 v93, v93, v119
	v_max_u32_e32 v94, v94, v104
	v_max_u32_e32 v89, v89, v108
	v_max_u32_e32 v102, v102, v110
	v_max_u32_e32 v87, v87, v96
	v_max_u32_e32 v91, v91, v112
	v_max_u32_e32 v80, v80, v116
	v_max_u32_e32 v118, v73, v98
	v_min_u32_e32 v98, v73, v98
	v_max_u32_e32 v73, v97, v93
	v_min_u32_e32 v93, v97, v93
	v_max_u32_e32 v97, v86, v94
	v_min_u32_e32 v94, v86, v94
	v_max_u32_e32 v86, v90, v89
	v_min_u32_e32 v89, v90, v89
	v_max_u32_e32 v90, v88, v102
	v_min_u32_e32 v102, v88, v102
	v_max_u32_e32 v88, v92, v87
	v_min_u32_e32 v87, v92, v87
	v_max_u32_e32 v92, v100, v91
	v_min_u32_e32 v91, v100, v91
	v_max_u32_e32 v100, v95, v80
	v_min_u32_e32 v80, v95, v80
	v_max_u32_e32 v95, v118, v90
	v_min_u32_e32 v90, v118, v90
	v_max_u32_e32 v118, v73, v88
	v_min_u32_e32 v88, v73, v88
	v_max_u32_e32 v73, v97, v92
	v_min_u32_e32 v92, v97, v92
	v_max_u32_e32 v97, v86, v100
	v_min_u32_e32 v100, v86, v100
	v_max_u32_e32 v86, v98, v102
	v_min_u32_e32 v102, v98, v102
	v_max_u32_e32 v98, v93, v87
	v_min_u32_e32 v87, v93, v87
	v_max_u32_e32 v93, v94, v91
	v_min_u32_e32 v91, v94, v91
	v_max_u32_e32 v94, v89, v80
	v_min_u32_e32 v80, v89, v80
	v_max_u32_e32 v89, v95, v73
	v_min_u32_e32 v73, v95, v73
	v_max_u32_e32 v95, v118, v97
	v_min_u32_e32 v97, v118, v97
	v_max_u32_e32 v118, v90, v92
	v_min_u32_e32 v92, v90, v92
	v_max_u32_e32 v90, v88, v100
	v_min_u32_e32 v100, v88, v100
	v_max_u32_e32 v88, v86, v93
	v_min_u32_e32 v93, v86, v93
	v_max_u32_e32 v86, v98, v94
	v_min_u32_e32 v94, v98, v94
	v_max_u32_e32 v98, v102, v91
	v_min_u32_e32 v91, v102, v91
	v_max_u32_e32 v102, v87, v80
	v_min_u32_e32 v80, v87, v80
	v_max_u32_e32 v87, v89, v95
	v_min_u32_e32 v95, v89, v95
	v_max_u32_e32 v89, v73, v97
	v_min_u32_e32 v97, v73, v97
	v_max_u32_e32 v73, v118, v90
	v_min_u32_e32 v90, v118, v90
	v_max_u32_e32 v118, v92, v100
	v_min_u32_e32 v100, v92, v100
	v_max_u32_e32 v92, v88, v86
	v_min_u32_e32 v86, v88, v86
	v_max_u32_e32 v88, v93, v94
	v_min_u32_e32 v94, v93, v94
	v_max_u32_e32 v93, v98, v102
	v_min_u32_e32 v102, v98, v102
	v_max_u32_e32 v98, v91, v80
	v_min_u32_e32 v80, v91, v80
	v_cvt_f32_f16_e32 v91, v16
	v_cvt_f32_f16_sdwa v115, v16 dst_sel:DWORD dst_unused:UNUSED_PAD src0_sel:WORD_1
	v_ashrrev_i32_e32 v109, 31, v91
	v_lshl_or_b32 v109, v109, 7, s33
	v_xor_b32_e32 v91, v91, v109
	v_xor_b32_e32 v91, 0x5f, v91
	v_ashrrev_i32_e32 v109, 31, v115
	v_lshl_or_b32 v109, v109, 7, s33
	v_xor_b32_e32 v115, v115, v109
	v_xor_b32_e32 v115, 0x5e, v115
; __device__ __forceinline__ unsigned f2key(float f) { const unsigned u = __float_as_uint(f); return (u & 0x80000000u) ? ~u : (u | 0x80000000u); }
; #define CE_DESC(a, b) do { const unsigned _mx = (a) > (b) ? (a) : (b), _mn = (a) > (b) ? (b) : (a); (a) = _mx; (b) = _mn; } while (0)
; __device__ __forceinline__ void sort16_desc(unsigned (&k)[16]) {
; #pragma unroll
;     for (int size = 2; size <= 16; size <<= 1)
; #pragma unroll
;         for (int stride = size >> 1; stride > 0; stride >>= 1)
; #pragma unroll
;             for (int i = 0; i < 16; ++i) { const int j = i ^ stride;
;                 if (j > i) { if ((i & size) == 0) CE_DESC(k[i], k[j]); else CE_DESC(k[j], k[i]); } }
; }
; __device__ __forceinline__ void peer_tile(const Args& A, LAS unsigned char* lds, int tile) {
;     ...
;                   for (int i = 0; i < 16; ++i) {
;                       const float lo = (float)__builtin_bit_cast(_Float16, (unsigned short)(sw[i] & 0xffffu)), hi = (float)__builtin_bit_cast(_Float16, (unsigned short)(sw[i] >> 16));
;                       const unsigned klo = (f2key(lo) & ~127u) | (unsigned)(127 - (32 * g + 2 * i)), khi = (f2key(hi) & ~127u) | (unsigned)(127 - (32 * g + 2 * i + 1));
;                       if (i < 8) { k0[2 * i] = klo; k0[2 * i + 1] = khi; } else { k1[2 * (i - 8)] = klo; k1[2 * (i - 8) + 1] = khi; } } }
	v_cvt_f32_f16_e32 v109, v17
	v_cvt_f32_f16_sdwa v117, v17 dst_sel:DWORD dst_unused:UNUSED_PAD src0_sel:WORD_1
	v_ashrrev_i32_e32 v111, 31, v109
	v_lshl_or_b32 v111, v111, 7, s33
	v_xor_b32_e32 v109, v109, v111
	v_xor_b32_e32 v109, 0x5d, v109
	v_ashrrev_i32_e32 v111, 31, v117
	v_lshl_or_b32 v111, v111, 7, s33
	v_xor_b32_e32 v117, v117, v111
	v_xor_b32_e32 v117, 0x5c, v117
	v_cvt_f32_f16_e32 v111, v18
	v_cvt_f32_f16_sdwa v106, v18 dst_sel:DWORD dst_unused:UNUSED_PAD src0_sel:WORD_1
	v_ashrrev_i32_e32 v103, 31, v111
	v_lshl_or_b32 v103, v103, 7, s33
	v_xor_b32_e32 v111, v111, v103
	v_xor_b32_e32 v111, 0x5b, v111
	v_ashrrev_i32_e32 v103, 31, v106
	v_lshl_or_b32 v103, v103, 7, s33
	v_xor_b32_e32 v106, v106, v103
	v_xor_b32_e32 v106, 0x5a, v106
	v_cvt_f32_f16_e32 v103, v19
	v_cvt_f32_f16_sdwa v107, v19 dst_sel:DWORD dst_unused:UNUSED_PAD src0_sel:WORD_1
	v_ashrrev_i32_e32 v105, 31, v103
	v_lshl_or_b32 v105, v105, 7, s33
	v_xor_b32_e32 v103, v103, v105
	v_xor_b32_e32 v103, 0x59, v103
	v_ashrrev_i32_e32 v105, 31, v107
	v_lshl_or_b32 v105, v105, 7, s33
	v_xor_b32_e32 v107, v107, v105
	v_xor_b32_e32 v107, 0x58, v107
	v_cvt_f32_f16_e32 v105, v20
	v_cvt_f32_f16_sdwa v119, v20 dst_sel:DWORD dst_unused:UNUSED_PAD src0_sel:WORD_1
	v_ashrrev_i32_e32 v104, 31, v105
	v_lshl_or_b32 v104, v104, 7, s33
	v_xor_b32_e32 v105, v105, v104
	v_xor_b32_e32 v105, 0x57, v105
	v_ashrrev_i32_e32 v104, 31, v119
	v_lshl_or_b32 v104, v104, 7, s33
	v_xor_b32_e32 v119, v119, v104
	v_xor_b32_e32 v119, 0x56, v119
	v_cvt_f32_f16_e32 v104, v21
	v_cvt_f32_f16_sdwa v108, v21 dst_sel:DWORD dst_unused:UNUSED_PAD src0_sel:WORD_1
	v_ashrrev_i32_e32 v110, 31, v104
	v_lshl_or_b32 v110, v110, 7, s33
	v_xor_b32_e32 v104, v104, v110
	v_xor_b32_e32 v104, 0x55, v104
	v_ashrrev_i32_e32 v110, 31, v108
	v_lshl_or_b32 v110, v110, 7, s33
	v_xor_b32_e32 v108, v108, v110
	v_xor_b32_e32 v108, 0x54, v108
	v_cvt_f32_f16_e32 v110, v22
	v_cvt_f32_f16_sdwa v96, v22 dst_sel:DWORD dst_unused:UNUSED_PAD src0_sel:WORD_1
	v_ashrrev_i32_e32 v112, 31, v110
	v_lshl_or_b32 v112, v112, 7, s33
	v_xor_b32_e32 v110, v110, v112
	v_xor_b32_e32 v110, 0x53, v110
	v_ashrrev_i32_e32 v112, 31, v96
	v_lshl_or_b32 v112, v112, 7, s33
	v_xor_b32_e32 v96, v96, v112
	v_xor_b32_e32 v96, 0x52, v96
	v_cvt_f32_f16_e32 v112, v23
	v_cvt_f32_f16_sdwa v116, v23 dst_sel:DWORD dst_unused:UNUSED_PAD src0_sel:WORD_1
	v_ashrrev_i32_e32 v114, 31, v112
	v_lshl_or_b32 v114, v114, 7, s33
	v_xor_b32_e32 v112, v112, v114
	v_xor_b32_e32 v112, 0x51, v112
	v_ashrrev_i32_e32 v114, 31, v116
	v_lshl_or_b32 v114, v114, 7, s33
	v_xor_b32_e32 v116, v116, v114
	v_xor_b32_e32 v116, 0x50, v116
	v_max_u32_e32 v114, v91, v115
	v_min_u32_e32 v115, v91, v115
	v_max_u32_e32 v91, v109, v117
	v_min_u32_e32 v117, v109, v117
	v_max_u32_e32 v109, v114, v91
	v_min_u32_e32 v91, v114, v91
	v_max_u32_e32 v114, v115, v117
	v_min_u32_e32 v117, v115, v117
	v_max_u32_e32 v115, v114, v91
	v_min_u32_e32 v91, v114, v91
	v_max_u32_e32 v114, v111, v106
	v_min_u32_e32 v106, v111, v106
	v_max_u32_e32 v111, v103, v107
	v_min_u32_e32 v107, v103, v107
	v_max_u32_e32 v103, v114, v111
	v_min_u32_e32 v111, v114, v111
	v_max_u32_e32 v114, v106, v107
	v_min_u32_e32 v107, v106, v107
	v_max_u32_e32 v106, v114, v111
	v_min_u32_e32 v111, v114, v111
	v_max_u32_e32 v114, v109, v103
	v_min_u32_e32 v103, v109, v103
	v_max_u32_e32 v109, v91, v111
	v_min_u32_e32 v111, v91, v111
	v_max_u32_e32 v91, v109, v103
	v_min_u32_e32 v103, v109, v103
	v_max_u32_e32 v109, v115, v106
	v_min_u32_e32 v106, v115, v106
	v_max_u32_e32 v115, v117, v107
	v_min_u32_e32 v107, v117, v107
	v_max_u32_e32 v117, v115, v106
	v_min_u32_e32 v106, v115, v106
	v_max_u32_e32 v115, v109, v91
	v_min_u32_e32 v91, v109, v91
	v_max_u32_e32 v109, v117, v103
	v_min_u32_e32 v103, v117, v103
	v_max_u32_e32 v117, v106, v111
	v_min_u32_e32 v111, v106, v111
	v_max_u32_e32 v106, v105, v119
	v_min_u32_e32 v119, v105, v119
	v_max_u32_e32 v105, v104, v108
	v_min_u32_e32 v108, v104, v108
	v_max_u32_e32 v104, v106, v105
	v_min_u32_e32 v105, v106, v105
	v_max_u32_e32 v106, v119, v108
	v_min_u32_e32 v108, v119, v108
	v_max_u32_e32 v119, v106, v105
	v_min_u32_e32 v105, v106, v105
	v_max_u32_e32 v106, v110, v96
	v_min_u32_e32 v96, v110, v96
	v_max_u32_e32 v110, v112, v116
	v_min_u32_e32 v116, v112, v116
	v_max_u32_e32 v112, v106, v110
	v_min_u32_e32 v110, v106, v110
	v_max_u32_e32 v106, v96, v116
	v_min_u32_e32 v116, v96, v116
	v_max_u32_e32 v96, v106, v110
	v_min_u32_e32 v110, v106, v110
	v_max_u32_e32 v106, v104, v112
	v_min_u32_e32 v112, v104, v112
	v_max_u32_e32 v104, v105, v110
	v_min_u32_e32 v110, v105, v110
	v_max_u32_e32 v105, v104, v112
	v_min_u32_e32 v112, v104, v112
	v_max_u32_e32 v104, v119, v96
	v_min_u32_e32 v96, v119, v96
	v_max_u32_e32 v119, v108, v116
	v_min_u32_e32 v116, v108, v116
	v_max_u32_e32 v108, v119, v96
	v_min_u32_e32 v96, v119, v96
	v_max_u32_e32 v119, v104, v105
	v_min_u32_e32 v105, v104, v105
	v_max_u32_e32 v104, v108, v112
	v_min_u32_e32 v112, v108, v112
	v_max_u32_e32 v108, v96, v110
	v_min_u32_e32 v110, v96, v110
	v_max_u32_e32 v96, v114, v106
	v_min_u32_e32 v106, v114, v106
	v_max_u32_e32 v114, v103, v112
	v_min_u32_e32 v112, v103, v112
	v_max_u32_e32 v103, v114, v106
	v_min_u32_e32 v106, v114, v106
	v_max_u32_e32 v114, v91, v105
	v_min_u32_e32 v105, v91, v105
	v_max_u32_e32 v91, v111, v110
	v_min_u32_e32 v110, v111, v110
	v_max_u32_e32 v111, v91, v105
	v_min_u32_e32 v105, v91, v105
	v_max_u32_e32 v91, v114, v103
	v_min_u32_e32 v103, v114, v103
	v_max_u32_e32 v114, v111, v106
	v_min_u32_e32 v106, v111, v106
	v_max_u32_e32 v111, v105, v112
	v_min_u32_e32 v112, v105, v112
	v_max_u32_e32 v105, v115, v119
	v_min_u32_e32 v119, v115, v119
; __device__ __forceinline__ unsigned f2key(float f) { const unsigned u = __float_as_uint(f); return (u & 0x80000000u) ? ~u : (u | 0x80000000u); }
; #define CE_DESC(a, b) do { const unsigned _mx = (a) > (b) ? (a) : (b), _mn = (a) > (b) ? (b) : (a); (a) = _mx; (b) = _mn; } while (0)
; __device__ __forceinline__ void sort16_desc(unsigned (&k)[16]) {
; #pragma unroll
;     for (int size = 2; size <= 16; size <<= 1)
; #pragma unroll
;         for (int stride = size >> 1; stride > 0; stride >>= 1)
; #pragma unroll
;             for (int i = 0; i < 16; ++i) { const int j = i ^ stride;
;                 if (j > i) { if ((i & size) == 0) CE_DESC(k[i], k[j]); else CE_DESC(k[j], k[i]); } }
; }
; __device__ __forceinline__ void merge16(unsigned (&a)[16], const unsigned (&b)[16]) {
; #pragma unroll
;     for (int i = 0; i < 16; ++i) a[i] = a[i] > b[15 - i] ? a[i] : b[15 - i];
; #pragma unroll
;     for (int stride = 8; stride > 0; stride >>= 1)
; #pragma unroll
;         for (int i = 0; i < 16; ++i) { const int j = i ^ stride; if (j > i) CE_DESC(a[i], a[j]); }
; }
; __device__ __forceinline__ void peer_tile(const Args& A, LAS unsigned char* lds, int tile) {
;     ...
;                   for (int i = 0; i < 16; ++i) {
;                       const float lo = (float)__builtin_bit_cast(_Float16, (unsigned short)(sw[i] & 0xffffu)), hi = (float)__builtin_bit_cast(_Float16, (unsigned short)(sw[i] >> 16));
;                       const unsigned klo = (f2key(lo) & ~127u) | (unsigned)(127 - (32 * g + 2 * i)), khi = (f2key(hi) & ~127u) | (unsigned)(127 - (32 * g + 2 * i + 1));
;                       if (i < 8) { k0[2 * i] = klo; k0[2 * i + 1] = khi; } else { k1[2 * (i - 8)] = klo; k1[2 * (i - 8) + 1] = khi; } } }
	v_max_u32_e32 v115, v117, v108
	v_min_u32_e32 v108, v117, v108
	v_max_u32_e32 v117, v115, v119
	v_min_u32_e32 v119, v115, v119
	v_max_u32_e32 v115, v109, v104
	v_min_u32_e32 v104, v109, v104
	v_max_u32_e32 v109, v107, v116
	v_min_u32_e32 v116, v107, v116
	v_max_u32_e32 v107, v109, v104
	v_min_u32_e32 v104, v109, v104
	v_max_u32_e32 v109, v115, v117
	v_min_u32_e32 v117, v115, v117
	v_max_u32_e32 v115, v107, v119
	v_min_u32_e32 v119, v107, v119
	v_max_u32_e32 v107, v104, v108
	v_min_u32_e32 v108, v104, v108
	v_max_u32_e32 v104, v105, v91
	v_min_u32_e32 v91, v105, v91
	v_max_u32_e32 v105, v109, v103
	v_min_u32_e32 v103, v109, v103
	v_max_u32_e32 v109, v117, v114
	v_min_u32_e32 v114, v117, v114
	v_max_u32_e32 v117, v115, v106
	v_min_u32_e32 v106, v115, v106
	v_max_u32_e32 v115, v119, v111
	v_min_u32_e32 v111, v119, v111
	v_max_u32_e32 v119, v107, v112
	v_min_u32_e32 v112, v107, v112
	v_max_u32_e32 v107, v108, v110
	v_min_u32_e32 v110, v108, v110
	v_max_u32_e32 v87, v87, v116
	v_max_u32_e32 v95, v95, v110
	v_max_u32_e32 v89, v89, v107
	v_max_u32_e32 v97, v97, v112
	v_max_u32_e32 v73, v73, v119
	v_max_u32_e32 v90, v90, v111
	v_max_u32_e32 v118, v118, v115
	v_max_u32_e32 v100, v100, v106
	v_max_u32_e32 v92, v92, v117
	v_max_u32_e32 v86, v86, v114
	v_max_u32_e32 v88, v88, v109
	v_max_u32_e32 v94, v94, v103
	v_max_u32_e32 v93, v93, v105
	v_max_u32_e32 v102, v102, v91
	v_max_u32_e32 v98, v98, v104
	v_max_u32_e32 v80, v80, v96
	v_max_u32_e32 v116, v87, v92
	v_min_u32_e32 v92, v87, v92
	v_max_u32_e32 v87, v95, v86
	v_min_u32_e32 v86, v95, v86
	v_max_u32_e32 v95, v89, v88
	v_min_u32_e32 v88, v89, v88
	v_max_u32_e32 v89, v97, v94
	v_min_u32_e32 v94, v97, v94
	v_max_u32_e32 v97, v73, v93
	v_min_u32_e32 v93, v73, v93
	v_max_u32_e32 v73, v90, v102
	v_min_u32_e32 v102, v90, v102
	v_max_u32_e32 v90, v118, v98
	v_min_u32_e32 v98, v118, v98
	v_max_u32_e32 v118, v100, v80
	v_min_u32_e32 v80, v100, v80
	v_max_u32_e32 v100, v116, v97
	v_min_u32_e32 v97, v116, v97
	v_max_u32_e32 v116, v87, v73
	v_min_u32_e32 v73, v87, v73
	v_max_u32_e32 v87, v95, v90
	v_min_u32_e32 v90, v95, v90
	v_max_u32_e32 v95, v89, v118
	v_min_u32_e32 v118, v89, v118
	v_max_u32_e32 v89, v92, v93
	v_min_u32_e32 v93, v92, v93
	v_max_u32_e32 v92, v86, v102
	v_min_u32_e32 v102, v86, v102
	v_max_u32_e32 v86, v88, v98
	v_min_u32_e32 v98, v88, v98
	v_max_u32_e32 v88, v94, v80
	v_min_u32_e32 v80, v94, v80
	v_max_u32_e32 v94, v100, v87
	v_min_u32_e32 v87, v100, v87
	v_max_u32_e32 v100, v116, v95
	v_min_u32_e32 v95, v116, v95
	v_max_u32_e32 v116, v97, v90
	v_min_u32_e32 v90, v97, v90
	v_max_u32_e32 v97, v73, v118
	v_min_u32_e32 v118, v73, v118
	v_max_u32_e32 v73, v89, v86
	v_min_u32_e32 v86, v89, v86
	v_max_u32_e32 v89, v92, v88
	v_min_u32_e32 v88, v92, v88
	v_max_u32_e32 v92, v93, v98
	v_min_u32_e32 v98, v93, v98
	v_max_u32_e32 v93, v102, v80
	v_min_u32_e32 v80, v102, v80
	v_max_u32_e32 v102, v94, v100
	v_min_u32_e32 v100, v94, v100
	v_max_u32_e32 v94, v87, v95
	v_min_u32_e32 v95, v87, v95
	v_max_u32_e32 v87, v116, v97
	v_min_u32_e32 v97, v116, v97
	v_max_u32_e32 v116, v90, v118
	v_min_u32_e32 v118, v90, v118
	v_max_u32_e32 v90, v73, v89
	v_min_u32_e32 v89, v73, v89
	v_max_u32_e32 v73, v86, v88
	v_min_u32_e32 v88, v86, v88
	v_max_u32_e32 v86, v92, v93
	v_min_u32_e32 v93, v92, v93
	v_max_u32_e32 v92, v98, v80
	v_min_u32_e32 v80, v98, v80
	v_cvt_f32_f16_e32 v98, v24
	v_cvt_f32_f16_sdwa v110, v24 dst_sel:DWORD dst_unused:UNUSED_PAD src0_sel:WORD_1
	v_ashrrev_i32_e32 v107, 31, v98
	v_lshl_or_b32 v107, v107, 7, s33
	v_xor_b32_e32 v98, v98, v107
	v_xor_b32_e32 v98, 0x4f, v98
	v_ashrrev_i32_e32 v107, 31, v110
	v_lshl_or_b32 v107, v107, 7, s33
	v_xor_b32_e32 v110, v110, v107
	v_xor_b32_e32 v110, 0x4e, v110
	v_cvt_f32_f16_e32 v107, v25
	v_cvt_f32_f16_sdwa v112, v25 dst_sel:DWORD dst_unused:UNUSED_PAD src0_sel:WORD_1
	v_ashrrev_i32_e32 v119, 31, v107
	v_lshl_or_b32 v119, v119, 7, s33
	v_xor_b32_e32 v107, v107, v119
	v_xor_b32_e32 v107, 0x4d, v107
	v_ashrrev_i32_e32 v119, 31, v112
	v_lshl_or_b32 v119, v119, 7, s33
	v_xor_b32_e32 v112, v112, v119
	v_xor_b32_e32 v112, 0x4c, v112
	v_cvt_f32_f16_e32 v119, v26
	v_cvt_f32_f16_sdwa v111, v26 dst_sel:DWORD dst_unused:UNUSED_PAD src0_sel:WORD_1
	v_ashrrev_i32_e32 v115, 31, v119
	v_lshl_or_b32 v115, v115, 7, s33
	v_xor_b32_e32 v119, v119, v115
	v_xor_b32_e32 v119, 0x4b, v119
	v_ashrrev_i32_e32 v115, 31, v111
	v_lshl_or_b32 v115, v115, 7, s33
	v_xor_b32_e32 v111, v111, v115
	v_xor_b32_e32 v111, 0x4a, v111
	v_cvt_f32_f16_e32 v115, v27
	v_cvt_f32_f16_sdwa v106, v27 dst_sel:DWORD dst_unused:UNUSED_PAD src0_sel:WORD_1
	v_ashrrev_i32_e32 v117, 31, v115
	v_lshl_or_b32 v117, v117, 7, s33
	v_xor_b32_e32 v115, v115, v117
	v_xor_b32_e32 v115, 0x49, v115
	v_ashrrev_i32_e32 v117, 31, v106
	v_lshl_or_b32 v117, v117, 7, s33
	v_xor_b32_e32 v106, v106, v117
	v_xor_b32_e32 v106, 0x48, v106
	v_cvt_f32_f16_e32 v117, v28
	v_cvt_f32_f16_sdwa v114, v28 dst_sel:DWORD dst_unused:UNUSED_PAD src0_sel:WORD_1
	v_ashrrev_i32_e32 v109, 31, v117
	v_lshl_or_b32 v109, v109, 7, s33
	v_xor_b32_e32 v117, v117, v109
	v_xor_b32_e32 v117, 0x47, v117
	v_ashrrev_i32_e32 v109, 31, v114
	v_lshl_or_b32 v109, v109, 7, s33
	v_xor_b32_e32 v114, v114, v109
	v_xor_b32_e32 v114, 0x46, v114
	v_cvt_f32_f16_e32 v109, v29
	v_cvt_f32_f16_sdwa v103, v29 dst_sel:DWORD dst_unused:UNUSED_PAD src0_sel:WORD_1
	v_ashrrev_i32_e32 v105, 31, v109
	v_lshl_or_b32 v105, v105, 7, s33
	v_xor_b32_e32 v109, v109, v105
	v_xor_b32_e32 v109, 0x45, v109
	v_ashrrev_i32_e32 v105, 31, v103
	v_lshl_or_b32 v105, v105, 7, s33
	v_xor_b32_e32 v103, v103, v105
	v_xor_b32_e32 v103, 0x44, v103
	v_cvt_f32_f16_e32 v105, v30
; __device__ __forceinline__ unsigned f2key(float f) { const unsigned u = __float_as_uint(f); return (u & 0x80000000u) ? ~u : (u | 0x80000000u); }
; #define CE_DESC(a, b) do { const unsigned _mx = (a) > (b) ? (a) : (b), _mn = (a) > (b) ? (b) : (a); (a) = _mx; (b) = _mn; } while (0)
; __device__ __forceinline__ void sort16_desc(unsigned (&k)[16]) {
; #pragma unroll
;     for (int size = 2; size <= 16; size <<= 1)
; #pragma unroll
;         for (int stride = size >> 1; stride > 0; stride >>= 1)
; #pragma unroll
;             for (int i = 0; i < 16; ++i) { const int j = i ^ stride;
;                 if (j > i) { if ((i & size) == 0) CE_DESC(k[i], k[j]); else CE_DESC(k[j], k[i]); } }
; }
; __device__ __forceinline__ void merge16(unsigned (&a)[16], const unsigned (&b)[16]) {
; #pragma unroll
;     for (int i = 0; i < 16; ++i) a[i] = a[i] > b[15 - i] ? a[i] : b[15 - i];
; #pragma unroll
;     for (int stride = 8; stride > 0; stride >>= 1)
; #pragma unroll
;         for (int i = 0; i < 16; ++i) { const int j = i ^ stride; if (j > i) CE_DESC(a[i], a[j]); }
; }
; __device__ __forceinline__ void peer_tile(const Args& A, LAS unsigned char* lds, int tile) {
;     ...
;                   for (int i = 0; i < 16; ++i) {
;                       const float lo = (float)__builtin_bit_cast(_Float16, (unsigned short)(sw[i] & 0xffffu)), hi = (float)__builtin_bit_cast(_Float16, (unsigned short)(sw[i] >> 16));
;                       const unsigned klo = (f2key(lo) & ~127u) | (unsigned)(127 - (32 * g + 2 * i)), khi = (f2key(hi) & ~127u) | (unsigned)(127 - (32 * g + 2 * i + 1));
;                       if (i < 8) { k0[2 * i] = klo; k0[2 * i + 1] = khi; } else { k1[2 * (i - 8)] = klo; k1[2 * (i - 8) + 1] = khi; } } }
	v_cvt_f32_f16_sdwa v91, v30 dst_sel:DWORD dst_unused:UNUSED_PAD src0_sel:WORD_1
	v_ashrrev_i32_e32 v104, 31, v105
	v_lshl_or_b32 v104, v104, 7, s33
	v_xor_b32_e32 v105, v105, v104
	v_xor_b32_e32 v105, 0x43, v105
	v_ashrrev_i32_e32 v104, 31, v91
	v_lshl_or_b32 v104, v104, 7, s33
	v_xor_b32_e32 v91, v91, v104
	v_xor_b32_e32 v91, 0x42, v91
	v_cvt_f32_f16_e32 v104, v31
	v_cvt_f32_f16_sdwa v96, v31 dst_sel:DWORD dst_unused:UNUSED_PAD src0_sel:WORD_1
	v_ashrrev_i32_e32 v108, 31, v104
	v_lshl_or_b32 v108, v108, 7, s33
	v_xor_b32_e32 v104, v104, v108
	v_xor_b32_e32 v104, 0x41, v104
	v_ashrrev_i32_e32 v108, 31, v96
	v_lshl_or_b32 v108, v108, 7, s33
	v_xor_b32_e32 v96, v96, v108
	v_xor_b32_e32 v96, 64, v96
	v_max_u32_e32 v108, v98, v110
	v_min_u32_e32 v110, v98, v110
	v_max_u32_e32 v98, v107, v112
	v_min_u32_e32 v112, v107, v112
	v_max_u32_e32 v107, v108, v98
	v_min_u32_e32 v98, v108, v98
	v_max_u32_e32 v108, v110, v112
	v_min_u32_e32 v112, v110, v112
	v_max_u32_e32 v110, v108, v98
	v_min_u32_e32 v98, v108, v98
	v_max_u32_e32 v108, v119, v111
	v_min_u32_e32 v111, v119, v111
	v_max_u32_e32 v119, v115, v106
	v_min_u32_e32 v106, v115, v106
	v_max_u32_e32 v115, v108, v119
	v_min_u32_e32 v119, v108, v119
	v_max_u32_e32 v108, v111, v106
	v_min_u32_e32 v106, v111, v106
	v_max_u32_e32 v111, v108, v119
	v_min_u32_e32 v119, v108, v119
	v_max_u32_e32 v108, v107, v115
	v_min_u32_e32 v115, v107, v115
	v_max_u32_e32 v107, v98, v119
	v_min_u32_e32 v119, v98, v119
	v_max_u32_e32 v98, v107, v115
	v_min_u32_e32 v115, v107, v115
	v_max_u32_e32 v107, v110, v111
	v_min_u32_e32 v111, v110, v111
	v_max_u32_e32 v110, v112, v106
	v_min_u32_e32 v106, v112, v106
	v_max_u32_e32 v112, v110, v111
	v_min_u32_e32 v111, v110, v111
	v_max_u32_e32 v110, v107, v98
	v_min_u32_e32 v98, v107, v98
	v_max_u32_e32 v107, v112, v115
	v_min_u32_e32 v115, v112, v115
	v_max_u32_e32 v112, v111, v119
	v_min_u32_e32 v119, v111, v119
	v_max_u32_e32 v111, v117, v114
	v_min_u32_e32 v114, v117, v114
	v_max_u32_e32 v117, v109, v103
	v_min_u32_e32 v103, v109, v103
	v_max_u32_e32 v109, v111, v117
	v_min_u32_e32 v117, v111, v117
	v_max_u32_e32 v111, v114, v103
	v_min_u32_e32 v103, v114, v103
	v_max_u32_e32 v114, v111, v117
	v_min_u32_e32 v117, v111, v117
	v_max_u32_e32 v111, v105, v91
	v_min_u32_e32 v91, v105, v91
	v_max_u32_e32 v105, v104, v96
	v_min_u32_e32 v96, v104, v96
	v_max_u32_e32 v104, v111, v105
	v_min_u32_e32 v105, v111, v105
	v_max_u32_e32 v111, v91, v96
	v_min_u32_e32 v96, v91, v96
	v_max_u32_e32 v91, v111, v105
	v_min_u32_e32 v105, v111, v105
	v_max_u32_e32 v111, v109, v104
	v_min_u32_e32 v104, v109, v104
	v_max_u32_e32 v109, v117, v105
	v_min_u32_e32 v105, v117, v105
	v_max_u32_e32 v117, v109, v104
	v_min_u32_e32 v104, v109, v104
	v_max_u32_e32 v109, v114, v91
	v_min_u32_e32 v91, v114, v91
	v_max_u32_e32 v114, v103, v96
	v_min_u32_e32 v96, v103, v96
	v_max_u32_e32 v103, v114, v91
	v_min_u32_e32 v91, v114, v91
	v_max_u32_e32 v114, v109, v117
	v_min_u32_e32 v117, v109, v117
	v_max_u32_e32 v109, v103, v104
	v_min_u32_e32 v104, v103, v104
	v_max_u32_e32 v103, v91, v105
	v_min_u32_e32 v105, v91, v105
	v_max_u32_e32 v91, v108, v111
	v_min_u32_e32 v111, v108, v111
	v_max_u32_e32 v108, v115, v104
	v_min_u32_e32 v104, v115, v104
	v_max_u32_e32 v115, v108, v111
	v_min_u32_e32 v111, v108, v111
	v_max_u32_e32 v108, v98, v117
	v_min_u32_e32 v117, v98, v117
	v_max_u32_e32 v98, v119, v105
	v_min_u32_e32 v105, v119, v105
	v_max_u32_e32 v119, v98, v117
	v_min_u32_e32 v117, v98, v117
	v_max_u32_e32 v98, v108, v115
	v_min_u32_e32 v115, v108, v115
	v_max_u32_e32 v108, v119, v111
	v_min_u32_e32 v111, v119, v111
	v_max_u32_e32 v119, v117, v104
	v_min_u32_e32 v104, v117, v104
	v_max_u32_e32 v117, v110, v114
	v_min_u32_e32 v114, v110, v114
	v_max_u32_e32 v110, v112, v103
	v_min_u32_e32 v103, v112, v103
	v_max_u32_e32 v112, v110, v114
	v_min_u32_e32 v114, v110, v114
	v_max_u32_e32 v110, v107, v109
	v_min_u32_e32 v109, v107, v109
	v_max_u32_e32 v107, v106, v96
	v_min_u32_e32 v96, v106, v96
	v_max_u32_e32 v106, v107, v109
	v_min_u32_e32 v109, v107, v109
	v_max_u32_e32 v107, v110, v112
	v_min_u32_e32 v112, v110, v112
	v_max_u32_e32 v110, v106, v114
	v_min_u32_e32 v114, v106, v114
	v_max_u32_e32 v106, v109, v103
	v_min_u32_e32 v103, v109, v103
	v_max_u32_e32 v109, v117, v98
	v_min_u32_e32 v98, v117, v98
	v_max_u32_e32 v117, v107, v115
	v_min_u32_e32 v115, v107, v115
	v_max_u32_e32 v107, v112, v108
	v_min_u32_e32 v108, v112, v108
	v_max_u32_e32 v112, v110, v111
	v_min_u32_e32 v111, v110, v111
	v_max_u32_e32 v110, v114, v119
	v_min_u32_e32 v119, v114, v119
	v_max_u32_e32 v114, v106, v104
	v_min_u32_e32 v104, v106, v104
	v_max_u32_e32 v106, v103, v105
	v_min_u32_e32 v105, v103, v105
	v_max_u32_e32 v102, v102, v96
	v_max_u32_e32 v100, v100, v105
	v_max_u32_e32 v94, v94, v106
	v_max_u32_e32 v95, v95, v104
	v_max_u32_e32 v87, v87, v114
	v_max_u32_e32 v97, v97, v119
	v_max_u32_e32 v116, v116, v110
	v_max_u32_e32 v118, v118, v111
	v_max_u32_e32 v90, v90, v112
	v_max_u32_e32 v89, v89, v108
	v_max_u32_e32 v73, v73, v107
	v_max_u32_e32 v88, v88, v115
	v_max_u32_e32 v86, v86, v117
	v_max_u32_e32 v93, v93, v98
	v_max_u32_e32 v92, v92, v109
	v_max_u32_e32 v80, v80, v91
	v_max_u32_e32 v96, v102, v90
	v_min_u32_e32 v90, v102, v90
	v_max_u32_e32 v102, v100, v89
	v_min_u32_e32 v89, v100, v89
	v_max_u32_e32 v100, v94, v73
	v_min_u32_e32 v73, v94, v73
	v_max_u32_e32 v94, v95, v88
	v_min_u32_e32 v88, v95, v88
	v_max_u32_e32 v95, v87, v86
	v_min_u32_e32 v86, v87, v86
	v_max_u32_e32 v87, v97, v93
	v_min_u32_e32 v93, v97, v93
	v_max_u32_e32 v97, v116, v92
	v_min_u32_e32 v92, v116, v92
	v_max_u32_e32 v116, v118, v80
	v_min_u32_e32 v80, v118, v80
; __device__ __forceinline__ unsigned f2key(float f) { const unsigned u = __float_as_uint(f); return (u & 0x80000000u) ? ~u : (u | 0x80000000u); }
; #define CE_DESC(a, b) do { const unsigned _mx = (a) > (b) ? (a) : (b), _mn = (a) > (b) ? (b) : (a); (a) = _mx; (b) = _mn; } while (0)
; __device__ __forceinline__ void merge16(unsigned (&a)[16], const unsigned (&b)[16]) {
; #pragma unroll
;     for (int i = 0; i < 16; ++i) a[i] = a[i] > b[15 - i] ? a[i] : b[15 - i];
; #pragma unroll
;     for (int stride = 8; stride > 0; stride >>= 1)
; #pragma unroll
;         for (int i = 0; i < 16; ++i) { const int j = i ^ stride; if (j > i) CE_DESC(a[i], a[j]); }
; }
; __device__ __forceinline__ void peer_tile(const Args& A, LAS unsigned char* lds, int tile) {
;     ...
;                 { const bf16_t* sp = QRY + m * 2048 + hp * 128 + 32 * g;
;                   const u32x4 s0 = *(const u32x4*)sp, s1 = *(const u32x4*)(sp + 8), s2 = *(const u32x4*)(sp + 16), s3 = *(const u32x4*)(sp + 24);
;                   const unsigned sw[16] = {s0.x, s0.y, s0.z, s0.w, s1.x, s1.y, s1.z, s1.w, s2.x, s2.y, s2.z, s2.w, s3.x, s3.y, s3.z, s3.w};
; #pragma unroll
;                   for (int i = 0; i < 16; ++i) {
;                       const float lo = (float)__builtin_bit_cast(_Float16, (unsigned short)(sw[i] & 0xffffu)), hi = (float)__builtin_bit_cast(_Float16, (unsigned short)(sw[i] >> 16));
;                       const unsigned klo = (f2key(lo) & ~127u) | (unsigned)(127 - (32 * g + 2 * i)), khi = (f2key(hi) & ~127u) | (unsigned)(127 - (32 * g + 2 * i + 1));
;                       if (i < 8) { k0[2 * i] = klo; k0[2 * i + 1] = khi; } else { k1[2 * (i - 8)] = klo; k1[2 * (i - 8) + 1] = khi; } } }
	v_max_u32_e32 v118, v96, v95
	v_min_u32_e32 v95, v96, v95
	v_max_u32_e32 v96, v102, v87
	v_min_u32_e32 v87, v102, v87
	v_max_u32_e32 v102, v100, v97
	v_min_u32_e32 v97, v100, v97
	v_max_u32_e32 v100, v94, v116
	v_min_u32_e32 v116, v94, v116
	v_max_u32_e32 v94, v90, v86
	v_min_u32_e32 v86, v90, v86
	v_max_u32_e32 v90, v89, v93
	v_min_u32_e32 v93, v89, v93
	v_max_u32_e32 v89, v73, v92
	v_min_u32_e32 v92, v73, v92
	v_max_u32_e32 v73, v88, v80
	v_min_u32_e32 v80, v88, v80
	v_max_u32_e32 v88, v118, v102
	v_min_u32_e32 v102, v118, v102
	v_max_u32_e32 v118, v96, v100
	v_min_u32_e32 v100, v96, v100
	v_max_u32_e32 v96, v95, v97
	v_min_u32_e32 v97, v95, v97
	v_max_u32_e32 v95, v87, v116
	v_min_u32_e32 v116, v87, v116
	v_max_u32_e32 v87, v94, v89
	v_min_u32_e32 v89, v94, v89
	v_max_u32_e32 v94, v90, v73
	v_min_u32_e32 v73, v90, v73
	v_max_u32_e32 v90, v86, v92
	v_min_u32_e32 v92, v86, v92
	v_max_u32_e32 v86, v93, v80
	v_min_u32_e32 v80, v93, v80
	v_max_u32_e32 v93, v88, v118
	v_min_u32_e32 v118, v88, v118
	v_max_u32_e32 v88, v102, v100
	v_min_u32_e32 v100, v102, v100
	v_max_u32_e32 v102, v96, v95
	v_min_u32_e32 v95, v96, v95
	v_max_u32_e32 v96, v97, v116
	v_min_u32_e32 v116, v97, v116
	v_max_u32_e32 v97, v87, v94
	v_min_u32_e32 v94, v87, v94
	v_max_u32_e32 v87, v89, v73
	v_min_u32_e32 v73, v89, v73
	v_max_u32_e32 v89, v90, v86
	v_min_u32_e32 v86, v90, v86
	v_max_u32_e32 v90, v92, v80
	v_min_u32_e32 v80, v92, v80
	s_waitcnt vmcnt(0)
	ds_write_b128 v64, v[32:35] offset:0
	ds_write_b128 v64, v[36:39] offset:1152
	ds_write_b128 v64, v[40:43] offset:2304
	ds_write_b128 v64, v[44:47] offset:3456
	ds_write_b128 v64, v[48:51] offset:4608
	ds_write_b128 v64, v[52:55] offset:5760
	ds_write_b128 v64, v[56:59] offset:6912
	ds_write_b128 v64, v[60:63] offset:8064
	s_waitcnt lgkmcnt(0)
	ds_read_b128 v[32:35], v65 offset:0
	ds_read_b128 v[36:39], v65 offset:16
	ds_read_b128 v[40:43], v65 offset:32
	ds_read_b128 v[44:47], v65 offset:48
	ds_read_b128 v[48:51], v65 offset:64
	ds_read_b128 v[52:55], v65 offset:80
	ds_read_b128 v[56:59], v65 offset:96
	ds_read_b128 v[60:63], v65 offset:112
	s_waitcnt lgkmcnt(0)
	v_cvt_f32_f16_e32 v92, v32
	v_cvt_f32_f16_sdwa v105, v32 dst_sel:DWORD dst_unused:UNUSED_PAD src0_sel:WORD_1
	v_ashrrev_i32_e32 v106, 31, v92
	v_lshl_or_b32 v106, v106, 7, s33
	v_xor_b32_e32 v92, v92, v106
	v_xor_b32_e32 v92, 63, v92
	v_ashrrev_i32_e32 v106, 31, v105
	v_lshl_or_b32 v106, v106, 7, s33
	v_xor_b32_e32 v105, v105, v106
	v_xor_b32_e32 v105, 62, v105
	v_cvt_f32_f16_e32 v106, v33
	v_cvt_f32_f16_sdwa v104, v33 dst_sel:DWORD dst_unused:UNUSED_PAD src0_sel:WORD_1
	v_ashrrev_i32_e32 v114, 31, v106
	v_lshl_or_b32 v114, v114, 7, s33
	v_xor_b32_e32 v106, v106, v114
	v_xor_b32_e32 v106, 61, v106
	v_ashrrev_i32_e32 v114, 31, v104
	v_lshl_or_b32 v114, v114, 7, s33
	v_xor_b32_e32 v104, v104, v114
	v_xor_b32_e32 v104, 60, v104
	v_cvt_f32_f16_e32 v114, v34
	v_cvt_f32_f16_sdwa v119, v34 dst_sel:DWORD dst_unused:UNUSED_PAD src0_sel:WORD_1
	v_ashrrev_i32_e32 v110, 31, v114
	v_lshl_or_b32 v110, v110, 7, s33
	v_xor_b32_e32 v114, v114, v110
	v_xor_b32_e32 v114, 59, v114
	v_ashrrev_i32_e32 v110, 31, v119
	v_lshl_or_b32 v110, v110, 7, s33
	v_xor_b32_e32 v119, v119, v110
	v_xor_b32_e32 v119, 58, v119
	v_cvt_f32_f16_e32 v110, v35
	v_cvt_f32_f16_sdwa v111, v35 dst_sel:DWORD dst_unused:UNUSED_PAD src0_sel:WORD_1
	v_ashrrev_i32_e32 v112, 31, v110
	v_lshl_or_b32 v112, v112, 7, s33
	v_xor_b32_e32 v110, v110, v112
	v_xor_b32_e32 v110, 57, v110
	v_ashrrev_i32_e32 v112, 31, v111
	v_lshl_or_b32 v112, v112, 7, s33
	v_xor_b32_e32 v111, v111, v112
	v_xor_b32_e32 v111, 56, v111
	v_cvt_f32_f16_e32 v112, v36
	v_cvt_f32_f16_sdwa v108, v36 dst_sel:DWORD dst_unused:UNUSED_PAD src0_sel:WORD_1
	v_ashrrev_i32_e32 v107, 31, v112
	v_lshl_or_b32 v107, v107, 7, s33
	v_xor_b32_e32 v112, v112, v107
	v_xor_b32_e32 v112, 55, v112
	v_ashrrev_i32_e32 v107, 31, v108
	v_lshl_or_b32 v107, v107, 7, s33
	v_xor_b32_e32 v108, v108, v107
	v_xor_b32_e32 v108, 54, v108
	v_cvt_f32_f16_e32 v107, v37
	v_cvt_f32_f16_sdwa v115, v37 dst_sel:DWORD dst_unused:UNUSED_PAD src0_sel:WORD_1
	v_ashrrev_i32_e32 v117, 31, v107
	v_lshl_or_b32 v117, v117, 7, s33
	v_xor_b32_e32 v107, v107, v117
	v_xor_b32_e32 v107, 53, v107
	v_ashrrev_i32_e32 v117, 31, v115
	v_lshl_or_b32 v117, v117, 7, s33
	v_xor_b32_e32 v115, v115, v117
	v_xor_b32_e32 v115, 52, v115
	v_cvt_f32_f16_e32 v117, v38
	v_cvt_f32_f16_sdwa v98, v38 dst_sel:DWORD dst_unused:UNUSED_PAD src0_sel:WORD_1
	v_ashrrev_i32_e32 v109, 31, v117
	v_lshl_or_b32 v109, v109, 7, s33
	v_xor_b32_e32 v117, v117, v109
	v_xor_b32_e32 v117, 51, v117
	v_ashrrev_i32_e32 v109, 31, v98
	v_lshl_or_b32 v109, v109, 7, s33
	v_xor_b32_e32 v98, v98, v109
	v_xor_b32_e32 v98, 50, v98
	v_cvt_f32_f16_e32 v109, v39
	v_cvt_f32_f16_sdwa v91, v39 dst_sel:DWORD dst_unused:UNUSED_PAD src0_sel:WORD_1
	v_ashrrev_i32_e32 v103, 31, v109
	v_lshl_or_b32 v103, v103, 7, s33
	v_xor_b32_e32 v109, v109, v103
	v_xor_b32_e32 v109, 49, v109
	v_ashrrev_i32_e32 v103, 31, v91
	v_lshl_or_b32 v103, v103, 7, s33
	v_xor_b32_e32 v91, v91, v103
	v_xor_b32_e32 v91, 48, v91
	v_max_u32_e32 v103, v92, v105
	v_min_u32_e32 v105, v92, v105
	v_max_u32_e32 v92, v106, v104
	v_min_u32_e32 v104, v106, v104
	v_max_u32_e32 v106, v103, v92
	v_min_u32_e32 v92, v103, v92
	v_max_u32_e32 v103, v105, v104
	v_min_u32_e32 v104, v105, v104
	v_max_u32_e32 v105, v103, v92
	v_min_u32_e32 v92, v103, v92
	v_max_u32_e32 v103, v114, v119
	v_min_u32_e32 v119, v114, v119
	v_max_u32_e32 v114, v110, v111
	v_min_u32_e32 v111, v110, v111
	v_max_u32_e32 v110, v103, v114
	v_min_u32_e32 v114, v103, v114
	v_max_u32_e32 v103, v119, v111
	v_min_u32_e32 v111, v119, v111
; #define CE_DESC(a, b) do { const unsigned _mx = (a) > (b) ? (a) : (b), _mn = (a) > (b) ? (b) : (a); (a) = _mx; (b) = _mn; } while (0)
; __device__ __forceinline__ void sort16_desc(unsigned (&k)[16]) {
; #pragma unroll
;     for (int size = 2; size <= 16; size <<= 1)
; #pragma unroll
;         for (int stride = size >> 1; stride > 0; stride >>= 1)
; #pragma unroll
;             for (int i = 0; i < 16; ++i) { const int j = i ^ stride;
;                 if (j > i) { if ((i & size) == 0) CE_DESC(k[i], k[j]); else CE_DESC(k[j], k[i]); } }
; }
; __device__ __forceinline__ void merge16(unsigned (&a)[16], const unsigned (&b)[16]) {
; #pragma unroll
;     for (int i = 0; i < 16; ++i) a[i] = a[i] > b[15 - i] ? a[i] : b[15 - i];
; #pragma unroll
;     for (int stride = 8; stride > 0; stride >>= 1)
; #pragma unroll
;         for (int i = 0; i < 16; ++i) { const int j = i ^ stride; if (j > i) CE_DESC(a[i], a[j]); }
; }
	v_max_u32_e32 v119, v103, v114
	v_min_u32_e32 v114, v103, v114
	v_max_u32_e32 v103, v106, v110
	v_min_u32_e32 v110, v106, v110
	v_max_u32_e32 v106, v92, v114
	v_min_u32_e32 v114, v92, v114
	v_max_u32_e32 v92, v106, v110
	v_min_u32_e32 v110, v106, v110
	v_max_u32_e32 v106, v105, v119
	v_min_u32_e32 v119, v105, v119
	v_max_u32_e32 v105, v104, v111
	v_min_u32_e32 v111, v104, v111
	v_max_u32_e32 v104, v105, v119
	v_min_u32_e32 v119, v105, v119
	v_max_u32_e32 v105, v106, v92
	v_min_u32_e32 v92, v106, v92
	v_max_u32_e32 v106, v104, v110
	v_min_u32_e32 v110, v104, v110
	v_max_u32_e32 v104, v119, v114
	v_min_u32_e32 v114, v119, v114
	v_max_u32_e32 v119, v112, v108
	v_min_u32_e32 v108, v112, v108
	v_max_u32_e32 v112, v107, v115
	v_min_u32_e32 v115, v107, v115
	v_max_u32_e32 v107, v119, v112
	v_min_u32_e32 v112, v119, v112
	v_max_u32_e32 v119, v108, v115
	v_min_u32_e32 v115, v108, v115
	v_max_u32_e32 v108, v119, v112
	v_min_u32_e32 v112, v119, v112
	v_max_u32_e32 v119, v117, v98
	v_min_u32_e32 v98, v117, v98
	v_max_u32_e32 v117, v109, v91
	v_min_u32_e32 v91, v109, v91
	v_max_u32_e32 v109, v119, v117
	v_min_u32_e32 v117, v119, v117
	v_max_u32_e32 v119, v98, v91
	v_min_u32_e32 v91, v98, v91
	v_max_u32_e32 v98, v119, v117
	v_min_u32_e32 v117, v119, v117
	v_max_u32_e32 v119, v107, v109
	v_min_u32_e32 v109, v107, v109
	v_max_u32_e32 v107, v112, v117
	v_min_u32_e32 v117, v112, v117
	v_max_u32_e32 v112, v107, v109
	v_min_u32_e32 v109, v107, v109
	v_max_u32_e32 v107, v108, v98
	v_min_u32_e32 v98, v108, v98
	v_max_u32_e32 v108, v115, v91
	v_min_u32_e32 v91, v115, v91
	v_max_u32_e32 v115, v108, v98
	v_min_u32_e32 v98, v108, v98
	v_max_u32_e32 v108, v107, v112
	v_min_u32_e32 v112, v107, v112
	v_max_u32_e32 v107, v115, v109
	v_min_u32_e32 v109, v115, v109
	v_max_u32_e32 v115, v98, v117
	v_min_u32_e32 v117, v98, v117
	v_max_u32_e32 v98, v103, v119
	v_min_u32_e32 v119, v103, v119
	v_max_u32_e32 v103, v110, v109
	v_min_u32_e32 v109, v110, v109
	v_max_u32_e32 v110, v103, v119
	v_min_u32_e32 v119, v103, v119
	v_max_u32_e32 v103, v92, v112
	v_min_u32_e32 v112, v92, v112
	v_max_u32_e32 v92, v114, v117
	v_min_u32_e32 v117, v114, v117
	v_max_u32_e32 v114, v92, v112
	v_min_u32_e32 v112, v92, v112
	v_max_u32_e32 v92, v103, v110
	v_min_u32_e32 v110, v103, v110
	v_max_u32_e32 v103, v114, v119
	v_min_u32_e32 v119, v114, v119
	v_max_u32_e32 v114, v112, v109
	v_min_u32_e32 v109, v112, v109
	v_max_u32_e32 v112, v105, v108
	v_min_u32_e32 v108, v105, v108
	v_max_u32_e32 v105, v104, v115
	v_min_u32_e32 v115, v104, v115
	v_max_u32_e32 v104, v105, v108
	v_min_u32_e32 v108, v105, v108
	v_max_u32_e32 v105, v106, v107
	v_min_u32_e32 v107, v106, v107
	v_max_u32_e32 v106, v111, v91
	v_min_u32_e32 v91, v111, v91
	v_max_u32_e32 v111, v106, v107
	v_min_u32_e32 v107, v106, v107
	v_max_u32_e32 v106, v105, v104
	v_min_u32_e32 v104, v105, v104
	v_max_u32_e32 v105, v111, v108
	v_min_u32_e32 v108, v111, v108
	v_max_u32_e32 v111, v107, v115
	v_min_u32_e32 v115, v107, v115
	v_max_u32_e32 v107, v112, v92
	v_min_u32_e32 v92, v112, v92
	v_max_u32_e32 v112, v106, v110
	v_min_u32_e32 v110, v106, v110
	v_max_u32_e32 v106, v104, v103
	v_min_u32_e32 v103, v104, v103
	v_max_u32_e32 v104, v105, v119
	v_min_u32_e32 v119, v105, v119
	v_max_u32_e32 v105, v108, v114
	v_min_u32_e32 v114, v108, v114
	v_max_u32_e32 v108, v111, v109
	v_min_u32_e32 v109, v111, v109
	v_max_u32_e32 v111, v115, v117
	v_min_u32_e32 v117, v115, v117
	v_max_u32_e32 v93, v93, v91
	v_max_u32_e32 v118, v118, v117
	v_max_u32_e32 v88, v88, v111
	v_max_u32_e32 v100, v100, v109
	v_max_u32_e32 v102, v102, v108
	v_max_u32_e32 v95, v95, v114
	v_max_u32_e32 v96, v96, v105
	v_max_u32_e32 v116, v116, v119
	v_max_u32_e32 v97, v97, v104
	v_max_u32_e32 v94, v94, v103
	v_max_u32_e32 v87, v87, v106
	v_max_u32_e32 v73, v73, v110
	v_max_u32_e32 v89, v89, v112
	v_max_u32_e32 v86, v86, v92
	v_max_u32_e32 v90, v90, v107
	v_max_u32_e32 v80, v80, v98
	v_max_u32_e32 v91, v93, v97
	v_min_u32_e32 v97, v93, v97
	v_max_u32_e32 v93, v118, v94
	v_min_u32_e32 v94, v118, v94
	v_max_u32_e32 v118, v88, v87
	v_min_u32_e32 v87, v88, v87
	v_max_u32_e32 v88, v100, v73
	v_min_u32_e32 v73, v100, v73
	v_max_u32_e32 v100, v102, v89
	v_min_u32_e32 v89, v102, v89
	v_max_u32_e32 v102, v95, v86
	v_min_u32_e32 v86, v95, v86
	v_max_u32_e32 v95, v96, v90
	v_min_u32_e32 v90, v96, v90
	v_max_u32_e32 v96, v116, v80
	v_min_u32_e32 v80, v116, v80
	v_max_u32_e32 v116, v91, v100
	v_min_u32_e32 v100, v91, v100
	v_max_u32_e32 v91, v93, v102
	v_min_u32_e32 v102, v93, v102
	v_max_u32_e32 v93, v118, v95
	v_min_u32_e32 v95, v118, v95
	v_max_u32_e32 v118, v88, v96
	v_min_u32_e32 v96, v88, v96
	v_max_u32_e32 v88, v97, v89
	v_min_u32_e32 v89, v97, v89
	v_max_u32_e32 v97, v94, v86
	v_min_u32_e32 v86, v94, v86
	v_max_u32_e32 v94, v87, v90
	v_min_u32_e32 v90, v87, v90
	v_max_u32_e32 v87, v73, v80
	v_min_u32_e32 v80, v73, v80
	v_max_u32_e32 v73, v116, v93
	v_min_u32_e32 v93, v116, v93
	v_max_u32_e32 v116, v91, v118
	v_min_u32_e32 v118, v91, v118
	v_max_u32_e32 v91, v100, v95
	v_min_u32_e32 v95, v100, v95
	v_max_u32_e32 v100, v102, v96
	v_min_u32_e32 v96, v102, v96
	v_max_u32_e32 v102, v88, v94
	v_min_u32_e32 v94, v88, v94
	v_max_u32_e32 v88, v97, v87
	v_min_u32_e32 v87, v97, v87
	v_max_u32_e32 v97, v89, v90
	v_min_u32_e32 v90, v89, v90
	v_max_u32_e32 v89, v86, v80
	v_min_u32_e32 v80, v86, v80
	v_max_u32_e32 v86, v73, v116
	v_min_u32_e32 v116, v73, v116
	v_max_u32_e32 v73, v93, v118
	v_min_u32_e32 v118, v93, v118
	v_max_u32_e32 v93, v91, v100
	v_min_u32_e32 v100, v91, v100
	v_max_u32_e32 v91, v95, v96
	v_min_u32_e32 v96, v95, v96
	v_max_u32_e32 v95, v102, v88
	v_min_u32_e32 v88, v102, v88
; __device__ __forceinline__ unsigned f2key(float f) { const unsigned u = __float_as_uint(f); return (u & 0x80000000u) ? ~u : (u | 0x80000000u); }
; #define CE_DESC(a, b) do { const unsigned _mx = (a) > (b) ? (a) : (b), _mn = (a) > (b) ? (b) : (a); (a) = _mx; (b) = _mn; } while (0)
; __device__ __forceinline__ void sort16_desc(unsigned (&k)[16]) {
; #pragma unroll
;     for (int size = 2; size <= 16; size <<= 1)
; #pragma unroll
;         for (int stride = size >> 1; stride > 0; stride >>= 1)
; #pragma unroll
;             for (int i = 0; i < 16; ++i) { const int j = i ^ stride;
;                 if (j > i) { if ((i & size) == 0) CE_DESC(k[i], k[j]); else CE_DESC(k[j], k[i]); } }
; }
; __device__ __forceinline__ void peer_tile(const Args& A, LAS unsigned char* lds, int tile) {
;     ...
;                   for (int i = 0; i < 16; ++i) {
;                       const float lo = (float)__builtin_bit_cast(_Float16, (unsigned short)(sw[i] & 0xffffu)), hi = (float)__builtin_bit_cast(_Float16, (unsigned short)(sw[i] >> 16));
;                       const unsigned klo = (f2key(lo) & ~127u) | (unsigned)(127 - (32 * g + 2 * i)), khi = (f2key(hi) & ~127u) | (unsigned)(127 - (32 * g + 2 * i + 1));
;                       if (i < 8) { k0[2 * i] = klo; k0[2 * i + 1] = khi; } else { k1[2 * (i - 8)] = klo; k1[2 * (i - 8) + 1] = khi; } } }
	v_max_u32_e32 v102, v94, v87
	v_min_u32_e32 v87, v94, v87
	v_max_u32_e32 v94, v97, v89
	v_min_u32_e32 v89, v97, v89
	v_max_u32_e32 v97, v90, v80
	v_min_u32_e32 v80, v90, v80
	v_cvt_f32_f16_e32 v90, v40
	v_cvt_f32_f16_sdwa v117, v40 dst_sel:DWORD dst_unused:UNUSED_PAD src0_sel:WORD_1
	v_ashrrev_i32_e32 v111, 31, v90
	v_lshl_or_b32 v111, v111, 7, s33
	v_xor_b32_e32 v90, v90, v111
	v_xor_b32_e32 v90, 47, v90
	v_ashrrev_i32_e32 v111, 31, v117
	v_lshl_or_b32 v111, v111, 7, s33
	v_xor_b32_e32 v117, v117, v111
	v_xor_b32_e32 v117, 46, v117
	v_cvt_f32_f16_e32 v111, v41
	v_cvt_f32_f16_sdwa v109, v41 dst_sel:DWORD dst_unused:UNUSED_PAD src0_sel:WORD_1
	v_ashrrev_i32_e32 v108, 31, v111
	v_lshl_or_b32 v108, v108, 7, s33
	v_xor_b32_e32 v111, v111, v108
	v_xor_b32_e32 v111, 45, v111
	v_ashrrev_i32_e32 v108, 31, v109
	v_lshl_or_b32 v108, v108, 7, s33
	v_xor_b32_e32 v109, v109, v108
	v_xor_b32_e32 v109, 44, v109
	v_cvt_f32_f16_e32 v108, v42
	v_cvt_f32_f16_sdwa v114, v42 dst_sel:DWORD dst_unused:UNUSED_PAD src0_sel:WORD_1
	v_ashrrev_i32_e32 v105, 31, v108
	v_lshl_or_b32 v105, v105, 7, s33
	v_xor_b32_e32 v108, v108, v105
	v_xor_b32_e32 v108, 43, v108
	v_ashrrev_i32_e32 v105, 31, v114
	v_lshl_or_b32 v105, v105, 7, s33
	v_xor_b32_e32 v114, v114, v105
	v_xor_b32_e32 v114, 42, v114
	v_cvt_f32_f16_e32 v105, v43
	v_cvt_f32_f16_sdwa v119, v43 dst_sel:DWORD dst_unused:UNUSED_PAD src0_sel:WORD_1
	v_ashrrev_i32_e32 v104, 31, v105
	v_lshl_or_b32 v104, v104, 7, s33
	v_xor_b32_e32 v105, v105, v104
	v_xor_b32_e32 v105, 41, v105
	v_ashrrev_i32_e32 v104, 31, v119
	v_lshl_or_b32 v104, v104, 7, s33
	v_xor_b32_e32 v119, v119, v104
	v_xor_b32_e32 v119, 40, v119
	v_cvt_f32_f16_e32 v104, v44
	v_cvt_f32_f16_sdwa v103, v44 dst_sel:DWORD dst_unused:UNUSED_PAD src0_sel:WORD_1
	v_ashrrev_i32_e32 v106, 31, v104
	v_lshl_or_b32 v106, v106, 7, s33
	v_xor_b32_e32 v104, v104, v106
	v_xor_b32_e32 v104, 39, v104
	v_ashrrev_i32_e32 v106, 31, v103
	v_lshl_or_b32 v106, v106, 7, s33
	v_xor_b32_e32 v103, v103, v106
	v_xor_b32_e32 v103, 38, v103
	v_cvt_f32_f16_e32 v106, v45
	v_cvt_f32_f16_sdwa v110, v45 dst_sel:DWORD dst_unused:UNUSED_PAD src0_sel:WORD_1
	v_ashrrev_i32_e32 v112, 31, v106
	v_lshl_or_b32 v112, v112, 7, s33
	v_xor_b32_e32 v106, v106, v112
	v_xor_b32_e32 v106, 37, v106
	v_ashrrev_i32_e32 v112, 31, v110
	v_lshl_or_b32 v112, v112, 7, s33
	v_xor_b32_e32 v110, v110, v112
	v_xor_b32_e32 v110, 36, v110
	v_cvt_f32_f16_e32 v112, v46
	v_cvt_f32_f16_sdwa v92, v46 dst_sel:DWORD dst_unused:UNUSED_PAD src0_sel:WORD_1
	v_ashrrev_i32_e32 v107, 31, v112
	v_lshl_or_b32 v107, v107, 7, s33
	v_xor_b32_e32 v112, v112, v107
	v_xor_b32_e32 v112, 35, v112
	v_ashrrev_i32_e32 v107, 31, v92
	v_lshl_or_b32 v107, v107, 7, s33
	v_xor_b32_e32 v92, v92, v107
	v_xor_b32_e32 v92, 34, v92
	v_cvt_f32_f16_e32 v107, v47
	v_cvt_f32_f16_sdwa v98, v47 dst_sel:DWORD dst_unused:UNUSED_PAD src0_sel:WORD_1
	v_ashrrev_i32_e32 v115, 31, v107
	v_lshl_or_b32 v115, v115, 7, s33
	v_xor_b32_e32 v107, v107, v115
	v_xor_b32_e32 v107, 33, v107
	v_ashrrev_i32_e32 v115, 31, v98
	v_lshl_or_b32 v115, v115, 7, s33
	v_xor_b32_e32 v98, v98, v115
	v_xor_b32_e32 v98, 32, v98
	v_max_u32_e32 v115, v90, v117
	v_min_u32_e32 v117, v90, v117
	v_max_u32_e32 v90, v111, v109
	v_min_u32_e32 v109, v111, v109
	v_max_u32_e32 v111, v115, v90
	v_min_u32_e32 v90, v115, v90
	v_max_u32_e32 v115, v117, v109
	v_min_u32_e32 v109, v117, v109
	v_max_u32_e32 v117, v115, v90
	v_min_u32_e32 v90, v115, v90
	v_max_u32_e32 v115, v108, v114
	v_min_u32_e32 v114, v108, v114
	v_max_u32_e32 v108, v105, v119
	v_min_u32_e32 v119, v105, v119
	v_max_u32_e32 v105, v115, v108
	v_min_u32_e32 v108, v115, v108
	v_max_u32_e32 v115, v114, v119
	v_min_u32_e32 v119, v114, v119
	v_max_u32_e32 v114, v115, v108
	v_min_u32_e32 v108, v115, v108
	v_max_u32_e32 v115, v111, v105
	v_min_u32_e32 v105, v111, v105
	v_max_u32_e32 v111, v90, v108
	v_min_u32_e32 v108, v90, v108
	v_max_u32_e32 v90, v111, v105
	v_min_u32_e32 v105, v111, v105
	v_max_u32_e32 v111, v117, v114
	v_min_u32_e32 v114, v117, v114
	v_max_u32_e32 v117, v109, v119
	v_min_u32_e32 v119, v109, v119
	v_max_u32_e32 v109, v117, v114
	v_min_u32_e32 v114, v117, v114
	v_max_u32_e32 v117, v111, v90
	v_min_u32_e32 v90, v111, v90
	v_max_u32_e32 v111, v109, v105
	v_min_u32_e32 v105, v109, v105
	v_max_u32_e32 v109, v114, v108
	v_min_u32_e32 v108, v114, v108
	v_max_u32_e32 v114, v104, v103
	v_min_u32_e32 v103, v104, v103
	v_max_u32_e32 v104, v106, v110
	v_min_u32_e32 v110, v106, v110
	v_max_u32_e32 v106, v114, v104
	v_min_u32_e32 v104, v114, v104
	v_max_u32_e32 v114, v103, v110
	v_min_u32_e32 v110, v103, v110
	v_max_u32_e32 v103, v114, v104
	v_min_u32_e32 v104, v114, v104
	v_max_u32_e32 v114, v112, v92
	v_min_u32_e32 v92, v112, v92
	v_max_u32_e32 v112, v107, v98
	v_min_u32_e32 v98, v107, v98
	v_max_u32_e32 v107, v114, v112
	v_min_u32_e32 v112, v114, v112
	v_max_u32_e32 v114, v92, v98
	v_min_u32_e32 v98, v92, v98
	v_max_u32_e32 v92, v114, v112
	v_min_u32_e32 v112, v114, v112
	v_max_u32_e32 v114, v106, v107
	v_min_u32_e32 v107, v106, v107
	v_max_u32_e32 v106, v104, v112
	v_min_u32_e32 v112, v104, v112
	v_max_u32_e32 v104, v106, v107
	v_min_u32_e32 v107, v106, v107
	v_max_u32_e32 v106, v103, v92
	v_min_u32_e32 v92, v103, v92
	v_max_u32_e32 v103, v110, v98
	v_min_u32_e32 v98, v110, v98
	v_max_u32_e32 v110, v103, v92
	v_min_u32_e32 v92, v103, v92
	v_max_u32_e32 v103, v106, v104
	v_min_u32_e32 v104, v106, v104
	v_max_u32_e32 v106, v110, v107
	v_min_u32_e32 v107, v110, v107
	v_max_u32_e32 v110, v92, v112
	v_min_u32_e32 v112, v92, v112
	v_max_u32_e32 v92, v115, v114
	v_min_u32_e32 v114, v115, v114
	v_max_u32_e32 v115, v105, v107
	v_min_u32_e32 v107, v105, v107
; __device__ __forceinline__ unsigned f2key(float f) { const unsigned u = __float_as_uint(f); return (u & 0x80000000u) ? ~u : (u | 0x80000000u); }
; #define CE_DESC(a, b) do { const unsigned _mx = (a) > (b) ? (a) : (b), _mn = (a) > (b) ? (b) : (a); (a) = _mx; (b) = _mn; } while (0)
; __device__ __forceinline__ void merge16(unsigned (&a)[16], const unsigned (&b)[16]) {
; #pragma unroll
;     for (int i = 0; i < 16; ++i) a[i] = a[i] > b[15 - i] ? a[i] : b[15 - i];
; #pragma unroll
;     for (int stride = 8; stride > 0; stride >>= 1)
; #pragma unroll
;         for (int i = 0; i < 16; ++i) { const int j = i ^ stride; if (j > i) CE_DESC(a[i], a[j]); }
; }
; __device__ __forceinline__ void peer_tile(const Args& A, LAS unsigned char* lds, int tile) {
;     ...
;                   for (int i = 0; i < 16; ++i) {
;                       const float lo = (float)__builtin_bit_cast(_Float16, (unsigned short)(sw[i] & 0xffffu)), hi = (float)__builtin_bit_cast(_Float16, (unsigned short)(sw[i] >> 16));
;                       const unsigned klo = (f2key(lo) & ~127u) | (unsigned)(127 - (32 * g + 2 * i)), khi = (f2key(hi) & ~127u) | (unsigned)(127 - (32 * g + 2 * i + 1));
;                       if (i < 8) { k0[2 * i] = klo; k0[2 * i + 1] = khi; } else { k1[2 * (i - 8)] = klo; k1[2 * (i - 8) + 1] = khi; } } }
;                 sort16_desc(k0); sort16_desc(k1); merge16(k0, k1);
	v_max_u32_e32 v105, v115, v114
	v_min_u32_e32 v114, v115, v114
	v_max_u32_e32 v115, v90, v104
	v_min_u32_e32 v104, v90, v104
	v_max_u32_e32 v90, v108, v112
	v_min_u32_e32 v112, v108, v112
	v_max_u32_e32 v108, v90, v104
	v_min_u32_e32 v104, v90, v104
	v_max_u32_e32 v90, v115, v105
	v_min_u32_e32 v105, v115, v105
	v_max_u32_e32 v115, v108, v114
	v_min_u32_e32 v114, v108, v114
	v_max_u32_e32 v108, v104, v107
	v_min_u32_e32 v107, v104, v107
	v_max_u32_e32 v104, v117, v103
	v_min_u32_e32 v103, v117, v103
	v_max_u32_e32 v117, v109, v110
	v_min_u32_e32 v110, v109, v110
	v_max_u32_e32 v109, v117, v103
	v_min_u32_e32 v103, v117, v103
	v_max_u32_e32 v117, v111, v106
	v_min_u32_e32 v106, v111, v106
	v_max_u32_e32 v111, v119, v98
	v_min_u32_e32 v98, v119, v98
	v_max_u32_e32 v119, v111, v106
	v_min_u32_e32 v106, v111, v106
	v_max_u32_e32 v111, v117, v109
	v_min_u32_e32 v109, v117, v109
	v_max_u32_e32 v117, v119, v103
	v_min_u32_e32 v103, v119, v103
	v_max_u32_e32 v119, v106, v110
	v_min_u32_e32 v110, v106, v110
	v_max_u32_e32 v106, v104, v90
	v_min_u32_e32 v90, v104, v90
	v_max_u32_e32 v104, v111, v105
	v_min_u32_e32 v105, v111, v105
	v_max_u32_e32 v111, v109, v115
	v_min_u32_e32 v115, v109, v115
	v_max_u32_e32 v109, v117, v114
	v_min_u32_e32 v114, v117, v114
	v_max_u32_e32 v117, v103, v108
	v_min_u32_e32 v108, v103, v108
	v_max_u32_e32 v103, v119, v107
	v_min_u32_e32 v107, v119, v107
	v_max_u32_e32 v119, v110, v112
	v_min_u32_e32 v112, v110, v112
	v_max_u32_e32 v86, v86, v98
	v_max_u32_e32 v116, v116, v112
	v_max_u32_e32 v73, v73, v119
	v_max_u32_e32 v118, v118, v107
	v_max_u32_e32 v93, v93, v103
	v_max_u32_e32 v100, v100, v108
	v_max_u32_e32 v91, v91, v117
	v_max_u32_e32 v96, v96, v114
	v_max_u32_e32 v95, v95, v109
	v_max_u32_e32 v88, v88, v115
	v_max_u32_e32 v102, v102, v111
	v_max_u32_e32 v87, v87, v105
	v_max_u32_e32 v94, v94, v104
	v_max_u32_e32 v89, v89, v90
	v_max_u32_e32 v97, v97, v106
	v_max_u32_e32 v80, v80, v92
	v_max_u32_e32 v98, v86, v95
	v_min_u32_e32 v95, v86, v95
	v_max_u32_e32 v86, v116, v88
	v_min_u32_e32 v88, v116, v88
	v_max_u32_e32 v116, v73, v102
	v_min_u32_e32 v102, v73, v102
	v_max_u32_e32 v73, v118, v87
	v_min_u32_e32 v87, v118, v87
	v_max_u32_e32 v118, v93, v94
	v_min_u32_e32 v94, v93, v94
	v_max_u32_e32 v93, v100, v89
	v_min_u32_e32 v89, v100, v89
	v_max_u32_e32 v100, v91, v97
	v_min_u32_e32 v97, v91, v97
	v_max_u32_e32 v91, v96, v80
	v_min_u32_e32 v80, v96, v80
	v_max_u32_e32 v96, v98, v118
	v_min_u32_e32 v118, v98, v118
	v_max_u32_e32 v98, v86, v93
	v_min_u32_e32 v93, v86, v93
	v_max_u32_e32 v86, v116, v100
	v_min_u32_e32 v100, v116, v100
	v_max_u32_e32 v116, v73, v91
	v_min_u32_e32 v91, v73, v91
	v_max_u32_e32 v73, v95, v94
	v_min_u32_e32 v94, v95, v94
	v_max_u32_e32 v95, v88, v89
	v_min_u32_e32 v89, v88, v89
	v_max_u32_e32 v88, v102, v97
	v_min_u32_e32 v97, v102, v97
	v_max_u32_e32 v102, v87, v80
	v_min_u32_e32 v80, v87, v80
	v_max_u32_e32 v87, v96, v86
	v_min_u32_e32 v86, v96, v86
	v_max_u32_e32 v96, v98, v116
	v_min_u32_e32 v116, v98, v116
	v_max_u32_e32 v98, v118, v100
	v_min_u32_e32 v100, v118, v100
	v_max_u32_e32 v118, v93, v91
	v_min_u32_e32 v91, v93, v91
	v_max_u32_e32 v93, v73, v88
	v_min_u32_e32 v88, v73, v88
	v_max_u32_e32 v73, v95, v102
	v_min_u32_e32 v102, v95, v102
	v_max_u32_e32 v95, v94, v97
	v_min_u32_e32 v97, v94, v97
	v_max_u32_e32 v94, v89, v80
	v_min_u32_e32 v80, v89, v80
	v_max_u32_e32 v89, v87, v96
	v_min_u32_e32 v96, v87, v96
	v_max_u32_e32 v87, v86, v116
	v_min_u32_e32 v116, v86, v116
	v_max_u32_e32 v86, v98, v118
	v_min_u32_e32 v118, v98, v118
	v_max_u32_e32 v98, v100, v91
	v_min_u32_e32 v91, v100, v91
	v_max_u32_e32 v100, v93, v73
	v_min_u32_e32 v73, v93, v73
	v_max_u32_e32 v93, v88, v102
	v_min_u32_e32 v102, v88, v102
	v_max_u32_e32 v88, v95, v94
	v_min_u32_e32 v94, v95, v94
	v_max_u32_e32 v95, v97, v80
	v_min_u32_e32 v80, v97, v80
	v_cvt_f32_f16_e32 v97, v48
	v_cvt_f32_f16_sdwa v112, v48 dst_sel:DWORD dst_unused:UNUSED_PAD src0_sel:WORD_1
	v_ashrrev_i32_e32 v119, 31, v97
	v_lshl_or_b32 v119, v119, 7, s33
	v_xor_b32_e32 v97, v97, v119
	v_xor_b32_e32 v97, 31, v97
	v_ashrrev_i32_e32 v119, 31, v112
	v_lshl_or_b32 v119, v119, 7, s33
	v_xor_b32_e32 v112, v112, v119
	v_xor_b32_e32 v112, 30, v112
	v_cvt_f32_f16_e32 v119, v49
	v_cvt_f32_f16_sdwa v107, v49 dst_sel:DWORD dst_unused:UNUSED_PAD src0_sel:WORD_1
	v_ashrrev_i32_e32 v103, 31, v119
	v_lshl_or_b32 v103, v103, 7, s33
	v_xor_b32_e32 v119, v119, v103
	v_xor_b32_e32 v119, 29, v119
	v_ashrrev_i32_e32 v103, 31, v107
	v_lshl_or_b32 v103, v103, 7, s33
	v_xor_b32_e32 v107, v107, v103
	v_xor_b32_e32 v107, 28, v107
	v_cvt_f32_f16_e32 v103, v50
	v_cvt_f32_f16_sdwa v108, v50 dst_sel:DWORD dst_unused:UNUSED_PAD src0_sel:WORD_1
	v_ashrrev_i32_e32 v117, 31, v103
	v_lshl_or_b32 v117, v117, 7, s33
	v_xor_b32_e32 v103, v103, v117
	v_xor_b32_e32 v103, 27, v103
	v_ashrrev_i32_e32 v117, 31, v108
	v_lshl_or_b32 v117, v117, 7, s33
	v_xor_b32_e32 v108, v108, v117
	v_xor_b32_e32 v108, 26, v108
	v_cvt_f32_f16_e32 v117, v51
	v_cvt_f32_f16_sdwa v114, v51 dst_sel:DWORD dst_unused:UNUSED_PAD src0_sel:WORD_1
	v_ashrrev_i32_e32 v109, 31, v117
	v_lshl_or_b32 v109, v109, 7, s33
	v_xor_b32_e32 v117, v117, v109
	v_xor_b32_e32 v117, 25, v117
	v_ashrrev_i32_e32 v109, 31, v114
	v_lshl_or_b32 v109, v109, 7, s33
	v_xor_b32_e32 v114, v114, v109
	v_xor_b32_e32 v114, 24, v114
	v_cvt_f32_f16_e32 v109, v52
	v_cvt_f32_f16_sdwa v115, v52 dst_sel:DWORD dst_unused:UNUSED_PAD src0_sel:WORD_1
	v_ashrrev_i32_e32 v111, 31, v109
	v_lshl_or_b32 v111, v111, 7, s33
	v_xor_b32_e32 v109, v109, v111
	v_xor_b32_e32 v109, 23, v109
	v_ashrrev_i32_e32 v111, 31, v115
	v_lshl_or_b32 v111, v111, 7, s33
; __device__ __forceinline__ unsigned f2key(float f) { const unsigned u = __float_as_uint(f); return (u & 0x80000000u) ? ~u : (u | 0x80000000u); }
; #define CE_DESC(a, b) do { const unsigned _mx = (a) > (b) ? (a) : (b), _mn = (a) > (b) ? (b) : (a); (a) = _mx; (b) = _mn; } while (0)
; __device__ __forceinline__ void sort16_desc(unsigned (&k)[16]) {
; #pragma unroll
;     for (int size = 2; size <= 16; size <<= 1)
; #pragma unroll
;         for (int stride = size >> 1; stride > 0; stride >>= 1)
; #pragma unroll
;             for (int i = 0; i < 16; ++i) { const int j = i ^ stride;
;                 if (j > i) { if ((i & size) == 0) CE_DESC(k[i], k[j]); else CE_DESC(k[j], k[i]); } }
; }
; __device__ __forceinline__ void merge16(unsigned (&a)[16], const unsigned (&b)[16]) {
; #pragma unroll
;     for (int i = 0; i < 16; ++i) a[i] = a[i] > b[15 - i] ? a[i] : b[15 - i];
; #pragma unroll
;     for (int stride = 8; stride > 0; stride >>= 1)
; #pragma unroll
;         for (int i = 0; i < 16; ++i) { const int j = i ^ stride; if (j > i) CE_DESC(a[i], a[j]); }
; }
; __device__ __forceinline__ void peer_tile(const Args& A, LAS unsigned char* lds, int tile) {
;     ...
;                   for (int i = 0; i < 16; ++i) {
;                       const float lo = (float)__builtin_bit_cast(_Float16, (unsigned short)(sw[i] & 0xffffu)), hi = (float)__builtin_bit_cast(_Float16, (unsigned short)(sw[i] >> 16));
;                       const unsigned klo = (f2key(lo) & ~127u) | (unsigned)(127 - (32 * g + 2 * i)), khi = (f2key(hi) & ~127u) | (unsigned)(127 - (32 * g + 2 * i + 1));
;                       if (i < 8) { k0[2 * i] = klo; k0[2 * i + 1] = khi; } else { k1[2 * (i - 8)] = klo; k1[2 * (i - 8) + 1] = khi; } } }
;                 sort16_desc(k0); sort16_desc(k1); merge16(k0, k1);
	v_xor_b32_e32 v115, v115, v111
	v_xor_b32_e32 v115, 22, v115
	v_cvt_f32_f16_e32 v111, v53
	v_cvt_f32_f16_sdwa v105, v53 dst_sel:DWORD dst_unused:UNUSED_PAD src0_sel:WORD_1
	v_ashrrev_i32_e32 v104, 31, v111
	v_lshl_or_b32 v104, v104, 7, s33
	v_xor_b32_e32 v111, v111, v104
	v_xor_b32_e32 v111, 21, v111
	v_ashrrev_i32_e32 v104, 31, v105
	v_lshl_or_b32 v104, v104, 7, s33
	v_xor_b32_e32 v105, v105, v104
	v_xor_b32_e32 v105, 20, v105
	v_cvt_f32_f16_e32 v104, v54
	v_cvt_f32_f16_sdwa v90, v54 dst_sel:DWORD dst_unused:UNUSED_PAD src0_sel:WORD_1
	v_ashrrev_i32_e32 v106, 31, v104
	v_lshl_or_b32 v106, v106, 7, s33
	v_xor_b32_e32 v104, v104, v106
	v_xor_b32_e32 v104, 19, v104
	v_ashrrev_i32_e32 v106, 31, v90
	v_lshl_or_b32 v106, v106, 7, s33
	v_xor_b32_e32 v90, v90, v106
	v_xor_b32_e32 v90, 18, v90
	v_cvt_f32_f16_e32 v106, v55
	v_cvt_f32_f16_sdwa v92, v55 dst_sel:DWORD dst_unused:UNUSED_PAD src0_sel:WORD_1
	v_ashrrev_i32_e32 v110, 31, v106
	v_lshl_or_b32 v110, v110, 7, s33
	v_xor_b32_e32 v106, v106, v110
	v_xor_b32_e32 v106, 17, v106
	v_ashrrev_i32_e32 v110, 31, v92
	v_lshl_or_b32 v110, v110, 7, s33
	v_xor_b32_e32 v92, v92, v110
	v_xor_b32_e32 v92, 16, v92
	v_max_u32_e32 v110, v97, v112
	v_min_u32_e32 v112, v97, v112
	v_max_u32_e32 v97, v119, v107
	v_min_u32_e32 v107, v119, v107
	v_max_u32_e32 v119, v110, v97
	v_min_u32_e32 v97, v110, v97
	v_max_u32_e32 v110, v112, v107
	v_min_u32_e32 v107, v112, v107
	v_max_u32_e32 v112, v110, v97
	v_min_u32_e32 v97, v110, v97
	v_max_u32_e32 v110, v103, v108
	v_min_u32_e32 v108, v103, v108
	v_max_u32_e32 v103, v117, v114
	v_min_u32_e32 v114, v117, v114
	v_max_u32_e32 v117, v110, v103
	v_min_u32_e32 v103, v110, v103
	v_max_u32_e32 v110, v108, v114
	v_min_u32_e32 v114, v108, v114
	v_max_u32_e32 v108, v110, v103
	v_min_u32_e32 v103, v110, v103
	v_max_u32_e32 v110, v119, v117
	v_min_u32_e32 v117, v119, v117
	v_max_u32_e32 v119, v97, v103
	v_min_u32_e32 v103, v97, v103
	v_max_u32_e32 v97, v119, v117
	v_min_u32_e32 v117, v119, v117
	v_max_u32_e32 v119, v112, v108
	v_min_u32_e32 v108, v112, v108
	v_max_u32_e32 v112, v107, v114
	v_min_u32_e32 v114, v107, v114
	v_max_u32_e32 v107, v112, v108
	v_min_u32_e32 v108, v112, v108
	v_max_u32_e32 v112, v119, v97
	v_min_u32_e32 v97, v119, v97
	v_max_u32_e32 v119, v107, v117
	v_min_u32_e32 v117, v107, v117
	v_max_u32_e32 v107, v108, v103
	v_min_u32_e32 v103, v108, v103
	v_max_u32_e32 v108, v109, v115
	v_min_u32_e32 v115, v109, v115
	v_max_u32_e32 v109, v111, v105
	v_min_u32_e32 v105, v111, v105
	v_max_u32_e32 v111, v108, v109
	v_min_u32_e32 v109, v108, v109
	v_max_u32_e32 v108, v115, v105
	v_min_u32_e32 v105, v115, v105
	v_max_u32_e32 v115, v108, v109
	v_min_u32_e32 v109, v108, v109
	v_max_u32_e32 v108, v104, v90
	v_min_u32_e32 v90, v104, v90
	v_max_u32_e32 v104, v106, v92
	v_min_u32_e32 v92, v106, v92
	v_max_u32_e32 v106, v108, v104
	v_min_u32_e32 v104, v108, v104
	v_max_u32_e32 v108, v90, v92
	v_min_u32_e32 v92, v90, v92
	v_max_u32_e32 v90, v108, v104
	v_min_u32_e32 v104, v108, v104
	v_max_u32_e32 v108, v111, v106
	v_min_u32_e32 v106, v111, v106
	v_max_u32_e32 v111, v109, v104
	v_min_u32_e32 v104, v109, v104
	v_max_u32_e32 v109, v111, v106
	v_min_u32_e32 v106, v111, v106
	v_max_u32_e32 v111, v115, v90
	v_min_u32_e32 v90, v115, v90
	v_max_u32_e32 v115, v105, v92
	v_min_u32_e32 v92, v105, v92
	v_max_u32_e32 v105, v115, v90
	v_min_u32_e32 v90, v115, v90
	v_max_u32_e32 v115, v111, v109
	v_min_u32_e32 v109, v111, v109
	v_max_u32_e32 v111, v105, v106
	v_min_u32_e32 v106, v105, v106
	v_max_u32_e32 v105, v90, v104
	v_min_u32_e32 v104, v90, v104
	v_max_u32_e32 v90, v110, v108
	v_min_u32_e32 v108, v110, v108
	v_max_u32_e32 v110, v117, v106
	v_min_u32_e32 v106, v117, v106
	v_max_u32_e32 v117, v110, v108
	v_min_u32_e32 v108, v110, v108
	v_max_u32_e32 v110, v97, v109
	v_min_u32_e32 v109, v97, v109
	v_max_u32_e32 v97, v103, v104
	v_min_u32_e32 v104, v103, v104
	v_max_u32_e32 v103, v97, v109
	v_min_u32_e32 v109, v97, v109
	v_max_u32_e32 v97, v110, v117
	v_min_u32_e32 v117, v110, v117
	v_max_u32_e32 v110, v103, v108
	v_min_u32_e32 v108, v103, v108
	v_max_u32_e32 v103, v109, v106
	v_min_u32_e32 v106, v109, v106
	v_max_u32_e32 v109, v112, v115
	v_min_u32_e32 v115, v112, v115
	v_max_u32_e32 v112, v107, v105
	v_min_u32_e32 v105, v107, v105
	v_max_u32_e32 v107, v112, v115
	v_min_u32_e32 v115, v112, v115
	v_max_u32_e32 v112, v119, v111
	v_min_u32_e32 v111, v119, v111
	v_max_u32_e32 v119, v114, v92
	v_min_u32_e32 v92, v114, v92
	v_max_u32_e32 v114, v119, v111
	v_min_u32_e32 v111, v119, v111
	v_max_u32_e32 v119, v112, v107
	v_min_u32_e32 v107, v112, v107
	v_max_u32_e32 v112, v114, v115
	v_min_u32_e32 v115, v114, v115
	v_max_u32_e32 v114, v111, v105
	v_min_u32_e32 v105, v111, v105
	v_max_u32_e32 v111, v109, v97
	v_min_u32_e32 v97, v109, v97
	v_max_u32_e32 v109, v119, v117
	v_min_u32_e32 v117, v119, v117
	v_max_u32_e32 v119, v107, v110
	v_min_u32_e32 v110, v107, v110
	v_max_u32_e32 v107, v112, v108
	v_min_u32_e32 v108, v112, v108
	v_max_u32_e32 v112, v115, v103
	v_min_u32_e32 v103, v115, v103
	v_max_u32_e32 v115, v114, v106
	v_min_u32_e32 v106, v114, v106
	v_max_u32_e32 v114, v105, v104
	v_min_u32_e32 v104, v105, v104
	v_max_u32_e32 v89, v89, v92
	v_max_u32_e32 v96, v96, v104
	v_max_u32_e32 v87, v87, v114
	v_max_u32_e32 v116, v116, v106
	v_max_u32_e32 v86, v86, v115
	v_max_u32_e32 v118, v118, v103
	v_max_u32_e32 v98, v98, v112
	v_max_u32_e32 v91, v91, v108
	v_max_u32_e32 v100, v100, v107
	v_max_u32_e32 v73, v73, v110
	v_max_u32_e32 v93, v93, v119
	v_max_u32_e32 v102, v102, v117
	v_max_u32_e32 v88, v88, v109
	v_max_u32_e32 v94, v94, v97
	v_max_u32_e32 v95, v95, v111
	v_max_u32_e32 v80, v80, v90
; __device__ __forceinline__ unsigned f2key(float f) { const unsigned u = __float_as_uint(f); return (u & 0x80000000u) ? ~u : (u | 0x80000000u); }
; #define CE_DESC(a, b) do { const unsigned _mx = (a) > (b) ? (a) : (b), _mn = (a) > (b) ? (b) : (a); (a) = _mx; (b) = _mn; } while (0)
; __device__ __forceinline__ void sort16_desc(unsigned (&k)[16]) {
; #pragma unroll
;     for (int size = 2; size <= 16; size <<= 1)
; #pragma unroll
;         for (int stride = size >> 1; stride > 0; stride >>= 1)
; #pragma unroll
;             for (int i = 0; i < 16; ++i) { const int j = i ^ stride;
;                 if (j > i) { if ((i & size) == 0) CE_DESC(k[i], k[j]); else CE_DESC(k[j], k[i]); } }
; }
; __device__ __forceinline__ void merge16(unsigned (&a)[16], const unsigned (&b)[16]) {
; #pragma unroll
;     for (int i = 0; i < 16; ++i) a[i] = a[i] > b[15 - i] ? a[i] : b[15 - i];
; #pragma unroll
;     for (int stride = 8; stride > 0; stride >>= 1)
; #pragma unroll
;         for (int i = 0; i < 16; ++i) { const int j = i ^ stride; if (j > i) CE_DESC(a[i], a[j]); }
; }
; __device__ __forceinline__ void peer_tile(const Args& A, LAS unsigned char* lds, int tile) {
;     ...
;                   for (int i = 0; i < 16; ++i) {
;                       const float lo = (float)__builtin_bit_cast(_Float16, (unsigned short)(sw[i] & 0xffffu)), hi = (float)__builtin_bit_cast(_Float16, (unsigned short)(sw[i] >> 16));
;                       const unsigned klo = (f2key(lo) & ~127u) | (unsigned)(127 - (32 * g + 2 * i)), khi = (f2key(hi) & ~127u) | (unsigned)(127 - (32 * g + 2 * i + 1));
;                       if (i < 8) { k0[2 * i] = klo; k0[2 * i + 1] = khi; } else { k1[2 * (i - 8)] = klo; k1[2 * (i - 8) + 1] = khi; } } }
;                 sort16_desc(k0); sort16_desc(k1); merge16(k0, k1);
	v_max_u32_e32 v92, v89, v100
	v_min_u32_e32 v100, v89, v100
	v_max_u32_e32 v89, v96, v73
	v_min_u32_e32 v73, v96, v73
	v_max_u32_e32 v96, v87, v93
	v_min_u32_e32 v93, v87, v93
	v_max_u32_e32 v87, v116, v102
	v_min_u32_e32 v102, v116, v102
	v_max_u32_e32 v116, v86, v88
	v_min_u32_e32 v88, v86, v88
	v_max_u32_e32 v86, v118, v94
	v_min_u32_e32 v94, v118, v94
	v_max_u32_e32 v118, v98, v95
	v_min_u32_e32 v95, v98, v95
	v_max_u32_e32 v98, v91, v80
	v_min_u32_e32 v80, v91, v80
	v_max_u32_e32 v91, v92, v116
	v_min_u32_e32 v116, v92, v116
	v_max_u32_e32 v92, v89, v86
	v_min_u32_e32 v86, v89, v86
	v_max_u32_e32 v89, v96, v118
	v_min_u32_e32 v118, v96, v118
	v_max_u32_e32 v96, v87, v98
	v_min_u32_e32 v98, v87, v98
	v_max_u32_e32 v87, v100, v88
	v_min_u32_e32 v88, v100, v88
	v_max_u32_e32 v100, v73, v94
	v_min_u32_e32 v94, v73, v94
	v_max_u32_e32 v73, v93, v95
	v_min_u32_e32 v95, v93, v95
	v_max_u32_e32 v93, v102, v80
	v_min_u32_e32 v80, v102, v80
	v_max_u32_e32 v102, v91, v89
	v_min_u32_e32 v89, v91, v89
	v_max_u32_e32 v91, v92, v96
	v_min_u32_e32 v96, v92, v96
	v_max_u32_e32 v92, v116, v118
	v_min_u32_e32 v118, v116, v118
	v_max_u32_e32 v116, v86, v98
	v_min_u32_e32 v98, v86, v98
	v_max_u32_e32 v86, v87, v73
	v_min_u32_e32 v73, v87, v73
	v_max_u32_e32 v87, v100, v93
	v_min_u32_e32 v93, v100, v93
	v_max_u32_e32 v100, v88, v95
	v_min_u32_e32 v95, v88, v95
	v_max_u32_e32 v88, v94, v80
	v_min_u32_e32 v80, v94, v80
	v_max_u32_e32 v94, v102, v91
	v_min_u32_e32 v91, v102, v91
	v_max_u32_e32 v102, v89, v96
	v_min_u32_e32 v96, v89, v96
	v_max_u32_e32 v89, v92, v116
	v_min_u32_e32 v116, v92, v116
	v_max_u32_e32 v92, v118, v98
	v_min_u32_e32 v98, v118, v98
	v_max_u32_e32 v118, v86, v87
	v_min_u32_e32 v87, v86, v87
	v_max_u32_e32 v86, v73, v93
	v_min_u32_e32 v93, v73, v93
	v_max_u32_e32 v73, v100, v88
	v_min_u32_e32 v88, v100, v88
	v_max_u32_e32 v100, v95, v80
	v_min_u32_e32 v80, v95, v80
	v_cvt_f32_f16_e32 v95, v56
	v_cvt_f32_f16_sdwa v104, v56 dst_sel:DWORD dst_unused:UNUSED_PAD src0_sel:WORD_1
	v_ashrrev_i32_e32 v114, 31, v95
	v_lshl_or_b32 v114, v114, 7, s33
	v_xor_b32_e32 v95, v95, v114
	v_xor_b32_e32 v95, 15, v95
	v_ashrrev_i32_e32 v114, 31, v104
	v_lshl_or_b32 v114, v114, 7, s33
	v_xor_b32_e32 v104, v104, v114
	v_xor_b32_e32 v104, 14, v104
	v_cvt_f32_f16_e32 v114, v57
	v_cvt_f32_f16_sdwa v106, v57 dst_sel:DWORD dst_unused:UNUSED_PAD src0_sel:WORD_1
	v_ashrrev_i32_e32 v115, 31, v114
	v_lshl_or_b32 v115, v115, 7, s33
	v_xor_b32_e32 v114, v114, v115
	v_xor_b32_e32 v114, 13, v114
	v_ashrrev_i32_e32 v115, 31, v106
	v_lshl_or_b32 v115, v115, 7, s33
	v_xor_b32_e32 v106, v106, v115
	v_xor_b32_e32 v106, 12, v106
	v_cvt_f32_f16_e32 v115, v58
	v_cvt_f32_f16_sdwa v103, v58 dst_sel:DWORD dst_unused:UNUSED_PAD src0_sel:WORD_1
	v_ashrrev_i32_e32 v112, 31, v115
	v_lshl_or_b32 v112, v112, 7, s33
	v_xor_b32_e32 v115, v115, v112
	v_xor_b32_e32 v115, 11, v115
	v_ashrrev_i32_e32 v112, 31, v103
	v_lshl_or_b32 v112, v112, 7, s33
	v_xor_b32_e32 v103, v103, v112
	v_xor_b32_e32 v103, 10, v103
	v_cvt_f32_f16_e32 v112, v59
	v_cvt_f32_f16_sdwa v108, v59 dst_sel:DWORD dst_unused:UNUSED_PAD src0_sel:WORD_1
	v_ashrrev_i32_e32 v107, 31, v112
	v_lshl_or_b32 v107, v107, 7, s33
	v_xor_b32_e32 v112, v112, v107
	v_xor_b32_e32 v112, 9, v112
	v_ashrrev_i32_e32 v107, 31, v108
	v_lshl_or_b32 v107, v107, 7, s33
	v_xor_b32_e32 v108, v108, v107
	v_xor_b32_e32 v108, 8, v108
	v_cvt_f32_f16_e32 v107, v60
	v_cvt_f32_f16_sdwa v110, v60 dst_sel:DWORD dst_unused:UNUSED_PAD src0_sel:WORD_1
	v_ashrrev_i32_e32 v119, 31, v107
	v_lshl_or_b32 v119, v119, 7, s33
	v_xor_b32_e32 v107, v107, v119
	v_xor_b32_e32 v107, 7, v107
	v_ashrrev_i32_e32 v119, 31, v110
	v_lshl_or_b32 v119, v119, 7, s33
	v_xor_b32_e32 v110, v110, v119
	v_xor_b32_e32 v110, 6, v110
	v_cvt_f32_f16_e32 v119, v61
	v_cvt_f32_f16_sdwa v117, v61 dst_sel:DWORD dst_unused:UNUSED_PAD src0_sel:WORD_1
	v_ashrrev_i32_e32 v109, 31, v119
	v_lshl_or_b32 v109, v109, 7, s33
	v_xor_b32_e32 v119, v119, v109
	v_xor_b32_e32 v119, 5, v119
	v_ashrrev_i32_e32 v109, 31, v117
	v_lshl_or_b32 v109, v109, 7, s33
	v_xor_b32_e32 v117, v117, v109
	v_xor_b32_e32 v117, 4, v117
	v_cvt_f32_f16_e32 v109, v62
	v_cvt_f32_f16_sdwa v97, v62 dst_sel:DWORD dst_unused:UNUSED_PAD src0_sel:WORD_1
	v_ashrrev_i32_e32 v111, 31, v109
	v_lshl_or_b32 v111, v111, 7, s33
	v_xor_b32_e32 v109, v109, v111
	v_xor_b32_e32 v109, 3, v109
	v_ashrrev_i32_e32 v111, 31, v97
	v_lshl_or_b32 v111, v111, 7, s33
	v_xor_b32_e32 v97, v97, v111
	v_xor_b32_e32 v97, 2, v97
	v_cvt_f32_f16_e32 v111, v63
	v_cvt_f32_f16_sdwa v90, v63 dst_sel:DWORD dst_unused:UNUSED_PAD src0_sel:WORD_1
	v_ashrrev_i32_e32 v105, 31, v111
	v_lshl_or_b32 v105, v105, 7, s33
	v_xor_b32_e32 v111, v111, v105
	v_xor_b32_e32 v111, 1, v111
	v_ashrrev_i32_e32 v105, 31, v90
	v_lshl_or_b32 v105, v105, 7, s33
	v_xor_b32_e32 v90, v90, v105
	v_xor_b32_e32 v90, 0, v90
	v_max_u32_e32 v105, v95, v104
	v_min_u32_e32 v104, v95, v104
	v_max_u32_e32 v95, v114, v106
	v_min_u32_e32 v106, v114, v106
	v_max_u32_e32 v114, v105, v95
	v_min_u32_e32 v95, v105, v95
	v_max_u32_e32 v105, v104, v106
	v_min_u32_e32 v106, v104, v106
	v_max_u32_e32 v104, v105, v95
	v_min_u32_e32 v95, v105, v95
	v_max_u32_e32 v105, v115, v103
	v_min_u32_e32 v103, v115, v103
	v_max_u32_e32 v115, v112, v108
	v_min_u32_e32 v108, v112, v108
	v_max_u32_e32 v112, v105, v115
	v_min_u32_e32 v115, v105, v115
	v_max_u32_e32 v105, v103, v108
	v_min_u32_e32 v108, v103, v108
	v_max_u32_e32 v103, v105, v115
	v_min_u32_e32 v115, v105, v115
	v_max_u32_e32 v105, v114, v112
	v_min_u32_e32 v112, v114, v112
	v_max_u32_e32 v114, v95, v115
	v_min_u32_e32 v115, v95, v115
	v_max_u32_e32 v95, v114, v112
; #define CE_DESC(a, b) do { const unsigned _mx = (a) > (b) ? (a) : (b), _mn = (a) > (b) ? (b) : (a); (a) = _mx; (b) = _mn; } while (0)
; __device__ __forceinline__ void sort16_desc(unsigned (&k)[16]) {
; #pragma unroll
;     for (int size = 2; size <= 16; size <<= 1)
; #pragma unroll
;         for (int stride = size >> 1; stride > 0; stride >>= 1)
; #pragma unroll
;             for (int i = 0; i < 16; ++i) { const int j = i ^ stride;
;                 if (j > i) { if ((i & size) == 0) CE_DESC(k[i], k[j]); else CE_DESC(k[j], k[i]); } }
; }
; __device__ __forceinline__ void merge16(unsigned (&a)[16], const unsigned (&b)[16]) {
; #pragma unroll
;     for (int i = 0; i < 16; ++i) a[i] = a[i] > b[15 - i] ? a[i] : b[15 - i];
; #pragma unroll
;     for (int stride = 8; stride > 0; stride >>= 1)
; #pragma unroll
;         for (int i = 0; i < 16; ++i) { const int j = i ^ stride; if (j > i) CE_DESC(a[i], a[j]); }
; }
; __device__ __forceinline__ void peer_tile(const Args& A, LAS unsigned char* lds, int tile) {
;     ...
;                 sort16_desc(k0); sort16_desc(k1); merge16(k0, k1);
	v_min_u32_e32 v112, v114, v112
	v_max_u32_e32 v114, v104, v103
	v_min_u32_e32 v103, v104, v103
	v_max_u32_e32 v104, v106, v108
	v_min_u32_e32 v108, v106, v108
	v_max_u32_e32 v106, v104, v103
	v_min_u32_e32 v103, v104, v103
	v_max_u32_e32 v104, v114, v95
	v_min_u32_e32 v95, v114, v95
	v_max_u32_e32 v114, v106, v112
	v_min_u32_e32 v112, v106, v112
	v_max_u32_e32 v106, v103, v115
	v_min_u32_e32 v115, v103, v115
	v_max_u32_e32 v103, v107, v110
	v_min_u32_e32 v110, v107, v110
	v_max_u32_e32 v107, v119, v117
	v_min_u32_e32 v117, v119, v117
	v_max_u32_e32 v119, v103, v107
	v_min_u32_e32 v107, v103, v107
	v_max_u32_e32 v103, v110, v117
	v_min_u32_e32 v117, v110, v117
	v_max_u32_e32 v110, v103, v107
	v_min_u32_e32 v107, v103, v107
	v_max_u32_e32 v103, v109, v97
	v_min_u32_e32 v97, v109, v97
	v_max_u32_e32 v109, v111, v90
	v_min_u32_e32 v90, v111, v90
	v_max_u32_e32 v111, v103, v109
	v_min_u32_e32 v109, v103, v109
	v_max_u32_e32 v103, v97, v90
	v_min_u32_e32 v90, v97, v90
	v_max_u32_e32 v97, v103, v109
	v_min_u32_e32 v109, v103, v109
	v_max_u32_e32 v103, v119, v111
	v_min_u32_e32 v111, v119, v111
	v_max_u32_e32 v119, v107, v109
	v_min_u32_e32 v109, v107, v109
	v_max_u32_e32 v107, v119, v111
	v_min_u32_e32 v111, v119, v111
	v_max_u32_e32 v119, v110, v97
	v_min_u32_e32 v97, v110, v97
	v_max_u32_e32 v110, v117, v90
	v_min_u32_e32 v90, v117, v90
	v_max_u32_e32 v117, v110, v97
	v_min_u32_e32 v97, v110, v97
	v_max_u32_e32 v110, v119, v107
	v_min_u32_e32 v107, v119, v107
	v_max_u32_e32 v119, v117, v111
	v_min_u32_e32 v111, v117, v111
	v_max_u32_e32 v117, v97, v109
	v_min_u32_e32 v109, v97, v109
	v_max_u32_e32 v97, v105, v103
	v_min_u32_e32 v103, v105, v103
	v_max_u32_e32 v105, v112, v111
	v_min_u32_e32 v111, v112, v111
	v_max_u32_e32 v112, v105, v103
	v_min_u32_e32 v103, v105, v103
	v_max_u32_e32 v105, v95, v107
	v_min_u32_e32 v107, v95, v107
	v_max_u32_e32 v95, v115, v109
	v_min_u32_e32 v109, v115, v109
	v_max_u32_e32 v115, v95, v107
	v_min_u32_e32 v107, v95, v107
	v_max_u32_e32 v95, v105, v112
	v_min_u32_e32 v112, v105, v112
	v_max_u32_e32 v105, v115, v103
	v_min_u32_e32 v103, v115, v103
	v_max_u32_e32 v115, v107, v111
	v_min_u32_e32 v111, v107, v111
	v_max_u32_e32 v107, v104, v110
	v_min_u32_e32 v110, v104, v110
	v_max_u32_e32 v104, v106, v117
	v_min_u32_e32 v117, v106, v117
	v_max_u32_e32 v106, v104, v110
	v_min_u32_e32 v110, v104, v110
	v_max_u32_e32 v104, v114, v119
	v_min_u32_e32 v119, v114, v119
	v_max_u32_e32 v114, v108, v90
	v_min_u32_e32 v90, v108, v90
	v_max_u32_e32 v108, v114, v119
	v_min_u32_e32 v119, v114, v119
	v_max_u32_e32 v114, v104, v106
	v_min_u32_e32 v106, v104, v106
	v_max_u32_e32 v104, v108, v110
	v_min_u32_e32 v110, v108, v110
	v_max_u32_e32 v108, v119, v117
	v_min_u32_e32 v117, v119, v117
	v_max_u32_e32 v119, v107, v95
	v_min_u32_e32 v95, v107, v95
	v_max_u32_e32 v107, v114, v112
	v_min_u32_e32 v112, v114, v112
	v_max_u32_e32 v114, v106, v105
	v_min_u32_e32 v105, v106, v105
	v_max_u32_e32 v106, v104, v103
	v_min_u32_e32 v103, v104, v103
	v_max_u32_e32 v104, v110, v115
	v_min_u32_e32 v115, v110, v115
	v_max_u32_e32 v110, v108, v111
	v_min_u32_e32 v111, v108, v111
	v_max_u32_e32 v108, v117, v109
	v_min_u32_e32 v109, v117, v109
	v_max_u32_e32 v94, v94, v90
	v_max_u32_e32 v91, v91, v109
	v_max_u32_e32 v102, v102, v108
	v_max_u32_e32 v96, v96, v111
	v_max_u32_e32 v89, v89, v110
	v_max_u32_e32 v116, v116, v115
	v_max_u32_e32 v92, v92, v104
	v_max_u32_e32 v98, v98, v103
	v_max_u32_e32 v118, v118, v106
	v_max_u32_e32 v87, v87, v105
	v_max_u32_e32 v86, v86, v114
	v_max_u32_e32 v93, v93, v112
	v_max_u32_e32 v73, v73, v107
	v_max_u32_e32 v88, v88, v95
	v_max_u32_e32 v100, v100, v119
	v_max_u32_e32 v80, v80, v97
	v_max_u32_e32 v90, v94, v118
	v_min_u32_e32 v118, v94, v118
	v_max_u32_e32 v94, v91, v87
	v_min_u32_e32 v87, v91, v87
	v_max_u32_e32 v91, v102, v86
	v_min_u32_e32 v86, v102, v86
	v_max_u32_e32 v102, v96, v93
	v_min_u32_e32 v93, v96, v93
	v_max_u32_e32 v96, v89, v73
	v_min_u32_e32 v73, v89, v73
	v_max_u32_e32 v89, v116, v88
	v_min_u32_e32 v88, v116, v88
	v_max_u32_e32 v116, v92, v100
	v_min_u32_e32 v100, v92, v100
	v_max_u32_e32 v92, v98, v80
	v_min_u32_e32 v80, v98, v80
	v_max_u32_e32 v98, v90, v96
	v_min_u32_e32 v96, v90, v96
	v_max_u32_e32 v90, v94, v89
	v_min_u32_e32 v89, v94, v89
	v_max_u32_e32 v94, v91, v116
	v_min_u32_e32 v116, v91, v116
	v_max_u32_e32 v91, v102, v92
	v_min_u32_e32 v92, v102, v92
	v_max_u32_e32 v102, v118, v73
	v_min_u32_e32 v73, v118, v73
	v_max_u32_e32 v118, v87, v88
	v_min_u32_e32 v88, v87, v88
	v_max_u32_e32 v87, v86, v100
	v_min_u32_e32 v100, v86, v100
	v_max_u32_e32 v86, v93, v80
	v_min_u32_e32 v80, v93, v80
	v_max_u32_e32 v93, v98, v94
	v_min_u32_e32 v94, v98, v94
	v_max_u32_e32 v98, v90, v91
	v_min_u32_e32 v91, v90, v91
	v_max_u32_e32 v90, v96, v116
	v_min_u32_e32 v116, v96, v116
	v_max_u32_e32 v96, v89, v92
	v_min_u32_e32 v92, v89, v92
	v_max_u32_e32 v89, v102, v87
	v_min_u32_e32 v87, v102, v87
	v_max_u32_e32 v102, v118, v86
	v_min_u32_e32 v86, v118, v86
	v_max_u32_e32 v118, v73, v100
	v_min_u32_e32 v100, v73, v100
	v_max_u32_e32 v73, v88, v80
	v_min_u32_e32 v80, v88, v80
	v_max_u32_e32 v88, v93, v98
	v_min_u32_e32 v98, v93, v98
	v_max_u32_e32 v93, v94, v91
	v_min_u32_e32 v91, v94, v91
	v_max_u32_e32 v94, v90, v96
	v_min_u32_e32 v96, v90, v96
	v_max_u32_e32 v90, v116, v92
	v_min_u32_e32 v92, v116, v92
	v_max_u32_e32 v116, v89, v102
	v_min_u32_e32 v102, v89, v102
	v_max_u32_e32 v89, v87, v86
	v_min_u32_e32 v86, v87, v86
	v_max_u32_e32 v87, v118, v73
	v_min_u32_e32 v73, v118, v73
	v_max_u32_e32 v118, v100, v80
	v_min_u32_e32 v80, v100, v80
	v_xor_b32_e32 v100, 0x7f, v76
	v_xor_b32_e32 v109, 0x7f, v75
; __device__ __forceinline__ float key2f(unsigned k) { const unsigned u = (k & 0x80000000u) ? (k & 0x7fffffffu) : ~k; return __uint_as_float(u); }
; __device__ __forceinline__ void peer_tile(const Args& A, LAS unsigned char* lds, int tile) {
;     ...
;             float va[16], vb[16];
; #pragma unroll
;             for (int i = 0; i < 16; ++i) { va[i] = key2f(L2[0][i] & ~127u); vb[i] = key2f(L2[1][i] & ~127u); idx[i] = 127u - (L2[0][i] & 127u); idx[16 + i] = 127u - (L2[1][i] & 127u); }
	v_and_b32_e32 v100, 0x7f, v100
	v_and_b32_e32 v109, 0x7f, v109
	ds_write2_b32 v67, v100, v109 offset0:0 offset1:1
	v_xor_b32_e32 v109, 0x7f, v71
	v_xor_b32_e32 v100, 0x7f, v82
	v_and_b32_e32 v109, 0x7f, v109
	v_and_b32_e32 v100, 0x7f, v100
	ds_write2_b32 v67, v109, v100 offset0:2 offset1:3
	v_xor_b32_e32 v100, 0x7f, v74
	v_xor_b32_e32 v109, 0x7f, v81
	v_and_b32_e32 v100, 0x7f, v100
	v_and_b32_e32 v109, 0x7f, v109
	ds_write2_b32 v67, v100, v109 offset0:4 offset1:5
	v_xor_b32_e32 v109, 0x7f, v78
	v_xor_b32_e32 v100, 0x7f, v72
	v_and_b32_e32 v109, 0x7f, v109
	v_and_b32_e32 v100, 0x7f, v100
	ds_write2_b32 v67, v109, v100 offset0:6 offset1:7
	v_xor_b32_e32 v100, 0x7f, v99
	v_xor_b32_e32 v109, 0x7f, v84
	v_and_b32_e32 v100, 0x7f, v100
	v_and_b32_e32 v109, 0x7f, v109
	ds_write2_b32 v67, v100, v109 offset0:8 offset1:9
	v_xor_b32_e32 v109, 0x7f, v79
	v_xor_b32_e32 v100, 0x7f, v70
	v_and_b32_e32 v109, 0x7f, v109
	v_and_b32_e32 v100, 0x7f, v100
	ds_write2_b32 v67, v109, v100 offset0:10 offset1:11
	v_xor_b32_e32 v100, 0x7f, v77
	v_xor_b32_e32 v109, 0x7f, v83
	v_and_b32_e32 v100, 0x7f, v100
	v_and_b32_e32 v109, 0x7f, v109
	ds_write2_b32 v67, v100, v109 offset0:12 offset1:13
	v_xor_b32_e32 v109, 0x7f, v101
	v_xor_b32_e32 v100, 0x7f, v85
	v_and_b32_e32 v109, 0x7f, v109
	v_and_b32_e32 v100, 0x7f, v100
	ds_write2_b32 v67, v109, v100 offset0:14 offset1:15
	v_xor_b32_e32 v100, 0x7f, v88
	v_xor_b32_e32 v109, 0x7f, v98
	v_and_b32_e32 v100, 0x7f, v100
	v_and_b32_e32 v109, 0x7f, v109
	ds_write2_b32 v67, v100, v109 offset0:16 offset1:17
	v_xor_b32_e32 v109, 0x7f, v93
	v_xor_b32_e32 v100, 0x7f, v91
	v_and_b32_e32 v109, 0x7f, v109
	v_and_b32_e32 v100, 0x7f, v100
	ds_write2_b32 v67, v109, v100 offset0:18 offset1:19
	v_xor_b32_e32 v100, 0x7f, v94
	v_xor_b32_e32 v109, 0x7f, v96
	v_and_b32_e32 v100, 0x7f, v100
	v_and_b32_e32 v109, 0x7f, v109
	ds_write2_b32 v67, v100, v109 offset0:20 offset1:21
	v_xor_b32_e32 v109, 0x7f, v90
	v_xor_b32_e32 v100, 0x7f, v92
	v_and_b32_e32 v109, 0x7f, v109
	v_and_b32_e32 v100, 0x7f, v100
	ds_write2_b32 v67, v109, v100 offset0:22 offset1:23
	v_xor_b32_e32 v100, 0x7f, v116
	v_xor_b32_e32 v109, 0x7f, v102
	v_and_b32_e32 v100, 0x7f, v100
	v_and_b32_e32 v109, 0x7f, v109
	ds_write2_b32 v67, v100, v109 offset0:24 offset1:25
	v_xor_b32_e32 v109, 0x7f, v89
	v_xor_b32_e32 v100, 0x7f, v86
	v_and_b32_e32 v109, 0x7f, v109
	v_and_b32_e32 v100, 0x7f, v100
	ds_write2_b32 v67, v109, v100 offset0:26 offset1:27
	v_xor_b32_e32 v100, 0x7f, v87
	v_xor_b32_e32 v109, 0x7f, v73
	v_and_b32_e32 v100, 0x7f, v100
	v_and_b32_e32 v109, 0x7f, v109
	ds_write2_b32 v67, v100, v109 offset0:28 offset1:29
	v_xor_b32_e32 v109, 0x7f, v118
	v_xor_b32_e32 v100, 0x7f, v80
	v_and_b32_e32 v109, 0x7f, v109
	v_and_b32_e32 v100, 0x7f, v100
	ds_write2_b32 v67, v109, v100 offset0:30 offset1:31
	v_ashrrev_i32_e32 v109, 31, v76
	v_lshrrev_b32_e32 v109, 1, v109
	v_and_b32_e32 v100, 0xffffff80, v76
	v_xnor_b32_e32 v100, v100, v109
	v_ashrrev_i32_e32 v108, 31, v75
	v_lshrrev_b32_e32 v108, 1, v108
	v_and_b32_e32 v109, 0xffffff80, v75
	v_xnor_b32_e32 v109, v109, v108
	v_ashrrev_i32_e32 v111, 31, v71
	v_lshrrev_b32_e32 v111, 1, v111
	v_and_b32_e32 v108, 0xffffff80, v71
	v_xnor_b32_e32 v108, v108, v111
	v_ashrrev_i32_e32 v110, 31, v82
	v_lshrrev_b32_e32 v110, 1, v110
	v_and_b32_e32 v111, 0xffffff80, v82
	v_xnor_b32_e32 v111, v111, v110
	v_ashrrev_i32_e32 v115, 31, v74
	v_lshrrev_b32_e32 v115, 1, v115
	v_and_b32_e32 v110, 0xffffff80, v74
	v_xnor_b32_e32 v110, v110, v115
	v_ashrrev_i32_e32 v104, 31, v81
	v_lshrrev_b32_e32 v104, 1, v104
	v_and_b32_e32 v115, 0xffffff80, v81
	v_xnor_b32_e32 v115, v115, v104
	v_ashrrev_i32_e32 v103, 31, v78
	v_lshrrev_b32_e32 v103, 1, v103
	v_and_b32_e32 v104, 0xffffff80, v78
	v_xnor_b32_e32 v104, v104, v103
	v_ashrrev_i32_e32 v106, 31, v72
	v_lshrrev_b32_e32 v106, 1, v106
	v_and_b32_e32 v103, 0xffffff80, v72
	v_xnor_b32_e32 v103, v103, v106
	v_ashrrev_i32_e32 v105, 31, v99
	v_lshrrev_b32_e32 v105, 1, v105
	v_and_b32_e32 v106, 0xffffff80, v99
	v_xnor_b32_e32 v106, v106, v105
	v_ashrrev_i32_e32 v114, 31, v84
	v_lshrrev_b32_e32 v114, 1, v114
	v_and_b32_e32 v105, 0xffffff80, v84
	v_xnor_b32_e32 v105, v105, v114
	v_ashrrev_i32_e32 v112, 31, v79
	v_lshrrev_b32_e32 v112, 1, v112
	v_and_b32_e32 v114, 0xffffff80, v79
	v_xnor_b32_e32 v114, v114, v112
	v_ashrrev_i32_e32 v107, 31, v70
	v_lshrrev_b32_e32 v107, 1, v107
	v_and_b32_e32 v112, 0xffffff80, v70
	v_xnor_b32_e32 v112, v112, v107
	v_ashrrev_i32_e32 v95, 31, v77
	v_lshrrev_b32_e32 v95, 1, v95
	v_and_b32_e32 v107, 0xffffff80, v77
	v_xnor_b32_e32 v107, v107, v95
	v_ashrrev_i32_e32 v119, 31, v83
	v_lshrrev_b32_e32 v119, 1, v119
	v_and_b32_e32 v95, 0xffffff80, v83
	v_xnor_b32_e32 v95, v95, v119
	v_ashrrev_i32_e32 v97, 31, v101
	v_lshrrev_b32_e32 v97, 1, v97
	v_and_b32_e32 v119, 0xffffff80, v101
	v_xnor_b32_e32 v119, v119, v97
	v_ashrrev_i32_e32 v117, 31, v85
	v_lshrrev_b32_e32 v117, 1, v117
	v_and_b32_e32 v97, 0xffffff80, v85
	v_xnor_b32_e32 v97, v97, v117
	v_ashrrev_i32_e32 v120, 31, v88
	v_lshrrev_b32_e32 v120, 1, v120
	v_and_b32_e32 v117, 0xffffff80, v88
	v_xnor_b32_e32 v117, v117, v120
	v_ashrrev_i32_e32 v121, 31, v98
	v_lshrrev_b32_e32 v121, 1, v121
	v_and_b32_e32 v120, 0xffffff80, v98
	v_xnor_b32_e32 v120, v120, v121
	v_ashrrev_i32_e32 v122, 31, v93
	v_lshrrev_b32_e32 v122, 1, v122
	v_and_b32_e32 v121, 0xffffff80, v93
	v_xnor_b32_e32 v121, v121, v122
	v_ashrrev_i32_e32 v123, 31, v91
	v_lshrrev_b32_e32 v123, 1, v123
	v_and_b32_e32 v122, 0xffffff80, v91
	v_xnor_b32_e32 v122, v122, v123
	v_ashrrev_i32_e32 v124, 31, v94
	v_lshrrev_b32_e32 v124, 1, v124
	v_and_b32_e32 v123, 0xffffff80, v94
	v_xnor_b32_e32 v123, v123, v124
; __device__ __forceinline__ float key2f(unsigned k) { const unsigned u = (k & 0x80000000u) ? (k & 0x7fffffffu) : ~k; return __uint_as_float(u); }
; #define CK(i, j) ((f2key(va[i] + vb[j]) & ~255u) | (unsigned)(255 - (16 * (i) + (j))))
; __device__ __forceinline__ void peer_tile(const Args& A, LAS unsigned char* lds, int tile) {
;     ...
;             for (int i = 0; i < 16; ++i) { va[i] = key2f(L2[0][i] & ~127u); vb[i] = key2f(L2[1][i] & ~127u); idx[i] = 127u - (L2[0][i] & 127u); idx[16 + i] = 127u - (L2[1][i] & 127u); }
;     ...
;             unsigned Lf[16], Bt[16];
; #pragma unroll
;             for (int j = 0; j < 16; ++j) Lf[j] = CK(0, j);
; #pragma unroll
;             for (int j = 0; j < 8; ++j) Bt[j] = CK(1, j);
; #pragma unroll
;             for (int j = 0; j < 5; ++j) Bt[8 + j] = CK(2, j);
; #pragma unroll
;             for (int j = 0; j < 3; ++j) Bt[13 + j] = CK(4, j);
	v_ashrrev_i32_e32 v125, 31, v96
	v_lshrrev_b32_e32 v125, 1, v125
	v_and_b32_e32 v124, 0xffffff80, v96
	v_xnor_b32_e32 v124, v124, v125
	v_ashrrev_i32_e32 v126, 31, v90
	v_lshrrev_b32_e32 v126, 1, v126
	v_and_b32_e32 v125, 0xffffff80, v90
	v_xnor_b32_e32 v125, v125, v126
	v_ashrrev_i32_e32 v127, 31, v92
	v_lshrrev_b32_e32 v127, 1, v127
	v_and_b32_e32 v126, 0xffffff80, v92
	v_xnor_b32_e32 v126, v126, v127
	v_ashrrev_i32_e32 v128, 31, v116
	v_lshrrev_b32_e32 v128, 1, v128
	v_and_b32_e32 v127, 0xffffff80, v116
	v_xnor_b32_e32 v127, v127, v128
	v_ashrrev_i32_e32 v129, 31, v102
	v_lshrrev_b32_e32 v129, 1, v129
	v_and_b32_e32 v128, 0xffffff80, v102
	v_xnor_b32_e32 v128, v128, v129
	v_ashrrev_i32_e32 v130, 31, v89
	v_lshrrev_b32_e32 v130, 1, v130
	v_and_b32_e32 v129, 0xffffff80, v89
	v_xnor_b32_e32 v129, v129, v130
	v_ashrrev_i32_e32 v131, 31, v86
	v_lshrrev_b32_e32 v131, 1, v131
	v_and_b32_e32 v130, 0xffffff80, v86
	v_xnor_b32_e32 v130, v130, v131
	v_ashrrev_i32_e32 v132, 31, v87
	v_lshrrev_b32_e32 v132, 1, v132
	v_and_b32_e32 v131, 0xffffff80, v87
	v_xnor_b32_e32 v131, v131, v132
	v_ashrrev_i32_e32 v133, 31, v73
	v_lshrrev_b32_e32 v133, 1, v133
	v_and_b32_e32 v132, 0xffffff80, v73
	v_xnor_b32_e32 v132, v132, v133
	v_ashrrev_i32_e32 v134, 31, v118
	v_lshrrev_b32_e32 v134, 1, v134
	v_and_b32_e32 v133, 0xffffff80, v118
	v_xnor_b32_e32 v133, v133, v134
	v_ashrrev_i32_e32 v135, 31, v80
	v_lshrrev_b32_e32 v135, 1, v135
	v_and_b32_e32 v134, 0xffffff80, v80
	v_xnor_b32_e32 v134, v134, v135
	v_add_f32_e32 v80, v100, v117
	v_ashrrev_i32_e32 v118, 31, v80
	v_and_b32_e32 v80, 0xffffff00, v80
	v_lshl_or_b32 v118, v118, 8, s33
	v_xor_b32_e32 v80, v80, v118
	v_xor_b32_e32 v80, 0xff, v80
	v_add_f32_e32 v118, v100, v120
	v_ashrrev_i32_e32 v73, 31, v118
	v_and_b32_e32 v118, 0xffffff00, v118
	v_lshl_or_b32 v73, v73, 8, s33
	v_xor_b32_e32 v118, v118, v73
	v_xor_b32_e32 v118, 0xfe, v118
	v_add_f32_e32 v73, v100, v121
	v_ashrrev_i32_e32 v87, 31, v73
	v_and_b32_e32 v73, 0xffffff00, v73
	v_lshl_or_b32 v87, v87, 8, s33
	v_xor_b32_e32 v73, v73, v87
	v_xor_b32_e32 v73, 0xfd, v73
	v_add_f32_e32 v87, v100, v122
	v_ashrrev_i32_e32 v86, 31, v87
	v_and_b32_e32 v87, 0xffffff00, v87
	v_lshl_or_b32 v86, v86, 8, s33
	v_xor_b32_e32 v87, v87, v86
	v_xor_b32_e32 v87, 0xfc, v87
	v_add_f32_e32 v86, v100, v123
	v_ashrrev_i32_e32 v89, 31, v86
	v_and_b32_e32 v86, 0xffffff00, v86
	v_lshl_or_b32 v89, v89, 8, s33
	v_xor_b32_e32 v86, v86, v89
	v_xor_b32_e32 v86, 0xfb, v86
	v_add_f32_e32 v89, v100, v124
	v_ashrrev_i32_e32 v102, 31, v89
	v_and_b32_e32 v89, 0xffffff00, v89
	v_lshl_or_b32 v102, v102, 8, s33
	v_xor_b32_e32 v89, v89, v102
	v_xor_b32_e32 v89, 0xfa, v89
	v_add_f32_e32 v102, v100, v125
	v_ashrrev_i32_e32 v116, 31, v102
	v_and_b32_e32 v102, 0xffffff00, v102
	v_lshl_or_b32 v116, v116, 8, s33
	v_xor_b32_e32 v102, v102, v116
	v_xor_b32_e32 v102, 0xf9, v102
	v_add_f32_e32 v116, v100, v126
	v_ashrrev_i32_e32 v92, 31, v116
	v_and_b32_e32 v116, 0xffffff00, v116
	v_lshl_or_b32 v92, v92, 8, s33
	v_xor_b32_e32 v116, v116, v92
	v_xor_b32_e32 v116, 0xf8, v116
	v_add_f32_e32 v92, v100, v127
	v_ashrrev_i32_e32 v90, 31, v92
	v_and_b32_e32 v92, 0xffffff00, v92
	v_lshl_or_b32 v90, v90, 8, s33
	v_xor_b32_e32 v92, v92, v90
	v_xor_b32_e32 v92, 0xf7, v92
	v_add_f32_e32 v90, v100, v128
	v_ashrrev_i32_e32 v96, 31, v90
	v_and_b32_e32 v90, 0xffffff00, v90
	v_lshl_or_b32 v96, v96, 8, s33
	v_xor_b32_e32 v90, v90, v96
	v_xor_b32_e32 v90, 0xf6, v90
	v_add_f32_e32 v96, v100, v129
	v_ashrrev_i32_e32 v94, 31, v96
	v_and_b32_e32 v96, 0xffffff00, v96
	v_lshl_or_b32 v94, v94, 8, s33
	v_xor_b32_e32 v96, v96, v94
	v_xor_b32_e32 v96, 0xf5, v96
	v_add_f32_e32 v94, v100, v130
	v_ashrrev_i32_e32 v91, 31, v94
	v_and_b32_e32 v94, 0xffffff00, v94
	v_lshl_or_b32 v91, v91, 8, s33
	v_xor_b32_e32 v94, v94, v91
	v_xor_b32_e32 v94, 0xf4, v94
	v_add_f32_e32 v91, v100, v131
	v_ashrrev_i32_e32 v93, 31, v91
	v_and_b32_e32 v91, 0xffffff00, v91
	v_lshl_or_b32 v93, v93, 8, s33
	v_xor_b32_e32 v91, v91, v93
	v_xor_b32_e32 v91, 0xf3, v91
	v_add_f32_e32 v93, v100, v132
	v_ashrrev_i32_e32 v98, 31, v93
	v_and_b32_e32 v93, 0xffffff00, v93
	v_lshl_or_b32 v98, v98, 8, s33
	v_xor_b32_e32 v93, v93, v98
	v_xor_b32_e32 v93, 0xf2, v93
	v_add_f32_e32 v98, v100, v133
	v_ashrrev_i32_e32 v88, 31, v98
	v_and_b32_e32 v98, 0xffffff00, v98
	v_lshl_or_b32 v88, v88, 8, s33
	v_xor_b32_e32 v98, v98, v88
	v_xor_b32_e32 v98, 0xf1, v98
	v_add_f32_e32 v88, v100, v134
	v_ashrrev_i32_e32 v85, 31, v88
	v_and_b32_e32 v88, 0xffffff00, v88
	v_lshl_or_b32 v85, v85, 8, s33
	v_xor_b32_e32 v88, v88, v85
	v_xor_b32_e32 v88, 0xf0, v88
	v_add_f32_e32 v85, v109, v117
	v_ashrrev_i32_e32 v101, 31, v85
	v_and_b32_e32 v85, 0xffffff00, v85
	v_lshl_or_b32 v101, v101, 8, s33
	v_xor_b32_e32 v85, v85, v101
	v_xor_b32_e32 v85, 0xef, v85
	v_add_f32_e32 v101, v109, v120
	v_ashrrev_i32_e32 v83, 31, v101
	v_and_b32_e32 v101, 0xffffff00, v101
	v_lshl_or_b32 v83, v83, 8, s33
	v_xor_b32_e32 v101, v101, v83
	v_xor_b32_e32 v101, 0xee, v101
	v_add_f32_e32 v83, v109, v121
	v_ashrrev_i32_e32 v77, 31, v83
	v_and_b32_e32 v83, 0xffffff00, v83
	v_lshl_or_b32 v77, v77, 8, s33
	v_xor_b32_e32 v83, v83, v77
	v_xor_b32_e32 v83, 0xed, v83
	v_add_f32_e32 v77, v109, v122
	v_ashrrev_i32_e32 v70, 31, v77
	v_and_b32_e32 v77, 0xffffff00, v77
	v_lshl_or_b32 v70, v70, 8, s33
	v_xor_b32_e32 v77, v77, v70
	v_xor_b32_e32 v77, 0xec, v77
	v_add_f32_e32 v70, v109, v123
	v_ashrrev_i32_e32 v79, 31, v70
	v_and_b32_e32 v70, 0xffffff00, v70
	v_lshl_or_b32 v79, v79, 8, s33
	v_xor_b32_e32 v70, v70, v79
	v_xor_b32_e32 v70, 0xeb, v70
	v_add_f32_e32 v79, v109, v124
	v_ashrrev_i32_e32 v84, 31, v79
	v_and_b32_e32 v79, 0xffffff00, v79
; #define CE_DESC(a, b) do { const unsigned _mx = (a) > (b) ? (a) : (b), _mn = (a) > (b) ? (b) : (a); (a) = _mx; (b) = _mn; } while (0)
; #define CK(i, j) ((f2key(va[i] + vb[j]) & ~255u) | (unsigned)(255 - (16 * (i) + (j))))
; __device__ __forceinline__ void sort16_desc(unsigned (&k)[16]) {
; #pragma unroll
;     for (int size = 2; size <= 16; size <<= 1)
; #pragma unroll
;         for (int stride = size >> 1; stride > 0; stride >>= 1)
; #pragma unroll
;             for (int i = 0; i < 16; ++i) { const int j = i ^ stride;
;                 if (j > i) { if ((i & size) == 0) CE_DESC(k[i], k[j]); else CE_DESC(k[j], k[i]); } }
; }
; __device__ __forceinline__ void peer_tile(const Args& A, LAS unsigned char* lds, int tile) {
;     ...
;             unsigned Lf[16], Bt[16];
; #pragma unroll
;             for (int j = 0; j < 16; ++j) Lf[j] = CK(0, j);
; #pragma unroll
;             for (int j = 0; j < 8; ++j) Bt[j] = CK(1, j);
; #pragma unroll
;             for (int j = 0; j < 5; ++j) Bt[8 + j] = CK(2, j);
; #pragma unroll
;             for (int j = 0; j < 3; ++j) Bt[13 + j] = CK(4, j);
;             sort16_desc(Bt); merge16(Lf, Bt);
	v_lshl_or_b32 v84, v84, 8, s33
	v_xor_b32_e32 v79, v79, v84
	v_xor_b32_e32 v79, 0xea, v79
	v_add_f32_e32 v84, v109, v125
	v_ashrrev_i32_e32 v99, 31, v84
	v_and_b32_e32 v84, 0xffffff00, v84
	v_lshl_or_b32 v99, v99, 8, s33
	v_xor_b32_e32 v84, v84, v99
	v_xor_b32_e32 v84, 0xe9, v84
	v_add_f32_e32 v99, v109, v126
	v_ashrrev_i32_e32 v72, 31, v99
	v_and_b32_e32 v99, 0xffffff00, v99
	v_lshl_or_b32 v72, v72, 8, s33
	v_xor_b32_e32 v99, v99, v72
	v_xor_b32_e32 v99, 0xe8, v99
	v_add_f32_e32 v72, v108, v117
	v_ashrrev_i32_e32 v78, 31, v72
	v_and_b32_e32 v72, 0xffffff00, v72
	v_lshl_or_b32 v78, v78, 8, s33
	v_xor_b32_e32 v72, v72, v78
	v_xor_b32_e32 v72, 0xdf, v72
	v_add_f32_e32 v78, v108, v120
	v_ashrrev_i32_e32 v81, 31, v78
	v_and_b32_e32 v78, 0xffffff00, v78
	v_lshl_or_b32 v81, v81, 8, s33
	v_xor_b32_e32 v78, v78, v81
	v_xor_b32_e32 v78, 0xde, v78
	v_add_f32_e32 v81, v108, v121
	v_ashrrev_i32_e32 v74, 31, v81
	v_and_b32_e32 v81, 0xffffff00, v81
	v_lshl_or_b32 v74, v74, 8, s33
	v_xor_b32_e32 v81, v81, v74
	v_xor_b32_e32 v81, 0xdd, v81
	v_add_f32_e32 v74, v108, v122
	v_ashrrev_i32_e32 v82, 31, v74
	v_and_b32_e32 v74, 0xffffff00, v74
	v_lshl_or_b32 v82, v82, 8, s33
	v_xor_b32_e32 v74, v74, v82
	v_xor_b32_e32 v74, 0xdc, v74
	v_add_f32_e32 v82, v108, v123
	v_ashrrev_i32_e32 v71, 31, v82
	v_and_b32_e32 v82, 0xffffff00, v82
	v_lshl_or_b32 v71, v71, 8, s33
	v_xor_b32_e32 v82, v82, v71
	v_xor_b32_e32 v82, 0xdb, v82
	v_add_f32_e32 v71, v110, v117
	v_ashrrev_i32_e32 v75, 31, v71
	v_and_b32_e32 v71, 0xffffff00, v71
	v_lshl_or_b32 v75, v75, 8, s33
	v_xor_b32_e32 v71, v71, v75
	v_xor_b32_e32 v71, 0xbf, v71
	v_add_f32_e32 v75, v110, v120
	v_ashrrev_i32_e32 v76, 31, v75
	v_and_b32_e32 v75, 0xffffff00, v75
	v_lshl_or_b32 v76, v76, 8, s33
	v_xor_b32_e32 v75, v75, v76
	v_xor_b32_e32 v75, 0xbe, v75
	v_add_f32_e32 v76, v110, v121
	v_ashrrev_i32_e32 v135, 31, v76
	v_and_b32_e32 v76, 0xffffff00, v76
	v_lshl_or_b32 v135, v135, 8, s33
	v_xor_b32_e32 v76, v76, v135
	v_xor_b32_e32 v76, 0xbd, v76
	v_max_u32_e32 v135, v85, v101
	v_min_u32_e32 v101, v85, v101
	v_max_u32_e32 v85, v83, v77
	v_min_u32_e32 v77, v83, v77
	v_max_u32_e32 v83, v135, v85
	v_min_u32_e32 v85, v135, v85
	v_max_u32_e32 v135, v101, v77
	v_min_u32_e32 v77, v101, v77
	v_max_u32_e32 v101, v135, v85
	v_min_u32_e32 v85, v135, v85
	v_max_u32_e32 v135, v70, v79
	v_min_u32_e32 v79, v70, v79
	v_max_u32_e32 v70, v84, v99
	v_min_u32_e32 v99, v84, v99
	v_max_u32_e32 v84, v135, v70
	v_min_u32_e32 v70, v135, v70
	v_max_u32_e32 v135, v79, v99
	v_min_u32_e32 v99, v79, v99
	v_max_u32_e32 v79, v135, v70
	v_min_u32_e32 v70, v135, v70
	v_max_u32_e32 v135, v83, v84
	v_min_u32_e32 v84, v83, v84
	v_max_u32_e32 v83, v85, v70
	v_min_u32_e32 v70, v85, v70
	v_max_u32_e32 v85, v83, v84
	v_min_u32_e32 v84, v83, v84
	v_max_u32_e32 v83, v101, v79
	v_min_u32_e32 v79, v101, v79
	v_max_u32_e32 v101, v77, v99
	v_min_u32_e32 v99, v77, v99
	v_max_u32_e32 v77, v101, v79
	v_min_u32_e32 v79, v101, v79
	v_max_u32_e32 v101, v83, v85
	v_min_u32_e32 v85, v83, v85
	v_max_u32_e32 v83, v77, v84
	v_min_u32_e32 v84, v77, v84
	v_max_u32_e32 v77, v79, v70
	v_min_u32_e32 v70, v79, v70
	v_max_u32_e32 v79, v72, v78
	v_min_u32_e32 v78, v72, v78
	v_max_u32_e32 v72, v81, v74
	v_min_u32_e32 v74, v81, v74
	v_max_u32_e32 v81, v79, v72
	v_min_u32_e32 v72, v79, v72
	v_max_u32_e32 v79, v78, v74
	v_min_u32_e32 v74, v78, v74
	v_max_u32_e32 v78, v79, v72
	v_min_u32_e32 v72, v79, v72
	v_max_u32_e32 v79, v82, v71
	v_min_u32_e32 v71, v82, v71
	v_max_u32_e32 v82, v75, v76
	v_min_u32_e32 v76, v75, v76
	v_max_u32_e32 v75, v79, v82
	v_min_u32_e32 v82, v79, v82
	v_max_u32_e32 v79, v71, v76
	v_min_u32_e32 v76, v71, v76
	v_max_u32_e32 v71, v79, v82
	v_min_u32_e32 v82, v79, v82
	v_max_u32_e32 v79, v81, v75
	v_min_u32_e32 v75, v81, v75
	v_max_u32_e32 v81, v72, v82
	v_min_u32_e32 v82, v72, v82
	v_max_u32_e32 v72, v81, v75
	v_min_u32_e32 v75, v81, v75
	v_max_u32_e32 v81, v78, v71
	v_min_u32_e32 v71, v78, v71
	v_max_u32_e32 v78, v74, v76
	v_min_u32_e32 v76, v74, v76
	v_max_u32_e32 v74, v78, v71
	v_min_u32_e32 v71, v78, v71
	v_max_u32_e32 v78, v81, v72
	v_min_u32_e32 v72, v81, v72
	v_max_u32_e32 v81, v74, v75
	v_min_u32_e32 v75, v74, v75
	v_max_u32_e32 v74, v71, v82
	v_min_u32_e32 v82, v71, v82
	v_max_u32_e32 v71, v135, v79
	v_min_u32_e32 v79, v135, v79
	v_max_u32_e32 v135, v84, v75
	v_min_u32_e32 v75, v84, v75
	v_max_u32_e32 v84, v135, v79
	v_min_u32_e32 v79, v135, v79
	v_max_u32_e32 v135, v85, v72
	v_min_u32_e32 v72, v85, v72
	v_max_u32_e32 v85, v70, v82
	v_min_u32_e32 v82, v70, v82
	v_max_u32_e32 v70, v85, v72
	v_min_u32_e32 v72, v85, v72
	v_max_u32_e32 v85, v135, v84
	v_min_u32_e32 v84, v135, v84
	v_max_u32_e32 v135, v70, v79
	v_min_u32_e32 v79, v70, v79
	v_max_u32_e32 v70, v72, v75
	v_min_u32_e32 v75, v72, v75
	v_max_u32_e32 v72, v101, v78
	v_min_u32_e32 v78, v101, v78
	v_max_u32_e32 v101, v77, v74
	v_min_u32_e32 v74, v77, v74
	v_max_u32_e32 v77, v101, v78
	v_min_u32_e32 v78, v101, v78
	v_max_u32_e32 v101, v83, v81
	v_min_u32_e32 v81, v83, v81
	v_max_u32_e32 v83, v99, v76
	v_min_u32_e32 v76, v99, v76
	v_max_u32_e32 v99, v83, v81
	v_min_u32_e32 v81, v83, v81
	v_max_u32_e32 v83, v101, v77
	v_min_u32_e32 v77, v101, v77
	v_max_u32_e32 v101, v99, v78
	v_min_u32_e32 v78, v99, v78
	v_max_u32_e32 v99, v81, v74
	v_min_u32_e32 v74, v81, v74
	v_max_u32_e32 v81, v72, v85
	v_min_u32_e32 v85, v72, v85
	v_max_u32_e32 v72, v83, v84
	v_min_u32_e32 v84, v83, v84
	v_max_u32_e32 v83, v77, v135
	v_min_u32_e32 v135, v77, v135
	v_max_u32_e32 v77, v101, v79
	v_min_u32_e32 v79, v101, v79
	v_max_u32_e32 v101, v78, v70
	v_min_u32_e32 v70, v78, v70
	v_max_u32_e32 v78, v99, v75
	v_min_u32_e32 v75, v99, v75
; #define CK(i, j) ((f2key(va[i] + vb[j]) & ~255u) | (unsigned)(255 - (16 * (i) + (j))))
; __device__ __forceinline__ void peer_tile(const Args& A, LAS unsigned char* lds, int tile) {
;     ...
;             sort16_desc(Bt); merge16(Lf, Bt);
; #pragma unroll
;             for (int j = 0; j < 4; ++j) Bt[j] = CK(3, j);
;             Bt[4] = CK(5, 0); Bt[5] = CK(5, 1); Bt[6] = CK(6, 0); Bt[7] = CK(6, 1); Bt[8] = CK(7, 0); Bt[9] = CK(7, 1);
;             Bt[10] = CK(8, 0); Bt[11] = CK(9, 0); Bt[12] = CK(10, 0); Bt[13] = CK(11, 0); Bt[14] = CK(12, 0); Bt[15] = CK(13, 0);
;             sort16_desc(Bt); merge16(Lf, Bt);
	v_max_u32_e32 v99, v74, v82
	v_min_u32_e32 v82, v74, v82
	v_max_u32_e32 v80, v80, v76
	v_max_u32_e32 v118, v118, v82
	v_max_u32_e32 v73, v73, v99
	v_max_u32_e32 v87, v87, v75
	v_max_u32_e32 v86, v86, v78
	v_max_u32_e32 v89, v89, v70
	v_max_u32_e32 v102, v102, v101
	v_max_u32_e32 v116, v116, v79
	v_max_u32_e32 v92, v92, v77
	v_max_u32_e32 v90, v90, v135
	v_max_u32_e32 v96, v96, v83
	v_max_u32_e32 v94, v94, v84
	v_max_u32_e32 v91, v91, v72
	v_max_u32_e32 v93, v93, v85
	v_max_u32_e32 v98, v98, v81
	v_max_u32_e32 v88, v88, v71
	v_max_u32_e32 v76, v80, v92
	v_min_u32_e32 v92, v80, v92
	v_max_u32_e32 v80, v118, v90
	v_min_u32_e32 v90, v118, v90
	v_max_u32_e32 v118, v73, v96
	v_min_u32_e32 v96, v73, v96
	v_max_u32_e32 v73, v87, v94
	v_min_u32_e32 v94, v87, v94
	v_max_u32_e32 v87, v86, v91
	v_min_u32_e32 v91, v86, v91
	v_max_u32_e32 v86, v89, v93
	v_min_u32_e32 v93, v89, v93
	v_max_u32_e32 v89, v102, v98
	v_min_u32_e32 v98, v102, v98
	v_max_u32_e32 v102, v116, v88
	v_min_u32_e32 v88, v116, v88
	v_max_u32_e32 v116, v76, v87
	v_min_u32_e32 v87, v76, v87
	v_max_u32_e32 v76, v80, v86
	v_min_u32_e32 v86, v80, v86
	v_max_u32_e32 v80, v118, v89
	v_min_u32_e32 v89, v118, v89
	v_max_u32_e32 v118, v73, v102
	v_min_u32_e32 v102, v73, v102
	v_max_u32_e32 v73, v92, v91
	v_min_u32_e32 v91, v92, v91
	v_max_u32_e32 v92, v90, v93
	v_min_u32_e32 v93, v90, v93
	v_max_u32_e32 v90, v96, v98
	v_min_u32_e32 v98, v96, v98
	v_max_u32_e32 v96, v94, v88
	v_min_u32_e32 v88, v94, v88
	v_max_u32_e32 v94, v116, v80
	v_min_u32_e32 v80, v116, v80
	v_max_u32_e32 v116, v76, v118
	v_min_u32_e32 v118, v76, v118
	v_max_u32_e32 v76, v87, v89
	v_min_u32_e32 v89, v87, v89
	v_max_u32_e32 v87, v86, v102
	v_min_u32_e32 v102, v86, v102
	v_max_u32_e32 v86, v73, v90
	v_min_u32_e32 v90, v73, v90
	v_max_u32_e32 v73, v92, v96
	v_min_u32_e32 v96, v92, v96
	v_max_u32_e32 v92, v91, v98
	v_min_u32_e32 v98, v91, v98
	v_max_u32_e32 v91, v93, v88
	v_min_u32_e32 v88, v93, v88
	v_max_u32_e32 v93, v94, v116
	v_min_u32_e32 v116, v94, v116
	v_max_u32_e32 v94, v80, v118
	v_min_u32_e32 v118, v80, v118
	v_max_u32_e32 v80, v76, v87
	v_min_u32_e32 v87, v76, v87
	v_max_u32_e32 v76, v89, v102
	v_min_u32_e32 v102, v89, v102
	v_max_u32_e32 v89, v86, v73
	v_min_u32_e32 v73, v86, v73
	v_max_u32_e32 v86, v90, v96
	v_min_u32_e32 v96, v90, v96
	v_max_u32_e32 v90, v92, v91
	v_min_u32_e32 v91, v92, v91
	v_max_u32_e32 v92, v98, v88
	v_min_u32_e32 v88, v98, v88
	v_add_f32_e32 v98, v111, v117
	v_ashrrev_i32_e32 v82, 31, v98
	v_and_b32_e32 v98, 0xffffff00, v98
	v_lshl_or_b32 v82, v82, 8, s33
	v_xor_b32_e32 v98, v98, v82
	v_xor_b32_e32 v98, 0xcf, v98
	v_add_f32_e32 v82, v111, v120
	v_ashrrev_i32_e32 v99, 31, v82
	v_and_b32_e32 v82, 0xffffff00, v82
	v_lshl_or_b32 v99, v99, 8, s33
	v_xor_b32_e32 v82, v82, v99
	v_xor_b32_e32 v82, 0xce, v82
	v_add_f32_e32 v99, v111, v121
	v_ashrrev_i32_e32 v75, 31, v99
	v_and_b32_e32 v99, 0xffffff00, v99
	v_lshl_or_b32 v75, v75, 8, s33
	v_xor_b32_e32 v99, v99, v75
	v_xor_b32_e32 v99, 0xcd, v99
	v_add_f32_e32 v75, v111, v122
	v_ashrrev_i32_e32 v78, 31, v75
	v_and_b32_e32 v75, 0xffffff00, v75
	v_lshl_or_b32 v78, v78, 8, s33
	v_xor_b32_e32 v75, v75, v78
	v_xor_b32_e32 v75, 0xcc, v75
	v_add_f32_e32 v78, v115, v117
	v_ashrrev_i32_e32 v70, 31, v78
	v_and_b32_e32 v78, 0xffffff00, v78
	v_lshl_or_b32 v70, v70, 8, s33
	v_xor_b32_e32 v78, v78, v70
	v_xor_b32_e32 v78, 0xaf, v78
	v_add_f32_e32 v70, v115, v120
	v_ashrrev_i32_e32 v101, 31, v70
	v_and_b32_e32 v70, 0xffffff00, v70
	v_lshl_or_b32 v101, v101, 8, s33
	v_xor_b32_e32 v70, v70, v101
	v_xor_b32_e32 v70, 0xae, v70
	v_add_f32_e32 v101, v104, v117
	v_ashrrev_i32_e32 v79, 31, v101
	v_and_b32_e32 v101, 0xffffff00, v101
	v_lshl_or_b32 v79, v79, 8, s33
	v_xor_b32_e32 v101, v101, v79
	v_xor_b32_e32 v101, 0x9f, v101
	v_add_f32_e32 v79, v104, v120
	v_ashrrev_i32_e32 v77, 31, v79
	v_and_b32_e32 v79, 0xffffff00, v79
	v_lshl_or_b32 v77, v77, 8, s33
	v_xor_b32_e32 v79, v79, v77
	v_xor_b32_e32 v79, 0x9e, v79
	v_add_f32_e32 v77, v103, v117
	v_ashrrev_i32_e32 v135, 31, v77
	v_and_b32_e32 v77, 0xffffff00, v77
	v_lshl_or_b32 v135, v135, 8, s33
	v_xor_b32_e32 v77, v77, v135
	v_xor_b32_e32 v77, 0x8f, v77
	v_add_f32_e32 v135, v103, v120
	v_ashrrev_i32_e32 v83, 31, v135
	v_and_b32_e32 v135, 0xffffff00, v135
	v_lshl_or_b32 v83, v83, 8, s33
	v_xor_b32_e32 v135, v135, v83
	v_xor_b32_e32 v135, 0x8e, v135
	v_add_f32_e32 v83, v106, v117
	v_ashrrev_i32_e32 v84, 31, v83
	v_and_b32_e32 v83, 0xffffff00, v83
	v_lshl_or_b32 v84, v84, 8, s33
	v_xor_b32_e32 v83, v83, v84
	v_xor_b32_e32 v83, 0x7f, v83
	v_add_f32_e32 v84, v105, v117
	v_ashrrev_i32_e32 v72, 31, v84
	v_and_b32_e32 v84, 0xffffff00, v84
	v_lshl_or_b32 v72, v72, 8, s33
	v_xor_b32_e32 v84, v84, v72
	v_xor_b32_e32 v84, 0x6f, v84
	v_add_f32_e32 v72, v114, v117
	v_ashrrev_i32_e32 v85, 31, v72
	v_and_b32_e32 v72, 0xffffff00, v72
	v_lshl_or_b32 v85, v85, 8, s33
	v_xor_b32_e32 v72, v72, v85
	v_xor_b32_e32 v72, 0x5f, v72
	v_add_f32_e32 v85, v112, v117
	v_ashrrev_i32_e32 v81, 31, v85
	v_and_b32_e32 v85, 0xffffff00, v85
	v_lshl_or_b32 v81, v81, 8, s33
	v_xor_b32_e32 v85, v85, v81
	v_xor_b32_e32 v85, 0x4f, v85
	v_add_f32_e32 v81, v107, v117
	v_ashrrev_i32_e32 v71, 31, v81
	v_and_b32_e32 v81, 0xffffff00, v81
	v_lshl_or_b32 v71, v71, 8, s33
	v_xor_b32_e32 v81, v81, v71
	v_xor_b32_e32 v81, 63, v81
	v_add_f32_e32 v71, v95, v117
	v_ashrrev_i32_e32 v74, 31, v71
	v_and_b32_e32 v71, 0xffffff00, v71
	v_lshl_or_b32 v74, v74, 8, s33
	v_xor_b32_e32 v71, v71, v74
	v_xor_b32_e32 v71, 47, v71
	v_max_u32_e32 v74, v98, v82
	v_min_u32_e32 v82, v98, v82
	v_max_u32_e32 v98, v99, v75
	v_min_u32_e32 v75, v99, v75
	v_max_u32_e32 v99, v74, v98
	v_min_u32_e32 v98, v74, v98
; #define CE_DESC(a, b) do { const unsigned _mx = (a) > (b) ? (a) : (b), _mn = (a) > (b) ? (b) : (a); (a) = _mx; (b) = _mn; } while (0)
; __device__ __forceinline__ void sort16_desc(unsigned (&k)[16]) {
; #pragma unroll
;     for (int size = 2; size <= 16; size <<= 1)
; #pragma unroll
;         for (int stride = size >> 1; stride > 0; stride >>= 1)
; #pragma unroll
;             for (int i = 0; i < 16; ++i) { const int j = i ^ stride;
;                 if (j > i) { if ((i & size) == 0) CE_DESC(k[i], k[j]); else CE_DESC(k[j], k[i]); } }
; }
; __device__ __forceinline__ void merge16(unsigned (&a)[16], const unsigned (&b)[16]) {
; #pragma unroll
;     for (int i = 0; i < 16; ++i) a[i] = a[i] > b[15 - i] ? a[i] : b[15 - i];
; #pragma unroll
;     for (int stride = 8; stride > 0; stride >>= 1)
; #pragma unroll
;         for (int i = 0; i < 16; ++i) { const int j = i ^ stride; if (j > i) CE_DESC(a[i], a[j]); }
; }
; __device__ __forceinline__ void peer_tile(const Args& A, LAS unsigned char* lds, int tile) {
;     ...
;             sort16_desc(Bt); merge16(Lf, Bt);
	v_max_u32_e32 v74, v82, v75
	v_min_u32_e32 v75, v82, v75
	v_max_u32_e32 v82, v74, v98
	v_min_u32_e32 v98, v74, v98
	v_max_u32_e32 v74, v78, v70
	v_min_u32_e32 v70, v78, v70
	v_max_u32_e32 v78, v101, v79
	v_min_u32_e32 v79, v101, v79
	v_max_u32_e32 v101, v74, v78
	v_min_u32_e32 v78, v74, v78
	v_max_u32_e32 v74, v70, v79
	v_min_u32_e32 v79, v70, v79
	v_max_u32_e32 v70, v74, v78
	v_min_u32_e32 v78, v74, v78
	v_max_u32_e32 v74, v99, v101
	v_min_u32_e32 v101, v99, v101
	v_max_u32_e32 v99, v98, v78
	v_min_u32_e32 v78, v98, v78
	v_max_u32_e32 v98, v99, v101
	v_min_u32_e32 v101, v99, v101
	v_max_u32_e32 v99, v82, v70
	v_min_u32_e32 v70, v82, v70
	v_max_u32_e32 v82, v75, v79
	v_min_u32_e32 v79, v75, v79
	v_max_u32_e32 v75, v82, v70
	v_min_u32_e32 v70, v82, v70
	v_max_u32_e32 v82, v99, v98
	v_min_u32_e32 v98, v99, v98
	v_max_u32_e32 v99, v75, v101
	v_min_u32_e32 v101, v75, v101
	v_max_u32_e32 v75, v70, v78
	v_min_u32_e32 v78, v70, v78
	v_max_u32_e32 v70, v77, v135
	v_min_u32_e32 v135, v77, v135
	v_max_u32_e32 v77, v83, v84
	v_min_u32_e32 v84, v83, v84
	v_max_u32_e32 v83, v70, v77
	v_min_u32_e32 v77, v70, v77
	v_max_u32_e32 v70, v135, v84
	v_min_u32_e32 v84, v135, v84
	v_max_u32_e32 v135, v70, v77
	v_min_u32_e32 v77, v70, v77
	v_max_u32_e32 v70, v72, v85
	v_min_u32_e32 v85, v72, v85
	v_max_u32_e32 v72, v81, v71
	v_min_u32_e32 v71, v81, v71
	v_max_u32_e32 v81, v70, v72
	v_min_u32_e32 v72, v70, v72
	v_max_u32_e32 v70, v85, v71
	v_min_u32_e32 v71, v85, v71
	v_max_u32_e32 v85, v70, v72
	v_min_u32_e32 v72, v70, v72
	v_max_u32_e32 v70, v83, v81
	v_min_u32_e32 v81, v83, v81
	v_max_u32_e32 v83, v77, v72
	v_min_u32_e32 v72, v77, v72
	v_max_u32_e32 v77, v83, v81
	v_min_u32_e32 v81, v83, v81
	v_max_u32_e32 v83, v135, v85
	v_min_u32_e32 v85, v135, v85
	v_max_u32_e32 v135, v84, v71
	v_min_u32_e32 v71, v84, v71
	v_max_u32_e32 v84, v135, v85
	v_min_u32_e32 v85, v135, v85
	v_max_u32_e32 v135, v83, v77
	v_min_u32_e32 v77, v83, v77
	v_max_u32_e32 v83, v84, v81
	v_min_u32_e32 v81, v84, v81
	v_max_u32_e32 v84, v85, v72
	v_min_u32_e32 v72, v85, v72
	v_max_u32_e32 v85, v74, v70
	v_min_u32_e32 v70, v74, v70
	v_max_u32_e32 v74, v101, v81
	v_min_u32_e32 v81, v101, v81
	v_max_u32_e32 v101, v74, v70
	v_min_u32_e32 v70, v74, v70
	v_max_u32_e32 v74, v98, v77
	v_min_u32_e32 v77, v98, v77
	v_max_u32_e32 v98, v78, v72
	v_min_u32_e32 v72, v78, v72
	v_max_u32_e32 v78, v98, v77
	v_min_u32_e32 v77, v98, v77
	v_max_u32_e32 v98, v74, v101
	v_min_u32_e32 v101, v74, v101
	v_max_u32_e32 v74, v78, v70
	v_min_u32_e32 v70, v78, v70
	v_max_u32_e32 v78, v77, v81
	v_min_u32_e32 v81, v77, v81
	v_max_u32_e32 v77, v82, v135
	v_min_u32_e32 v135, v82, v135
	v_max_u32_e32 v82, v75, v84
	v_min_u32_e32 v84, v75, v84
	v_max_u32_e32 v75, v82, v135
	v_min_u32_e32 v135, v82, v135
	v_max_u32_e32 v82, v99, v83
	v_min_u32_e32 v83, v99, v83
	v_max_u32_e32 v99, v79, v71
	v_min_u32_e32 v71, v79, v71
	v_max_u32_e32 v79, v99, v83
	v_min_u32_e32 v83, v99, v83
	v_max_u32_e32 v99, v82, v75
	v_min_u32_e32 v75, v82, v75
	v_max_u32_e32 v82, v79, v135
	v_min_u32_e32 v135, v79, v135
	v_max_u32_e32 v79, v83, v84
	v_min_u32_e32 v84, v83, v84
	v_max_u32_e32 v83, v77, v98
	v_min_u32_e32 v98, v77, v98
	v_max_u32_e32 v77, v99, v101
	v_min_u32_e32 v101, v99, v101
	v_max_u32_e32 v99, v75, v74
	v_min_u32_e32 v74, v75, v74
	v_max_u32_e32 v75, v82, v70
	v_min_u32_e32 v70, v82, v70
	v_max_u32_e32 v82, v135, v78
	v_min_u32_e32 v78, v135, v78
	v_max_u32_e32 v135, v79, v81
	v_min_u32_e32 v81, v79, v81
	v_max_u32_e32 v79, v84, v72
	v_min_u32_e32 v72, v84, v72
	v_max_u32_e32 v93, v93, v71
	v_max_u32_e32 v116, v116, v72
	v_max_u32_e32 v94, v94, v79
	v_max_u32_e32 v118, v118, v81
	v_max_u32_e32 v80, v80, v135
	v_max_u32_e32 v87, v87, v78
	v_max_u32_e32 v76, v76, v82
	v_max_u32_e32 v102, v102, v70
	v_max_u32_e32 v89, v89, v75
	v_max_u32_e32 v73, v73, v74
	v_max_u32_e32 v86, v86, v99
	v_max_u32_e32 v96, v96, v101
	v_max_u32_e32 v90, v90, v77
	v_max_u32_e32 v91, v91, v98
	v_max_u32_e32 v92, v92, v83
	v_max_u32_e32 v88, v88, v85
	v_max_u32_e32 v71, v93, v89
	v_min_u32_e32 v89, v93, v89
	v_max_u32_e32 v93, v116, v73
	v_min_u32_e32 v73, v116, v73
	v_max_u32_e32 v116, v94, v86
	v_min_u32_e32 v86, v94, v86
	v_max_u32_e32 v94, v118, v96
	v_min_u32_e32 v96, v118, v96
	v_max_u32_e32 v118, v80, v90
	v_min_u32_e32 v90, v80, v90
	v_max_u32_e32 v80, v87, v91
	v_min_u32_e32 v91, v87, v91
	v_max_u32_e32 v87, v76, v92
	v_min_u32_e32 v92, v76, v92
	v_max_u32_e32 v76, v102, v88
	v_min_u32_e32 v88, v102, v88
	v_max_u32_e32 v102, v71, v118
	v_min_u32_e32 v118, v71, v118
	v_max_u32_e32 v71, v93, v80
	v_min_u32_e32 v80, v93, v80
	v_max_u32_e32 v93, v116, v87
	v_min_u32_e32 v87, v116, v87
	v_max_u32_e32 v116, v94, v76
	v_min_u32_e32 v76, v94, v76
	v_max_u32_e32 v94, v89, v90
	v_min_u32_e32 v90, v89, v90
	v_max_u32_e32 v89, v73, v91
	v_min_u32_e32 v91, v73, v91
	v_max_u32_e32 v73, v86, v92
	v_min_u32_e32 v92, v86, v92
	v_max_u32_e32 v86, v96, v88
	v_min_u32_e32 v88, v96, v88
	v_max_u32_e32 v96, v102, v93
	v_min_u32_e32 v93, v102, v93
	v_max_u32_e32 v102, v71, v116
	v_min_u32_e32 v116, v71, v116
	v_max_u32_e32 v71, v118, v87
	v_min_u32_e32 v87, v118, v87
	v_max_u32_e32 v118, v80, v76
	v_min_u32_e32 v76, v80, v76
	v_max_u32_e32 v80, v94, v73
	v_min_u32_e32 v73, v94, v73
	v_max_u32_e32 v94, v89, v86
	v_min_u32_e32 v86, v89, v86
	v_max_u32_e32 v89, v90, v92
	v_min_u32_e32 v92, v90, v92
	v_max_u32_e32 v90, v91, v88
	v_min_u32_e32 v88, v91, v88
	v_max_u32_e32 v91, v96, v102
	v_min_u32_e32 v102, v96, v102
	v_max_u32_e32 v96, v93, v116
	v_min_u32_e32 v116, v93, v116
	v_max_u32_e32 v93, v71, v118
	v_min_u32_e32 v118, v71, v118
	v_max_u32_e32 v71, v87, v76
	v_min_u32_e32 v76, v87, v76
; __device__ __forceinline__ float key2f(unsigned k) { const unsigned u = (k & 0x80000000u) ? (k & 0x7fffffffu) : ~k; return __uint_as_float(u); }
; #define CE_DESC(a, b) do { const unsigned _mx = (a) > (b) ? (a) : (b), _mn = (a) > (b) ? (b) : (a); (a) = _mx; (b) = _mn; } while (0)
; #define CK(i, j) ((f2key(va[i] + vb[j]) & ~255u) | (unsigned)(255 - (16 * (i) + (j))))
; __device__ __forceinline__ void peer_tile(const Args& A, LAS unsigned char* lds, int tile) {
;     ...
;             { unsigned x0 = CK(14, 0), x1 = CK(15, 0);
; #pragma unroll
;               for (int i = 0; i < 16; ++i) CE_DESC(Lf[i], x0);
; #pragma unroll
;               for (int i = 0; i < 16; ++i) CE_DESC(Lf[i], x1); }
;     ...
;             float fv[16], den = 0.f; const float f0 = key2f(Lf[0] & ~255u);
; #pragma unroll
;             for (int k = 0; k < 16; ++k) { fv[k] = __expf(key2f(Lf[k] & ~255u) - f0); den += fv[k]; }
	v_max_u32_e32 v87, v80, v94
	v_min_u32_e32 v94, v80, v94
	v_max_u32_e32 v80, v73, v86
	v_min_u32_e32 v86, v73, v86
	v_max_u32_e32 v73, v89, v90
	v_min_u32_e32 v90, v89, v90
	v_max_u32_e32 v89, v92, v88
	v_min_u32_e32 v88, v92, v88
	v_add_f32_e32 v92, v119, v117
	v_ashrrev_i32_e32 v72, 31, v92
	v_and_b32_e32 v92, 0xffffff00, v92
	v_lshl_or_b32 v72, v72, 8, s33
	v_xor_b32_e32 v92, v92, v72
	v_xor_b32_e32 v92, 31, v92
	v_max_u32_e32 v72, v91, v92
	v_min_u32_e32 v92, v91, v92
	v_max_u32_e32 v91, v102, v92
	v_min_u32_e32 v92, v102, v92
	v_max_u32_e32 v102, v96, v92
	v_min_u32_e32 v92, v96, v92
	v_max_u32_e32 v96, v116, v92
	v_min_u32_e32 v92, v116, v92
	v_max_u32_e32 v116, v93, v92
	v_min_u32_e32 v92, v93, v92
	v_max_u32_e32 v93, v118, v92
	v_min_u32_e32 v92, v118, v92
	v_max_u32_e32 v118, v71, v92
	v_min_u32_e32 v92, v71, v92
	v_max_u32_e32 v71, v76, v92
	v_min_u32_e32 v92, v76, v92
	v_max_u32_e32 v76, v87, v92
	v_min_u32_e32 v92, v87, v92
	v_max_u32_e32 v87, v94, v92
	v_min_u32_e32 v92, v94, v92
	v_max_u32_e32 v94, v80, v92
	v_min_u32_e32 v92, v80, v92
	v_max_u32_e32 v80, v86, v92
	v_min_u32_e32 v92, v86, v92
	v_max_u32_e32 v86, v73, v92
	v_min_u32_e32 v92, v73, v92
	v_max_u32_e32 v73, v90, v92
	v_min_u32_e32 v92, v90, v92
	v_max_u32_e32 v90, v89, v92
	v_min_u32_e32 v92, v89, v92
	v_max_u32_e32 v89, v88, v92
	v_min_u32_e32 v92, v88, v92
	v_add_f32_e32 v92, v97, v117
	v_ashrrev_i32_e32 v88, 31, v92
	v_and_b32_e32 v92, 0xffffff00, v92
	v_lshl_or_b32 v88, v88, 8, s33
	v_xor_b32_e32 v92, v92, v88
	v_xor_b32_e32 v92, 15, v92
	v_max_u32_e32 v88, v72, v92
	v_min_u32_e32 v92, v72, v92
	v_max_u32_e32 v72, v91, v92
	v_min_u32_e32 v92, v91, v92
	v_max_u32_e32 v91, v102, v92
	v_min_u32_e32 v92, v102, v92
	v_max_u32_e32 v102, v96, v92
	v_min_u32_e32 v92, v96, v92
	v_max_u32_e32 v96, v116, v92
	v_min_u32_e32 v92, v116, v92
	v_max_u32_e32 v116, v93, v92
	v_min_u32_e32 v92, v93, v92
	v_max_u32_e32 v93, v118, v92
	v_min_u32_e32 v92, v118, v92
	v_max_u32_e32 v118, v71, v92
	v_min_u32_e32 v92, v71, v92
	v_max_u32_e32 v71, v76, v92
	v_min_u32_e32 v92, v76, v92
	v_max_u32_e32 v76, v87, v92
	v_min_u32_e32 v92, v87, v92
	v_max_u32_e32 v87, v94, v92
	v_min_u32_e32 v92, v94, v92
	v_max_u32_e32 v94, v80, v92
	v_min_u32_e32 v92, v80, v92
	v_max_u32_e32 v80, v86, v92
	v_min_u32_e32 v92, v86, v92
	v_max_u32_e32 v86, v73, v92
	v_min_u32_e32 v92, v73, v92
	v_max_u32_e32 v73, v90, v92
	v_min_u32_e32 v92, v90, v92
	v_max_u32_e32 v90, v89, v92
	v_min_u32_e32 v92, v89, v92
	v_ashrrev_i32_e32 v133, 31, v88
	v_lshrrev_b32_e32 v133, 1, v133
	v_and_b32_e32 v134, 0xffffff00, v88
	v_xnor_b32_e32 v134, v134, v133
	v_ashrrev_i32_e32 v131, 31, v88
	v_lshrrev_b32_e32 v131, 1, v131
	v_and_b32_e32 v132, 0xffffff00, v88
	v_xnor_b32_e32 v132, v132, v131
	v_sub_f32_e32 v132, v132, v134
	v_mul_f32_e32 v132, 0x3fb8aa3b, v132
	v_exp_f32_e32 v132, v132
	v_ashrrev_i32_e32 v130, 31, v72
	v_lshrrev_b32_e32 v130, 1, v130
	v_and_b32_e32 v131, 0xffffff00, v72
	v_xnor_b32_e32 v131, v131, v130
	v_sub_f32_e32 v131, v131, v134
	v_mul_f32_e32 v131, 0x3fb8aa3b, v131
	v_exp_f32_e32 v131, v131
	v_ashrrev_i32_e32 v129, 31, v91
	v_lshrrev_b32_e32 v129, 1, v129
	v_and_b32_e32 v130, 0xffffff00, v91
	v_xnor_b32_e32 v130, v130, v129
	v_sub_f32_e32 v130, v130, v134
	v_mul_f32_e32 v130, 0x3fb8aa3b, v130
	v_exp_f32_e32 v130, v130
	v_ashrrev_i32_e32 v128, 31, v102
	v_lshrrev_b32_e32 v128, 1, v128
	v_and_b32_e32 v129, 0xffffff00, v102
	v_xnor_b32_e32 v129, v129, v128
	v_sub_f32_e32 v129, v129, v134
	v_mul_f32_e32 v129, 0x3fb8aa3b, v129
	v_exp_f32_e32 v129, v129
	v_ashrrev_i32_e32 v127, 31, v96
	v_lshrrev_b32_e32 v127, 1, v127
	v_and_b32_e32 v128, 0xffffff00, v96
	v_xnor_b32_e32 v128, v128, v127
	v_sub_f32_e32 v128, v128, v134
	v_mul_f32_e32 v128, 0x3fb8aa3b, v128
	v_exp_f32_e32 v128, v128
	v_ashrrev_i32_e32 v126, 31, v116
	v_lshrrev_b32_e32 v126, 1, v126
	v_and_b32_e32 v127, 0xffffff00, v116
	v_xnor_b32_e32 v127, v127, v126
	v_sub_f32_e32 v127, v127, v134
	v_mul_f32_e32 v127, 0x3fb8aa3b, v127
	v_exp_f32_e32 v127, v127
	v_ashrrev_i32_e32 v125, 31, v93
	v_lshrrev_b32_e32 v125, 1, v125
	v_and_b32_e32 v126, 0xffffff00, v93
	v_xnor_b32_e32 v126, v126, v125
	v_sub_f32_e32 v126, v126, v134
	v_mul_f32_e32 v126, 0x3fb8aa3b, v126
	v_exp_f32_e32 v126, v126
	v_ashrrev_i32_e32 v124, 31, v118
	v_lshrrev_b32_e32 v124, 1, v124
	v_and_b32_e32 v125, 0xffffff00, v118
	v_xnor_b32_e32 v125, v125, v124
	v_sub_f32_e32 v125, v125, v134
	v_mul_f32_e32 v125, 0x3fb8aa3b, v125
	v_exp_f32_e32 v125, v125
	v_ashrrev_i32_e32 v123, 31, v71
	v_lshrrev_b32_e32 v123, 1, v123
	v_and_b32_e32 v124, 0xffffff00, v71
	v_xnor_b32_e32 v124, v124, v123
	v_sub_f32_e32 v124, v124, v134
	v_mul_f32_e32 v124, 0x3fb8aa3b, v124
	v_exp_f32_e32 v124, v124
	v_ashrrev_i32_e32 v122, 31, v76
	v_lshrrev_b32_e32 v122, 1, v122
	v_and_b32_e32 v123, 0xffffff00, v76
	v_xnor_b32_e32 v123, v123, v122
	v_sub_f32_e32 v123, v123, v134
	v_mul_f32_e32 v123, 0x3fb8aa3b, v123
	v_exp_f32_e32 v123, v123
	v_ashrrev_i32_e32 v121, 31, v87
	v_lshrrev_b32_e32 v121, 1, v121
	v_and_b32_e32 v122, 0xffffff00, v87
	v_xnor_b32_e32 v122, v122, v121
	v_sub_f32_e32 v122, v122, v134
	v_mul_f32_e32 v122, 0x3fb8aa3b, v122
	v_exp_f32_e32 v122, v122
	v_ashrrev_i32_e32 v120, 31, v94
	v_lshrrev_b32_e32 v120, 1, v120
	v_and_b32_e32 v121, 0xffffff00, v94
	v_xnor_b32_e32 v121, v121, v120
	v_sub_f32_e32 v121, v121, v134
	v_mul_f32_e32 v121, 0x3fb8aa3b, v121
	v_exp_f32_e32 v121, v121
	v_ashrrev_i32_e32 v117, 31, v80
	v_lshrrev_b32_e32 v117, 1, v117
	v_and_b32_e32 v120, 0xffffff00, v80
	v_xnor_b32_e32 v120, v120, v117
	v_sub_f32_e32 v120, v120, v134
	v_mul_f32_e32 v120, 0x3fb8aa3b, v120
	v_exp_f32_e32 v120, v120
; #define LDS_WAIT() asm volatile("s_waitcnt lgkmcnt(0)" ::: "memory")
; __device__ __forceinline__ float key2f(unsigned k) { const unsigned u = (k & 0x80000000u) ? (k & 0x7fffffffu) : ~k; return __uint_as_float(u); }
; __device__ __forceinline__ void peer_tile(const Args& A, LAS unsigned char* lds, int tile) {
;     ...
;             float fv[16], den = 0.f; const float f0 = key2f(Lf[0] & ~255u);
; #pragma unroll
;             for (int k = 0; k < 16; ++k) { fv[k] = __expf(key2f(Lf[k] & ~255u) - f0); den += fv[k]; }
;             const float rden = 1.f / den;
;             LDS_WAIT();
; #pragma unroll
;             for (int k = 0; k < 16; ++k) { const unsigned code = 255u - (Lf[k] & 255u); const unsigned e = idx[code >> 4] * 128u + idx[16 + (code & 15u)];
;                 u32x2 sv; sv.x = e; sv.y = __float_as_uint(fv[k] * rden); SEL[(tl * 8 + h) * 16 + k] = sv; }
	v_ashrrev_i32_e32 v97, 31, v86
	v_lshrrev_b32_e32 v97, 1, v97
	v_and_b32_e32 v117, 0xffffff00, v86
	v_xnor_b32_e32 v117, v117, v97
	v_sub_f32_e32 v117, v117, v134
	v_mul_f32_e32 v117, 0x3fb8aa3b, v117
	v_exp_f32_e32 v117, v117
	v_ashrrev_i32_e32 v119, 31, v73
	v_lshrrev_b32_e32 v119, 1, v119
	v_and_b32_e32 v97, 0xffffff00, v73
	v_xnor_b32_e32 v97, v97, v119
	v_sub_f32_e32 v97, v97, v134
	v_mul_f32_e32 v97, 0x3fb8aa3b, v97
	v_exp_f32_e32 v97, v97
	v_ashrrev_i32_e32 v95, 31, v90
	v_lshrrev_b32_e32 v95, 1, v95
	v_and_b32_e32 v119, 0xffffff00, v90
	v_xnor_b32_e32 v119, v119, v95
	v_sub_f32_e32 v119, v119, v134
	v_mul_f32_e32 v119, 0x3fb8aa3b, v119
	v_exp_f32_e32 v119, v119
	v_add_f32_e32 v133, 0, v132
	v_add_f32_e32 v133, v133, v131
	v_add_f32_e32 v133, v133, v130
	v_add_f32_e32 v133, v133, v129
	v_add_f32_e32 v133, v133, v128
	v_add_f32_e32 v133, v133, v127
	v_add_f32_e32 v133, v133, v126
	v_add_f32_e32 v133, v133, v125
	v_add_f32_e32 v133, v133, v124
	v_add_f32_e32 v133, v133, v123
	v_add_f32_e32 v133, v133, v122
	v_add_f32_e32 v133, v133, v121
	v_add_f32_e32 v133, v133, v120
	v_add_f32_e32 v133, v133, v117
	v_add_f32_e32 v133, v133, v97
	v_add_f32_e32 v133, v133, v119
	v_div_scale_f32 v95, s[0:1], v133, v133, 1.0
	v_rcp_f32_e32 v107, v95
	s_nop 0
	v_fma_f32 v112, -v95, v107, 1.0
	v_fmac_f32_e32 v107, v112, v107
	v_div_scale_f32 v112, vcc, 1.0, v133, 1.0
	v_mul_f32_e32 v114, v112, v107
	v_fma_f32 v105, -v95, v114, v112
	v_fmac_f32_e32 v114, v105, v107
	v_fma_f32 v95, -v95, v114, v112
	s_nop 1
	v_div_fmas_f32 v95, v95, v107, v114
	v_div_fixup_f32 v95, v95, v133, 1.0
	s_waitcnt lgkmcnt(0)
	v_xor_b32_e32 v105, 0xff, v88
	v_bfe_u32 v114, v105, 4, 4
	v_and_b32_e32 v105, 15, v105
	v_lshl_add_u32 v114, v114, 2, v67
	v_lshl_add_u32 v105, v105, 2, v67
	ds_read_b32 v114, v114
	ds_read_b32 v105, v105 offset:64
	v_xor_b32_e32 v112, 0xff, v72
	v_bfe_u32 v107, v112, 4, 4
	v_and_b32_e32 v112, 15, v112
	v_lshl_add_u32 v107, v107, 2, v67
	v_lshl_add_u32 v112, v112, 2, v67
	ds_read_b32 v107, v107
	ds_read_b32 v112, v112 offset:64
	v_xor_b32_e32 v106, 0xff, v91
	v_bfe_u32 v103, v106, 4, 4
	v_and_b32_e32 v106, 15, v106
	v_lshl_add_u32 v103, v103, 2, v67
	v_lshl_add_u32 v106, v106, 2, v67
	ds_read_b32 v103, v103
	ds_read_b32 v106, v106 offset:64
	v_xor_b32_e32 v104, 0xff, v102
	v_bfe_u32 v115, v104, 4, 4
	v_and_b32_e32 v104, 15, v104
	v_lshl_add_u32 v115, v115, 2, v67
	v_lshl_add_u32 v104, v104, 2, v67
	ds_read_b32 v115, v115
	ds_read_b32 v104, v104 offset:64
	v_xor_b32_e32 v110, 0xff, v96
	v_bfe_u32 v111, v110, 4, 4
	v_and_b32_e32 v110, 15, v110
	v_lshl_add_u32 v111, v111, 2, v67
	v_lshl_add_u32 v110, v110, 2, v67
	ds_read_b32 v111, v111
	ds_read_b32 v110, v110 offset:64
	v_xor_b32_e32 v108, 0xff, v116
	v_bfe_u32 v109, v108, 4, 4
	v_and_b32_e32 v108, 15, v108
	v_lshl_add_u32 v109, v109, 2, v67
	v_lshl_add_u32 v108, v108, 2, v67
	ds_read_b32 v109, v109
	ds_read_b32 v108, v108 offset:64
	v_xor_b32_e32 v100, 0xff, v93
	v_bfe_u32 v92, v100, 4, 4
	v_and_b32_e32 v100, 15, v100
	v_lshl_add_u32 v92, v92, 2, v67
	v_lshl_add_u32 v100, v100, 2, v67
	ds_read_b32 v92, v92
	ds_read_b32 v100, v100 offset:64
	v_xor_b32_e32 v89, 0xff, v118
	v_bfe_u32 v79, v89, 4, 4
	v_and_b32_e32 v89, 15, v89
	v_lshl_add_u32 v79, v79, 2, v67
	v_lshl_add_u32 v89, v89, 2, v67
	ds_read_b32 v79, v79
	ds_read_b32 v89, v89 offset:64
	v_xor_b32_e32 v81, 0xff, v71
	v_bfe_u32 v135, v81, 4, 4
	v_and_b32_e32 v81, 15, v81
	v_lshl_add_u32 v135, v135, 2, v67
	v_lshl_add_u32 v81, v81, 2, v67
	ds_read_b32 v135, v135
	ds_read_b32 v81, v81 offset:64
	v_xor_b32_e32 v78, 0xff, v76
	v_bfe_u32 v82, v78, 4, 4
	v_and_b32_e32 v78, 15, v78
	v_lshl_add_u32 v82, v82, 2, v67
	v_lshl_add_u32 v78, v78, 2, v67
	ds_read_b32 v82, v82
	ds_read_b32 v78, v78 offset:64
	v_xor_b32_e32 v70, 0xff, v87
	v_bfe_u32 v75, v70, 4, 4
	v_and_b32_e32 v70, 15, v70
	v_lshl_add_u32 v75, v75, 2, v67
	v_lshl_add_u32 v70, v70, 2, v67
	ds_read_b32 v75, v75
	ds_read_b32 v70, v70 offset:64
	v_xor_b32_e32 v74, 0xff, v94
	v_bfe_u32 v99, v74, 4, 4
	v_and_b32_e32 v74, 15, v74
	v_lshl_add_u32 v99, v99, 2, v67
	v_lshl_add_u32 v74, v74, 2, v67
	ds_read_b32 v99, v99
	ds_read_b32 v74, v74 offset:64
	v_xor_b32_e32 v101, 0xff, v80
	v_bfe_u32 v77, v101, 4, 4
	v_and_b32_e32 v101, 15, v101
	v_lshl_add_u32 v77, v77, 2, v67
	v_lshl_add_u32 v101, v101, 2, v67
	ds_read_b32 v77, v77
	ds_read_b32 v101, v101 offset:64
	v_xor_b32_e32 v98, 0xff, v86
	v_bfe_u32 v83, v98, 4, 4
	v_and_b32_e32 v98, 15, v98
	v_lshl_add_u32 v83, v83, 2, v67
	v_lshl_add_u32 v98, v98, 2, v67
	ds_read_b32 v83, v83
	ds_read_b32 v98, v98 offset:64
	v_xor_b32_e32 v85, 0xff, v73
	v_bfe_u32 v84, v85, 4, 4
	v_and_b32_e32 v85, 15, v85
	v_lshl_add_u32 v84, v84, 2, v67
	v_lshl_add_u32 v85, v85, 2, v67
	ds_read_b32 v84, v84
	ds_read_b32 v85, v85 offset:64
	v_xor_b32_e32 v136, 0xff, v90
	v_bfe_u32 v137, v136, 4, 4
	v_and_b32_e32 v136, 15, v136
	v_lshl_add_u32 v137, v137, 2, v67
	v_lshl_add_u32 v136, v136, 2, v67
	ds_read_b32 v137, v137
	ds_read_b32 v136, v136 offset:64
	s_waitcnt lgkmcnt(0)
	v_lshl_add_u32 v138, v114, 7, v105
	v_mul_f32_e32 v139, v132, v95
	v_lshl_add_u32 v140, v107, 7, v112
	v_mul_f32_e32 v141, v131, v95
	ds_write_b128 v68, v[138:141] offset:0
	v_lshl_add_u32 v138, v103, 7, v106
	v_mul_f32_e32 v139, v130, v95
	v_lshl_add_u32 v140, v115, 7, v104
	v_mul_f32_e32 v141, v129, v95
	ds_write_b128 v68, v[138:141] offset:16
	v_lshl_add_u32 v138, v111, 7, v110
	v_mul_f32_e32 v139, v128, v95
	v_lshl_add_u32 v140, v109, 7, v108
	v_mul_f32_e32 v141, v127, v95
	ds_write_b128 v68, v[138:141] offset:32
	v_lshl_add_u32 v138, v92, 7, v100
	v_mul_f32_e32 v139, v126, v95
	v_lshl_add_u32 v140, v79, 7, v89
	v_mul_f32_e32 v141, v125, v95
	ds_write_b128 v68, v[138:141] offset:48
	v_lshl_add_u32 v138, v135, 7, v81
	v_mul_f32_e32 v139, v124, v95
	v_lshl_add_u32 v140, v82, 7, v78
	v_mul_f32_e32 v141, v123, v95
	ds_write_b128 v68, v[138:141] offset:64
	v_lshl_add_u32 v138, v75, 7, v70
	v_mul_f32_e32 v139, v122, v95
	v_lshl_add_u32 v140, v99, 7, v74
	v_mul_f32_e32 v141, v121, v95
	ds_write_b128 v68, v[138:141] offset:80
	v_lshl_add_u32 v138, v77, 7, v101
	v_mul_f32_e32 v139, v120, v95
	v_lshl_add_u32 v140, v83, 7, v98
	v_mul_f32_e32 v141, v117, v95
	ds_write_b128 v68, v[138:141] offset:96
	v_lshl_add_u32 v138, v84, 7, v85
	v_mul_f32_e32 v139, v97, v95
	v_lshl_add_u32 v140, v137, 7, v136
	v_mul_f32_e32 v141, v119, v95
	ds_write_b128 v68, v[138:141] offset:112

; __device__ __forceinline__ unsigned pk2(float lo, float hi) { const f32x2 v = {lo, hi}; const bf16x2_t b = __builtin_convertvector(v, bf16x2_t); return __builtin_bit_cast(unsigned, b); }
; __device__ __forceinline__ float bflo(unsigned u) { return __uint_as_float(u << 16); }
; __device__ __forceinline__ float bfhi(unsigned u) { return __uint_as_float(u & 0xffff0000u); }
; __device__ __forceinline__ void peer_tile(const Args& A, LAS unsigned char* lds, int tile) {
;     ...
;     const unsigned char* T8v = T8 + (size_t)16384 * 1024;
;     const bf16_t* A3 = (const bf16_t*)(A.ws + WS_A3); const float* RSq = (const float*)(A.ws + WS_RS);
;     for (int pass = 0; pass < 2; ++pass) {
;         const int tb = 8 * w + 4 * pass;
;         u32x4 xpa[4], xpb[4]; f32x2 oacc[4][8];
; #pragma unroll
;         for (int tk = 0; tk < 4; ++tk) { const size_t m = (size_t)tile * 64 + tb + tk;
;             { const u32x4 ra = *(const u32x4*)(A3 + m * 1024 + 16 * lane), rb = *(const u32x4*)(A3 + m * 1024 + 16 * lane + 8);
;               float xr_; { const f32x4 p0 = *(const f32x4*)(RSq + m * 16), p1 = *(const f32x4*)(RSq + m * 16 + 4), p2 = *(const f32x4*)(RSq + m * 16 + 8), p3 = *(const f32x4*)(RSq + m * 16 + 12);
;                 const f32x4 ps = (p0 + p1) + (p2 + p3); xr_ = rsqrtf(((ps[0] + ps[1]) + (ps[2] + ps[3])) * (1.f / 1024.f) + 1e-6f); }
;               const unsigned rr[8] = {ra.x, ra.y, ra.z, ra.w, rb.x, rb.y, rb.z, rb.w}; unsigned hh[8];
;               const float* sp = MOD + (int)(m >> 11) * 6144 + 3072 + 16 * lane;
; #pragma unroll
;               for (int q = 0; q < 8; ++q) { const f32x2 sh = *(const f32x2*)(sp + 2 * q); hh[q] = pk2(bflo(rr[q]) * xr_ + sh[0], bfhi(rr[q]) * xr_ + sh[1]); }
;               xpa[tk] = (u32x4){hh[0], hh[1], hh[2], hh[3]}; xpb[tk] = (u32x4){hh[4], hh[5], hh[6], hh[7]}; }
	s_mov_b64 exec, -1
	v_and_b32_e32 v240, 63, v214
	v_lshrrev_b32_e32 v242, 6, v214
	v_lshlrev_b32_e32 v240, 4, v240
	v_readfirstlane_b32 s16, v242
	v_lshlrev_b32_e32 v245, 1, v240
	v_lshlrev_b32_e32 v246, 2, v240
	v_lshrrev_b32_e32 v247, 4, v240
	v_and_b32_e32 v247, 48, v247
	v_mov_b32_e32 v244, 0
	v_mov_b32_e32 v243, 0x358637bd
	v_mov_b32_e32 v242, 0xbf3a00e3
	s_add_u32 s4, s50, 0x1000000
	s_addc_u32 s5, s51, 0
	s_add_u32 s6, s50, 0x2000000
	s_addc_u32 s7, s51, 0
	s_add_u32 s8, s50, 0x3000000
	s_addc_u32 s9, s51, 0
	s_add_u32 s52, s50, 0x3010000
	s_addc_u32 s53, s51, 0
	s_add_u32 s12, s50, 0xb000000
	s_addc_u32 s13, s51, 0
	s_add_u32 s14, s50, 0xd000000
	s_addc_u32 s15, s51, 0
	s_lshr_b32 s0, s2, 5
	s_mul_i32 s0, s0, 0x6000
	s_add_u32 s10, s50, s0
	s_addc_u32 s11, s51, 0
	s_add_u32 s80, s10, 0x4000
	s_addc_u32 s81, s11, 0
	s_add_u32 s82, s10, 0x6000
	s_addc_u32 s83, s11, 0
	s_mul_i32 s22, s16, 9920
	s_cmp_eq_u32 s16, 7
	s_cselect_b32 s22, 0x21000, s22
	s_mov_b32 s85, 0xffffffff
	s_mov_b32 s72, 0x3e6d3388
	s_mov_b32 s56, s4
	s_and_b32 s57, s5, 0xffff
	s_or_b32 s57, s57, 0x04000000
	s_mov_b32 s58, 16384
	s_mov_b32 s59, 0x00027000
	s_mov_b32 s60, s6
	s_and_b32 s61, s7, 0xffff
	s_or_b32 s61, s61, 0x04000000
	s_mov_b32 s62, 16384
	s_mov_b32 s63, 0x00027000
	s_lshl_b32 s76, s16, 3
	s_lshl_b32 s0, s2, 6
	s_add_i32 s77, s0, s76
	global_load_dwordx4 v[192:195], v246, s[80:81] offset:0
	global_load_dwordx4 v[196:199], v246, s[80:81] offset:16
	global_load_dwordx4 v[200:203], v246, s[80:81] offset:32
	global_load_dwordx4 v[204:207], v246, s[80:81] offset:48
	s_add_i32 s0, s77, 0
	s_lshl_b32 s1, s0, 11
	s_add_u32 s78, s12, s1
	s_addc_u32 s79, s13, 0
	global_load_dwordx4 v[128:131], v245, s[78:79]
	global_load_dwordx4 v[132:135], v245, s[78:79] offset:16
	global_load_dwordx4 v[136:139], v245, s[78:79] offset:2048
	global_load_dwordx4 v[140:143], v245, s[78:79] offset:2064
	s_lshl_b32 s1, s0, 6
	s_add_u32 s78, s14, s1
	s_addc_u32 s79, s15, 0
	global_load_dwordx4 v[144:147], v244, s[78:79] offset:0
	global_load_dwordx4 v[148:151], v244, s[78:79] offset:16
	global_load_dwordx4 v[152:155], v244, s[78:79] offset:32
	global_load_dwordx4 v[156:159], v244, s[78:79] offset:48
	global_load_dwordx4 v[160:163], v244, s[78:79] offset:64
	global_load_dwordx4 v[164:167], v244, s[78:79] offset:80
	global_load_dwordx4 v[168:171], v244, s[78:79] offset:96
	global_load_dwordx4 v[172:175], v244, s[78:79] offset:112
	s_waitcnt lgkmcnt(0)
	s_barrier
	s_add_i32 s0, s77, 2
	s_lshl_b32 s1, s0, 11
	s_add_u32 s78, s12, s1
	s_addc_u32 s79, s13, 0
	global_load_dwordx4 v[176:179], v245, s[78:79]
	global_load_dwordx4 v[180:183], v245, s[78:79] offset:16
	global_load_dwordx4 v[184:187], v245, s[78:79] offset:2048
	global_load_dwordx4 v[188:191], v245, s[78:79] offset:2064
	s_lshl_b32 s1, s0, 6
	s_add_u32 s78, s14, s1
	s_addc_u32 s79, s15, 0
	global_load_dwordx4 v[216:219], v244, s[78:79] offset:0
	global_load_dwordx4 v[220:223], v244, s[78:79] offset:16
	global_load_dwordx4 v[224:227], v244, s[78:79] offset:32
	global_load_dwordx4 v[228:231], v244, s[78:79] offset:48
	global_load_dwordx4 v[232:235], v244, s[78:79] offset:64
	global_load_dwordx4 v[236:239], v244, s[78:79] offset:80
	global_load_dwordx4 v[248:251], v244, s[78:79] offset:96
	global_load_dwordx4 v[252:255], v244, s[78:79] offset:112
	s_waitcnt vmcnt(12)
	v_pk_add_f32 v[144:145], v[144:145], v[148:149]
	v_pk_add_f32 v[146:147], v[146:147], v[150:151]
	v_pk_add_f32 v[152:153], v[152:153], v[156:157]
	v_pk_add_f32 v[154:155], v[154:155], v[158:159]
	v_pk_add_f32 v[144:145], v[144:145], v[152:153]
	v_pk_add_f32 v[146:147], v[146:147], v[154:155]
	v_add_f32_e32 v144, v144, v145
	v_add_f32_e32 v146, v146, v147
	v_add_f32_e32 v144, v144, v146
	v_fmamk_f32 v144, v144, 0x3a800000, v243
	v_rsq_f32_e32 v144, v144
	v_pk_add_f32 v[160:161], v[160:161], v[164:165]
	v_pk_add_f32 v[162:163], v[162:163], v[166:167]
	v_pk_add_f32 v[168:169], v[168:169], v[172:173]
	v_pk_add_f32 v[170:171], v[170:171], v[174:175]
	v_pk_add_f32 v[160:161], v[160:161], v[168:169]
	v_pk_add_f32 v[162:163], v[162:163], v[170:171]
	v_add_f32_e32 v160, v160, v161
	v_add_f32_e32 v162, v162, v163
	v_add_f32_e32 v160, v160, v162
	v_fmamk_f32 v160, v160, 0x3a800000, v243
	v_rsq_f32_e32 v160, v160
	v_lshlrev_b32_e32 v208, 16, v128
	v_and_b32_e32 v209, 0xffff0000, v128
	v_fma_f32 v208, v208, v144, v192
	v_fma_f32 v209, v209, v144, v193
	v_cvt_pk_bf16_f32 v210, v208, v209
	v_lshlrev_b32_e32 v0, 16, v210
	v_and_b32_e32 v1, 0xffff0000, v210
	v_lshlrev_b32_e32 v208, 16, v129
	v_and_b32_e32 v209, 0xffff0000, v129
	v_fma_f32 v208, v208, v144, v194
	v_fma_f32 v209, v209, v144, v195
	v_cvt_pk_bf16_f32 v210, v208, v209
	v_lshlrev_b32_e32 v2, 16, v210
	v_and_b32_e32 v3, 0xffff0000, v210
	v_lshlrev_b32_e32 v208, 16, v130
	v_and_b32_e32 v209, 0xffff0000, v130
	v_fma_f32 v208, v208, v144, v196
	v_fma_f32 v209, v209, v144, v197
	v_cvt_pk_bf16_f32 v210, v208, v209
	v_lshlrev_b32_e32 v4, 16, v210
	v_and_b32_e32 v5, 0xffff0000, v210
	v_lshlrev_b32_e32 v208, 16, v131
	v_and_b32_e32 v209, 0xffff0000, v131
	v_fma_f32 v208, v208, v144, v198
	v_fma_f32 v209, v209, v144, v199
	v_cvt_pk_bf16_f32 v210, v208, v209
	v_lshlrev_b32_e32 v6, 16, v210
	v_and_b32_e32 v7, 0xffff0000, v210
	v_lshlrev_b32_e32 v208, 16, v132
	v_and_b32_e32 v209, 0xffff0000, v132
	v_fma_f32 v208, v208, v144, v200
	v_fma_f32 v209, v209, v144, v201
	v_cvt_pk_bf16_f32 v210, v208, v209
	v_lshlrev_b32_e32 v8, 16, v210
	v_and_b32_e32 v9, 0xffff0000, v210
	v_lshlrev_b32_e32 v208, 16, v133
	v_and_b32_e32 v209, 0xffff0000, v133
	v_fma_f32 v208, v208, v144, v202
	v_fma_f32 v209, v209, v144, v203
	v_cvt_pk_bf16_f32 v210, v208, v209
; __device__ __forceinline__ unsigned pk2(float lo, float hi) { const f32x2 v = {lo, hi}; const bf16x2_t b = __builtin_convertvector(v, bf16x2_t); return __builtin_bit_cast(unsigned, b); }
; __device__ __forceinline__ float bflo(unsigned u) { return __uint_as_float(u << 16); }
; __device__ __forceinline__ float bfhi(unsigned u) { return __uint_as_float(u & 0xffff0000u); }
; __device__ __forceinline__ void peer_tile(const Args& A, LAS unsigned char* lds, int tile) {
;     ...
;         for (int tk = 0; tk < 4; ++tk) { const size_t m = (size_t)tile * 64 + tb + tk;
;             { const u32x4 ra = *(const u32x4*)(A3 + m * 1024 + 16 * lane), rb = *(const u32x4*)(A3 + m * 1024 + 16 * lane + 8);
;               float xr_; { const f32x4 p0 = *(const f32x4*)(RSq + m * 16), p1 = *(const f32x4*)(RSq + m * 16 + 4), p2 = *(const f32x4*)(RSq + m * 16 + 8), p3 = *(const f32x4*)(RSq + m * 16 + 12);
;                 const f32x4 ps = (p0 + p1) + (p2 + p3); xr_ = rsqrtf(((ps[0] + ps[1]) + (ps[2] + ps[3])) * (1.f / 1024.f) + 1e-6f); }
;               const unsigned rr[8] = {ra.x, ra.y, ra.z, ra.w, rb.x, rb.y, rb.z, rb.w}; unsigned hh[8];
;               const float* sp = MOD + (int)(m >> 11) * 6144 + 3072 + 16 * lane;
; #pragma unroll
;               for (int q = 0; q < 8; ++q) { const f32x2 sh = *(const f32x2*)(sp + 2 * q); hh[q] = pk2(bflo(rr[q]) * xr_ + sh[0], bfhi(rr[q]) * xr_ + sh[1]); }
;               xpa[tk] = (u32x4){hh[0], hh[1], hh[2], hh[3]}; xpb[tk] = (u32x4){hh[4], hh[5], hh[6], hh[7]}; }
	v_lshlrev_b32_e32 v10, 16, v210
	v_and_b32_e32 v11, 0xffff0000, v210
	v_lshlrev_b32_e32 v208, 16, v134
	v_and_b32_e32 v209, 0xffff0000, v134
	v_fma_f32 v208, v208, v144, v204
	v_fma_f32 v209, v209, v144, v205
	v_cvt_pk_bf16_f32 v210, v208, v209
	v_lshlrev_b32_e32 v12, 16, v210
	v_and_b32_e32 v13, 0xffff0000, v210
	v_lshlrev_b32_e32 v208, 16, v135
	v_and_b32_e32 v209, 0xffff0000, v135
	v_fma_f32 v208, v208, v144, v206
	v_fma_f32 v209, v209, v144, v207
	v_cvt_pk_bf16_f32 v210, v208, v209
	v_lshlrev_b32_e32 v14, 16, v210
	v_and_b32_e32 v15, 0xffff0000, v210
	v_lshlrev_b32_e32 v208, 16, v136
	v_and_b32_e32 v209, 0xffff0000, v136
	v_fma_f32 v208, v208, v160, v192
	v_fma_f32 v209, v209, v160, v193
	v_cvt_pk_bf16_f32 v210, v208, v209
	v_lshlrev_b32_e32 v16, 16, v210
	v_and_b32_e32 v17, 0xffff0000, v210
	v_lshlrev_b32_e32 v208, 16, v137
	v_and_b32_e32 v209, 0xffff0000, v137
	v_fma_f32 v208, v208, v160, v194
	v_fma_f32 v209, v209, v160, v195
	v_cvt_pk_bf16_f32 v210, v208, v209
	v_lshlrev_b32_e32 v18, 16, v210
	v_and_b32_e32 v19, 0xffff0000, v210
	v_lshlrev_b32_e32 v208, 16, v138
	v_and_b32_e32 v209, 0xffff0000, v138
	v_fma_f32 v208, v208, v160, v196
	v_fma_f32 v209, v209, v160, v197
	v_cvt_pk_bf16_f32 v210, v208, v209
	v_lshlrev_b32_e32 v20, 16, v210
	v_and_b32_e32 v21, 0xffff0000, v210
	v_lshlrev_b32_e32 v208, 16, v139
	v_and_b32_e32 v209, 0xffff0000, v139
	v_fma_f32 v208, v208, v160, v198
	v_fma_f32 v209, v209, v160, v199
	v_cvt_pk_bf16_f32 v210, v208, v209
	v_lshlrev_b32_e32 v22, 16, v210
	v_and_b32_e32 v23, 0xffff0000, v210
	v_lshlrev_b32_e32 v208, 16, v140
	v_and_b32_e32 v209, 0xffff0000, v140
	v_fma_f32 v208, v208, v160, v200
	v_fma_f32 v209, v209, v160, v201
	v_cvt_pk_bf16_f32 v210, v208, v209
	v_lshlrev_b32_e32 v24, 16, v210
	v_and_b32_e32 v25, 0xffff0000, v210
	v_lshlrev_b32_e32 v208, 16, v141
	v_and_b32_e32 v209, 0xffff0000, v141
	v_fma_f32 v208, v208, v160, v202
	v_fma_f32 v209, v209, v160, v203
	v_cvt_pk_bf16_f32 v210, v208, v209
	v_lshlrev_b32_e32 v26, 16, v210
	v_and_b32_e32 v27, 0xffff0000, v210
	v_lshlrev_b32_e32 v208, 16, v142
	v_and_b32_e32 v209, 0xffff0000, v142
	v_fma_f32 v208, v208, v160, v204
	v_fma_f32 v209, v209, v160, v205
	v_cvt_pk_bf16_f32 v210, v208, v209
	v_lshlrev_b32_e32 v28, 16, v210
	v_and_b32_e32 v29, 0xffff0000, v210
	v_lshlrev_b32_e32 v208, 16, v143
	v_and_b32_e32 v209, 0xffff0000, v143
	v_fma_f32 v208, v208, v160, v206
	v_fma_f32 v209, v209, v160, v207
	v_cvt_pk_bf16_f32 v210, v208, v209
	v_lshlrev_b32_e32 v30, 16, v210
	v_and_b32_e32 v31, 0xffff0000, v210
	s_nop 0
	s_add_i32 s0, s77, 4
	s_lshl_b32 s1, s0, 11
	s_add_u32 s78, s12, s1
	s_addc_u32 s79, s13, 0
	global_load_dwordx4 v[128:131], v245, s[78:79]
	global_load_dwordx4 v[132:135], v245, s[78:79] offset:16
	global_load_dwordx4 v[136:139], v245, s[78:79] offset:2048
	global_load_dwordx4 v[140:143], v245, s[78:79] offset:2064
	s_lshl_b32 s1, s0, 6
	s_add_u32 s78, s14, s1
	s_addc_u32 s79, s15, 0
	global_load_dwordx4 v[144:147], v244, s[78:79] offset:0
	global_load_dwordx4 v[148:151], v244, s[78:79] offset:16
	global_load_dwordx4 v[152:155], v244, s[78:79] offset:32
	global_load_dwordx4 v[156:159], v244, s[78:79] offset:48
	global_load_dwordx4 v[160:163], v244, s[78:79] offset:64
	global_load_dwordx4 v[164:167], v244, s[78:79] offset:80
	global_load_dwordx4 v[168:171], v244, s[78:79] offset:96
	global_load_dwordx4 v[172:175], v244, s[78:79] offset:112
	s_waitcnt vmcnt(12)
	v_pk_add_f32 v[216:217], v[216:217], v[220:221]
	v_pk_add_f32 v[218:219], v[218:219], v[222:223]
	v_pk_add_f32 v[224:225], v[224:225], v[228:229]
	v_pk_add_f32 v[226:227], v[226:227], v[230:231]
	v_pk_add_f32 v[216:217], v[216:217], v[224:225]
	v_pk_add_f32 v[218:219], v[218:219], v[226:227]
	v_add_f32_e32 v216, v216, v217
	v_add_f32_e32 v218, v218, v219
	v_add_f32_e32 v216, v216, v218
	v_fmamk_f32 v216, v216, 0x3a800000, v243
	v_rsq_f32_e32 v216, v216
	v_pk_add_f32 v[232:233], v[232:233], v[236:237]
	v_pk_add_f32 v[234:235], v[234:235], v[238:239]
	v_pk_add_f32 v[248:249], v[248:249], v[252:253]
	v_pk_add_f32 v[250:251], v[250:251], v[254:255]
	v_pk_add_f32 v[232:233], v[232:233], v[248:249]
	v_pk_add_f32 v[234:235], v[234:235], v[250:251]
	v_add_f32_e32 v232, v232, v233
	v_add_f32_e32 v234, v234, v235
	v_add_f32_e32 v232, v232, v234
	v_fmamk_f32 v232, v232, 0x3a800000, v243
	v_rsq_f32_e32 v232, v232
	v_lshlrev_b32_e32 v208, 16, v176
	v_and_b32_e32 v209, 0xffff0000, v176
	v_fma_f32 v208, v208, v216, v192
	v_fma_f32 v209, v209, v216, v193
	v_cvt_pk_bf16_f32 v210, v208, v209
	v_lshlrev_b32_e32 v32, 16, v210
	v_and_b32_e32 v33, 0xffff0000, v210
	v_lshlrev_b32_e32 v208, 16, v177
	v_and_b32_e32 v209, 0xffff0000, v177
	v_fma_f32 v208, v208, v216, v194
	v_fma_f32 v209, v209, v216, v195
	v_cvt_pk_bf16_f32 v210, v208, v209
	v_lshlrev_b32_e32 v34, 16, v210
	v_and_b32_e32 v35, 0xffff0000, v210
	v_lshlrev_b32_e32 v208, 16, v178
	v_and_b32_e32 v209, 0xffff0000, v178
	v_fma_f32 v208, v208, v216, v196
	v_fma_f32 v209, v209, v216, v197
	v_cvt_pk_bf16_f32 v210, v208, v209
	v_lshlrev_b32_e32 v36, 16, v210
	v_and_b32_e32 v37, 0xffff0000, v210
	v_lshlrev_b32_e32 v208, 16, v179
	v_and_b32_e32 v209, 0xffff0000, v179
	v_fma_f32 v208, v208, v216, v198
	v_fma_f32 v209, v209, v216, v199
	v_cvt_pk_bf16_f32 v210, v208, v209
	v_lshlrev_b32_e32 v38, 16, v210
	v_and_b32_e32 v39, 0xffff0000, v210
	v_lshlrev_b32_e32 v208, 16, v180
	v_and_b32_e32 v209, 0xffff0000, v180
	v_fma_f32 v208, v208, v216, v200
	v_fma_f32 v209, v209, v216, v201
	v_cvt_pk_bf16_f32 v210, v208, v209
	v_lshlrev_b32_e32 v40, 16, v210
	v_and_b32_e32 v41, 0xffff0000, v210
	v_lshlrev_b32_e32 v208, 16, v181
	v_and_b32_e32 v209, 0xffff0000, v181
; __device__ __forceinline__ unsigned pk2(float lo, float hi) { const f32x2 v = {lo, hi}; const bf16x2_t b = __builtin_convertvector(v, bf16x2_t); return __builtin_bit_cast(unsigned, b); }
; __device__ __forceinline__ float bflo(unsigned u) { return __uint_as_float(u << 16); }
; __device__ __forceinline__ float bfhi(unsigned u) { return __uint_as_float(u & 0xffff0000u); }
; __device__ __forceinline__ void peer_tile(const Args& A, LAS unsigned char* lds, int tile) {
;     ...
;         for (int tk = 0; tk < 4; ++tk) { const size_t m = (size_t)tile * 64 + tb + tk;
;             { const u32x4 ra = *(const u32x4*)(A3 + m * 1024 + 16 * lane), rb = *(const u32x4*)(A3 + m * 1024 + 16 * lane + 8);
;               float xr_; { const f32x4 p0 = *(const f32x4*)(RSq + m * 16), p1 = *(const f32x4*)(RSq + m * 16 + 4), p2 = *(const f32x4*)(RSq + m * 16 + 8), p3 = *(const f32x4*)(RSq + m * 16 + 12);
;                 const f32x4 ps = (p0 + p1) + (p2 + p3); xr_ = rsqrtf(((ps[0] + ps[1]) + (ps[2] + ps[3])) * (1.f / 1024.f) + 1e-6f); }
;               const unsigned rr[8] = {ra.x, ra.y, ra.z, ra.w, rb.x, rb.y, rb.z, rb.w}; unsigned hh[8];
;               const float* sp = MOD + (int)(m >> 11) * 6144 + 3072 + 16 * lane;
; #pragma unroll
;               for (int q = 0; q < 8; ++q) { const f32x2 sh = *(const f32x2*)(sp + 2 * q); hh[q] = pk2(bflo(rr[q]) * xr_ + sh[0], bfhi(rr[q]) * xr_ + sh[1]); }
;               xpa[tk] = (u32x4){hh[0], hh[1], hh[2], hh[3]}; xpb[tk] = (u32x4){hh[4], hh[5], hh[6], hh[7]}; }
	v_fma_f32 v208, v208, v216, v202
	v_fma_f32 v209, v209, v216, v203
	v_cvt_pk_bf16_f32 v210, v208, v209
	v_lshlrev_b32_e32 v42, 16, v210
	v_and_b32_e32 v43, 0xffff0000, v210
	v_lshlrev_b32_e32 v208, 16, v182
	v_and_b32_e32 v209, 0xffff0000, v182
	v_fma_f32 v208, v208, v216, v204
	v_fma_f32 v209, v209, v216, v205
	v_cvt_pk_bf16_f32 v210, v208, v209
	v_lshlrev_b32_e32 v44, 16, v210
	v_and_b32_e32 v45, 0xffff0000, v210
	v_lshlrev_b32_e32 v208, 16, v183
	v_and_b32_e32 v209, 0xffff0000, v183
	v_fma_f32 v208, v208, v216, v206
	v_fma_f32 v209, v209, v216, v207
	v_cvt_pk_bf16_f32 v210, v208, v209
	v_lshlrev_b32_e32 v46, 16, v210
	v_and_b32_e32 v47, 0xffff0000, v210
	v_lshlrev_b32_e32 v208, 16, v184
	v_and_b32_e32 v209, 0xffff0000, v184
	v_fma_f32 v208, v208, v232, v192
	v_fma_f32 v209, v209, v232, v193
	v_cvt_pk_bf16_f32 v210, v208, v209
	v_lshlrev_b32_e32 v48, 16, v210
	v_and_b32_e32 v49, 0xffff0000, v210
	v_lshlrev_b32_e32 v208, 16, v185
	v_and_b32_e32 v209, 0xffff0000, v185
	v_fma_f32 v208, v208, v232, v194
	v_fma_f32 v209, v209, v232, v195
	v_cvt_pk_bf16_f32 v210, v208, v209
	v_lshlrev_b32_e32 v50, 16, v210
	v_and_b32_e32 v51, 0xffff0000, v210
	v_lshlrev_b32_e32 v208, 16, v186
	v_and_b32_e32 v209, 0xffff0000, v186
	v_fma_f32 v208, v208, v232, v196
	v_fma_f32 v209, v209, v232, v197
	v_cvt_pk_bf16_f32 v210, v208, v209
	v_lshlrev_b32_e32 v52, 16, v210
	v_and_b32_e32 v53, 0xffff0000, v210
	v_lshlrev_b32_e32 v208, 16, v187
	v_and_b32_e32 v209, 0xffff0000, v187
	v_fma_f32 v208, v208, v232, v198
	v_fma_f32 v209, v209, v232, v199
	v_cvt_pk_bf16_f32 v210, v208, v209
	v_lshlrev_b32_e32 v54, 16, v210
	v_and_b32_e32 v55, 0xffff0000, v210
	v_lshlrev_b32_e32 v208, 16, v188
	v_and_b32_e32 v209, 0xffff0000, v188
	v_fma_f32 v208, v208, v232, v200
	v_fma_f32 v209, v209, v232, v201
	v_cvt_pk_bf16_f32 v210, v208, v209
	v_lshlrev_b32_e32 v56, 16, v210
	v_and_b32_e32 v57, 0xffff0000, v210
	v_lshlrev_b32_e32 v208, 16, v189
	v_and_b32_e32 v209, 0xffff0000, v189
	v_fma_f32 v208, v208, v232, v202
	v_fma_f32 v209, v209, v232, v203
	v_cvt_pk_bf16_f32 v210, v208, v209
	v_lshlrev_b32_e32 v58, 16, v210
	v_and_b32_e32 v59, 0xffff0000, v210
	v_lshlrev_b32_e32 v208, 16, v190
	v_and_b32_e32 v209, 0xffff0000, v190
	v_fma_f32 v208, v208, v232, v204
	v_fma_f32 v209, v209, v232, v205
	v_cvt_pk_bf16_f32 v210, v208, v209
	v_lshlrev_b32_e32 v60, 16, v210
	v_and_b32_e32 v61, 0xffff0000, v210
	v_lshlrev_b32_e32 v208, 16, v191
	v_and_b32_e32 v209, 0xffff0000, v191
	v_fma_f32 v208, v208, v232, v206
	v_fma_f32 v209, v209, v232, v207
	v_cvt_pk_bf16_f32 v210, v208, v209
	v_lshlrev_b32_e32 v62, 16, v210
	v_and_b32_e32 v63, 0xffff0000, v210
	s_nop 0
	s_add_i32 s0, s77, 6
	s_lshl_b32 s1, s0, 11
	s_add_u32 s78, s12, s1
	s_addc_u32 s79, s13, 0
	global_load_dwordx4 v[176:179], v245, s[78:79]
	global_load_dwordx4 v[180:183], v245, s[78:79] offset:16
	global_load_dwordx4 v[184:187], v245, s[78:79] offset:2048
	global_load_dwordx4 v[188:191], v245, s[78:79] offset:2064
	s_lshl_b32 s1, s0, 6
	s_add_u32 s78, s14, s1
	s_addc_u32 s79, s15, 0
	global_load_dwordx4 v[216:219], v244, s[78:79] offset:0
	global_load_dwordx4 v[220:223], v244, s[78:79] offset:16
	global_load_dwordx4 v[224:227], v244, s[78:79] offset:32
	global_load_dwordx4 v[228:231], v244, s[78:79] offset:48
	global_load_dwordx4 v[232:235], v244, s[78:79] offset:64
	global_load_dwordx4 v[236:239], v244, s[78:79] offset:80
	global_load_dwordx4 v[248:251], v244, s[78:79] offset:96
	global_load_dwordx4 v[252:255], v244, s[78:79] offset:112
	s_waitcnt vmcnt(12)
	v_pk_add_f32 v[144:145], v[144:145], v[148:149]
	v_pk_add_f32 v[146:147], v[146:147], v[150:151]
	v_pk_add_f32 v[152:153], v[152:153], v[156:157]
	v_pk_add_f32 v[154:155], v[154:155], v[158:159]
	v_pk_add_f32 v[144:145], v[144:145], v[152:153]
	v_pk_add_f32 v[146:147], v[146:147], v[154:155]
	v_add_f32_e32 v144, v144, v145
	v_add_f32_e32 v146, v146, v147
	v_add_f32_e32 v144, v144, v146
	v_fmamk_f32 v144, v144, 0x3a800000, v243
	v_rsq_f32_e32 v144, v144
	v_pk_add_f32 v[160:161], v[160:161], v[164:165]
	v_pk_add_f32 v[162:163], v[162:163], v[166:167]
	v_pk_add_f32 v[168:169], v[168:169], v[172:173]
	v_pk_add_f32 v[170:171], v[170:171], v[174:175]
	v_pk_add_f32 v[160:161], v[160:161], v[168:169]
	v_pk_add_f32 v[162:163], v[162:163], v[170:171]
	v_add_f32_e32 v160, v160, v161
	v_add_f32_e32 v162, v162, v163
	v_add_f32_e32 v160, v160, v162
	v_fmamk_f32 v160, v160, 0x3a800000, v243
	v_rsq_f32_e32 v160, v160
	v_lshlrev_b32_e32 v208, 16, v128
	v_and_b32_e32 v209, 0xffff0000, v128
	v_fma_f32 v208, v208, v144, v192
	v_fma_f32 v209, v209, v144, v193
	v_cvt_pk_bf16_f32 v210, v208, v209
	v_lshlrev_b32_e32 v64, 16, v210
	v_and_b32_e32 v65, 0xffff0000, v210
	v_lshlrev_b32_e32 v208, 16, v129
	v_and_b32_e32 v209, 0xffff0000, v129
	v_fma_f32 v208, v208, v144, v194
	v_fma_f32 v209, v209, v144, v195
	v_cvt_pk_bf16_f32 v210, v208, v209
	v_lshlrev_b32_e32 v66, 16, v210
	v_and_b32_e32 v67, 0xffff0000, v210
	v_lshlrev_b32_e32 v208, 16, v130
	v_and_b32_e32 v209, 0xffff0000, v130
	v_fma_f32 v208, v208, v144, v196
	v_fma_f32 v209, v209, v144, v197
	v_cvt_pk_bf16_f32 v210, v208, v209
	v_lshlrev_b32_e32 v68, 16, v210
	v_and_b32_e32 v69, 0xffff0000, v210
	v_lshlrev_b32_e32 v208, 16, v131
	v_and_b32_e32 v209, 0xffff0000, v131
	v_fma_f32 v208, v208, v144, v198
	v_fma_f32 v209, v209, v144, v199
	v_cvt_pk_bf16_f32 v210, v208, v209
	v_lshlrev_b32_e32 v70, 16, v210
	v_and_b32_e32 v71, 0xffff0000, v210
	v_lshlrev_b32_e32 v208, 16, v132
	v_and_b32_e32 v209, 0xffff0000, v132
	v_fma_f32 v208, v208, v144, v200
	v_fma_f32 v209, v209, v144, v201
	v_cvt_pk_bf16_f32 v210, v208, v209
	v_lshlrev_b32_e32 v72, 16, v210
; __device__ __forceinline__ unsigned pk2(float lo, float hi) { const f32x2 v = {lo, hi}; const bf16x2_t b = __builtin_convertvector(v, bf16x2_t); return __builtin_bit_cast(unsigned, b); }
; __device__ __forceinline__ float bflo(unsigned u) { return __uint_as_float(u << 16); }
; __device__ __forceinline__ float bfhi(unsigned u) { return __uint_as_float(u & 0xffff0000u); }
; __device__ __forceinline__ void peer_tile(const Args& A, LAS unsigned char* lds, int tile) {
;     ...
;         for (int tk = 0; tk < 4; ++tk) { const size_t m = (size_t)tile * 64 + tb + tk;
;             { const u32x4 ra = *(const u32x4*)(A3 + m * 1024 + 16 * lane), rb = *(const u32x4*)(A3 + m * 1024 + 16 * lane + 8);
;               float xr_; { const f32x4 p0 = *(const f32x4*)(RSq + m * 16), p1 = *(const f32x4*)(RSq + m * 16 + 4), p2 = *(const f32x4*)(RSq + m * 16 + 8), p3 = *(const f32x4*)(RSq + m * 16 + 12);
;                 const f32x4 ps = (p0 + p1) + (p2 + p3); xr_ = rsqrtf(((ps[0] + ps[1]) + (ps[2] + ps[3])) * (1.f / 1024.f) + 1e-6f); }
;               const unsigned rr[8] = {ra.x, ra.y, ra.z, ra.w, rb.x, rb.y, rb.z, rb.w}; unsigned hh[8];
;               const float* sp = MOD + (int)(m >> 11) * 6144 + 3072 + 16 * lane;
; #pragma unroll
;               for (int q = 0; q < 8; ++q) { const f32x2 sh = *(const f32x2*)(sp + 2 * q); hh[q] = pk2(bflo(rr[q]) * xr_ + sh[0], bfhi(rr[q]) * xr_ + sh[1]); }
;               xpa[tk] = (u32x4){hh[0], hh[1], hh[2], hh[3]}; xpb[tk] = (u32x4){hh[4], hh[5], hh[6], hh[7]}; }
	v_and_b32_e32 v73, 0xffff0000, v210
	v_lshlrev_b32_e32 v208, 16, v133
	v_and_b32_e32 v209, 0xffff0000, v133
	v_fma_f32 v208, v208, v144, v202
	v_fma_f32 v209, v209, v144, v203
	v_cvt_pk_bf16_f32 v210, v208, v209
	v_lshlrev_b32_e32 v74, 16, v210
	v_and_b32_e32 v75, 0xffff0000, v210
	v_lshlrev_b32_e32 v208, 16, v134
	v_and_b32_e32 v209, 0xffff0000, v134
	v_fma_f32 v208, v208, v144, v204
	v_fma_f32 v209, v209, v144, v205
	v_cvt_pk_bf16_f32 v210, v208, v209
	v_lshlrev_b32_e32 v76, 16, v210
	v_and_b32_e32 v77, 0xffff0000, v210
	v_lshlrev_b32_e32 v208, 16, v135
	v_and_b32_e32 v209, 0xffff0000, v135
	v_fma_f32 v208, v208, v144, v206
	v_fma_f32 v209, v209, v144, v207
	v_cvt_pk_bf16_f32 v210, v208, v209
	v_lshlrev_b32_e32 v78, 16, v210
	v_and_b32_e32 v79, 0xffff0000, v210
	v_lshlrev_b32_e32 v208, 16, v136
	v_and_b32_e32 v209, 0xffff0000, v136
	v_fma_f32 v208, v208, v160, v192
	v_fma_f32 v209, v209, v160, v193
	v_cvt_pk_bf16_f32 v210, v208, v209
	v_lshlrev_b32_e32 v80, 16, v210
	v_and_b32_e32 v81, 0xffff0000, v210
	v_lshlrev_b32_e32 v208, 16, v137
	v_and_b32_e32 v209, 0xffff0000, v137
	v_fma_f32 v208, v208, v160, v194
	v_fma_f32 v209, v209, v160, v195
	v_cvt_pk_bf16_f32 v210, v208, v209
	v_lshlrev_b32_e32 v82, 16, v210
	v_and_b32_e32 v83, 0xffff0000, v210
	v_lshlrev_b32_e32 v208, 16, v138
	v_and_b32_e32 v209, 0xffff0000, v138
	v_fma_f32 v208, v208, v160, v196
	v_fma_f32 v209, v209, v160, v197
	v_cvt_pk_bf16_f32 v210, v208, v209
	v_lshlrev_b32_e32 v84, 16, v210
	v_and_b32_e32 v85, 0xffff0000, v210
	v_lshlrev_b32_e32 v208, 16, v139
	v_and_b32_e32 v209, 0xffff0000, v139
	v_fma_f32 v208, v208, v160, v198
	v_fma_f32 v209, v209, v160, v199
	v_cvt_pk_bf16_f32 v210, v208, v209
	v_lshlrev_b32_e32 v86, 16, v210
	v_and_b32_e32 v87, 0xffff0000, v210
	v_lshlrev_b32_e32 v208, 16, v140
	v_and_b32_e32 v209, 0xffff0000, v140
	v_fma_f32 v208, v208, v160, v200
	v_fma_f32 v209, v209, v160, v201
	v_cvt_pk_bf16_f32 v210, v208, v209
	v_lshlrev_b32_e32 v88, 16, v210
	v_and_b32_e32 v89, 0xffff0000, v210
	v_lshlrev_b32_e32 v208, 16, v141
	v_and_b32_e32 v209, 0xffff0000, v141
	v_fma_f32 v208, v208, v160, v202
	v_fma_f32 v209, v209, v160, v203
	v_cvt_pk_bf16_f32 v210, v208, v209
	v_lshlrev_b32_e32 v90, 16, v210
	v_and_b32_e32 v91, 0xffff0000, v210
	v_lshlrev_b32_e32 v208, 16, v142
	v_and_b32_e32 v209, 0xffff0000, v142
	v_fma_f32 v208, v208, v160, v204
	v_fma_f32 v209, v209, v160, v205
	v_cvt_pk_bf16_f32 v210, v208, v209
	v_lshlrev_b32_e32 v92, 16, v210
	v_and_b32_e32 v93, 0xffff0000, v210
	v_lshlrev_b32_e32 v208, 16, v143
	v_and_b32_e32 v209, 0xffff0000, v143
	v_fma_f32 v208, v208, v160, v206
	v_fma_f32 v209, v209, v160, v207
	v_cvt_pk_bf16_f32 v210, v208, v209
	v_lshlrev_b32_e32 v94, 16, v210
	v_and_b32_e32 v95, 0xffff0000, v210
	s_nop 0
	s_waitcnt vmcnt(0)
	v_pk_add_f32 v[216:217], v[216:217], v[220:221]
	v_pk_add_f32 v[218:219], v[218:219], v[222:223]
	v_pk_add_f32 v[224:225], v[224:225], v[228:229]
	v_pk_add_f32 v[226:227], v[226:227], v[230:231]
	v_pk_add_f32 v[216:217], v[216:217], v[224:225]
	v_pk_add_f32 v[218:219], v[218:219], v[226:227]
	v_add_f32_e32 v216, v216, v217
	v_add_f32_e32 v218, v218, v219
	v_add_f32_e32 v216, v216, v218
	v_fmamk_f32 v216, v216, 0x3a800000, v243
	v_rsq_f32_e32 v216, v216
	v_pk_add_f32 v[232:233], v[232:233], v[236:237]
	v_pk_add_f32 v[234:235], v[234:235], v[238:239]
	v_pk_add_f32 v[248:249], v[248:249], v[252:253]
	v_pk_add_f32 v[250:251], v[250:251], v[254:255]
	v_pk_add_f32 v[232:233], v[232:233], v[248:249]
	v_pk_add_f32 v[234:235], v[234:235], v[250:251]
	v_add_f32_e32 v232, v232, v233
	v_add_f32_e32 v234, v234, v235
	v_add_f32_e32 v232, v232, v234
	v_fmamk_f32 v232, v232, 0x3a800000, v243
	v_rsq_f32_e32 v232, v232
	v_lshlrev_b32_e32 v208, 16, v176
	v_and_b32_e32 v209, 0xffff0000, v176
	v_fma_f32 v208, v208, v216, v192
	v_fma_f32 v209, v209, v216, v193
	v_cvt_pk_bf16_f32 v210, v208, v209
	v_lshlrev_b32_e32 v96, 16, v210
	v_and_b32_e32 v97, 0xffff0000, v210
	v_lshlrev_b32_e32 v208, 16, v177
	v_and_b32_e32 v209, 0xffff0000, v177
	v_fma_f32 v208, v208, v216, v194
	v_fma_f32 v209, v209, v216, v195
	v_cvt_pk_bf16_f32 v210, v208, v209
	v_lshlrev_b32_e32 v98, 16, v210
	v_and_b32_e32 v99, 0xffff0000, v210
	v_lshlrev_b32_e32 v208, 16, v178
	v_and_b32_e32 v209, 0xffff0000, v178
	v_fma_f32 v208, v208, v216, v196
	v_fma_f32 v209, v209, v216, v197
	v_cvt_pk_bf16_f32 v210, v208, v209
	v_lshlrev_b32_e32 v100, 16, v210
	v_and_b32_e32 v101, 0xffff0000, v210
	v_lshlrev_b32_e32 v208, 16, v179
	v_and_b32_e32 v209, 0xffff0000, v179
	v_fma_f32 v208, v208, v216, v198
	v_fma_f32 v209, v209, v216, v199
	v_cvt_pk_bf16_f32 v210, v208, v209
	v_lshlrev_b32_e32 v102, 16, v210
	v_and_b32_e32 v103, 0xffff0000, v210
	v_lshlrev_b32_e32 v208, 16, v180
	v_and_b32_e32 v209, 0xffff0000, v180
	v_fma_f32 v208, v208, v216, v200
	v_fma_f32 v209, v209, v216, v201
	v_cvt_pk_bf16_f32 v210, v208, v209
	v_lshlrev_b32_e32 v104, 16, v210
	v_and_b32_e32 v105, 0xffff0000, v210
	v_lshlrev_b32_e32 v208, 16, v181
	v_and_b32_e32 v209, 0xffff0000, v181
	v_fma_f32 v208, v208, v216, v202
	v_fma_f32 v209, v209, v216, v203
	v_cvt_pk_bf16_f32 v210, v208, v209
	v_lshlrev_b32_e32 v106, 16, v210
	v_and_b32_e32 v107, 0xffff0000, v210
	v_lshlrev_b32_e32 v208, 16, v182
	v_and_b32_e32 v209, 0xffff0000, v182
	v_fma_f32 v208, v208, v216, v204
	v_fma_f32 v209, v209, v216, v205
	v_cvt_pk_bf16_f32 v210, v208, v209
	v_lshlrev_b32_e32 v108, 16, v210
	v_and_b32_e32 v109, 0xffff0000, v210
	v_lshlrev_b32_e32 v208, 16, v183
	v_and_b32_e32 v209, 0xffff0000, v183
	v_fma_f32 v208, v208, v216, v206
	v_fma_f32 v209, v209, v216, v207
	v_cvt_pk_bf16_f32 v210, v208, v209
	v_lshlrev_b32_e32 v110, 16, v210
; __device__ __forceinline__ unsigned pk2(float lo, float hi) { const f32x2 v = {lo, hi}; const bf16x2_t b = __builtin_convertvector(v, bf16x2_t); return __builtin_bit_cast(unsigned, b); }
; __device__ __forceinline__ float bflo(unsigned u) { return __uint_as_float(u << 16); }
; __device__ __forceinline__ void peer_tile(const Args& A, LAS unsigned char* lds, int tile) {
;     ...
;     for (int ti = 0; ti < 8; ++ti) {
;         const int tl = 8 * w + ti;
;         const u32x2 e0 = SEL[tl * 128 + lane], e1 = SEL[tl * 128 + 64 + lane];
;         const int p0 = (int)(e0.x >> 10), p1 = (int)(e1.x >> 10);
;         int off = 0;
;         for (int p = 0; p < 16; ++p) {
;             const unsigned long long m0 = __ballot(p0 == p), m1 = __ballot(p1 == p);
;             const int c0 = __popcll(m0), c1 = __popcll(m1);
;             const int r0 = __builtin_amdgcn_mbcnt_hi((unsigned)(m0 >> 32), __builtin_amdgcn_mbcnt_lo((unsigned)m0, 0u));
;             const int r1 = __builtin_amdgcn_mbcnt_hi((unsigned)(m1 >> 32), __builtin_amdgcn_mbcnt_lo((unsigned)m1, 0u));
;             if (p0 == p) SORT[tl * 128 + off + r0] = e0;
;             if (p1 == p) SORT[tl * 128 + off + c0 + r1] = e1;
;             if (lane == 0) OFFS[tl * 17 + p] = off;
;             off += c0 + c1;
;         }
;         if (lane == 0) OFFS[tl * 17 + 16] = off;
;     }
;     ...
;         for (int tk = 0; tk < 4; ++tk) { const size_t m = (size_t)tile * 64 + tb + tk;
;             { const u32x4 ra = *(const u32x4*)(A3 + m * 1024 + 16 * lane), rb = *(const u32x4*)(A3 + m * 1024 + 16 * lane + 8);
;               float xr_; { const f32x4 p0 = *(const f32x4*)(RSq + m * 16), p1 = *(const f32x4*)(RSq + m * 16 + 4), p2 = *(const f32x4*)(RSq + m * 16 + 8), p3 = *(const f32x4*)(RSq + m * 16 + 12);
;                 const f32x4 ps = (p0 + p1) + (p2 + p3); xr_ = rsqrtf(((ps[0] + ps[1]) + (ps[2] + ps[3])) * (1.f / 1024.f) + 1e-6f); }
;               const unsigned rr[8] = {ra.x, ra.y, ra.z, ra.w, rb.x, rb.y, rb.z, rb.w}; unsigned hh[8];
;               const float* sp = MOD + (int)(m >> 11) * 6144 + 3072 + 16 * lane;
; #pragma unroll
;               for (int q = 0; q < 8; ++q) { const f32x2 sh = *(const f32x2*)(sp + 2 * q); hh[q] = pk2(bflo(rr[q]) * xr_ + sh[0], bfhi(rr[q]) * xr_ + sh[1]); }
;               xpa[tk] = (u32x4){hh[0], hh[1], hh[2], hh[3]}; xpb[tk] = (u32x4){hh[4], hh[5], hh[6], hh[7]}; }
	v_and_b32_e32 v111, 0xffff0000, v210
	v_lshlrev_b32_e32 v208, 16, v184
	v_and_b32_e32 v209, 0xffff0000, v184
	v_fma_f32 v208, v208, v232, v192
	v_fma_f32 v209, v209, v232, v193
	v_cvt_pk_bf16_f32 v210, v208, v209
	v_lshlrev_b32_e32 v112, 16, v210
	v_and_b32_e32 v113, 0xffff0000, v210
	v_lshlrev_b32_e32 v208, 16, v185
	v_and_b32_e32 v209, 0xffff0000, v185
	v_fma_f32 v208, v208, v232, v194
	v_fma_f32 v209, v209, v232, v195
	v_cvt_pk_bf16_f32 v210, v208, v209
	v_lshlrev_b32_e32 v114, 16, v210
	v_and_b32_e32 v115, 0xffff0000, v210
	v_lshlrev_b32_e32 v208, 16, v186
	v_and_b32_e32 v209, 0xffff0000, v186
	v_fma_f32 v208, v208, v232, v196
	v_fma_f32 v209, v209, v232, v197
	v_cvt_pk_bf16_f32 v210, v208, v209
	v_lshlrev_b32_e32 v116, 16, v210
	v_and_b32_e32 v117, 0xffff0000, v210
	v_lshlrev_b32_e32 v208, 16, v187
	v_and_b32_e32 v209, 0xffff0000, v187
	v_fma_f32 v208, v208, v232, v198
	v_fma_f32 v209, v209, v232, v199
	v_cvt_pk_bf16_f32 v210, v208, v209
	v_lshlrev_b32_e32 v118, 16, v210
	v_and_b32_e32 v119, 0xffff0000, v210
	v_lshlrev_b32_e32 v208, 16, v188
	v_and_b32_e32 v209, 0xffff0000, v188
	v_fma_f32 v208, v208, v232, v200
	v_fma_f32 v209, v209, v232, v201
	v_cvt_pk_bf16_f32 v210, v208, v209
	v_lshlrev_b32_e32 v120, 16, v210
	v_and_b32_e32 v121, 0xffff0000, v210
	v_lshlrev_b32_e32 v208, 16, v189
	v_and_b32_e32 v209, 0xffff0000, v189
	v_fma_f32 v208, v208, v232, v202
	v_fma_f32 v209, v209, v232, v203
	v_cvt_pk_bf16_f32 v210, v208, v209
	v_lshlrev_b32_e32 v122, 16, v210
	v_and_b32_e32 v123, 0xffff0000, v210
	v_lshlrev_b32_e32 v208, 16, v190
	v_and_b32_e32 v209, 0xffff0000, v190
	v_fma_f32 v208, v208, v232, v204
	v_fma_f32 v209, v209, v232, v205
	v_cvt_pk_bf16_f32 v210, v208, v209
	v_lshlrev_b32_e32 v124, 16, v210
	v_and_b32_e32 v125, 0xffff0000, v210
	v_lshlrev_b32_e32 v208, 16, v191
	v_and_b32_e32 v209, 0xffff0000, v191
	v_fma_f32 v208, v208, v232, v206
	v_fma_f32 v209, v209, v232, v207
	v_cvt_pk_bf16_f32 v210, v208, v209
	v_lshlrev_b32_e32 v126, 16, v210
	v_and_b32_e32 v127, 0xffff0000, v210
	s_nop 0
	s_mov_b32 s24, s8
	s_and_b32 s25, s9, 0xffff
	s_mov_b32 s26, 0x20000
	s_mov_b32 s27, 0x00027000
	s_lshl_b32 s0, s76, 10
	s_add_i32 s0, s0, 0x11000
	s_sub_i32 s85, s0, s22
	v_mov_b32_e32 v224, 0x7fffffff
	v_mov_b32_e32 v225, 0x7fffffff
	v_mov_b32_e32 v226, 0x7fffffff
	v_mov_b32_e32 v227, 0x7fffffff
	v_mov_b32_e32 v228, 0
	v_mov_b32_e32 v229, 0
	v_mov_b32_e32 v230, 0
	v_mov_b32_e32 v231, 0
	v_add_u32_e32 v232, s22, v240
	ds_write_b128 v232, v[224:227] offset:0
	ds_write_b128 v232, v[228:231] offset:4992
	ds_write_b128 v232, v[224:227] offset:1024
	ds_write_b128 v232, v[228:231] offset:6016
	ds_write_b128 v232, v[224:227] offset:2048
	ds_write_b128 v232, v[228:231] offset:7040
	ds_write_b128 v232, v[224:227] offset:3072
	ds_write_b128 v232, v[228:231] offset:8064
	s_mov_b32 exec_hi, 0x00ffffff
	ds_write_b128 v232, v[224:227] offset:4096
	s_mov_b32 exec_hi, 0x000fffff
	ds_write_b128 v232, v[228:231] offset:9088
	s_mov_b64 exec, -1
	v_lshrrev_b32_e32 v221, 2, v240
	v_add_u32_e32 v221, s22, v221
	ds_write_b32 v221, v228 offset:4224
	v_lshrrev_b32_e32 v233, 1, v240
	s_lshl_b32 s0, s76, 10
	s_add_i32 s0, s0, 0x11000
	v_add_u32_e32 v233, s0, v233
	ds_read_b64 v[128:129], v233 offset:0
	ds_read_b64 v[130:131], v233 offset:512
	ds_read_b64 v[132:133], v233 offset:1024
	ds_read_b64 v[134:135], v233 offset:1536
	ds_read_b64 v[136:137], v233 offset:2048
	ds_read_b64 v[138:139], v233 offset:2560
	ds_read_b64 v[140:141], v233 offset:3072
	ds_read_b64 v[142:143], v233 offset:3584
	ds_read_b64 v[144:145], v233 offset:4096
	ds_read_b64 v[146:147], v233 offset:4608
	ds_read_b64 v[148:149], v233 offset:5120
	ds_read_b64 v[150:151], v233 offset:5632
	ds_read_b64 v[152:153], v233 offset:6144
	ds_read_b64 v[154:155], v233 offset:6656
	ds_read_b64 v[156:157], v233 offset:7168
	ds_read_b64 v[158:159], v233 offset:7680
	v_mov_b32_e32 v220, 1
	v_lshrrev_b32_e32 v200, 4, v240
	v_lshrrev_b32_e32 v201, 3, v200
	v_and_b32_e32 v200, 7, v200
	s_add_i32 s3, s22, 4224
	s_and_b32 s1, s32, 7
	s_waitcnt lgkmcnt(0)
	v_lshrrev_b32_e32 v160, 11, v128
	v_subrev_u32_e32 v160, s1, v160
	v_and_b32_e32 v160, 7, v160
	v_lshl_add_u32 v176, v160, 2, s3
	v_lshrrev_b32_e32 v161, 11, v130
	v_subrev_u32_e32 v161, s1, v161
	v_and_b32_e32 v161, 7, v161
	v_lshl_add_u32 v177, v161, 2, s3
	v_lshrrev_b32_e32 v162, 11, v132
	v_subrev_u32_e32 v162, s1, v162
	v_and_b32_e32 v162, 7, v162
	v_lshl_add_u32 v178, v162, 2, s3
	v_lshrrev_b32_e32 v163, 11, v134
	v_subrev_u32_e32 v163, s1, v163
	v_and_b32_e32 v163, 7, v163
	v_lshl_add_u32 v179, v163, 2, s3
	v_lshrrev_b32_e32 v164, 11, v136
	v_subrev_u32_e32 v164, s1, v164
	v_and_b32_e32 v164, 7, v164
	v_lshl_add_u32 v180, v164, 2, s3
	v_lshrrev_b32_e32 v165, 11, v138
	v_subrev_u32_e32 v165, s1, v165
	v_and_b32_e32 v165, 7, v165
	v_lshl_add_u32 v181, v165, 2, s3
	v_lshrrev_b32_e32 v166, 11, v140
	v_subrev_u32_e32 v166, s1, v166
	v_and_b32_e32 v166, 7, v166
	v_lshl_add_u32 v182, v166, 2, s3
	v_lshrrev_b32_e32 v167, 11, v142
	v_subrev_u32_e32 v167, s1, v167
	v_and_b32_e32 v167, 7, v167
	v_lshl_add_u32 v183, v167, 2, s3
	v_lshrrev_b32_e32 v168, 11, v144
	v_subrev_u32_e32 v168, s1, v168
	v_and_b32_e32 v168, 7, v168
	v_lshl_add_u32 v184, v168, 2, s3
	v_lshrrev_b32_e32 v169, 11, v146
	v_subrev_u32_e32 v169, s1, v169
	v_and_b32_e32 v169, 7, v169
	v_lshl_add_u32 v185, v169, 2, s3
	v_lshrrev_b32_e32 v170, 11, v148
	v_subrev_u32_e32 v170, s1, v170
	v_and_b32_e32 v170, 7, v170
	v_lshl_add_u32 v186, v170, 2, s3
	v_lshrrev_b32_e32 v171, 11, v150
	v_subrev_u32_e32 v171, s1, v171
	v_and_b32_e32 v171, 7, v171
	v_lshl_add_u32 v187, v171, 2, s3
	v_lshrrev_b32_e32 v172, 11, v152
; __device__ __forceinline__ void peer_tile(const Args& A, LAS unsigned char* lds, int tile) {
;     ...
;     for (int ti = 0; ti < 8; ++ti) {
;         const int tl = 8 * w + ti;
;         const u32x2 e0 = SEL[tl * 128 + lane], e1 = SEL[tl * 128 + 64 + lane];
;         const int p0 = (int)(e0.x >> 10), p1 = (int)(e1.x >> 10);
;         int off = 0;
;         for (int p = 0; p < 16; ++p) {
;             const unsigned long long m0 = __ballot(p0 == p), m1 = __ballot(p1 == p);
;             const int c0 = __popcll(m0), c1 = __popcll(m1);
;             const int r0 = __builtin_amdgcn_mbcnt_hi((unsigned)(m0 >> 32), __builtin_amdgcn_mbcnt_lo((unsigned)m0, 0u));
;             const int r1 = __builtin_amdgcn_mbcnt_hi((unsigned)(m1 >> 32), __builtin_amdgcn_mbcnt_lo((unsigned)m1, 0u));
;             if (p0 == p) SORT[tl * 128 + off + r0] = e0;
;             if (p1 == p) SORT[tl * 128 + off + c0 + r1] = e1;
;             if (lane == 0) OFFS[tl * 17 + p] = off;
;             off += c0 + c1;
;         }
;         if (lane == 0) OFFS[tl * 17 + 16] = off;
;     }
	v_subrev_u32_e32 v172, s1, v172
	v_and_b32_e32 v172, 7, v172
	v_lshl_add_u32 v188, v172, 2, s3
	v_lshrrev_b32_e32 v173, 11, v154
	v_subrev_u32_e32 v173, s1, v173
	v_and_b32_e32 v173, 7, v173
	v_lshl_add_u32 v189, v173, 2, s3
	v_lshrrev_b32_e32 v174, 11, v156
	v_subrev_u32_e32 v174, s1, v174
	v_and_b32_e32 v174, 7, v174
	v_lshl_add_u32 v190, v174, 2, s3
	v_lshrrev_b32_e32 v175, 11, v158
	v_subrev_u32_e32 v175, s1, v175
	v_and_b32_e32 v175, 7, v175
	v_lshl_add_u32 v191, v175, 2, s3
	v_lshlrev_b32_e32 v206, 3, v128
	buffer_load_dwordx2 v[224:225], v206, s[24:27], 0 offen
	v_lshlrev_b32_e32 v206, 3, v130
	buffer_load_dwordx2 v[226:227], v206, s[24:27], 0 offen
	v_lshlrev_b32_e32 v206, 3, v132
	buffer_load_dwordx2 v[228:229], v206, s[24:27], 0 offen
	v_lshlrev_b32_e32 v206, 3, v134
	buffer_load_dwordx2 v[230:231], v206, s[24:27], 0 offen
	v_lshlrev_b32_e32 v206, 3, v136
	buffer_load_dwordx2 v[232:233], v206, s[24:27], 0 offen
	v_lshlrev_b32_e32 v206, 3, v138
	buffer_load_dwordx2 v[234:235], v206, s[24:27], 0 offen
	v_lshlrev_b32_e32 v206, 3, v140
	buffer_load_dwordx2 v[236:237], v206, s[24:27], 0 offen
	v_lshlrev_b32_e32 v206, 3, v142
	buffer_load_dwordx2 v[238:239], v206, s[24:27], 0 offen
	v_lshlrev_b32_e32 v206, 3, v144
	buffer_load_dwordx2 v[248:249], v206, s[24:27], 0 offen
	v_lshlrev_b32_e32 v206, 3, v146
	buffer_load_dwordx2 v[250:251], v206, s[24:27], 0 offen
	v_lshlrev_b32_e32 v206, 3, v148
	buffer_load_dwordx2 v[252:253], v206, s[24:27], 0 offen
	v_lshlrev_b32_e32 v206, 3, v150
	buffer_load_dwordx2 v[254:255], v206, s[24:27], 0 offen
	ds_add_rtn_u32 v176, v176, v220 offset:0
	ds_add_rtn_u32 v177, v177, v220 offset:0
	ds_add_rtn_u32 v178, v178, v220 offset:32
	ds_add_rtn_u32 v179, v179, v220 offset:32
	ds_add_rtn_u32 v180, v180, v220 offset:64
	ds_add_rtn_u32 v181, v181, v220 offset:64
	ds_add_rtn_u32 v182, v182, v220 offset:96
	ds_add_rtn_u32 v183, v183, v220 offset:96
	ds_add_rtn_u32 v184, v184, v220 offset:128
	ds_add_rtn_u32 v185, v185, v220 offset:128
	ds_add_rtn_u32 v186, v186, v220 offset:160
	ds_add_rtn_u32 v187, v187, v220 offset:160
	ds_add_rtn_u32 v188, v188, v220 offset:192
	ds_add_rtn_u32 v189, v189, v220 offset:192
	ds_add_rtn_u32 v190, v190, v220 offset:224
	ds_add_rtn_u32 v191, v191, v220 offset:224
	v_lshl_add_u32 v207, v201, 5, s3
	ds_read_b32 v203, v221 offset:4224
	ds_read_b128 v[192:195], v207
	ds_read_b128 v[196:199], v207 offset:16
	v_mov_b32_e32 v202, 0
	s_waitcnt lgkmcnt(0)
	v_cmp_lt_u32_e64 s[38:39], 0, v200
	v_cmp_lt_u32_e64 s[40:41], 1, v200
	v_cmp_lt_u32_e64 s[42:43], 2, v200
	v_cmp_lt_u32_e64 s[44:45], 3, v200
	v_cmp_lt_u32_e64 s[64:65], 4, v200
	v_cmp_lt_u32_e64 s[66:67], 5, v200
	v_cmp_lt_u32_e64 s[94:95], 6, v200
	v_cndmask_b32_e64 v206, 0, v192, s[38:39]
	v_add_u32_e32 v202, v202, v206
	v_cndmask_b32_e64 v206, 0, v193, s[40:41]
	v_add_u32_e32 v202, v202, v206
	v_cndmask_b32_e64 v206, 0, v194, s[42:43]
	v_add_u32_e32 v202, v202, v206
	v_cndmask_b32_e64 v206, 0, v195, s[44:45]
	v_add_u32_e32 v202, v202, v206
	v_cndmask_b32_e64 v206, 0, v196, s[64:65]
	v_add_u32_e32 v202, v202, v206
	v_cndmask_b32_e64 v206, 0, v197, s[66:67]
	v_add_u32_e32 v202, v202, v206
	v_cndmask_b32_e64 v206, 0, v198, s[94:95]
	v_add_u32_e32 v202, v202, v206
	v_add_u32_e32 v204, 3, v202
	v_add3_u32 v212, v202, v203, 3
	v_lshrrev_b32_e32 v204, 2, v204
	v_lshrrev_b32_e32 v212, 2, v212
	v_sub_u32_e32 v212, v212, v204
	v_lshl_add_u32 v207, v200, 3, v201
	v_lshl_add_u32 v207, v207, 2, s3
	ds_write_b32 v207, v212 offset:256
	v_lshl_add_u32 v208, v200, 5, s3
	ds_read_b128 v[192:195], v208 offset:256
	ds_read_b128 v[196:199], v208 offset:272
	v_mov_b32_e32 v205, 0
	s_waitcnt lgkmcnt(0)
	v_cmp_lt_u32_e64 s[38:39], 0, v201
	v_cmp_lt_u32_e64 s[40:41], 1, v201
	v_cmp_lt_u32_e64 s[42:43], 2, v201
	v_cmp_lt_u32_e64 s[44:45], 3, v201
	v_cmp_lt_u32_e64 s[64:65], 4, v201
	v_cmp_lt_u32_e64 s[66:67], 5, v201
	v_cmp_lt_u32_e64 s[94:95], 6, v201
	v_cndmask_b32_e64 v206, 0, v192, s[38:39]
	v_add_u32_e32 v205, v205, v206
	v_cndmask_b32_e64 v206, 0, v193, s[40:41]
	v_add_u32_e32 v205, v205, v206
	v_cndmask_b32_e64 v206, 0, v194, s[42:43]
	v_add_u32_e32 v205, v205, v206
	v_cndmask_b32_e64 v206, 0, v195, s[44:45]
	v_add_u32_e32 v205, v205, v206
	v_cndmask_b32_e64 v206, 0, v196, s[64:65]
	v_add_u32_e32 v205, v205, v206
	v_cndmask_b32_e64 v206, 0, v197, s[66:67]
	v_add_u32_e32 v205, v205, v206
	v_cndmask_b32_e64 v206, 0, v198, s[94:95]
	v_add_u32_e32 v205, v205, v206
	v_add_u32_e32 v206, v192, v193
	v_add_u32_e32 v206, v206, v194
	v_add_u32_e32 v206, v206, v195
	v_add_u32_e32 v206, v206, v196
	v_add_u32_e32 v206, v206, v197
	v_add_u32_e32 v206, v206, v198
	v_add_u32_e32 v206, v206, v199
	v_lshl_add_u32 v207, v200, 2, s3
	ds_write_b32 v207, v206 offset:512
	v_mov_b32_e32 v207, s3
	ds_read_b128 v[192:195], v207 offset:512
	ds_read_b128 v[196:199], v207 offset:528
	ds_write_b32 v221, v202 offset:4224
	s_waitcnt lgkmcnt(0)
	v_cmp_lt_u32_e64 s[38:39], 0, v200
	v_cmp_lt_u32_e64 s[40:41], 1, v200
	v_cmp_lt_u32_e64 s[42:43], 2, v200
	v_cmp_lt_u32_e64 s[44:45], 3, v200
	v_cmp_lt_u32_e64 s[64:65], 4, v200
	v_cmp_lt_u32_e64 s[66:67], 5, v200
	v_cmp_lt_u32_e64 s[94:95], 6, v200
	v_cndmask_b32_e64 v206, 0, v192, s[38:39]
	v_add_u32_e32 v205, v205, v206
	v_cndmask_b32_e64 v206, 0, v193, s[40:41]
	v_add_u32_e32 v205, v205, v206
	v_cndmask_b32_e64 v206, 0, v194, s[42:43]
	v_add_u32_e32 v205, v205, v206
	v_cndmask_b32_e64 v206, 0, v195, s[44:45]
	v_add_u32_e32 v205, v205, v206
	v_cndmask_b32_e64 v206, 0, v196, s[64:65]
	v_add_u32_e32 v205, v205, v206
	v_cndmask_b32_e64 v206, 0, v197, s[66:67]
	v_add_u32_e32 v205, v205, v206
	v_cndmask_b32_e64 v206, 0, v198, s[94:95]
	v_add_u32_e32 v205, v205, v206
	v_sub_u32_e32 v205, v205, v204
	v_lshrrev_b32_e32 v208, 4, v240
	v_and_b32_e32 v222, 31, v208
	v_lshrrev_b32_e32 v208, 5, v208
	v_add_u32_e32 v207, 0, v208
	v_lshl_add_u32 v206, v207, 5, s3
	ds_read_b128 v[192:195], v206
	ds_read_b128 v[196:199], v206 offset:16
	v_lshlrev_b32_e32 v206, 2, v222
	v_lshlrev_b32_e32 v223, 3, v207
	s_waitcnt lgkmcnt(0)
; __device__ __forceinline__ void peer_tile(const Args& A, LAS unsigned char* lds, int tile) {
;     ...
;     for (int ti = 0; ti < 8; ++ti) {
;         const int tl = 8 * w + ti;
;         const u32x2 e0 = SEL[tl * 128 + lane], e1 = SEL[tl * 128 + 64 + lane];
;         const int p0 = (int)(e0.x >> 10), p1 = (int)(e1.x >> 10);
;         int off = 0;
;         for (int p = 0; p < 16; ++p) {
;             const unsigned long long m0 = __ballot(p0 == p), m1 = __ballot(p1 == p);
;             const int c0 = __popcll(m0), c1 = __popcll(m1);
;             const int r0 = __builtin_amdgcn_mbcnt_hi((unsigned)(m0 >> 32), __builtin_amdgcn_mbcnt_lo((unsigned)m0, 0u));
;             const int r1 = __builtin_amdgcn_mbcnt_hi((unsigned)(m1 >> 32), __builtin_amdgcn_mbcnt_lo((unsigned)m1, 0u));
;             if (p0 == p) SORT[tl * 128 + off + r0] = e0;
;             if (p1 == p) SORT[tl * 128 + off + c0 + r1] = e1;
;             if (lane == 0) OFFS[tl * 17 + p] = off;
;             off += c0 + c1;
;         }
;         if (lane == 0) OFFS[tl * 17 + 16] = off;
;     }
	v_cmp_le_u32_e64 s[38:39], v193, v206
	v_cmp_le_u32_e64 s[40:41], v194, v206
	v_cmp_le_u32_e64 s[42:43], v195, v206
	v_cmp_le_u32_e64 s[44:45], v196, v206
	v_cmp_le_u32_e64 s[64:65], v197, v206
	v_cmp_le_u32_e64 s[66:67], v198, v206
	v_cmp_le_u32_e64 s[94:95], v199, v206
	v_addc_co_u32_e64 v223, s[92:93], 0, v223, s[38:39]
	v_addc_co_u32_e64 v223, s[92:93], 0, v223, s[40:41]
	v_addc_co_u32_e64 v223, s[92:93], 0, v223, s[42:43]
	v_addc_co_u32_e64 v223, s[92:93], 0, v223, s[44:45]
	v_addc_co_u32_e64 v223, s[92:93], 0, v223, s[64:65]
	v_addc_co_u32_e64 v223, s[92:93], 0, v223, s[66:67]
	v_addc_co_u32_e64 v223, s[92:93], 0, v223, s[94:95]
	v_lshlrev_b32_e32 v223, 2, v223
	ds_bpermute_b32 v216, v223, v205
	v_add_u32_e32 v207, 2, v208
	v_lshl_add_u32 v206, v207, 5, s3
	ds_read_b128 v[192:195], v206
	ds_read_b128 v[196:199], v206 offset:16
	v_lshlrev_b32_e32 v206, 2, v222
	v_lshlrev_b32_e32 v223, 3, v207
	s_waitcnt lgkmcnt(0)
	v_cmp_le_u32_e64 s[38:39], v193, v206
	v_cmp_le_u32_e64 s[40:41], v194, v206
	v_cmp_le_u32_e64 s[42:43], v195, v206
	v_cmp_le_u32_e64 s[44:45], v196, v206
	v_cmp_le_u32_e64 s[64:65], v197, v206
	v_cmp_le_u32_e64 s[66:67], v198, v206
	v_cmp_le_u32_e64 s[94:95], v199, v206
	v_addc_co_u32_e64 v223, s[92:93], 0, v223, s[38:39]
	v_addc_co_u32_e64 v223, s[92:93], 0, v223, s[40:41]
	v_addc_co_u32_e64 v223, s[92:93], 0, v223, s[42:43]
	v_addc_co_u32_e64 v223, s[92:93], 0, v223, s[44:45]
	v_addc_co_u32_e64 v223, s[92:93], 0, v223, s[64:65]
	v_addc_co_u32_e64 v223, s[92:93], 0, v223, s[66:67]
	v_addc_co_u32_e64 v223, s[92:93], 0, v223, s[94:95]
	v_lshlrev_b32_e32 v223, 2, v223
	ds_bpermute_b32 v217, v223, v205
	v_add_u32_e32 v207, 4, v208
	v_lshl_add_u32 v206, v207, 5, s3
	ds_read_b128 v[192:195], v206
	ds_read_b128 v[196:199], v206 offset:16
	v_lshlrev_b32_e32 v206, 2, v222
	v_lshlrev_b32_e32 v223, 3, v207
	s_waitcnt lgkmcnt(0)
	v_cmp_le_u32_e64 s[38:39], v193, v206
	v_cmp_le_u32_e64 s[40:41], v194, v206
	v_cmp_le_u32_e64 s[42:43], v195, v206
	v_cmp_le_u32_e64 s[44:45], v196, v206
	v_cmp_le_u32_e64 s[64:65], v197, v206
	v_cmp_le_u32_e64 s[66:67], v198, v206
	v_cmp_le_u32_e64 s[94:95], v199, v206
	v_addc_co_u32_e64 v223, s[92:93], 0, v223, s[38:39]
	v_addc_co_u32_e64 v223, s[92:93], 0, v223, s[40:41]
	v_addc_co_u32_e64 v223, s[92:93], 0, v223, s[42:43]
	v_addc_co_u32_e64 v223, s[92:93], 0, v223, s[44:45]
	v_addc_co_u32_e64 v223, s[92:93], 0, v223, s[64:65]
	v_addc_co_u32_e64 v223, s[92:93], 0, v223, s[66:67]
	v_addc_co_u32_e64 v223, s[92:93], 0, v223, s[94:95]
	v_lshlrev_b32_e32 v223, 2, v223
	ds_bpermute_b32 v218, v223, v205
	v_add_u32_e32 v207, 6, v208
	v_lshl_add_u32 v206, v207, 5, s3
	ds_read_b128 v[192:195], v206
	ds_read_b128 v[196:199], v206 offset:16
	v_lshlrev_b32_e32 v206, 2, v222
	v_lshlrev_b32_e32 v223, 3, v207
	s_waitcnt lgkmcnt(0)
	v_cmp_le_u32_e64 s[38:39], v193, v206
	v_cmp_le_u32_e64 s[40:41], v194, v206
	v_cmp_le_u32_e64 s[42:43], v195, v206
	v_cmp_le_u32_e64 s[44:45], v196, v206
	v_cmp_le_u32_e64 s[64:65], v197, v206
	v_cmp_le_u32_e64 s[66:67], v198, v206
	v_cmp_le_u32_e64 s[94:95], v199, v206
	v_addc_co_u32_e64 v223, s[92:93], 0, v223, s[38:39]
	v_addc_co_u32_e64 v223, s[92:93], 0, v223, s[40:41]
	v_addc_co_u32_e64 v223, s[92:93], 0, v223, s[42:43]
	v_addc_co_u32_e64 v223, s[92:93], 0, v223, s[44:45]
	v_addc_co_u32_e64 v223, s[92:93], 0, v223, s[64:65]
	v_addc_co_u32_e64 v223, s[92:93], 0, v223, s[66:67]
	v_addc_co_u32_e64 v223, s[92:93], 0, v223, s[94:95]
	v_lshlrev_b32_e32 v223, 2, v223
	ds_bpermute_b32 v219, v223, v205
	s_waitcnt lgkmcnt(0)
	v_add_u32_e32 v216, v216, v222
	v_add_u32_e32 v217, v217, v222
	v_add_u32_e32 v218, v218, v222
	v_add_u32_e32 v219, v219, v222
	v_lshlrev_b32_e32 v206, 3, v152
	buffer_load_dwordx2 v[192:193], v206, s[24:27], 0 offen
	v_lshlrev_b32_e32 v206, 3, v154
	buffer_load_dwordx2 v[194:195], v206, s[24:27], 0 offen
	v_lshlrev_b32_e32 v206, 3, v156
	buffer_load_dwordx2 v[196:197], v206, s[24:27], 0 offen
	v_lshlrev_b32_e32 v206, 3, v158
	buffer_load_dwordx2 v[198:199], v206, s[24:27], 0 offen
	v_lshlrev_b32_e32 v160, 2, v160
	ds_bpermute_b32 v160, v160, v202
	v_lshlrev_b32_e32 v161, 2, v161
	ds_bpermute_b32 v161, v161, v202
	v_lshlrev_b32_e32 v162, 2, v162
	v_add_u32_e32 v162, 32, v162
	ds_bpermute_b32 v162, v162, v202
	v_lshlrev_b32_e32 v163, 2, v163
	v_add_u32_e32 v163, 32, v163
	ds_bpermute_b32 v163, v163, v202
	v_lshlrev_b32_e32 v164, 2, v164
	v_add_u32_e32 v164, 64, v164
	ds_bpermute_b32 v164, v164, v202
	v_lshlrev_b32_e32 v165, 2, v165
	v_add_u32_e32 v165, 64, v165
	ds_bpermute_b32 v165, v165, v202
	v_lshlrev_b32_e32 v166, 2, v166
	v_add_u32_e32 v166, 96, v166
	ds_bpermute_b32 v166, v166, v202
	v_lshlrev_b32_e32 v167, 2, v167
	v_add_u32_e32 v167, 96, v167
	ds_bpermute_b32 v167, v167, v202
	v_lshlrev_b32_e32 v168, 2, v168
	v_add_u32_e32 v168, 128, v168
	ds_bpermute_b32 v168, v168, v202
	v_lshlrev_b32_e32 v169, 2, v169
	v_add_u32_e32 v169, 128, v169
	ds_bpermute_b32 v169, v169, v202
	v_lshlrev_b32_e32 v170, 2, v170
	v_add_u32_e32 v170, 160, v170
	ds_bpermute_b32 v170, v170, v202
	v_lshlrev_b32_e32 v171, 2, v171
	v_add_u32_e32 v171, 160, v171
	ds_bpermute_b32 v171, v171, v202
	v_lshlrev_b32_e32 v172, 2, v172
	v_add_u32_e32 v172, 192, v172
	ds_bpermute_b32 v172, v172, v202
	v_lshlrev_b32_e32 v173, 2, v173
	v_add_u32_e32 v173, 192, v173
	ds_bpermute_b32 v173, v173, v202
	v_lshlrev_b32_e32 v174, 2, v174
	v_add_u32_e32 v174, 224, v174
	ds_bpermute_b32 v174, v174, v202
	v_lshlrev_b32_e32 v175, 2, v175
	v_add_u32_e32 v175, 224, v175
	ds_bpermute_b32 v175, v175, v202
	s_waitcnt lgkmcnt(0)
; __device__ __forceinline__ void peer_tile(const Args& A, LAS unsigned char* lds, int tile) {
;     ...
;     for (int ti = 0; ti < 8; ++ti) {
;         const int tl = 8 * w + ti;
;         const u32x2 e0 = SEL[tl * 128 + lane], e1 = SEL[tl * 128 + 64 + lane];
;         const int p0 = (int)(e0.x >> 10), p1 = (int)(e1.x >> 10);
;         int off = 0;
;         for (int p = 0; p < 16; ++p) {
;             const unsigned long long m0 = __ballot(p0 == p), m1 = __ballot(p1 == p);
;             const int c0 = __popcll(m0), c1 = __popcll(m1);
;             const int r0 = __builtin_amdgcn_mbcnt_hi((unsigned)(m0 >> 32), __builtin_amdgcn_mbcnt_lo((unsigned)m0, 0u));
;             const int r1 = __builtin_amdgcn_mbcnt_hi((unsigned)(m1 >> 32), __builtin_amdgcn_mbcnt_lo((unsigned)m1, 0u));
;             if (p0 == p) SORT[tl * 128 + off + r0] = e0;
;             if (p1 == p) SORT[tl * 128 + off + c0 + r1] = e1;
;             if (lane == 0) OFFS[tl * 17 + p] = off;
;             off += c0 + c1;
;         }
;         if (lane == 0) OFFS[tl * 17 + 16] = off;
;     }
	v_add_u32_e32 v176, v176, v160
	v_lshrrev_b32_e32 v160, 2, v176
	v_and_b32_e32 v176, 3, v176
	v_lshlrev_b32_e32 v160, 2, v160
	ds_bpermute_b32 v160, v160, v216
	v_add_u32_e32 v177, v177, v161
	v_lshrrev_b32_e32 v161, 2, v177
	v_and_b32_e32 v177, 3, v177
	v_lshlrev_b32_e32 v161, 2, v161
	ds_bpermute_b32 v161, v161, v216
	v_add_u32_e32 v178, v178, v162
	v_lshrrev_b32_e32 v162, 2, v178
	v_and_b32_e32 v178, 3, v178
	v_lshlrev_b32_e32 v162, 2, v162
	v_add_u32_e32 v162, 128, v162
	ds_bpermute_b32 v162, v162, v216
	v_add_u32_e32 v179, v179, v163
	v_lshrrev_b32_e32 v163, 2, v179
	v_and_b32_e32 v179, 3, v179
	v_lshlrev_b32_e32 v163, 2, v163
	v_add_u32_e32 v163, 128, v163
	ds_bpermute_b32 v163, v163, v216
	v_add_u32_e32 v180, v180, v164
	v_lshrrev_b32_e32 v164, 2, v180
	v_and_b32_e32 v180, 3, v180
	v_lshlrev_b32_e32 v164, 2, v164
	ds_bpermute_b32 v164, v164, v217
	v_add_u32_e32 v181, v181, v165
	v_lshrrev_b32_e32 v165, 2, v181
	v_and_b32_e32 v181, 3, v181
	v_lshlrev_b32_e32 v165, 2, v165
	ds_bpermute_b32 v165, v165, v217
	v_add_u32_e32 v182, v182, v166
	v_lshrrev_b32_e32 v166, 2, v182
	v_and_b32_e32 v182, 3, v182
	v_lshlrev_b32_e32 v166, 2, v166
	v_add_u32_e32 v166, 128, v166
	ds_bpermute_b32 v166, v166, v217
	v_add_u32_e32 v183, v183, v167
	v_lshrrev_b32_e32 v167, 2, v183
	v_and_b32_e32 v183, 3, v183
	v_lshlrev_b32_e32 v167, 2, v167
	v_add_u32_e32 v167, 128, v167
	ds_bpermute_b32 v167, v167, v217
	v_add_u32_e32 v184, v184, v168
	v_lshrrev_b32_e32 v168, 2, v184
	v_and_b32_e32 v184, 3, v184
	v_lshlrev_b32_e32 v168, 2, v168
	ds_bpermute_b32 v168, v168, v218
	v_add_u32_e32 v185, v185, v169
	v_lshrrev_b32_e32 v169, 2, v185
	v_and_b32_e32 v185, 3, v185
	v_lshlrev_b32_e32 v169, 2, v169
	ds_bpermute_b32 v169, v169, v218
	v_add_u32_e32 v186, v186, v170
	v_lshrrev_b32_e32 v170, 2, v186
	v_and_b32_e32 v186, 3, v186
	v_lshlrev_b32_e32 v170, 2, v170
	v_add_u32_e32 v170, 128, v170
	ds_bpermute_b32 v170, v170, v218
	v_add_u32_e32 v187, v187, v171
	v_lshrrev_b32_e32 v171, 2, v187
	v_and_b32_e32 v187, 3, v187
	v_lshlrev_b32_e32 v171, 2, v171
	v_add_u32_e32 v171, 128, v171
	ds_bpermute_b32 v171, v171, v218
	v_add_u32_e32 v188, v188, v172
	v_lshrrev_b32_e32 v172, 2, v188
	v_and_b32_e32 v188, 3, v188
	v_lshlrev_b32_e32 v172, 2, v172
	ds_bpermute_b32 v172, v172, v219
	v_add_u32_e32 v189, v189, v173
	v_lshrrev_b32_e32 v173, 2, v189
	v_and_b32_e32 v189, 3, v189
	v_lshlrev_b32_e32 v173, 2, v173
	ds_bpermute_b32 v173, v173, v219
	v_add_u32_e32 v190, v190, v174
	v_lshrrev_b32_e32 v174, 2, v190
	v_and_b32_e32 v190, 3, v190
	v_lshlrev_b32_e32 v174, 2, v174
	v_add_u32_e32 v174, 128, v174
	ds_bpermute_b32 v174, v174, v219
	v_add_u32_e32 v191, v191, v175
	v_lshrrev_b32_e32 v175, 2, v191
	v_and_b32_e32 v191, 3, v191
	v_lshlrev_b32_e32 v175, 2, v175
	v_add_u32_e32 v175, 128, v175
	ds_bpermute_b32 v175, v175, v219
	s_waitcnt lgkmcnt(0)
	v_lshl_add_u32 v160, v160, 4, s22
	v_lshl_add_u32 v160, v176, 2, v160
	ds_write_b32 v160, v128
	ds_write_b32 v160, v129 offset:4992
	v_lshl_add_u32 v161, v161, 4, s22
	v_lshl_add_u32 v161, v177, 2, v161
	ds_write_b32 v161, v130
	ds_write_b32 v161, v131 offset:4992
	v_lshl_add_u32 v162, v162, 4, s22
	v_lshl_add_u32 v162, v178, 2, v162
	ds_write_b32 v162, v132
	ds_write_b32 v162, v133 offset:4992
	v_lshl_add_u32 v163, v163, 4, s22
	v_lshl_add_u32 v163, v179, 2, v163
	ds_write_b32 v163, v134
	ds_write_b32 v163, v135 offset:4992
	v_lshl_add_u32 v164, v164, 4, s22
	v_lshl_add_u32 v164, v180, 2, v164
	ds_write_b32 v164, v136
	ds_write_b32 v164, v137 offset:4992
	v_lshl_add_u32 v165, v165, 4, s22
	v_lshl_add_u32 v165, v181, 2, v165
	ds_write_b32 v165, v138
	ds_write_b32 v165, v139 offset:4992
	v_lshl_add_u32 v166, v166, 4, s22
	v_lshl_add_u32 v166, v182, 2, v166
	ds_write_b32 v166, v140
	ds_write_b32 v166, v141 offset:4992
	v_lshl_add_u32 v167, v167, 4, s22
	v_lshl_add_u32 v167, v183, 2, v167
	ds_write_b32 v167, v142
	ds_write_b32 v167, v143 offset:4992
	v_lshl_add_u32 v168, v168, 4, s22
	v_lshl_add_u32 v168, v184, 2, v168
	ds_write_b32 v168, v144
	ds_write_b32 v168, v145 offset:4992
	v_lshl_add_u32 v169, v169, 4, s22
	v_lshl_add_u32 v169, v185, 2, v169
	ds_write_b32 v169, v146
	ds_write_b32 v169, v147 offset:4992
	v_lshl_add_u32 v170, v170, 4, s22
	v_lshl_add_u32 v170, v186, 2, v170
	ds_write_b32 v170, v148
	ds_write_b32 v170, v149 offset:4992
	v_lshl_add_u32 v171, v171, 4, s22
	v_lshl_add_u32 v171, v187, 2, v171
	ds_write_b32 v171, v150
	ds_write_b32 v171, v151 offset:4992
	v_lshl_add_u32 v172, v172, 4, s22
	v_lshl_add_u32 v172, v188, 2, v172
	ds_write_b32 v172, v152
	ds_write_b32 v172, v153 offset:4992
	v_lshl_add_u32 v173, v173, 4, s22
	v_lshl_add_u32 v173, v189, 2, v173
	ds_write_b32 v173, v154
	ds_write_b32 v173, v155 offset:4992
	v_lshl_add_u32 v174, v174, 4, s22
	v_lshl_add_u32 v174, v190, 2, v174
	ds_write_b32 v174, v156
	ds_write_b32 v174, v157 offset:4992
	v_lshl_add_u32 v175, v175, 4, s22
	v_lshl_add_u32 v175, v191, 2, v175
	ds_write_b32 v175, v158
	ds_write_b32 v175, v159 offset:4992
	s_waitcnt vmcnt(0)
; #define IT_ADVANCE() do { it_j += 4; while (it_j >= it_end) { if (it_done) break; ++it_tk; if (it_tk == 4) { it_tk = 0; ++it_p; if (it_p == 16) { it_done = true; it_p = 15; it_j = 0; it_end = 1; break; } } \
;             it_j = __builtin_amdgcn_readfirstlane(OFFS[(tb + it_tk) * 17 + it_p]); it_end = __builtin_amdgcn_readfirstlane(OFFS[(tb + it_tk) * 17 + it_p + 1]); } } while (0)
; __device__ __forceinline__ void peer_tile(const Args& A, LAS unsigned char* lds, int tile) {
;     ...
;         int it_p = 0, it_tk = -1, it_j = 0, it_end = 0; bool it_done = false;
;     ...
;         u32x4 uA[4], vA[4], uB[4], vB[4]; float cgA = 0.f, suA = 0.f, svA = 0.f, cgB = 0.f, suB = 0.f, svB = 0.f;
; #pragma unroll
;         for (int k = 0; k < 4; ++k) { uA[k] = (u32x4){0u, 0u, 0u, 0u}; vA[k] = uA[k]; uB[k] = uA[k]; vB[k] = uA[k]; }
;         IT_ADVANCE();
;         LOAD_SET(uA, vA, cgA, suA, svA);
	v_add_u32_e32 v160, s85, v160
	ds_write_b32 v160, v224
	ds_write_b32 v160, v225 offset:4096
	v_add_u32_e32 v161, s85, v161
	ds_write_b32 v161, v226
	ds_write_b32 v161, v227 offset:4096
	v_add_u32_e32 v162, s85, v162
	ds_write_b32 v162, v228
	ds_write_b32 v162, v229 offset:4096
	v_add_u32_e32 v163, s85, v163
	ds_write_b32 v163, v230
	ds_write_b32 v163, v231 offset:4096
	v_add_u32_e32 v164, s85, v164
	ds_write_b32 v164, v232
	ds_write_b32 v164, v233 offset:4096
	v_add_u32_e32 v165, s85, v165
	ds_write_b32 v165, v234
	ds_write_b32 v165, v235 offset:4096
	v_add_u32_e32 v166, s85, v166
	ds_write_b32 v166, v236
	ds_write_b32 v166, v237 offset:4096
	v_add_u32_e32 v167, s85, v167
	ds_write_b32 v167, v238
	ds_write_b32 v167, v239 offset:4096
	v_add_u32_e32 v168, s85, v168
	ds_write_b32 v168, v248
	ds_write_b32 v168, v249 offset:4096
	v_add_u32_e32 v169, s85, v169
	ds_write_b32 v169, v250
	ds_write_b32 v169, v251 offset:4096
	v_add_u32_e32 v170, s85, v170
	ds_write_b32 v170, v252
	ds_write_b32 v170, v253 offset:4096
	v_add_u32_e32 v171, s85, v171
	ds_write_b32 v171, v254
	ds_write_b32 v171, v255 offset:4096
	v_add_u32_e32 v172, s85, v172
	ds_write_b32 v172, v192
	ds_write_b32 v172, v193 offset:4096
	v_add_u32_e32 v173, s85, v173
	ds_write_b32 v173, v194
	ds_write_b32 v173, v195 offset:4096
	v_add_u32_e32 v174, s85, v174
	ds_write_b32 v174, v196
	ds_write_b32 v174, v197 offset:4096
	v_add_u32_e32 v175, s85, v175
	ds_write_b32 v175, v198
	ds_write_b32 v175, v199 offset:4096
	v_mov_b32_e32 v206, 0x7fffffff
	ds_write_b32 v221, v206 offset:4224
	ds_write_b32 v221, v206 offset:4480
	ds_write_b32 v221, v206 offset:4736
	s_mov_b32 s91, 256
	s_add_i32 s20, s91, 3
	s_and_b32 s20, s20, -4
	s_mov_b32 s24, s8
	s_and_b32 s25, s9, 0xffff
	s_mov_b32 s26, 0x20000
	s_mov_b32 s27, 0x00027000
	s_mov_b32 s28, s52
	s_and_b32 s29, s53, 0xffff
	s_mov_b32 s30, 0x20000
	s_mov_b32 s31, 0x00027000
	s_waitcnt vmcnt(0) lgkmcnt(0)
	v_mov_b32_e32 v213, s22
	v_mov_b32_e32 v233, v240
	v_mov_b32_e32 v235, v240
	v_mov_b32_e32 v237, v240
	v_mov_b32_e32 v239, v240
	ds_read_b32 v232, v213 offset:0
	ds_read_b32 v234, v213 offset:4
	ds_read_b32 v236, v213 offset:8
	ds_read_b32 v238, v213 offset:12
	s_waitcnt lgkmcnt(0)
	buffer_load_dwordx4 v[128:131], v[232:233], s[56:59], 0 idxen offen
	buffer_load_dwordx4 v[132:135], v[234:235], s[56:59], 0 idxen offen
	buffer_load_dwordx4 v[136:139], v[236:237], s[56:59], 0 idxen offen
	buffer_load_dwordx4 v[140:143], v[238:239], s[56:59], 0 idxen offen
	ds_read_b32 v232, v213 offset:16
	ds_read_b32 v234, v213 offset:20
	ds_read_b32 v236, v213 offset:24
	ds_read_b32 v238, v213 offset:28
	s_waitcnt lgkmcnt(0)
	buffer_load_dwordx4 v[144:147], v[232:233], s[56:59], 0 idxen offen
	buffer_load_dwordx4 v[148:151], v[234:235], s[56:59], 0 idxen offen
	buffer_load_dwordx4 v[152:155], v[236:237], s[56:59], 0 idxen offen
	buffer_load_dwordx4 v[156:159], v[238:239], s[56:59], 0 idxen offen
	ds_read_b32 v232, v213 offset:32
	ds_read_b32 v234, v213 offset:36
	ds_read_b32 v236, v213 offset:40
	ds_read_b32 v238, v213 offset:44
	s_waitcnt lgkmcnt(0)
	buffer_load_dwordx4 v[160:163], v[232:233], s[56:59], 0 idxen offen
	buffer_load_dwordx4 v[164:167], v[234:235], s[56:59], 0 idxen offen
	buffer_load_dwordx4 v[168:171], v[236:237], s[56:59], 0 idxen offen
	buffer_load_dwordx4 v[172:175], v[238:239], s[56:59], 0 idxen offen
	ds_read_b32 v232, v213 offset:48
	ds_read_b32 v234, v213 offset:52
	ds_read_b32 v236, v213 offset:56
	ds_read_b32 v238, v213 offset:60
	s_mov_b32 s21, 0
	s_mov_b32 s89, -1
	s_mov_b32 s86, 0
	v_lshrrev_b32_e32 v208, 6, v240
	v_and_b32_e32 v208, 3, v208
	v_lshrrev_b32_e32 v209, 1, v208
	v_lshlrev_b32_e32 v208, 1, v208
	v_and_b32_e32 v208, 2, v208
	v_or_b32_e32 v208, v208, v209
	v_lshlrev_b32_e32 v208, 2, v208
	v_add3_u32 v211, v208, v247, s22
	v_add_u32_e32 v250, s85, v211
	ds_read_b32 v252, v250
	ds_read_b32 v253, v250 offset:4096
	ds_read_b32 v249, v211 offset:4992
	s_branch .LU_sw0
